# v93 stack + software-pipelined LDS reads in the GLA phases (ldspipe)
# speedup vs baseline: 1.0186x; 1.0056x over previous
.LBB0_464:
	s_waitcnt lgkmcnt(0)
	ds_read_b128 v[94:97], v149 offset:6144
	ds_read_b128 v[98:101], v149 offset:6160
	s_waitcnt vmcnt(5)
	v_lshlrev_b32_e32 v102, 16, v22
	v_and_b32_e32 v103, 0xffff0000, v22
	s_add_i32 s46, s47, s46
	s_waitcnt lgkmcnt(1)
	v_mul_f32_e32 v94, 0xbfb8aa3b, v94
	v_mul_f32_e32 v95, 0xbfb8aa3b, v95
	v_exp_f32_e32 v94, v94
	v_exp_f32_e32 v95, v95
	v_mul_f32_e32 v22, 0xbfb8aa3b, v96
	v_exp_f32_e32 v96, v22
	v_mul_f32_e32 v22, 0xbfb8aa3b, v97
	v_exp_f32_e32 v97, v22
	v_pk_mul_f32 v[94:95], v[94:95], v[102:103]
	s_add_i32 s83, s83, 1
	v_cvt_pk_bf16_f32 v22, v94, v95
	v_lshlrev_b32_e32 v94, 16, v23
	v_and_b32_e32 v95, 0xffff0000, v23
	s_waitcnt lgkmcnt(0)
	v_mul_f32_e32 v23, 0xbfb8aa3b, v98
	v_pk_mul_f32 v[94:95], v[96:97], v[94:95]
	v_exp_f32_e32 v96, v23
	v_mul_f32_e32 v23, 0xbfb8aa3b, v99
	v_exp_f32_e32 v97, v23
	v_cvt_pk_bf16_f32 v23, v94, v95
	v_lshlrev_b32_e32 v94, 16, v24
	v_and_b32_e32 v95, 0xffff0000, v24
	v_mul_f32_e32 v24, 0xbfb8aa3b, v100
	v_pk_mul_f32 v[94:95], v[96:97], v[94:95]
	v_exp_f32_e32 v96, v24
	v_mul_f32_e32 v24, 0xbfb8aa3b, v101
	v_exp_f32_e32 v97, v24
	v_cvt_pk_bf16_f32 v24, v94, v95
	v_lshlrev_b32_e32 v94, 16, v25
	v_and_b32_e32 v95, 0xffff0000, v25
	v_pk_mul_f32 v[94:95], v[96:97], v[94:95]
	s_waitcnt vmcnt(4)
	v_lshlrev_b32_e32 v98, 16, v6
	v_cvt_pk_bf16_f32 v25, v94, v95
	ds_write_b128 v150, v[22:25] offset:56320
	ds_read_b128 v[224:227], v151 offset:6144
	ds_read_b128 v[94:97], v151 offset:6160
	v_and_b32_e32 v99, 0xffff0000, v6
	s_mul_i32 s53, s46, 0x1800
	s_mul_hi_i32 s52, s46, 0x1800
	s_waitcnt lgkmcnt(1)
	v_mul_f32_e32 v22, 0xbfb8aa3b, v224
	v_mul_f32_e32 v23, 0xbfb8aa3b, v225
	v_exp_f32_e32 v22, v22
	v_exp_f32_e32 v23, v23
	v_mul_f32_e32 v6, 0xbfb8aa3b, v226
	v_exp_f32_e32 v24, v6
	v_mul_f32_e32 v6, 0xbfb8aa3b, v227
	v_exp_f32_e32 v25, v6
	v_pk_mul_f32 v[22:23], v[22:23], v[98:99]
	s_add_u32 s50, s80, s53
	v_cvt_pk_bf16_f32 v6, v22, v23
	v_lshlrev_b32_e32 v22, 16, v7
	v_and_b32_e32 v23, 0xffff0000, v7
	s_waitcnt lgkmcnt(0)
	v_mul_f32_e32 v7, 0xbfb8aa3b, v94
	v_pk_mul_f32 v[22:23], v[24:25], v[22:23]
	v_exp_f32_e32 v24, v7
	v_mul_f32_e32 v7, 0xbfb8aa3b, v95
	v_exp_f32_e32 v25, v7
	v_cvt_pk_bf16_f32 v7, v22, v23
	v_lshlrev_b32_e32 v22, 16, v8
	v_and_b32_e32 v23, 0xffff0000, v8
	v_mul_f32_e32 v8, 0xbfb8aa3b, v96
	v_pk_mul_f32 v[22:23], v[24:25], v[22:23]
	v_exp_f32_e32 v24, v8
	v_mul_f32_e32 v8, 0xbfb8aa3b, v97
	v_exp_f32_e32 v25, v8
	v_cvt_pk_bf16_f32 v8, v22, v23
	v_lshlrev_b32_e32 v22, 16, v9
	v_and_b32_e32 v23, 0xffff0000, v9
	v_pk_mul_f32 v[22:23], v[24:25], v[22:23]
	s_addc_u32 s51, s81, s52
	v_cvt_pk_bf16_f32 v9, v22, v23
	ds_write_b128 v152, v[6:9] offset:56320
	s_waitcnt vmcnt(3)
	ds_write_b128 v153, v[2:5]
	s_waitcnt vmcnt(2)
	ds_write_b128 v155, v[10:13]
	s_waitcnt vmcnt(1)
	ds_write_b128 v153, v[14:17] offset:16896
	s_waitcnt vmcnt(0)
	ds_write_b128 v156, v[18:21]
	v_lshl_add_u64 v[2:3], s[50:51], 0, v[112:113]
	s_add_u32 s50, s38, s53
	s_addc_u32 s51, s39, s52
	s_add_u32 s50, s50, s76
	s_addc_u32 s51, s51, 0
	s_add_u32 s50, s50, 0xad20800
	global_load_dwordx4 v[22:25], v[2:3], off offset:1024
	v_add_co_u32_e32 v2, vcc, s63, v2
	s_addc_u32 s51, s51, 0
	s_nop 0
	v_addc_co_u32_e32 v3, vcc, 0, v3, vcc
	v_lshl_add_u64 v[18:19], s[50:51], 0, v[114:115]
	v_add_co_u32_e32 v10, vcc, s64, v18
	global_load_dwordx4 v[6:9], v[2:3], off offset:1024
	s_nop 0
	v_addc_co_u32_e32 v11, vcc, 0, v19, vcc
	v_add_co_u32_e32 v14, vcc, s63, v18
	global_load_dwordx4 v[2:5], v[18:19], off
	s_nop 0
	v_addc_co_u32_e32 v15, vcc, 0, v19, vcc
	v_add_co_u32_e32 v18, vcc, s65, v18
	global_load_dwordx4 v[10:13], v[10:11], off
	s_nop 0
	v_addc_co_u32_e32 v19, vcc, 0, v19, vcc
	global_load_dwordx4 v[14:17], v[14:15], off
	v_lshl_add_u32 v167, s87, 9, v128
	global_load_dwordx4 v[18:21], v[18:19], off
	s_waitcnt lgkmcnt(0)
	s_barrier
	s_waitcnt lgkmcnt(0)
	ds_read_b64_tr_b16 v[96:97], v158 offset:57408
	ds_read_b64_tr_b16 v[94:95], v158 offset:56320
	ds_read_b64_tr_b16 v[108:109], v157 offset:2112
	ds_read_b64_tr_b16 v[106:107], v157
	ds_read_b64_tr_b16 v[102:103], v157 offset:32
	ds_read_b64_tr_b16 v[104:105], v157 offset:2144
	ds_read_b64_tr_b16 v[224:225], v158 offset:65024
	ds_read_b64_tr_b16 v[226:227], v159 offset:57408
	ds_read_b64_tr_b16 v[98:99], v157 offset:16896
	ds_read_b64_tr_b16 v[100:101], v157 offset:19008
	s_waitcnt lgkmcnt(6)
	v_mfma_f32_16x16x32_bf16 v[70:73], v[94:97], v[106:109], v[70:73]
	s_nop 0
	s_nop 0
	s_nop 0
	s_cmp_eq_u32 s43, s83
	s_waitcnt lgkmcnt(4)
	v_mfma_f32_16x16x32_bf16 v[74:77], v[94:97], v[102:105], v[74:77]
	ds_read_b64_tr_b16 v[94:95], v157 offset:16928
	ds_read_b64_tr_b16 v[96:97], v157 offset:19040
	ds_read_b64_tr_b16 v[172:173], v158 offset:56352
	ds_read_b64_tr_b16 v[174:175], v158 offset:57440
	ds_read_b64_tr_b16 v[230:231], v159 offset:57440
	ds_read_b64_tr_b16 v[228:229], v158 offset:65056
	ds_read_b64_tr_b16 v[232:233], v158 offset:56384
	ds_read_b64_tr_b16 v[234:235], v158 offset:57472
	ds_read_b64_tr_b16 v[236:237], v158 offset:65088
	ds_read_b64_tr_b16 v[238:239], v159 offset:57472
	ds_read_b64_tr_b16 v[244:245], v158 offset:56416
	ds_read_b64_tr_b16 v[246:247], v158 offset:57504
	s_nop 0
	s_nop 0
	s_nop 0
	s_nop 0
	s_nop 0
	s_waitcnt lgkmcnt(12)
	v_mfma_f32_16x16x32_bf16 v[70:73], v[224:227], v[98:101], v[70:73]
	s_waitcnt lgkmcnt(10)
	v_mfma_f32_16x16x32_bf16 v[74:77], v[224:227], v[94:97], v[74:77]
	ds_read_b64_tr_b16 v[224:225], v158 offset:65120
	ds_read_b64_tr_b16 v[226:227], v159 offset:57504
	s_nop 0
	s_nop 0
	s_waitcnt lgkmcnt(10)
	v_mfma_f32_16x16x32_bf16 v[58:61], v[172:175], v[106:109], v[58:61]
	v_mfma_f32_16x16x32_bf16 v[82:85], v[172:175], v[102:105], v[82:85]
	s_waitcnt lgkmcnt(8)
	v_mfma_f32_16x16x32_bf16 v[58:61], v[228:231], v[98:101], v[58:61]
	v_mfma_f32_16x16x32_bf16 v[82:85], v[228:231], v[94:97], v[82:85]
	ds_read_b64_tr_b16 v[228:229], v158 offset:56448
	ds_read_b64_tr_b16 v[230:231], v158 offset:57536
	s_nop 0
	s_nop 0
	s_waitcnt lgkmcnt(8)
	v_mfma_f32_16x16x32_bf16 v[66:69], v[232:235], v[106:109], v[66:69]
	v_mfma_f32_16x16x32_bf16 v[78:81], v[232:235], v[102:105], v[78:81]
	ds_read_b64_tr_b16 v[232:233], v158 offset:65152
	ds_read_b64_tr_b16 v[234:235], v159 offset:57536
	s_nop 0
	s_nop 0
	s_waitcnt lgkmcnt(8)
	v_mfma_f32_16x16x32_bf16 v[66:69], v[236:239], v[98:101], v[66:69]
	v_mfma_f32_16x16x32_bf16 v[78:81], v[236:239], v[94:97], v[78:81]
	ds_read_b64_tr_b16 v[236:237], v158 offset:56480
	ds_read_b64_tr_b16 v[238:239], v158 offset:57568
	s_nop 0
	s_nop 0
	s_waitcnt lgkmcnt(8)
	v_mfma_f32_16x16x32_bf16 v[62:65], v[244:247], v[106:109], v[62:65]
	v_mfma_f32_16x16x32_bf16 v[86:89], v[244:247], v[102:105], v[86:89]
	ds_read_b64_tr_b16 v[244:245], v158 offset:65184
	ds_read_b64_tr_b16 v[246:247], v159 offset:57568
	s_nop 0
	s_nop 0
	s_waitcnt lgkmcnt(8)
	v_mfma_f32_16x16x32_bf16 v[62:65], v[224:227], v[98:101], v[62:65]
	v_mfma_f32_16x16x32_bf16 v[86:89], v[224:227], v[94:97], v[86:89]
	ds_read_b64_tr_b16 v[224:225], v158 offset:56512
	ds_read_b64_tr_b16 v[226:227], v158 offset:57600
	s_nop 0
	s_nop 0
	s_waitcnt lgkmcnt(8)
	v_mfma_f32_16x16x32_bf16 v[38:41], v[228:231], v[106:109], v[38:41]
	v_mfma_f32_16x16x32_bf16 v[50:53], v[228:231], v[102:105], v[50:53]
	ds_read_b64_tr_b16 v[228:229], v158 offset:65216
	ds_read_b64_tr_b16 v[230:231], v159 offset:57600
	s_nop 0
	s_nop 0
	s_waitcnt lgkmcnt(8)
	v_mfma_f32_16x16x32_bf16 v[38:41], v[232:235], v[98:101], v[38:41]
	v_mfma_f32_16x16x32_bf16 v[50:53], v[232:235], v[94:97], v[50:53]
	ds_read_b64_tr_b16 v[232:233], v158 offset:56544
	ds_read_b64_tr_b16 v[234:235], v158 offset:57632
	s_nop 0
	s_nop 0
	s_waitcnt lgkmcnt(8)
	v_mfma_f32_16x16x32_bf16 v[30:33], v[236:239], v[106:109], v[30:33]
	v_mfma_f32_16x16x32_bf16 v[54:57], v[236:239], v[102:105], v[54:57]
	s_nop 0
	s_nop 0
	s_waitcnt lgkmcnt(6)
	v_mfma_f32_16x16x32_bf16 v[30:33], v[244:247], v[98:101], v[30:33]
	v_mfma_f32_16x16x32_bf16 v[54:57], v[244:247], v[94:97], v[54:57]
	s_nop 0
	s_nop 0
	s_waitcnt lgkmcnt(4)
	v_mfma_f32_16x16x32_bf16 v[42:45], v[224:227], v[106:109], v[42:45]
	v_mfma_f32_16x16x32_bf16 v[46:49], v[224:227], v[102:105], v[46:49]
	s_nop 0
	s_nop 0
	s_waitcnt lgkmcnt(2)
	v_mfma_f32_16x16x32_bf16 v[42:45], v[228:231], v[98:101], v[42:45]
	v_mfma_f32_16x16x32_bf16 v[46:49], v[228:231], v[94:97], v[46:49]
	s_nop 0
	s_nop 0
	s_waitcnt lgkmcnt(0)
	v_mfma_f32_16x16x32_bf16 v[34:37], v[232:235], v[106:109], v[34:37]
	ds_read_b64_tr_b16 v[106:107], v158 offset:65248
	ds_read_b64_tr_b16 v[108:109], v159 offset:57632
	ds_read_b128 v[168:171], v167 offset:4096
	ds_read_b128 v[236:239], v167 offset:4160
	ds_read_b128 v[244:247], v167 offset:4224
	ds_read_b128 v[224:227], v167 offset:4288
	ds_read_b128 v[228:231], v167 offset:4352
	v_mfma_f32_16x16x32_bf16 v[102:105], v[232:235], v[102:105], v[26:29]
	ds_read_b128 v[232:235], v167 offset:4416
	s_nop 0
	s_waitcnt lgkmcnt(6)
	v_mfma_f32_16x16x32_bf16 v[26:29], v[106:109], v[98:101], v[34:37]
	s_nop 1
	s_nop 0
	s_waitcnt lgkmcnt(5)
	v_mov_b32_e32 v98, v168
	s_nop 0
	v_mov_b32_e32 v99, v169
	s_nop 0
	v_mov_b32_e32 v100, v170
	s_nop 0
	v_mov_b32_e32 v101, v171
	s_nop 0
	v_mfma_f32_16x16x32_bf16 v[94:97], v[106:109], v[94:97], v[102:105]
	v_mul_f32_e64 v70, v70, v98
	v_mul_f32_e64 v71, v71, v99
	v_pk_mul_f32 v[74:75], v[74:75], v[98:99]
	v_pk_mul_f32 v[72:73], v[72:73], v[100:101]
	s_nop 0
	s_waitcnt lgkmcnt(4)
	v_mov_b32_e32 v102, v236
	s_nop 0
	v_mov_b32_e32 v103, v237
	s_nop 0
	v_mov_b32_e32 v104, v238
	s_nop 0
	v_mov_b32_e32 v105, v239
	ds_read_b128 v[236:239], v167 offset:4480
	s_nop 0
	v_pk_mul_f32 v[76:77], v[76:77], v[100:101]
	v_pk_mul_f32 v[58:59], v[58:59], v[102:103]
	v_pk_mul_f32 v[82:83], v[82:83], v[102:103]
	v_pk_mul_f32 v[60:61], v[60:61], v[104:105]
	s_nop 0
	s_waitcnt lgkmcnt(4)
	v_mov_b32_e32 v98, v244
	s_nop 0
	v_mov_b32_e32 v99, v245
	s_nop 0
	v_mov_b32_e32 v100, v246
	s_nop 0
	v_mov_b32_e32 v101, v247
	ds_read_b128 v[244:247], v167 offset:4544
	s_nop 0
	v_pk_mul_f32 v[84:85], v[84:85], v[104:105]
	v_pk_mul_f32 v[66:67], v[66:67], v[98:99]
	v_pk_mul_f32 v[78:79], v[78:79], v[98:99]
	v_pk_mul_f32 v[68:69], v[68:69], v[100:101]
	s_nop 0
	s_waitcnt lgkmcnt(4)
	v_mov_b32_e32 v102, v224
	s_nop 0
	v_mov_b32_e32 v103, v225
	s_nop 0
	v_mov_b32_e32 v104, v226
	s_nop 0
	v_mov_b32_e32 v105, v227
	s_nop 0
	v_pk_mul_f32 v[80:81], v[80:81], v[100:101]
	v_pk_mul_f32 v[62:63], v[62:63], v[102:103]
	v_pk_mul_f32 v[86:87], v[86:87], v[102:103]
	v_pk_mul_f32 v[64:65], v[64:65], v[104:105]
	s_nop 0
	s_waitcnt lgkmcnt(3)
	v_mov_b32_e32 v98, v228
	s_nop 0
	v_mov_b32_e32 v99, v229
	s_nop 0
	v_mov_b32_e32 v100, v230
	s_nop 0
	v_mov_b32_e32 v101, v231
	s_nop 0
	v_pk_mul_f32 v[88:89], v[88:89], v[104:105]
	v_pk_mul_f32 v[38:39], v[38:39], v[98:99]
	v_pk_mul_f32 v[50:51], v[50:51], v[98:99]
	v_pk_mul_f32 v[40:41], v[40:41], v[100:101]
	s_nop 0
	s_waitcnt lgkmcnt(2)
	v_mov_b32_e32 v102, v232
	s_nop 0
	v_mov_b32_e32 v103, v233
	s_nop 0
	v_mov_b32_e32 v104, v234
	s_nop 0
	v_mov_b32_e32 v105, v235
	s_nop 0
	v_pk_mul_f32 v[52:53], v[52:53], v[100:101]
	v_pk_mul_f32 v[30:31], v[30:31], v[102:103]
	v_pk_mul_f32 v[54:55], v[54:55], v[102:103]
	v_pk_mul_f32 v[32:33], v[32:33], v[104:105]
	s_nop 0
	s_waitcnt lgkmcnt(1)
	v_mov_b32_e32 v98, v236
	s_nop 0
	v_mov_b32_e32 v99, v237
	s_nop 0
	v_mov_b32_e32 v100, v238
	s_nop 0
	v_mov_b32_e32 v101, v239
	s_nop 0
	v_pk_mul_f32 v[56:57], v[56:57], v[104:105]
	v_pk_mul_f32 v[42:43], v[42:43], v[98:99]
	v_pk_mul_f32 v[44:45], v[44:45], v[100:101]
	v_pk_mul_f32 v[48:49], v[48:49], v[100:101]
	s_nop 0
	s_waitcnt lgkmcnt(0)
	v_mov_b32_e32 v102, v244
	v_mov_b32_e32 v34, v245
	v_mov_b32_e32 v35, v246
	v_mov_b32_e32 v104, v35
	s_nop 0
	v_mov_b32_e32 v105, v247
	v_mov_b32_e32 v103, v34
	v_pk_mul_f32 v[46:47], v[46:47], v[98:99]
	v_pk_mul_f32 v[36:37], v[28:29], v[104:105]
	v_pk_mul_f32 v[34:35], v[26:27], v[102:103]
	v_pk_mul_f32 v[28:29], v[96:97], v[104:105]
	v_pk_mul_f32 v[26:27], v[94:95], v[102:103]
	s_waitcnt lgkmcnt(0)
	s_cbranch_scc1 .LBB0_480
.LBB0_465:
	s_and_b32 s87, s83, 1
	s_cmp_eq_u32 s87, 0
	s_cselect_b64 s[50:51], -1, 0
	s_and_b64 s[30:31], s[50:51], exec
	s_cselect_b32 s30, 0xf0, s67
	v_and_b32_e32 v98, 63, v154
	v_lshl_add_u32 v98, v98, 2, s30
	s_waitcnt lgkmcnt(0)
	ds_read2st64_b32 v[100:101], v98 offset1:1
	ds_read2st64_b32 v[102:103], v98 offset0:2 offset1:3
	ds_read2st64_b32 v[104:105], v98 offset0:4 offset1:5
	ds_read2st64_b32 v[108:109], v98 offset0:8 offset1:9
	ds_read2st64_b32 v[224:225], v98 offset0:6 offset1:7
	ds_read2st64_b32 v[228:229], v98 offset0:10 offset1:11
	ds_read2st64_b32 v[232:233], v98 offset0:12 offset1:13
	ds_read2st64_b32 v[236:237], v98 offset0:14 offset1:15
	s_mov_b64 s[52:53], -1
	s_waitcnt lgkmcnt(7)
	v_mfma_f32_16x16x4_f32 v[94:97], v100, v166, 0
	s_andn2_b64 vcc, exec, s[48:49]
	v_mfma_f32_16x16x4_f32 v[94:97], v101, v165, v[94:97]
	s_waitcnt lgkmcnt(6)
	v_mfma_f32_16x16x4_f32 v[94:97], v102, v164, v[94:97]
	v_mfma_f32_16x16x4_f32 v[94:97], v103, v163, v[94:97]
	s_waitcnt lgkmcnt(5)
	v_mfma_f32_16x16x4_f32 v[100:103], v104, v166, 0
	s_nop 7
	v_add_f32_e32 v94, v162, v94
	v_min_f32_e32 v99, 0, v94
	v_mul_f32_e64 v94, |v94|, s68
	v_exp_f32_e32 v94, v94
	v_add_f32_e32 v95, v162, v95
	v_add_f32_e32 v96, v162, v96
	v_add_f32_e32 v97, v162, v97
	v_add_f32_e32 v94, 1.0, v94
	v_log_f32_e32 v94, v94
	v_mfma_f32_16x16x4_f32 v[100:103], v105, v165, v[100:103]
	s_nop 0
	v_fmac_f32_e32 v99, 0xbf317218, v94
	v_mul_f32_e32 v94, 0x3d800000, v99
	v_min_f32_e32 v99, 0, v95
	v_mul_f32_e64 v95, |v95|, s68
	v_exp_f32_e32 v95, v95
	s_waitcnt lgkmcnt(3)
	v_mfma_f32_16x16x4_f32 v[100:103], v224, v164, v[100:103]
	v_add_f32_e32 v95, 1.0, v95
	v_log_f32_e32 v95, v95
	s_nop 0
	v_fmac_f32_e32 v99, 0xbf317218, v95
	v_mul_f32_e32 v95, 0x3d800000, v99
	v_min_f32_e32 v99, 0, v96
	v_mul_f32_e64 v96, |v96|, s68
	v_exp_f32_e32 v96, v96
	v_mfma_f32_16x16x4_f32 v[100:103], v225, v163, v[100:103]
	v_add_f32_e32 v96, 1.0, v96
	v_log_f32_e32 v96, v96
	s_nop 0
	v_fmac_f32_e32 v99, 0xbf317218, v96
	v_mul_f32_e32 v96, 0x3d800000, v99
	v_min_f32_e32 v99, 0, v97
	v_mul_f32_e64 v97, |v97|, s68
	v_exp_f32_e32 v97, v97
	v_mfma_f32_16x16x4_f32 v[104:107], v108, v166, 0
	v_add_f32_e32 v97, 1.0, v97
	v_log_f32_e32 v97, v97
	s_nop 0
	v_fmac_f32_e32 v99, 0xbf317218, v97
	v_mul_f32_e32 v97, 0x3d800000, v99
	v_add_f32_e32 v99, v162, v100
	v_min_f32_e32 v100, 0, v99
	v_mul_f32_e64 v99, |v99|, s68
	v_exp_f32_e32 v99, v99
	v_mfma_f32_16x16x4_f32 v[104:107], v109, v165, v[104:107]
	s_nop 0
	v_add_f32_e32 v99, 1.0, v99
	v_log_f32_e32 v99, v99
	s_nop 0
	v_fmac_f32_e32 v100, 0xbf317218, v99
	v_mul_f32_e32 v99, 0x3d800000, v100
	v_add_f32_e32 v100, v162, v101
	v_min_f32_e32 v101, 0, v100
	v_mul_f32_e64 v100, |v100|, s68
	v_exp_f32_e32 v100, v100
	s_waitcnt lgkmcnt(2)
	v_mfma_f32_16x16x4_f32 v[104:107], v228, v164, v[104:107]
	v_add_f32_e32 v100, 1.0, v100
	v_log_f32_e32 v100, v100
	s_nop 0
	v_fmac_f32_e32 v101, 0xbf317218, v100
	v_mul_f32_e32 v100, 0x3d800000, v101
	v_add_f32_e32 v101, v162, v102
	v_min_f32_e32 v102, 0, v101
	v_mul_f32_e64 v101, |v101|, s68
	v_exp_f32_e32 v101, v101
	v_mfma_f32_16x16x4_f32 v[104:107], v229, v163, v[104:107]
	s_nop 0
	v_add_f32_e32 v101, 1.0, v101
	v_log_f32_e32 v101, v101
	s_nop 0
	v_fmac_f32_e32 v102, 0xbf317218, v101
	v_mul_f32_e32 v101, 0x3d800000, v102
	v_add_f32_e32 v102, v162, v103
	v_min_f32_e32 v103, 0, v102
	v_mul_f32_e64 v102, |v102|, s68
	v_exp_f32_e32 v102, v102
	s_waitcnt lgkmcnt(1)
	v_mfma_f32_16x16x4_f32 v[168:171], v232, v166, 0
	v_add_f32_e32 v102, 1.0, v102
	v_log_f32_e32 v102, v102
	s_nop 0
	v_fmac_f32_e32 v103, 0xbf317218, v102
	v_mul_f32_e32 v102, 0x3d800000, v103
	v_add_f32_e32 v103, v162, v104
	v_min_f32_e32 v104, 0, v103
	v_mul_f32_e64 v103, |v103|, s68
	v_exp_f32_e32 v103, v103
	v_mfma_f32_16x16x4_f32 v[168:171], v233, v165, v[168:171]
	s_nop 0
	v_add_f32_e32 v103, 1.0, v103
	v_log_f32_e32 v103, v103
	s_nop 0
	v_fmac_f32_e32 v104, 0xbf317218, v103
	v_mul_f32_e32 v103, 0x3d800000, v104
	v_add_f32_e32 v104, v162, v105
	v_min_f32_e32 v105, 0, v104
	v_mul_f32_e64 v104, |v104|, s68
	v_exp_f32_e32 v104, v104
	s_waitcnt lgkmcnt(0)
	v_mfma_f32_16x16x4_f32 v[168:171], v236, v164, v[168:171]
	v_add_f32_e32 v104, 1.0, v104
	v_log_f32_e32 v104, v104
	s_nop 0
	v_fmac_f32_e32 v105, 0xbf317218, v104
	v_mul_f32_e32 v104, 0x3d800000, v105
	v_add_f32_e32 v105, v162, v106
	v_min_f32_e32 v106, 0, v105
	v_mul_f32_e64 v105, |v105|, s68
	v_exp_f32_e32 v105, v105
	v_mfma_f32_16x16x4_f32 v[168:171], v237, v163, v[168:171]
	v_add_f32_e32 v105, 1.0, v105
	v_log_f32_e32 v105, v105
	s_nop 0
	v_fmac_f32_e32 v106, 0xbf317218, v105
	v_mul_f32_e32 v105, 0x3d800000, v106
	v_add_f32_e32 v106, v162, v107
	v_min_f32_e32 v107, 0, v106
	v_mul_f32_e64 v106, |v106|, s68
	v_exp_f32_e32 v106, v106
	s_nop 0
	v_add_f32_e32 v98, v162, v168
	v_add_f32_e32 v106, 1.0, v106
	v_log_f32_e32 v106, v106
	s_nop 0
	v_fmac_f32_e32 v107, 0xbf317218, v106
	v_mul_f32_e32 v106, 0x3d800000, v107
	v_min_f32_e32 v107, 0, v98
	v_mul_f32_e64 v98, |v98|, s68
	v_exp_f32_e32 v98, v98
	s_nop 0
	v_add_f32_e32 v98, 1.0, v98
	v_log_f32_e32 v98, v98
	s_nop 0
	v_fmac_f32_e32 v107, 0xbf317218, v98
	v_mul_f32_e32 v98, 0x3d800000, v107
	v_add_f32_e32 v107, v162, v169
	v_min_f32_e32 v108, 0, v107
	v_mul_f32_e64 v107, |v107|, s68
	v_exp_f32_e32 v107, v107
	s_nop 0
	v_add_f32_e32 v107, 1.0, v107
	v_log_f32_e32 v107, v107
	s_nop 0
	v_fmac_f32_e32 v108, 0xbf317218, v107
	v_mul_f32_e32 v107, 0x3d800000, v108
	v_add_f32_e32 v108, v162, v170
	v_min_f32_e32 v109, 0, v108
	v_mul_f32_e64 v108, |v108|, s68
	v_exp_f32_e32 v108, v108
	s_nop 0
	v_add_f32_e32 v108, 1.0, v108
	v_log_f32_e32 v108, v108
	s_nop 0
	v_fmac_f32_e32 v109, 0xbf317218, v108
	v_add_f32_e32 v108, v162, v171
	v_mul_f32_e32 v167, 0x3d800000, v109
	v_min_f32_e32 v109, 0, v108
	v_mul_f32_e64 v108, |v108|, s68
	v_exp_f32_e32 v108, v108
	s_nop 0
	v_add_f32_e32 v108, 1.0, v108
	v_log_f32_e32 v108, v108
	s_nop 0
	v_fmac_f32_e32 v109, 0xbf317218, v108
	v_cndmask_b32_e64 v108, 0, 1, s[48:49]
	v_mul_f32_e32 v182, 0x3d800000, v109
	v_cmp_ne_u32_e64 s[30:31], 1, v108
	s_waitcnt lgkmcnt(0)
	s_cbranch_vccnz .LBB0_467
	v_add_f32_e32 v108, 0, v182
	v_add_f32_e32 v109, v167, v108
	v_add_f32_e32 v168, v107, v109
	v_add_f32_e32 v169, v98, v168
	v_add_f32_e32 v170, v106, v169
	v_add_f32_e32 v171, v105, v170
	v_add_f32_e32 v172, v104, v171
	v_add_f32_e32 v173, v103, v172
	v_add_f32_e32 v174, v102, v173
	v_add_f32_e32 v175, v101, v174
	v_add_f32_e32 v176, v100, v175
	v_add_f32_e32 v177, v99, v176
	v_add_f32_e32 v178, v97, v177
	v_add_f32_e32 v179, v96, v178
	v_add_f32_e32 v180, v95, v179
	v_add_f32_e32 v181, v94, v180
	s_mov_b64 s[52:53], 0

.LBB0_480:
	v_and_b32_e32 v108, 63, v154
	v_lshl_add_u32 v108, v108, 2, s67
	s_waitcnt lgkmcnt(0)
	ds_read2st64_b32 v[94:95], v108 offset1:1
	ds_read2st64_b32 v[224:225], v108 offset0:2 offset1:3
	ds_read2st64_b32 v[226:227], v108 offset0:4 offset1:5
	ds_read2st64_b32 v[228:229], v108 offset0:6 offset1:7
	ds_read2st64_b32 v[232:233], v108 offset0:8 offset1:9
	ds_read2st64_b32 v[236:237], v108 offset0:10 offset1:11
	ds_read2st64_b32 v[244:245], v108 offset0:12 offset1:13
	s_and_b64 vcc, exec, s[30:31]
	s_mov_b64 s[46:47], -1
	s_waitcnt lgkmcnt(6)
	v_mfma_f32_16x16x4_f32 v[90:93], v94, v166, 0
	v_mfma_f32_16x16x4_f32 v[90:93], v95, v165, v[90:93]
	s_waitcnt lgkmcnt(5)
	v_mfma_f32_16x16x4_f32 v[90:93], v224, v164, v[90:93]
	s_waitcnt lgkmcnt(4)
	v_mfma_f32_16x16x4_f32 v[94:97], v226, v166, 0
	v_mfma_f32_16x16x4_f32 v[90:93], v225, v163, v[90:93]
	s_nop 9
	v_add_f32_e32 v98, v162, v92
	v_add_f32_e32 v99, v162, v93
	v_mfma_f32_16x16x4_f32 v[92:95], v227, v165, v[94:97]
	v_mul_f32_e64 v105, |v98|, s68
	v_exp_f32_e32 v96, v105
	v_add_f32_e32 v91, v162, v91
	v_add_f32_e32 v90, v162, v90
	v_min_f32_e32 v104, 0, v91
	v_add_f32_e32 v96, 1.0, v96
	v_log_f32_e32 v101, v96
	s_waitcnt lgkmcnt(3)
	v_mfma_f32_16x16x4_f32 v[94:97], v228, v164, v[92:95]
	v_mul_f32_e64 v91, |v91|, s68
	v_min_f32_e32 v100, 0, v90
	v_mul_f32_e64 v90, |v90|, s68
	v_exp_f32_e32 v91, v91
	v_mul_f32_e64 v92, |v99|, s68
	v_exp_f32_e32 v90, v90
	v_exp_f32_e32 v93, v92
	v_mfma_f32_16x16x4_f32 v[94:97], v229, v163, v[94:97]
	s_nop 0
	v_add_f32_e32 v91, 1.0, v91
	v_min_f32_e32 v92, 0, v98
	v_add_f32_e32 v90, 1.0, v90
	v_log_f32_e32 v91, v91
	v_add_f32_e32 v93, 1.0, v93
	v_log_f32_e32 v90, v90
	s_nop 2
	v_add_f32_e32 v94, v162, v94
	v_mul_f32_e64 v98, |v94|, s68
	v_exp_f32_e32 v98, v98
	v_log_f32_e32 v93, v93
	v_fmac_f32_e32 v104, 0xbf317218, v91
	v_min_f32_e32 v99, 0, v99
	v_add_f32_e32 v98, 1.0, v98
	v_add_f32_e32 v95, v162, v95
	v_fmac_f32_e32 v100, 0xbf317218, v90
	v_mul_f32_e32 v91, 0x3d800000, v104
	v_fmac_f32_e32 v99, 0xbf317218, v93
	v_log_f32_e32 v104, v98
	v_mul_f32_e64 v98, |v95|, s68
	v_mul_f32_e32 v90, 0x3d800000, v100
	v_fmac_f32_e32 v92, 0xbf317218, v101
	v_mul_f32_e32 v93, 0x3d800000, v99
	v_exp_f32_e32 v105, v98
	s_waitcnt lgkmcnt(2)
	v_mfma_f32_16x16x4_f32 v[98:101], v232, v166, 0
	v_min_f32_e32 v94, 0, v94
	v_fmac_f32_e32 v94, 0xbf317218, v104
	v_add_f32_e32 v102, 1.0, v105
	s_nop 0
	v_add_f32_e32 v106, v162, v96
	v_mul_f32_e64 v96, |v106|, s68
	v_exp_f32_e32 v96, v96
	v_mfma_f32_16x16x4_f32 v[98:101], v233, v165, v[98:101]
	v_log_f32_e32 v102, v102
	v_min_f32_e32 v95, 0, v95
	v_add_f32_e32 v96, 1.0, v96
	v_add_f32_e32 v103, v162, v97
	v_fmac_f32_e32 v95, 0xbf317218, v102
	v_log_f32_e32 v102, v96
	v_mul_f32_e32 v92, 0x3d800000, v92
	s_waitcnt lgkmcnt(1)
	v_mfma_f32_16x16x4_f32 v[96:99], v236, v164, v[98:101]
	s_nop 0
	v_mul_f32_e64 v100, |v103|, s68
	v_exp_f32_e32 v100, v100
	v_min_f32_e32 v104, 0, v106
	v_fmac_f32_e32 v104, 0xbf317218, v102
	s_nop 0
	v_add_f32_e32 v100, 1.0, v100
	v_log_f32_e32 v102, v100
	v_mfma_f32_16x16x4_f32 v[98:101], v237, v163, v[96:99]
	v_min_f32_e32 v103, 0, v103
	v_mul_f32_e32 v94, 0x3d800000, v94
	v_fmac_f32_e32 v103, 0xbf317218, v102
	v_mul_f32_e32 v95, 0x3d800000, v95
	s_nop 5
	v_add_f32_e32 v98, v162, v98
	v_mul_f32_e64 v96, |v98|, s68
	v_exp_f32_e32 v97, v96
	v_add_f32_e32 v99, v162, v99
	v_mul_f32_e32 v96, 0x3d800000, v104
	v_min_f32_e32 v98, 0, v98
	v_add_f32_e32 v97, 1.0, v97
	v_log_f32_e32 v102, v97
	v_mul_f32_e64 v97, |v99|, s68
	v_exp_f32_e32 v104, v97
	v_mul_f32_e32 v97, 0x3d800000, v103
	v_fmac_f32_e32 v98, 0xbf317218, v102
	v_min_f32_e32 v99, 0, v99
	v_add_f32_e32 v102, 1.0, v104
	v_log_f32_e32 v109, v102
	s_waitcnt lgkmcnt(0)
	v_mfma_f32_16x16x4_f32 v[102:105], v244, v166, 0
	v_add_f32_e32 v100, v162, v100
	v_min_f32_e32 v106, 0, v100
	v_fmac_f32_e32 v99, 0xbf317218, v109
	ds_read2st64_b32 v[108:109], v108 offset0:14 offset1:15
	v_mul_f32_e64 v100, |v100|, s68
	v_exp_f32_e32 v100, v100
	v_mul_f32_e32 v98, 0x3d800000, v98
	v_mfma_f32_16x16x4_f32 v[102:105], v245, v165, v[102:105]
	v_add_f32_e32 v107, v162, v101
	v_mul_f32_e64 v101, |v107|, s68
	v_add_f32_e32 v100, 1.0, v100
	v_exp_f32_e32 v165, v101
	v_log_f32_e32 v166, v100
	v_mul_f32_e32 v99, 0x3d800000, v99
	v_fmac_f32_e32 v106, 0xbf317218, v166
	s_waitcnt lgkmcnt(0)
	v_mfma_f32_16x16x4_f32 v[100:103], v108, v164, v[102:105]
	s_nop 0
	v_add_f32_e32 v104, 1.0, v165
	v_log_f32_e32 v104, v104
	v_min_f32_e32 v105, 0, v107
	v_mul_f32_e32 v168, 0x3d800000, v106
	v_fmac_f32_e32 v105, 0xbf317218, v104
	v_mul_f32_e32 v169, 0x3d800000, v105
	v_mfma_f32_16x16x4_f32 v[100:103], v109, v163, v[100:103]
	s_nop 9
	v_add_f32_e32 v100, v162, v100
	v_mul_f32_e64 v104, |v100|, s68
	v_exp_f32_e32 v104, v104
	v_add_f32_e32 v101, v162, v101
	v_mul_f32_e64 v105, |v101|, s68
	v_exp_f32_e32 v105, v105
	v_add_f32_e32 v104, 1.0, v104
	v_log_f32_e32 v104, v104
	v_min_f32_e32 v100, 0, v100
	v_add_f32_e32 v105, 1.0, v105
	v_log_f32_e32 v105, v105
	v_fmac_f32_e32 v100, 0xbf317218, v104
	v_mul_f32_e32 v170, 0x3d800000, v100
	v_min_f32_e32 v100, 0, v101
	v_fmac_f32_e32 v100, 0xbf317218, v105
	v_mul_f32_e32 v171, 0x3d800000, v100
	v_add_f32_e32 v100, v162, v102
	v_mul_f32_e64 v101, |v100|, s68
	v_exp_f32_e32 v101, v101
	v_add_f32_e32 v102, v162, v103
	v_mul_f32_e64 v103, |v102|, s68
	v_exp_f32_e32 v103, v103
	v_add_f32_e32 v101, 1.0, v101
	v_log_f32_e32 v101, v101
	v_min_f32_e32 v100, 0, v100
	v_add_f32_e32 v103, 1.0, v103
	v_log_f32_e32 v103, v103
	v_fmac_f32_e32 v100, 0xbf317218, v101
	v_mul_f32_e32 v172, 0x3d800000, v100
	v_min_f32_e32 v100, 0, v102
	v_fmac_f32_e32 v100, 0xbf317218, v103
	v_mul_f32_e32 v173, 0x3d800000, v100
	s_waitcnt lgkmcnt(0)
	s_cbranch_vccnz .LBB0_482
	v_add_f32_e32 v100, 0, v173
	v_add_f32_e32 v101, v172, v100
	v_add_f32_e32 v102, v171, v101
	v_add_f32_e32 v103, v170, v102
	v_add_f32_e32 v104, v169, v103
	v_add_f32_e32 v105, v168, v104
	v_add_f32_e32 v106, v99, v105
	v_add_f32_e32 v107, v98, v106
	v_add_f32_e32 v108, v97, v107
	v_add_f32_e32 v109, v96, v108
	v_add_f32_e32 v162, v95, v109
	v_add_f32_e32 v163, v94, v162
	v_add_f32_e32 v164, v93, v163
	v_add_f32_e32 v165, v92, v164
	v_add_f32_e32 v166, v91, v165
	v_add_f32_e32 v167, v90, v166
	s_mov_b64 s[46:47], 0

.LBB0_490:
	s_or_b64 exec, exec, s[30:31]
	s_waitcnt lgkmcnt(0)
	ds_read_b128 v[90:93], v149 offset:6144
	ds_read_b128 v[94:97], v149 offset:6160
	s_waitcnt vmcnt(5)
	v_lshlrev_b32_e32 v98, 16, v22
	v_and_b32_e32 v99, 0xffff0000, v22
	s_waitcnt lgkmcnt(1)
	v_mul_f32_e32 v90, 0xbfb8aa3b, v90
	v_mul_f32_e32 v91, 0xbfb8aa3b, v91
	v_exp_f32_e32 v90, v90
	v_exp_f32_e32 v91, v91
	v_mul_f32_e32 v22, 0xbfb8aa3b, v92
	v_exp_f32_e32 v92, v22
	v_mul_f32_e32 v22, 0xbfb8aa3b, v93
	v_exp_f32_e32 v93, v22
	v_pk_mul_f32 v[90:91], v[90:91], v[98:99]
	s_nop 0
	v_cvt_pk_bf16_f32 v22, v90, v91
	v_lshlrev_b32_e32 v90, 16, v23
	v_and_b32_e32 v91, 0xffff0000, v23
	s_waitcnt lgkmcnt(0)
	v_mul_f32_e32 v23, 0xbfb8aa3b, v94
	v_pk_mul_f32 v[90:91], v[92:93], v[90:91]
	v_exp_f32_e32 v92, v23
	v_mul_f32_e32 v23, 0xbfb8aa3b, v95
	v_exp_f32_e32 v93, v23
	v_cvt_pk_bf16_f32 v23, v90, v91
	v_lshlrev_b32_e32 v90, 16, v24
	v_and_b32_e32 v91, 0xffff0000, v24
	v_mul_f32_e32 v24, 0xbfb8aa3b, v96
	v_pk_mul_f32 v[90:91], v[92:93], v[90:91]
	v_exp_f32_e32 v92, v24
	v_mul_f32_e32 v24, 0xbfb8aa3b, v97
	v_exp_f32_e32 v93, v24
	v_cvt_pk_bf16_f32 v24, v90, v91
	v_lshlrev_b32_e32 v90, 16, v25
	v_and_b32_e32 v91, 0xffff0000, v25
	v_pk_mul_f32 v[90:91], v[92:93], v[90:91]
	s_waitcnt vmcnt(4)
	v_lshlrev_b32_e32 v94, 16, v6
	v_cvt_pk_bf16_f32 v25, v90, v91
	ds_write_b128 v150, v[22:25] offset:56320
	ds_read_b128 v[224:227], v151 offset:6144
	ds_read_b128 v[90:93], v151 offset:6160
	v_and_b32_e32 v95, 0xffff0000, v6
	s_waitcnt lgkmcnt(1)
	v_mul_f32_e32 v22, 0xbfb8aa3b, v224
	v_mul_f32_e32 v23, 0xbfb8aa3b, v225
	v_exp_f32_e32 v22, v22
	v_exp_f32_e32 v23, v23
	v_mul_f32_e32 v6, 0xbfb8aa3b, v226
	v_exp_f32_e32 v24, v6
	v_mul_f32_e32 v6, 0xbfb8aa3b, v227
	v_exp_f32_e32 v25, v6
	v_pk_mul_f32 v[22:23], v[22:23], v[94:95]
	s_nop 0
	v_cvt_pk_bf16_f32 v6, v22, v23
	v_lshlrev_b32_e32 v22, 16, v7
	v_and_b32_e32 v23, 0xffff0000, v7
	s_waitcnt lgkmcnt(0)
	v_mul_f32_e32 v7, 0xbfb8aa3b, v90
	v_pk_mul_f32 v[22:23], v[24:25], v[22:23]
	v_exp_f32_e32 v24, v7
	v_mul_f32_e32 v7, 0xbfb8aa3b, v91
	v_exp_f32_e32 v25, v7
	v_cvt_pk_bf16_f32 v7, v22, v23
	v_lshlrev_b32_e32 v22, 16, v8
	v_and_b32_e32 v23, 0xffff0000, v8
	v_mul_f32_e32 v8, 0xbfb8aa3b, v92
	v_pk_mul_f32 v[22:23], v[24:25], v[22:23]
	v_exp_f32_e32 v24, v8
	v_mul_f32_e32 v8, 0xbfb8aa3b, v93
	v_exp_f32_e32 v25, v8
	v_cvt_pk_bf16_f32 v8, v22, v23
	v_lshlrev_b32_e32 v22, 16, v9
	v_and_b32_e32 v23, 0xffff0000, v9
	v_pk_mul_f32 v[22:23], v[24:25], v[22:23]
	s_nop 0
	v_cvt_pk_bf16_f32 v9, v22, v23
	ds_write_b128 v152, v[6:9] offset:56320
	s_waitcnt vmcnt(3)
	ds_write_b128 v153, v[2:5]
	s_waitcnt vmcnt(2)
	ds_write_b128 v155, v[10:13]
	s_waitcnt vmcnt(1)
	ds_write_b128 v153, v[14:17] offset:16896
	s_waitcnt vmcnt(0)
	ds_write_b128 v156, v[18:21]
	s_waitcnt lgkmcnt(0)
	s_barrier
	s_waitcnt lgkmcnt(0)
	ds_read_b64_tr_b16 v[4:5], v158 offset:57408
	ds_read_b64_tr_b16 v[2:3], v158 offset:56320
	ds_read_b64_tr_b16 v[8:9], v157 offset:2112
	ds_read_b64_tr_b16 v[6:7], v157
	ds_read_b64_tr_b16 v[12:13], v157 offset:2144
	ds_read_b64_tr_b16 v[10:11], v157 offset:32
	ds_read_b64_tr_b16 v[14:15], v158 offset:56352
	ds_read_b64_tr_b16 v[18:19], v158 offset:56384
	ds_read_b64_tr_b16 v[22:23], v158 offset:56416
	ds_read_b64_tr_b16 v[16:17], v158 offset:57440
	ds_read_b64_tr_b16 v[20:21], v158 offset:57472
	ds_read_b64_tr_b16 v[24:25], v158 offset:57504
	ds_read_b64_tr_b16 v[224:225], v158 offset:65024
	ds_read_b64_tr_b16 v[226:227], v159 offset:57408
	ds_read_b64_tr_b16 v[94:95], v157 offset:16896
	ds_read_b64_tr_b16 v[96:97], v157 offset:19008
	ds_read_b64_tr_b16 v[100:101], v157 offset:19040
	ds_read_b64_tr_b16 v[98:99], v157 offset:16928
	ds_read_b64_tr_b16 v[228:229], v158 offset:65056
	ds_read_b64_tr_b16 v[102:103], v158 offset:65088
	ds_read_b64_tr_b16 v[106:107], v158 offset:65120
	ds_read_b64_tr_b16 v[230:231], v159 offset:57440
	ds_read_b64_tr_b16 v[104:105], v159 offset:57472
	ds_read_b64_tr_b16 v[108:109], v159 offset:57504
	ds_read_b64_tr_b16 v[232:233], v158 offset:56448
	ds_read_b64_tr_b16 v[234:235], v158 offset:57536
	s_waitcnt lgkmcnt(15)
	v_mfma_f32_16x16x32_bf16 v[58:61], v[14:17], v[6:9], v[58:61]
	v_mfma_f32_16x16x32_bf16 v[14:17], v[14:17], v[10:13], v[82:85]
	v_mfma_f32_16x16x32_bf16 v[70:73], v[2:5], v[6:9], v[70:73]
	v_mfma_f32_16x16x32_bf16 v[2:5], v[2:5], v[10:13], v[74:77]
	s_nop 2
	s_nop 0
	s_nop 0
	s_nop 0
	s_nop 0
	s_nop 0
	s_nop 0
	s_waitcnt lgkmcnt(4)
	v_mfma_f32_16x16x32_bf16 v[58:61], v[228:231], v[94:97], v[58:61]
	v_mfma_f32_16x16x32_bf16 v[14:17], v[228:231], v[98:101], v[14:17]
	s_nop 0
	s_nop 0
	v_mfma_f32_16x16x32_bf16 v[66:69], v[18:21], v[6:9], v[66:69]
	v_mfma_f32_16x16x32_bf16 v[18:21], v[18:21], v[10:13], v[78:81]
	ds_read_b64_tr_b16 v[78:79], v158 offset:56480
	ds_read_b64_tr_b16 v[82:83], v158 offset:56512
	v_mfma_f32_16x16x32_bf16 v[62:65], v[22:25], v[6:9], v[62:65]
	v_mfma_f32_16x16x32_bf16 v[22:25], v[22:25], v[10:13], v[86:89]
	ds_read_b64_tr_b16 v[86:87], v158 offset:56544
	ds_read_b64_tr_b16 v[80:81], v158 offset:57568
	ds_read_b64_tr_b16 v[84:85], v158 offset:57600
	ds_read_b64_tr_b16 v[88:89], v158 offset:57632
	ds_read_b64_tr_b16 v[90:91], v158 offset:65152
	ds_read_b64_tr_b16 v[92:93], v159 offset:57536
	ds_read_b64_tr_b16 v[236:237], v158 offset:65184
	s_nop 0
	s_nop 0
	s_nop 0
	s_nop 0
	s_nop 0
	s_nop 0
	s_nop 0
	s_waitcnt lgkmcnt(4)
	v_mfma_f32_16x16x32_bf16 v[42:45], v[82:85], v[6:9], v[42:45]
	v_mfma_f32_16x16x32_bf16 v[46:49], v[82:85], v[10:13], v[46:49]
	v_add_u32_e32 v82, s43, v128
	s_ashr_i32 s43, s42, 31
	s_lshl_b64 s[30:31], s[42:43], 17
	v_mfma_f32_16x16x32_bf16 v[70:73], v[224:227], v[94:97], v[70:73]
	v_mfma_f32_16x16x32_bf16 v[2:5], v[224:227], v[98:101], v[2:5]
	s_nop 0
	s_nop 0
	v_mfma_f32_16x16x32_bf16 v[66:69], v[102:105], v[94:97], v[66:69]
	v_mfma_f32_16x16x32_bf16 v[18:21], v[102:105], v[98:101], v[18:21]
	ds_read_b64_tr_b16 v[102:103], v158 offset:65216
	v_mfma_f32_16x16x32_bf16 v[62:65], v[106:109], v[94:97], v[62:65]
	v_mfma_f32_16x16x32_bf16 v[22:25], v[106:109], v[98:101], v[22:25]
	ds_read_b64_tr_b16 v[106:107], v158 offset:65248
	ds_read_b64_tr_b16 v[238:239], v159 offset:57568
	ds_read_b64_tr_b16 v[104:105], v159 offset:57600
	ds_read_b64_tr_b16 v[108:109], v159 offset:57632
	ds_read_b128 v[244:247], v82 offset:4096
	ds_read_b128 v[228:231], v82 offset:4160
	ds_read_b128 v[224:227], v82 offset:4224
	v_mfma_f32_16x16x32_bf16 v[38:41], v[232:235], v[6:9], v[38:41]
	v_mfma_f32_16x16x32_bf16 v[50:53], v[232:235], v[10:13], v[50:53]
	ds_read_b128 v[232:235], v82 offset:4288
	s_nop 0
	s_nop 0
	s_nop 0
	s_nop 0
	s_nop 0
	s_nop 0
	v_mfma_f32_16x16x32_bf16 v[54:57], v[78:81], v[10:13], v[54:57]
	s_waitcnt lgkmcnt(12)
	v_mfma_f32_16x16x32_bf16 v[10:13], v[86:89], v[10:13], v[26:29]
	s_nop 2
	s_nop 0
	v_mfma_f32_16x16x32_bf16 v[30:33], v[78:81], v[6:9], v[30:33]
	v_mfma_f32_16x16x32_bf16 v[6:9], v[86:89], v[6:9], v[34:37]
	s_nop 2
	s_nop 0
	s_nop 0
	s_waitcnt lgkmcnt(6)
	v_mfma_f32_16x16x32_bf16 v[30:33], v[236:239], v[94:97], v[30:33]
	s_nop 0
	v_mfma_f32_16x16x32_bf16 v[54:57], v[236:239], v[98:101], v[54:57]
	ds_read_b128 v[236:239], v82 offset:4352
	s_waitcnt lgkmcnt(4)
	v_mov_b32_e32 v74, v244
	v_mov_b32_e32 v26, v245
	v_mov_b32_e32 v27, v246
	v_mov_b32_e32 v76, v27
	s_nop 0
	v_mov_b32_e32 v77, v247
	ds_read_b128 v[244:247], v82 offset:4416
	v_mov_b32_e32 v75, v26
	v_mfma_f32_16x16x32_bf16 v[38:41], v[90:93], v[94:97], v[38:41]
	v_mul_f32_e64 v28, v72, v76
	v_mul_f32_e64 v29, v73, v77
	v_pk_mul_f32 v[4:5], v[4:5], v[76:77]
	s_waitcnt lgkmcnt(4)
	v_mov_b32_e32 v76, v228
	v_mov_b32_e32 v34, v229
	v_mov_b32_e32 v35, v230
	v_mov_b32_e32 v78, v35
	s_nop 0
	v_mov_b32_e32 v79, v231
	v_mov_b32_e32 v77, v34
	s_nop 0
	v_pk_mul_f32 v[26:27], v[70:71], v[74:75]
	s_nop 0
	v_pk_mul_f32 v[2:3], v[2:3], v[74:75]
	v_pk_mul_f32 v[60:61], v[60:61], v[78:79]
	s_nop 0
	s_waitcnt lgkmcnt(3)
	v_mov_b32_e32 v74, v224
	v_mov_b32_e32 v34, v225
	v_mov_b32_e32 v35, v226
	v_mov_b32_e32 v75, v34
	v_mov_b32_e32 v80, v35
	s_nop 0
	v_mov_b32_e32 v81, v227
	v_pk_mul_f32 v[34:35], v[66:67], v[74:75]
	s_waitcnt lgkmcnt(2)
	v_mov_b32_e32 v66, v232
	v_mov_b32_e32 v67, v234
	v_pk_mul_f32 v[58:59], v[58:59], v[76:77]
	v_pk_mul_f32 v[16:17], v[16:17], v[78:79]
	v_pk_mul_f32 v[14:15], v[14:15], v[76:77]
	v_mov_b32_e32 v76, v66
	v_mov_b32_e32 v66, v233
	v_mov_b32_e32 v78, v67
	v_mov_b32_e32 v67, v235
	v_pk_mul_f32 v[36:37], v[68:69], v[80:81]
	v_mov_b32_e32 v79, v67
	v_mov_b32_e32 v77, v66
	s_nop 0
	s_nop 0
	v_pk_mul_f32 v[18:19], v[18:19], v[74:75]
	v_mfma_f32_16x16x32_bf16 v[50:53], v[90:93], v[98:101], v[50:53]
	v_mul_f32_e64 v64, v64, v78
	v_mul_f32_e64 v65, v65, v79
	s_nop 0
	s_waitcnt lgkmcnt(1)
	v_mov_b32_e32 v74, v236
	v_mov_b32_e32 v75, v237
	v_mov_b32_e32 v66, v238
	v_mov_b32_e32 v67, v239
	s_nop 0
	s_nop 0
	v_pk_mul_f32 v[62:63], v[62:63], v[76:77]
	v_pk_mul_f32 v[24:25], v[24:25], v[78:79]
	v_pk_mul_f32 v[22:23], v[22:23], v[76:77]
	v_pk_mul_f32 v[40:41], v[40:41], v[66:67]
	v_pk_mul_f32 v[52:53], v[52:53], v[66:67]
	s_waitcnt lgkmcnt(0)
	v_mov_b32_e32 v66, v244
	v_mov_b32_e32 v67, v246
	v_mov_b32_e32 v76, v66
	v_mov_b32_e32 v66, v245
	v_mov_b32_e32 v78, v67
	s_nop 0
	v_mov_b32_e32 v79, v247
	v_mov_b32_e32 v77, v66
	ds_read_b128 v[66:69], v82 offset:4480
	ds_read_b128 v[70:73], v82 offset:4544
	v_mfma_f32_16x16x32_bf16 v[42:45], v[102:105], v[94:97], v[42:45]
	v_mul_f32_e64 v20, v20, v80
	v_mul_f32_e64 v21, v21, v81
	s_nop 0
	s_nop 0
	s_nop 0
	v_mfma_f32_16x16x32_bf16 v[46:49], v[102:105], v[98:101], v[46:49]
	s_nop 0
	s_nop 0
	v_pk_mul_f32 v[38:39], v[38:39], v[74:75]
	v_pk_mul_f32 v[50:51], v[50:51], v[74:75]
	s_nop 0
	s_waitcnt lgkmcnt(1)
	v_pk_mul_f32 v[42:43], v[42:43], v[66:67]
	s_nop 1
	v_pk_mul_f32 v[46:47], v[46:47], v[66:67]
	v_lshl_add_u64 v[66:67], v[120:121], 0, s[30:31]
	s_movk_i32 s30, 0x2000
	global_store_dwordx4 v[66:67], v[26:29], off
	s_nop 0
	v_pk_mul_f32 v[32:33], v[32:33], v[78:79]
	v_add_co_u32_e32 v26, vcc, s30, v66
	s_movk_i32 s30, 0x4000
	s_nop 0
	v_addc_co_u32_e32 v27, vcc, 0, v67, vcc
	global_store_dwordx4 v[26:27], v[2:5], off
	v_pk_mul_f32 v[30:31], v[30:31], v[76:77]
	s_nop 0
	v_add_co_u32_e32 v2, vcc, s30, v66
	s_movk_i32 s30, 0x6000
	s_nop 0
	v_addc_co_u32_e32 v3, vcc, 0, v67, vcc
	global_store_dwordx4 v[2:3], v[58:61], off
	v_add_co_u32_e32 v2, vcc, s30, v66
	s_nop 0
	s_nop 0
	v_addc_co_u32_e32 v3, vcc, 0, v67, vcc
	global_store_dwordx4 v[2:3], v[14:17], off
	v_add_co_u32_e32 v2, vcc, s62, v66
	v_pk_mul_f32 v[56:57], v[56:57], v[78:79]
	s_nop 0
	v_addc_co_u32_e32 v3, vcc, 0, v67, vcc
	global_store_dwordx4 v[2:3], v[34:37], off
	v_add_co_u32_e32 v2, vcc, s69, v66
	v_pk_mul_f32 v[54:55], v[54:55], v[76:77]
	s_nop 0
	v_addc_co_u32_e32 v3, vcc, 0, v67, vcc
	global_store_dwordx4 v[2:3], v[18:21], off
	v_add_co_u32_e32 v2, vcc, s70, v66
	s_nop 0
	v_addc_co_u32_e32 v3, vcc, 0, v67, vcc
	global_store_dwordx4 v[2:3], v[62:65], off
	v_add_co_u32_e32 v2, vcc, s71, v66
	s_nop 0
	s_nop 0
	v_addc_co_u32_e32 v3, vcc, 0, v67, vcc
	global_store_dwordx4 v[2:3], v[22:25], off
	v_add_co_u32_e32 v2, vcc, s72, v66
	s_nop 0
	s_nop 0
	v_addc_co_u32_e32 v3, vcc, 0, v67, vcc
	global_store_dwordx4 v[2:3], v[38:41], off
	v_add_co_u32_e32 v2, vcc, s66, v66
	s_nop 0
	s_nop 0
	v_addc_co_u32_e32 v3, vcc, 0, v67, vcc
	global_store_dwordx4 v[2:3], v[50:53], off
	v_add_co_u32_e32 v2, vcc, s73, v66
	v_mfma_f32_16x16x32_bf16 v[6:9], v[106:109], v[94:97], v[6:9]
	s_nop 0
	v_addc_co_u32_e32 v3, vcc, 0, v67, vcc
	global_store_dwordx4 v[2:3], v[30:33], off
	v_add_co_u32_e32 v2, vcc, s74, v66
	v_pk_mul_f32 v[44:45], v[44:45], v[68:69]
	s_nop 0
	v_addc_co_u32_e32 v3, vcc, 0, v67, vcc
	global_store_dwordx4 v[2:3], v[54:57], off
	v_add_co_u32_e32 v2, vcc, s64, v66
	s_nop 0
	s_nop 0
	s_nop 0
	s_nop 0
	v_addc_co_u32_e32 v3, vcc, 0, v67, vcc
	global_store_dwordx4 v[2:3], v[42:45], off
	v_add_co_u32_e32 v2, vcc, s75, v66
	v_mfma_f32_16x16x32_bf16 v[10:13], v[106:109], v[98:101], v[10:13]
	v_mul_f32_e64 v48, v48, v68
	v_mul_f32_e64 v49, v49, v69
	v_addc_co_u32_e32 v3, vcc, 0, v67, vcc
	global_store_dwordx4 v[2:3], v[46:49], off
	v_add_co_u32_e32 v2, vcc, 0x1c000, v66
	s_waitcnt lgkmcnt(0)
	v_pk_mul_f32 v[8:9], v[8:9], v[72:73]
	v_pk_mul_f32 v[6:7], v[6:7], v[70:71]
	v_addc_co_u32_e32 v3, vcc, 0, v67, vcc
	global_store_dwordx4 v[2:3], v[6:9], off
	v_add_co_u32_e32 v2, vcc, 0x1e000, v66
	v_pk_mul_f32 v[12:13], v[12:13], v[72:73]
	v_pk_mul_f32 v[10:11], v[10:11], v[70:71]
	v_addc_co_u32_e32 v3, vcc, 0, v67, vcc
	global_store_dwordx4 v[2:3], v[10:13], off
	s_and_saveexec_b64 s[30:31], s[4:5]
	s_waitcnt lgkmcnt(0)
	s_cbranch_execz .LBB0_450
	v_mul_f32_e32 v1, 0x3fb8aa3b, v1
	v_exp_f32_e32 v1, v1
	s_lshl_b64 s[46:47], s[42:43], 9
	v_lshl_add_u64 v[2:3], v[118:119], 0, s[46:47]
	global_store_dword v[2:3], v1, off
	s_branch .LBB0_450

.LBB0_501:
	ds_read_b128 v[160:163], v149 offset:6144
	ds_read_b128 v[164:167], v149 offset:6160
	s_waitcnt vmcnt(6)
	v_lshlrev_b32_e32 v108, 16, v98
	v_and_b32_e32 v109, 0xffff0000, v98
	v_cvt_pk_bf16_f32 v180, v34, v35
	s_waitcnt lgkmcnt(1)
	v_mul_f32_e32 v1, 0xbfb8aa3b, v160
	v_mul_f32_e32 v107, 0xbfb8aa3b, v161
	v_exp_f32_e32 v168, v1
	v_exp_f32_e32 v169, v107
	v_mul_f32_e32 v1, 0xbfb8aa3b, v162
	v_exp_f32_e32 v170, v1
	v_mul_f32_e32 v1, 0xbfb8aa3b, v163
	v_exp_f32_e32 v171, v1
	s_waitcnt lgkmcnt(0)
	v_mul_f32_e32 v1, 0xbfb8aa3b, v164
	v_pk_mul_f32 v[108:109], v[168:169], v[108:109]
	v_exp_f32_e32 v168, v1
	v_mul_f32_e32 v1, 0xbfb8aa3b, v165
	v_exp_f32_e32 v169, v1
	v_cvt_pk_bf16_f32 v98, v108, v109
	v_lshlrev_b32_e32 v108, 16, v99
	v_and_b32_e32 v109, 0xffff0000, v99
	v_pk_mul_f32 v[108:109], v[170:171], v[108:109]
	v_mul_f32_e32 v1, 0xbfb8aa3b, v166
	v_cvt_pk_bf16_f32 v99, v108, v109
	v_lshlrev_b32_e32 v108, 16, v100
	v_and_b32_e32 v109, 0xffff0000, v100
	v_pk_mul_f32 v[108:109], v[168:169], v[108:109]
	v_exp_f32_e32 v168, v1
	v_mul_f32_e32 v1, 0xbfb8aa3b, v167
	v_exp_f32_e32 v169, v1
	v_cvt_pk_bf16_f32 v100, v108, v109
	v_lshlrev_b32_e32 v108, 16, v101
	v_and_b32_e32 v109, 0xffff0000, v101
	v_pk_mul_f32 v[108:109], v[168:169], v[108:109]
	v_mul_f32_e32 v1, 0x3fb8aa3b, v160
	v_cvt_pk_bf16_f32 v101, v108, v109
	v_exp_f32_e32 v108, v1
	v_mul_f32_e32 v1, 0x3fb8aa3b, v161
	v_exp_f32_e32 v109, v1
	ds_write_b128 v135, v[98:101] offset:56320
	v_lshlrev_b32_e32 v98, 16, v94
	v_and_b32_e32 v99, 0xffff0000, v94
	v_pk_mul_f32 v[100:101], v[108:109], s[40:41] op_sel_hi:[1,0]
	v_mul_f32_e32 v1, 0x3fb8aa3b, v162
	v_pk_mul_f32 v[98:99], v[100:101], v[98:99]
	v_exp_f32_e32 v100, v1
	v_mul_f32_e32 v1, 0x3fb8aa3b, v163
	v_exp_f32_e32 v101, v1
	v_cvt_pk_bf16_f32 v94, v98, v99
	v_lshlrev_b32_e32 v98, 16, v95
	v_and_b32_e32 v99, 0xffff0000, v95
	v_pk_mul_f32 v[100:101], v[100:101], s[40:41] op_sel_hi:[1,0]
	v_mul_f32_e32 v1, 0x3fb8aa3b, v164
	v_pk_mul_f32 v[98:99], v[100:101], v[98:99]
	v_exp_f32_e32 v100, v1
	v_mul_f32_e32 v1, 0x3fb8aa3b, v165
	v_exp_f32_e32 v101, v1
	v_cvt_pk_bf16_f32 v95, v98, v99
	v_lshlrev_b32_e32 v98, 16, v96
	v_and_b32_e32 v99, 0xffff0000, v96
	v_pk_mul_f32 v[100:101], v[100:101], s[40:41] op_sel_hi:[1,0]
	v_mul_f32_e32 v1, 0x3fb8aa3b, v166
	v_pk_mul_f32 v[98:99], v[100:101], v[98:99]
	v_exp_f32_e32 v100, v1
	v_mul_f32_e32 v1, 0x3fb8aa3b, v167
	v_exp_f32_e32 v101, v1
	v_cvt_pk_bf16_f32 v96, v98, v99
	v_lshlrev_b32_e32 v98, 16, v97
	v_and_b32_e32 v99, 0xffff0000, v97
	v_pk_mul_f32 v[100:101], v[100:101], s[40:41] op_sel_hi:[1,0]
	s_waitcnt vmcnt(4)
	v_lshlrev_b32_e32 v160, 16, v90
	v_pk_mul_f32 v[98:99], v[100:101], v[98:99]
	v_and_b32_e32 v161, 0xffff0000, v90
	v_cvt_pk_bf16_f32 v97, v98, v99
	ds_write_b128 v135, v[94:97] offset:38912
	ds_read_b128 v[94:97], v151 offset:6144
	ds_read_b128 v[98:101], v151 offset:6160
	v_cvt_pk_bf16_f32 v181, v36, v37
	v_cvt_pk_bf16_f32 v182, v30, v31
	v_cvt_pk_bf16_f32 v183, v32, v33
	s_waitcnt lgkmcnt(1)
	v_mul_f32_e32 v1, 0xbfb8aa3b, v94
	v_exp_f32_e32 v108, v1
	v_mul_f32_e32 v1, 0xbfb8aa3b, v95
	v_exp_f32_e32 v109, v1
	v_mul_f32_e32 v1, 0xbfb8aa3b, v96
	v_add_u32_e32 v107, 0xa800, v147
	s_add_u32 s46, s46, 0x60000
	v_pk_mul_f32 v[108:109], v[108:109], v[160:161]
	v_exp_f32_e32 v160, v1
	v_mul_f32_e32 v1, 0xbfb8aa3b, v97
	v_exp_f32_e32 v161, v1
	v_cvt_pk_bf16_f32 v90, v108, v109
	v_lshlrev_b32_e32 v108, 16, v91
	v_and_b32_e32 v109, 0xffff0000, v91
	s_waitcnt lgkmcnt(0)
	v_mul_f32_e32 v1, 0xbfb8aa3b, v98
	v_pk_mul_f32 v[108:109], v[160:161], v[108:109]
	v_exp_f32_e32 v160, v1
	v_mul_f32_e32 v1, 0xbfb8aa3b, v99
	v_exp_f32_e32 v161, v1
	v_cvt_pk_bf16_f32 v91, v108, v109
	v_lshlrev_b32_e32 v108, 16, v92
	v_and_b32_e32 v109, 0xffff0000, v92
	v_mul_f32_e32 v1, 0xbfb8aa3b, v100
	v_pk_mul_f32 v[108:109], v[160:161], v[108:109]
	v_exp_f32_e32 v160, v1
	v_mul_f32_e32 v1, 0xbfb8aa3b, v101
	v_exp_f32_e32 v161, v1
	v_mul_f32_e32 v1, 0x3fb8aa3b, v94
	v_exp_f32_e32 v94, v1
	v_mul_f32_e32 v1, 0x3fb8aa3b, v95
	v_exp_f32_e32 v95, v1
	v_cvt_pk_bf16_f32 v92, v108, v109
	v_lshlrev_b32_e32 v108, 16, v93
	v_and_b32_e32 v109, 0xffff0000, v93
	v_pk_mul_f32 v[108:109], v[160:161], v[108:109]
	v_mul_f32_e32 v1, 0x3fb8aa3b, v96
	v_cvt_pk_bf16_f32 v93, v108, v109
	ds_write_b128 v136, v[90:93] offset:56320
	v_lshlrev_b32_e32 v90, 16, v86
	v_and_b32_e32 v91, 0xffff0000, v86
	v_pk_mul_f32 v[92:93], v[94:95], s[40:41] op_sel_hi:[1,0]
	v_add_u32_e32 v108, 0xb800, v147
	v_pk_mul_f32 v[90:91], v[92:93], v[90:91]
	v_exp_f32_e32 v92, v1
	v_mul_f32_e32 v1, 0x3fb8aa3b, v97
	v_exp_f32_e32 v93, v1
	v_cvt_pk_bf16_f32 v86, v90, v91
	v_lshlrev_b32_e32 v90, 16, v87
	v_and_b32_e32 v91, 0xffff0000, v87
	v_pk_mul_f32 v[92:93], v[92:93], s[40:41] op_sel_hi:[1,0]
	v_mul_f32_e32 v1, 0x3fb8aa3b, v98
	v_pk_mul_f32 v[90:91], v[92:93], v[90:91]
	v_exp_f32_e32 v92, v1
	v_mul_f32_e32 v1, 0x3fb8aa3b, v99
	v_exp_f32_e32 v93, v1
	v_cvt_pk_bf16_f32 v87, v90, v91
	v_lshlrev_b32_e32 v90, 16, v88
	v_and_b32_e32 v91, 0xffff0000, v88
	v_pk_mul_f32 v[92:93], v[92:93], s[40:41] op_sel_hi:[1,0]
	v_mul_f32_e32 v1, 0x3fb8aa3b, v100
	v_pk_mul_f32 v[90:91], v[92:93], v[90:91]
	v_exp_f32_e32 v92, v1
	v_mul_f32_e32 v1, 0x3fb8aa3b, v101
	v_exp_f32_e32 v93, v1
	v_cvt_pk_bf16_f32 v88, v90, v91
	v_lshlrev_b32_e32 v90, 16, v89
	v_and_b32_e32 v91, 0xffff0000, v89
	v_pk_mul_f32 v[92:93], v[92:93], s[40:41] op_sel_hi:[1,0]
	v_add_u32_e32 v109, 0xc800, v147
	v_pk_mul_f32 v[90:91], v[92:93], v[90:91]
	s_addc_u32 s47, s47, 0
	v_cvt_pk_bf16_f32 v89, v90, v91
	ds_write_b128 v136, v[86:89] offset:38912
	s_waitcnt vmcnt(3)
	ds_write_b128 v153, v[70:73]
	s_waitcnt vmcnt(2)
	ds_write_b128 v155, v[74:77]
	s_waitcnt vmcnt(1)
	ds_write_b128 v153, v[78:81] offset:16896
	s_waitcnt vmcnt(0)
	ds_write_b128 v156, v[82:85]
	s_waitcnt lgkmcnt(0)
	s_barrier
	s_waitcnt lgkmcnt(0)
	ds_read_b128 v[70:73], v142 offset:56320
	ds_read_b128 v[224:227], v142 offset:56384
	ds_read_b128 v[228:231], v134 offset:38912
	ds_read_b128 v[82:85], v134 offset:38976
	ds_read_b128 v[86:89], v142 offset:56448
	ds_read_b128 v[232:235], v142 offset:56512
	ds_read_b128 v[90:93], v134 offset:39040
	ds_read_b128 v[94:97], v134 offset:39104
	s_waitcnt lgkmcnt(5)
	v_mfma_f32_16x16x32_bf16 v[70:73], v[70:73], v[228:231], 0
	s_add_i32 s30, s30, 64
	s_waitcnt lgkmcnt(4)
	v_mfma_f32_16x16x32_bf16 v[70:73], v[224:227], v[82:85], v[70:73]
	s_nop 0
	s_nop 0
	s_nop 0
	s_waitcnt lgkmcnt(1)
	v_mfma_f32_16x16x32_bf16 v[70:73], v[86:89], v[90:93], v[70:73]
	s_waitcnt lgkmcnt(0)
	v_mfma_f32_16x16x32_bf16 v[70:73], v[232:235], v[94:97], v[70:73]
	v_mov_b32_e32 v74, s59
	s_nop 6
	v_cndmask_b32_e64 v1, v70, v74, s[14:15]
	v_cndmask_b32_e64 v1, v1, v70, s[16:17]
	v_cndmask_b32_e64 v70, 0, v71, s[16:17]
	v_cndmask_b32_e64 v71, v72, 0, s[18:19]
	v_cndmask_b32_e64 v72, v73, 0, s[20:21]
	v_cvt_pk_bf16_f32 v70, v1, v70
	v_cvt_pk_bf16_f32 v71, v71, v72
	ds_write_b64 v143, v[70:71]
	ds_read_b128 v[236:239], v144 offset:56320
	ds_read_b128 v[244:247], v144 offset:56384
	ds_read_b128 v[78:81], v144 offset:56448
	ds_read_b128 v[74:77], v144 offset:56512
	s_waitcnt lgkmcnt(3)
	v_mfma_f32_16x16x32_bf16 v[70:73], v[236:239], v[228:231], 0
	s_nop 0
	s_waitcnt lgkmcnt(2)
	v_mfma_f32_16x16x32_bf16 v[70:73], v[244:247], v[82:85], v[70:73]
	s_nop 0
	s_waitcnt lgkmcnt(1)
	v_mfma_f32_16x16x32_bf16 v[70:73], v[78:81], v[90:93], v[70:73]
	s_waitcnt lgkmcnt(0)
	v_mfma_f32_16x16x32_bf16 v[70:73], v[74:77], v[94:97], v[70:73]
	v_mov_b32_e32 v74, s59
	s_nop 6
	v_cndmask_b32_e64 v1, v70, v74, s[22:23]
	v_cndmask_b32_e64 v1, v1, v70, s[24:25]
	v_cndmask_b32_e64 v70, 0, v71, s[24:25]
	v_cndmask_b32_e64 v71, v72, 0, s[26:27]
	v_cndmask_b32_e64 v72, v73, 0, s[28:29]
	v_cvt_pk_bf16_f32 v70, v1, v70
	v_cvt_pk_bf16_f32 v71, v71, v72
	ds_write_b64 v145, v[70:71]
	s_waitcnt lgkmcnt(0)
	s_barrier
	s_waitcnt lgkmcnt(0)
	ds_read_b64_tr_b16 v[76:77], v157 offset:2112
	ds_read_b64_tr_b16 v[74:75], v157
	ds_read_b64_tr_b16 v[80:81], v157 offset:2144
	ds_read_b64_tr_b16 v[78:79], v157 offset:32
	ds_read_b128 v[224:227], v146
	ds_read_b128 v[228:231], v146 offset:64
	ds_read_b64_tr_b16 v[82:83], v157 offset:16896
	ds_read_b64_tr_b16 v[84:85], v157 offset:19008
	ds_read_b64_tr_b16 v[72:73], v157 offset:19040
	ds_read_b64_tr_b16 v[70:71], v157 offset:16928
	ds_read_b128 v[232:235], v146 offset:2304
	ds_read_b128 v[236:239], v146 offset:2368
	ds_read_b128 v[244:247], v146 offset:4608
	s_waitcnt lgkmcnt(8)
	v_mfma_f32_16x16x32_bf16 v[90:93], v[74:77], v[224:227], 0
	s_nop 0
	s_nop 0
	v_add_u32_e32 v1, 0x9800, v147
	v_mfma_f32_16x16x32_bf16 v[94:97], v[78:81], v[224:227], 0
	ds_read_b128 v[224:227], v146 offset:4672
	s_nop 0
	s_nop 0
	s_waitcnt lgkmcnt(6)
	v_mfma_f32_16x16x32_bf16 v[90:93], v[82:85], v[228:231], v[90:93]
	s_waitcnt lgkmcnt(4)
	v_mfma_f32_16x16x32_bf16 v[86:89], v[70:73], v[228:231], v[94:97]
	ds_read_b128 v[228:231], v146 offset:6912
	s_nop 2
	s_nop 0
	s_nop 0
	s_waitcnt lgkmcnt(4)
	v_mfma_f32_16x16x32_bf16 v[160:163], v[74:77], v[232:235], 0
	v_mfma_f32_16x16x32_bf16 v[94:97], v[78:81], v[232:235], 0
	ds_read_b128 v[232:235], v146 offset:6976
	s_waitcnt lgkmcnt(4)
	v_mfma_f32_16x16x32_bf16 v[160:163], v[82:85], v[236:239], v[160:163]
	v_mfma_f32_16x16x32_bf16 v[94:97], v[70:73], v[236:239], v[94:97]
	ds_read2_b64 v[236:239], v1 offset1:4
	s_nop 0
	s_nop 0
	s_waitcnt lgkmcnt(4)
	v_mfma_f32_16x16x32_bf16 v[168:171], v[74:77], v[244:247], 0
	v_mfma_f32_16x16x32_bf16 v[98:101], v[78:81], v[244:247], 0
	ds_read2_b64 v[244:247], v1 offset0:8 offset1:12
	s_waitcnt lgkmcnt(4)
	v_mfma_f32_16x16x32_bf16 v[168:171], v[82:85], v[224:227], v[168:171]
	v_mfma_f32_16x16x32_bf16 v[98:101], v[70:73], v[224:227], v[98:101]
	ds_read2_b64 v[224:227], v107 offset0:32 offset1:36
	s_nop 0
	s_nop 0
	s_nop 0
	s_nop 0
	s_waitcnt lgkmcnt(4)
	v_mfma_f32_16x16x32_bf16 v[176:179], v[74:77], v[228:231], 0
	v_mfma_f32_16x16x32_bf16 v[164:167], v[78:81], v[228:231], 0
	ds_read2_b64 v[228:231], v108 offset0:64 offset1:68
	s_waitcnt lgkmcnt(4)
	v_mfma_f32_16x16x32_bf16 v[176:179], v[82:85], v[232:235], v[176:179]
	v_mfma_f32_16x16x32_bf16 v[164:167], v[70:73], v[232:235], v[164:167]
	ds_read2_b64 v[232:235], v109 offset0:96 offset1:100
	v_cvt_pk_bf16_f32 v172, v14, v15
	v_cvt_pk_bf16_f32 v173, v16, v17
	v_cvt_pk_bf16_f32 v174, v58, v59
	v_cvt_pk_bf16_f32 v175, v60, v61
	s_waitcnt lgkmcnt(4)
	v_mfma_f32_16x16x32_bf16 v[90:93], v[180:183], v[236:239], v[90:93]
	v_mfma_f32_16x16x32_bf16 v[86:89], v[172:175], v[236:239], v[86:89]
	ds_read2_b64 v[236:239], v107 offset0:40 offset1:44
	s_nop 0
	s_waitcnt lgkmcnt(3)
	v_mfma_f32_16x16x32_bf16 v[160:163], v[180:183], v[224:227], v[160:163]
	v_mfma_f32_16x16x32_bf16 v[94:97], v[172:175], v[224:227], v[94:97]
	ds_read2_b64 v[224:227], v108 offset0:72 offset1:76
	s_nop 0
	s_waitcnt lgkmcnt(3)
	v_mfma_f32_16x16x32_bf16 v[168:171], v[180:183], v[228:231], v[168:171]
	v_mfma_f32_16x16x32_bf16 v[98:101], v[172:175], v[228:231], v[98:101]
	ds_read2_b64 v[228:231], v109 offset0:104 offset1:108
	s_nop 0
	s_waitcnt lgkmcnt(3)
	v_mfma_f32_16x16x32_bf16 v[176:179], v[180:183], v[232:235], v[176:179]
	v_cvt_pk_bf16_f32 v180, v54, v55
	v_cvt_pk_bf16_f32 v181, v56, v57
	v_cvt_pk_bf16_f32 v182, v62, v63
	v_cvt_pk_bf16_f32 v183, v64, v65
	v_mfma_f32_16x16x32_bf16 v[164:167], v[172:175], v[232:235], v[164:167]
	ds_read2_b64 v[232:235], v1 offset0:16 offset1:20
	v_cvt_pk_bf16_f32 v172, v46, v47
	v_cvt_pk_bf16_f32 v173, v48, v49
	v_cvt_pk_bf16_f32 v174, v66, v67
	v_cvt_pk_bf16_f32 v175, v68, v69
	s_nop 0
	s_waitcnt lgkmcnt(3)
	v_mfma_f32_16x16x32_bf16 v[160:163], v[180:183], v[236:239], v[160:163]
	v_mfma_f32_16x16x32_bf16 v[94:97], v[172:175], v[236:239], v[94:97]
	ds_read2_b64 v[236:239], v107 offset0:48 offset1:52
	s_nop 0
	s_waitcnt lgkmcnt(3)
	v_mfma_f32_16x16x32_bf16 v[168:171], v[180:183], v[224:227], v[168:171]
	v_mfma_f32_16x16x32_bf16 v[98:101], v[172:175], v[224:227], v[98:101]
	ds_read2_b64 v[224:227], v108 offset0:80 offset1:84
	s_nop 0
	v_mfma_f32_16x16x32_bf16 v[90:93], v[180:183], v[244:247], v[90:93]
	v_mfma_f32_16x16x32_bf16 v[86:89], v[172:175], v[244:247], v[86:89]
	ds_read2_b64 v[244:247], v109 offset0:112 offset1:116
	s_nop 0
	s_waitcnt lgkmcnt(4)
	v_mfma_f32_16x16x32_bf16 v[176:179], v[180:183], v[228:231], v[176:179]
	v_cvt_pk_bf16_f32 v180, v22, v23
	v_cvt_pk_bf16_f32 v181, v24, v25
	v_cvt_pk_bf16_f32 v182, v18, v19
	v_cvt_pk_bf16_f32 v183, v20, v21
	v_mfma_f32_16x16x32_bf16 v[164:167], v[172:175], v[228:231], v[164:167]
	ds_read2_b64 v[228:231], v1 offset0:24 offset1:28
	v_cvt_pk_bf16_f32 v172, v10, v11
	v_cvt_pk_bf16_f32 v173, v12, v13
	v_cvt_pk_bf16_f32 v174, v50, v51
	v_cvt_pk_bf16_f32 v175, v52, v53
	s_nop 0
	s_waitcnt lgkmcnt(3)
	v_mfma_f32_16x16x32_bf16 v[160:163], v[180:183], v[236:239], v[160:163]
	v_mfma_f32_16x16x32_bf16 v[94:97], v[172:175], v[236:239], v[94:97]
	ds_read2_b64 v[236:239], v107 offset0:56 offset1:60
	s_nop 0
	s_waitcnt lgkmcnt(3)
	v_mfma_f32_16x16x32_bf16 v[168:171], v[180:183], v[224:227], v[168:171]
	v_mfma_f32_16x16x32_bf16 v[98:101], v[172:175], v[224:227], v[98:101]
	ds_read2_b64 v[224:227], v108 offset0:88 offset1:92
	s_nop 0
	v_mfma_f32_16x16x32_bf16 v[90:93], v[180:183], v[232:235], v[90:93]
	v_mfma_f32_16x16x32_bf16 v[86:89], v[172:175], v[232:235], v[86:89]
	ds_read2_b64 v[232:235], v109 offset0:120 offset1:124
	s_nop 0
	v_lshl_add_u32 v1, s79, 9, v128
	s_waitcnt lgkmcnt(4)
	v_mfma_f32_16x16x32_bf16 v[176:179], v[180:183], v[244:247], v[176:179]
	v_cvt_pk_bf16_f32 v180, v38, v39
	v_cvt_pk_bf16_f32 v181, v40, v41
	v_cvt_pk_bf16_f32 v182, v26, v27
	v_cvt_pk_bf16_f32 v183, v28, v29
	v_mfma_f32_16x16x32_bf16 v[164:167], v[172:175], v[244:247], v[164:167]
	ds_read_b64_tr_b16 v[246:247], v158 offset:57408
	ds_read_b64_tr_b16 v[244:245], v158 offset:56320
	v_cvt_pk_bf16_f32 v172, v42, v43
	v_cvt_pk_bf16_f32 v173, v44, v45
	v_cvt_pk_bf16_f32 v174, v6, v7
	v_cvt_pk_bf16_f32 v175, v8, v9
	s_nop 0
	s_waitcnt lgkmcnt(4)
	v_mfma_f32_16x16x32_bf16 v[160:163], v[180:183], v[236:239], v[160:163]
	v_mfma_f32_16x16x32_bf16 v[94:97], v[172:175], v[236:239], v[94:97]
	ds_read_b64_tr_b16 v[236:237], v158 offset:56352
	ds_read_b64_tr_b16 v[184:185], v158 offset:56384
	ds_read_b64_tr_b16 v[188:189], v158 offset:56416
	ds_read_b64_tr_b16 v[238:239], v158 offset:57440
	ds_read_b64_tr_b16 v[186:187], v158 offset:57472
	ds_read_b64_tr_b16 v[190:191], v158 offset:57504
	ds_read_b64_tr_b16 v[192:193], v158 offset:65024
	ds_read_b64_tr_b16 v[194:195], v159 offset:57408
	s_nop 0
	s_waitcnt lgkmcnt(11)
	v_mfma_f32_16x16x32_bf16 v[168:171], v[180:183], v[224:227], v[168:171]
	v_mfma_f32_16x16x32_bf16 v[98:101], v[172:175], v[224:227], v[98:101]
	ds_read_b64_tr_b16 v[224:225], v158 offset:65056
	ds_read_b64_tr_b16 v[196:197], v158 offset:65088
	ds_read_b64_tr_b16 v[200:201], v158 offset:65120
	ds_read_b64_tr_b16 v[226:227], v159 offset:57440
	ds_read_b64_tr_b16 v[198:199], v159 offset:57472
	ds_read_b64_tr_b16 v[202:203], v159 offset:57504
	s_nop 0
	v_mfma_f32_16x16x32_bf16 v[90:93], v[180:183], v[228:231], v[90:93]
	s_waitcnt lgkmcnt(15)
	v_mfma_f32_16x16x32_bf16 v[176:179], v[180:183], v[232:235], v[176:179]
	s_nop 0
	s_nop 0
	s_nop 3
	v_cvt_pk_bf16_f32 v90, v90, v91
	v_cvt_pk_bf16_f32 v91, v92, v93
	v_mfma_f32_16x16x32_bf16 v[86:89], v[172:175], v[228:231], v[86:89]
	ds_read_b64_tr_b16 v[228:229], v158 offset:56448
	ds_read_b64_tr_b16 v[230:231], v158 offset:57536
	ds_read_b64_tr_b16 v[180:181], v158 offset:56480
	v_lshl_add_u64 v[92:93], s[44:45], 0, v[116:117]
	s_add_u32 s44, s44, 0x20000
	s_addc_u32 s45, s45, 0
	v_mfma_f32_16x16x32_bf16 v[164:167], v[172:175], v[232:235], v[164:167]
	s_nop 0
	s_nop 0
	s_nop 0
	s_nop 0
	s_nop 0
	s_nop 0
	s_nop 0
	s_nop 0
	v_cvt_pk_bf16_f32 v86, v86, v87
	s_waitcnt lgkmcnt(13)
	v_mfma_f32_16x16x32_bf16 v[30:33], v[236:239], v[74:77], v[30:33]
	v_cvt_pk_bf16_f32 v87, v88, v89
	v_add_co_u32_e32 v88, vcc, s62, v92
	v_mfma_f32_16x16x32_bf16 v[58:61], v[236:239], v[78:81], v[58:61]
	s_nop 0
	v_addc_co_u32_e32 v89, vcc, 0, v93, vcc
	s_add_i32 s78, s78, 1
	v_mfma_f32_16x16x32_bf16 v[34:37], v[244:247], v[74:77], v[34:37]
	s_cmp_lg_u32 s46, 0x180000
	v_mfma_f32_16x16x32_bf16 v[14:17], v[244:247], v[78:81], v[14:17]
	s_nop 0
	s_nop 0
	s_nop 0
	s_nop 0
	s_nop 0
	s_nop 0
	s_nop 0
	s_nop 0
	s_waitcnt lgkmcnt(5)
	v_mfma_f32_16x16x32_bf16 v[30:33], v[224:227], v[82:85], v[30:33]
	v_mfma_f32_16x16x32_bf16 v[58:61], v[224:227], v[70:73], v[58:61]
	v_mfma_f32_16x16x32_bf16 v[54:57], v[184:187], v[74:77], v[54:57]
	v_mfma_f32_16x16x32_bf16 v[46:49], v[184:187], v[78:81], v[46:49]
	ds_read_b64_tr_b16 v[184:185], v158 offset:56512
	v_mfma_f32_16x16x32_bf16 v[62:65], v[188:191], v[74:77], v[62:65]
	v_mfma_f32_16x16x32_bf16 v[66:69], v[188:191], v[78:81], v[66:69]
	ds_read_b64_tr_b16 v[188:189], v158 offset:56544
	ds_read_b64_tr_b16 v[182:183], v158 offset:57568
	ds_read_b64_tr_b16 v[186:187], v158 offset:57600
	ds_read_b64_tr_b16 v[190:191], v158 offset:57632
	s_nop 0
	s_nop 0
	s_nop 0
	s_nop 0
	s_nop 0
	s_nop 0
	v_mfma_f32_16x16x32_bf16 v[34:37], v[192:195], v[82:85], v[34:37]
	v_mfma_f32_16x16x32_bf16 v[14:17], v[192:195], v[70:73], v[14:17]
	ds_read_b64_tr_b16 v[192:193], v158 offset:65152
	ds_read_b64_tr_b16 v[194:195], v159 offset:57536
	ds_read_b64_tr_b16 v[172:173], v158 offset:65184
	s_waitcnt lgkmcnt(12)
	v_mfma_f32_16x16x32_bf16 v[54:57], v[196:199], v[82:85], v[54:57]
	v_mfma_f32_16x16x32_bf16 v[46:49], v[196:199], v[70:73], v[46:49]
	ds_read_b64_tr_b16 v[196:197], v158 offset:65216
	s_waitcnt lgkmcnt(12)
	v_mfma_f32_16x16x32_bf16 v[62:65], v[200:203], v[82:85], v[62:65]
	v_mfma_f32_16x16x32_bf16 v[66:69], v[200:203], v[70:73], v[66:69]
	ds_read_b64_tr_b16 v[200:201], v158 offset:65248
	ds_read_b64_tr_b16 v[174:175], v159 offset:57568
	ds_read_b64_tr_b16 v[198:199], v159 offset:57600
	ds_read_b64_tr_b16 v[202:203], v159 offset:57632
	ds_read_b128 v[232:235], v1 offset:4096
	ds_read_b128 v[236:239], v1 offset:4160
	ds_read_b128 v[244:247], v1 offset:4224
	ds_read_b128 v[224:227], v1 offset:4288
	s_waitcnt lgkmcnt(15)
	v_mfma_f32_16x16x32_bf16 v[22:25], v[228:231], v[74:77], v[22:25]
	v_mfma_f32_16x16x32_bf16 v[10:13], v[228:231], v[78:81], v[10:13]
	ds_read_b128 v[228:231], v1 offset:4352
	s_nop 0
	s_nop 0
	s_nop 0
	s_nop 0
	s_nop 0
	s_nop 0
	global_store_dwordx2 v[92:93], v[86:87], off offset:32
	v_cvt_pk_bf16_f32 v86, v160, v161
	s_waitcnt lgkmcnt(15)
	v_mfma_f32_16x16x32_bf16 v[18:21], v[180:183], v[74:77], v[18:21]
	v_cvt_pk_bf16_f32 v87, v162, v163
	global_store_dwordx2 v[88:89], v[86:87], off
	v_cvt_pk_bf16_f32 v86, v94, v95
	v_mfma_f32_16x16x32_bf16 v[50:53], v[180:183], v[78:81], v[50:53]
	v_cvt_pk_bf16_f32 v87, v96, v97
	global_store_dwordx2 v[88:89], v[86:87], off offset:32
	v_add_co_u32_e32 v88, vcc, s72, v92
	s_waitcnt lgkmcnt(14)
	v_mfma_f32_16x16x32_bf16 v[38:41], v[184:187], v[74:77], v[38:41]
	v_cvt_pk_bf16_f32 v86, v168, v169
	v_cvt_pk_bf16_f32 v87, v170, v171
	v_addc_co_u32_e32 v89, vcc, 0, v93, vcc
	v_mfma_f32_16x16x32_bf16 v[42:45], v[184:187], v[78:81], v[42:45]
	global_store_dwordx2 v[88:89], v[86:87], off
	v_cvt_pk_bf16_f32 v86, v98, v99
	v_cvt_pk_bf16_f32 v87, v100, v101
	s_waitcnt lgkmcnt(13)
	v_mfma_f32_16x16x32_bf16 v[26:29], v[188:191], v[74:77], v[26:29]
	s_nop 0
	global_store_dwordx2 v[88:89], v[86:87], off offset:32
	v_add_co_u32_e32 v88, vcc, s64, v92
	v_mfma_f32_16x16x32_bf16 v[6:9], v[188:191], v[78:81], v[6:9]
	s_nop 0
	s_nop 0
	s_nop 0
	s_waitcnt lgkmcnt(11)
	v_mfma_f32_16x16x32_bf16 v[10:13], v[192:195], v[70:73], v[10:13]
	s_nop 0
	s_nop 0
	s_nop 0
	s_waitcnt lgkmcnt(7)
	v_mfma_f32_16x16x32_bf16 v[50:53], v[172:175], v[70:73], v[50:53]
	s_nop 0
	s_nop 0
	s_nop 0
	s_waitcnt lgkmcnt(6)
	v_mfma_f32_16x16x32_bf16 v[42:45], v[196:199], v[70:73], v[42:45]
	v_cvt_pk_bf16_f32 v86, v176, v177
	s_waitcnt lgkmcnt(4)
	v_pk_mul_f32 v[36:37], v[36:37], v[234:235]
	v_pk_mul_f32 v[34:35], v[34:35], v[232:233]
	v_mfma_f32_16x16x32_bf16 v[6:9], v[200:203], v[70:73], v[6:9]
	s_waitcnt lgkmcnt(3)
	v_mov_b32_e32 v70, v236
	v_mov_b32_e32 v71, v238
	v_mov_b32_e32 v78, v70
	v_mov_b32_e32 v70, v237
	v_mov_b32_e32 v80, v71
	s_nop 0
	v_mov_b32_e32 v81, v239
	ds_read_b128 v[236:239], v1 offset:4416
	v_mov_b32_e32 v79, v70
	s_nop 0
	v_pk_mul_f32 v[16:17], v[16:17], v[234:235]
	v_pk_mul_f32 v[14:15], v[14:15], v[232:233]
	ds_read_b128 v[232:235], v1 offset:4480
	s_nop 0
	v_mfma_f32_16x16x32_bf16 v[22:25], v[192:195], v[82:85], v[22:25]
	s_nop 0
	v_pk_mul_f32 v[32:33], v[32:33], v[80:81]
	v_pk_mul_f32 v[30:31], v[30:31], v[78:79]
	v_mfma_f32_16x16x32_bf16 v[18:21], v[172:175], v[82:85], v[18:21]
	v_mul_f32_e64 v60, v60, v80
	v_mul_f32_e64 v61, v61, v81
	v_pk_mul_f32 v[58:59], v[58:59], v[78:79]
	v_cvt_pk_bf16_f32 v87, v178, v179
	v_mfma_f32_16x16x32_bf16 v[38:41], v[196:199], v[82:85], v[38:41]
	v_addc_co_u32_e32 v89, vcc, 0, v93, vcc
	global_store_dwordx2 v[88:89], v[86:87], off
	v_mfma_f32_16x16x32_bf16 v[26:29], v[200:203], v[82:85], v[26:29]
	s_waitcnt lgkmcnt(4)
	v_mov_b32_e32 v82, v244
	v_mov_b32_e32 v83, v245
	v_mov_b32_e32 v70, v246
	v_mov_b32_e32 v71, v247
	ds_read_b128 v[244:247], v1 offset:4544
	s_nop 0
	s_nop 0
	s_nop 0
	v_cvt_pk_bf16_f32 v86, v164, v165
	v_cvt_pk_bf16_f32 v87, v166, v167
	v_pk_mul_f32 v[56:57], v[56:57], v[70:71]
	v_pk_mul_f32 v[48:49], v[48:49], v[70:71]
	s_waitcnt lgkmcnt(4)
	v_mov_b32_e32 v70, v224
	v_mov_b32_e32 v71, v226
	v_mov_b32_e32 v78, v70
	v_mov_b32_e32 v70, v225
	v_mov_b32_e32 v80, v71
	s_nop 0
	v_mov_b32_e32 v81, v227
	v_mov_b32_e32 v79, v70
	s_nop 0
	s_nop 0
	v_pk_mul_f32 v[54:55], v[54:55], v[82:83]
	v_pk_mul_f32 v[46:47], v[46:47], v[82:83]
	v_pk_mul_f32 v[64:65], v[64:65], v[80:81]
	s_nop 0
	s_waitcnt lgkmcnt(3)
	v_mov_b32_e32 v82, v228
	v_mov_b32_e32 v83, v229
	v_mov_b32_e32 v70, v230
	v_mov_b32_e32 v71, v231
	s_nop 0
	s_nop 0
	v_pk_mul_f32 v[62:63], v[62:63], v[78:79]
	v_pk_mul_f32 v[68:69], v[68:69], v[80:81]
	v_pk_mul_f32 v[66:67], v[66:67], v[78:79]
	v_pk_mul_f32 v[24:25], v[24:25], v[70:71]
	v_pk_mul_f32 v[12:13], v[12:13], v[70:71]
	s_waitcnt lgkmcnt(2)
	v_mov_b32_e32 v70, v236
	v_mov_b32_e32 v71, v238
	v_mov_b32_e32 v78, v70
	v_mov_b32_e32 v70, v237
	v_mov_b32_e32 v80, v71
	s_nop 0
	v_mov_b32_e32 v81, v239
	v_mov_b32_e32 v79, v70
	s_nop 0
	s_nop 0
	s_nop 0
	v_pk_mul_f32 v[20:21], v[20:21], v[80:81]
	v_pk_mul_f32 v[18:19], v[18:19], v[78:79]
	s_nop 0
	s_waitcnt lgkmcnt(1)
	v_mov_b32_e32 v70, v232
	v_mov_b32_e32 v1, v233
	v_mov_b32_e32 v71, v234
	v_mov_b32_e32 v72, v71
	s_nop 0
	v_mov_b32_e32 v73, v235
	v_mov_b32_e32 v71, v1
	s_nop 0
	s_waitcnt lgkmcnt(0)
	v_mov_b32_e32 v74, v244
	v_mov_b32_e32 v1, v245
	v_mov_b32_e32 v75, v246
	v_mov_b32_e32 v76, v75
	s_nop 0
	v_mov_b32_e32 v77, v247
	v_mov_b32_e32 v75, v1
	v_pk_mul_f32 v[22:23], v[22:23], v[82:83]
	v_pk_mul_f32 v[10:11], v[10:11], v[82:83]
	v_pk_mul_f32 v[52:53], v[52:53], v[80:81]
	v_pk_mul_f32 v[50:51], v[50:51], v[78:79]
	v_pk_mul_f32 v[40:41], v[40:41], v[72:73]
	v_pk_mul_f32 v[38:39], v[38:39], v[70:71]
	v_pk_mul_f32 v[44:45], v[44:45], v[72:73]
	v_pk_mul_f32 v[42:43], v[42:43], v[70:71]
	v_pk_mul_f32 v[28:29], v[28:29], v[76:77]
	v_pk_mul_f32 v[26:27], v[26:27], v[74:75]
	v_pk_mul_f32 v[8:9], v[8:9], v[76:77]
	v_pk_mul_f32 v[6:7], v[6:7], v[74:75]
	global_store_dwordx2 v[92:93], v[90:91], off
	global_store_dwordx2 v[88:89], v[86:87], off offset:32
	s_waitcnt lgkmcnt(0)
	s_cbranch_scc0 .LBB0_451
.LBB0_502:
	s_add_u32 s50, s53, s46
	s_addc_u32 s51, s77, s47
	s_add_u32 s31, s43, s46
	s_addc_u32 s48, s52, s47
	s_add_u32 s80, s31, s76
	s_addc_u32 s81, s48, 0
	s_and_b32 s79, s78, 1
	s_cmp_eq_u32 s79, 0
	s_cselect_b64 s[48:49], -1, 0
	s_and_b64 s[82:83], s[48:49], exec
	s_cselect_b32 s31, 0xf0, s67
	v_and_b32_e32 v1, 63, v154
	v_lshl_add_u32 v1, v1, 2, s31
	s_waitcnt lgkmcnt(0)
	ds_read2st64_b32 v[74:75], v1 offset1:1
	ds_read2st64_b32 v[224:225], v1 offset0:4 offset1:5
	ds_read2st64_b32 v[228:229], v1 offset0:2 offset1:3
	ds_read2st64_b32 v[232:233], v1 offset0:6 offset1:7
	ds_read2st64_b32 v[236:237], v1 offset0:8 offset1:9
	ds_read2st64_b32 v[244:245], v1 offset0:10 offset1:11
	v_lshl_add_u64 v[76:77], s[50:51], 0, v[112:113]
	s_nop 0
	global_load_dwordx4 v[94:97], v[76:77], off
	global_load_dwordx4 v[98:101], v[76:77], off offset:1024
	s_nop 0
	v_lshl_add_u64 v[84:85], s[80:81], 0, v[114:115]
	s_mov_b32 s31, 0x3d800000
	s_waitcnt vmcnt(6)
	s_waitcnt lgkmcnt(5)
	v_mfma_f32_16x16x4_f32 v[70:73], v74, v102, 0
	v_add_co_u32_e32 v74, vcc, s63, v76
	s_waitcnt vmcnt(5)
	v_mfma_f32_16x16x4_f32 v[70:73], v75, v103, v[70:73]
	v_addc_co_u32_e32 v75, vcc, 0, v77, vcc
	global_load_dwordx4 v[86:89], v[74:75], off
	global_load_dwordx4 v[90:93], v[74:75], off offset:1024
	v_add_co_u32_e32 v74, vcc, s64, v84
	s_nop 1
	v_addc_co_u32_e32 v75, vcc, 0, v85, vcc
	s_waitcnt vmcnt(6)
	s_waitcnt lgkmcnt(3)
	v_mfma_f32_16x16x4_f32 v[160:163], v228, v104, v[70:73]
	v_add_co_u32_e32 v168, vcc, s63, v84
	global_load_dwordx4 v[70:73], v[84:85], off
	s_nop 0
	global_load_dwordx4 v[74:77], v[74:75], off
	v_addc_co_u32_e32 v169, vcc, 0, v85, vcc
	v_mfma_f32_16x16x4_f32 v[78:81], v224, v102, 0
	v_add_co_u32_e32 v82, vcc, s65, v84
	s_waitcnt vmcnt(7)
	v_mfma_f32_16x16x4_f32 v[160:163], v229, v105, v[160:163]
	ds_read2st64_b32 v[228:229], v1 offset0:12 offset1:13
	v_mfma_f32_16x16x4_f32 v[164:167], v225, v103, v[78:81]
	ds_read2st64_b32 v[224:225], v1 offset0:14 offset1:15
	v_addc_co_u32_e32 v83, vcc, 0, v85, vcc
	s_nop 4
	global_load_dwordx4 v[78:81], v[168:169], off
	s_nop 0
	global_load_dwordx4 v[82:85], v[82:83], off
	s_nop 0
	s_waitcnt vmcnt(8)
	v_add_f32_e32 v107, v106, v160
	v_min_f32_e32 v170, 0, v107
	v_mul_f32_e64 v107, |v107|, s68
	v_exp_f32_e32 v107, v107
	v_add_f32_e32 v108, v106, v161
	v_add_f32_e32 v109, v106, v162
	v_mul_f32_e64 v160, |v108|, s68
	v_mul_f32_e64 v161, |v109|, s68
	v_exp_f32_e32 v160, v160
	v_exp_f32_e32 v161, v161
	v_add_f32_e32 v107, 1.0, v107
	v_log_f32_e32 v107, v107
	s_waitcnt lgkmcnt(4)
	v_mfma_f32_16x16x4_f32 v[164:167], v232, v104, v[164:167]
	v_add_f32_e32 v160, 1.0, v160
	v_add_f32_e32 v161, 1.0, v161
	v_log_f32_e32 v160, v160
	v_fmac_f32_e32 v170, 0xbf317218, v107
	v_log_f32_e32 v107, v161
	v_min_f32_e32 v171, 0, v108
	v_min_f32_e32 v172, 0, v109
	v_fmac_f32_e32 v171, 0xbf317218, v160
	v_fmac_f32_e32 v172, 0xbf317218, v107
	v_add_f32_e32 v107, v106, v163
	v_mfma_f32_16x16x4_f32 v[160:163], v233, v105, v[164:167]
	v_mul_f32_e64 v108, |v107|, s68
	v_exp_f32_e32 v168, v108
	v_min_f32_e32 v107, 0, v107
	v_add_f32_e32 v165, 1.0, v168
	v_log_f32_e32 v165, v165
	s_nop 4
	v_add_f32_e32 v160, v106, v160
	v_mul_f32_e64 v108, |v160|, s68
	v_exp_f32_e32 v164, v108
	s_nop 0
	v_min_f32_e32 v173, 0, v160
	v_fmac_f32_e32 v107, 0xbf317218, v165
	v_add_f32_e32 v164, 1.0, v164
	v_log_f32_e32 v164, v164
	s_nop 0
	v_add_f32_e32 v174, v106, v162
	v_add_f32_e32 v176, v106, v163
	v_fmac_f32_e32 v173, 0xbf317218, v164
	s_waitcnt lgkmcnt(3)
	v_mfma_f32_16x16x4_f32 v[164:167], v236, v102, 0
	v_add_f32_e32 v108, v106, v161
	v_mul_f32_e64 v160, |v108|, s68
	v_mul_f32_e64 v161, |v174|, s68
	v_exp_f32_e32 v160, v160
	v_exp_f32_e32 v161, v161
	v_min_f32_e32 v175, 0, v108
	v_mul_f32_e64 v177, |v176|, s68
	v_mfma_f32_16x16x4_f32 v[164:167], v237, v103, v[164:167]
	v_add_f32_e32 v108, 1.0, v160
	v_add_f32_e32 v109, 1.0, v161
	v_log_f32_e32 v108, v108
	v_log_f32_e32 v109, v109
	v_min_f32_e32 v174, 0, v174
	v_min_f32_e32 v176, 0, v176
	v_fmac_f32_e32 v175, 0xbf317218, v108
	s_waitcnt lgkmcnt(2)
	v_mfma_f32_16x16x4_f32 v[160:163], v244, v104, v[164:167]
	s_nop 0
	v_exp_f32_e32 v164, v177
	v_fmac_f32_e32 v174, 0xbf317218, v109
	v_add_f32_e32 v108, 1.0, v164
	v_log_f32_e32 v164, v108
	s_nop 0
	v_mfma_f32_16x16x4_f32 v[160:163], v245, v105, v[160:163]
	v_fmac_f32_e32 v176, 0xbf317218, v164
	s_nop 8
	v_add_f32_e32 v160, v106, v160
	v_mul_f32_e64 v164, |v160|, s68
	v_exp_f32_e32 v168, v164
	s_waitcnt lgkmcnt(1)
	v_mfma_f32_16x16x4_f32 v[164:167], v228, v102, 0
	v_add_f32_e32 v161, v106, v161
	v_mul_f32_e64 v169, |v161|, s68
	v_exp_f32_e32 v108, v169
	v_min_f32_e32 v177, 0, v160
	v_add_f32_e32 v160, 1.0, v168
	s_nop 0
	v_add_f32_e32 v108, 1.0, v108
	v_mfma_f32_16x16x4_f32 v[164:167], v229, v103, v[164:167]
	v_log_f32_e32 v160, v160
	v_log_f32_e32 v108, v108
	v_min_f32_e32 v1, 0, v161
	v_add_f32_e32 v178, v106, v163
	v_fmac_f32_e32 v177, 0xbf317218, v160
	v_fmac_f32_e32 v1, 0xbf317218, v108
	v_add_f32_e32 v108, v106, v162
	s_waitcnt lgkmcnt(0)
	v_mfma_f32_16x16x4_f32 v[160:163], v224, v104, v[164:167]
	v_mul_f32_e64 v109, |v108|, s68
	v_exp_f32_e32 v109, v109
	v_mul_f32_e64 v164, |v178|, s68
	v_exp_f32_e32 v164, v164
	v_min_f32_e32 v108, 0, v108
	v_add_f32_e32 v109, 1.0, v109
	v_log_f32_e32 v109, v109
	v_mfma_f32_16x16x4_f32 v[160:163], v225, v105, v[160:163]
	v_add_f32_e32 v164, 1.0, v164
	v_log_f32_e32 v164, v164
	v_fmac_f32_e32 v108, 0xbf317218, v109
	v_min_f32_e32 v109, 0, v178
	v_fmac_f32_e32 v109, 0xbf317218, v164
	s_nop 4
	v_add_f32_e32 v160, v106, v160
	v_mul_f32_e64 v165, |v160|, s68
	v_exp_f32_e32 v165, v165
	v_add_f32_e32 v161, v106, v161
	v_min_f32_e32 v160, 0, v160
	v_add_f32_e32 v162, v106, v162
	v_add_f32_e32 v164, 1.0, v165
	v_mul_f32_e64 v165, |v161|, s68
	v_log_f32_e32 v164, v164
	v_exp_f32_e32 v165, v165
	v_add_f32_e32 v163, v106, v163
	v_mul_f32_e64 v166, |v163|, s68
	v_fmac_f32_e32 v160, 0xbf317218, v164
	v_add_f32_e32 v164, 1.0, v165
	v_mul_f32_e64 v165, |v162|, s68
	v_log_f32_e32 v164, v164
	v_exp_f32_e32 v165, v165
	v_exp_f32_e32 v166, v166
	v_min_f32_e32 v161, 0, v161
	v_fmac_f32_e32 v161, 0xbf317218, v164
	v_add_f32_e32 v164, 1.0, v165
	v_log_f32_e32 v164, v164
	v_add_f32_e32 v165, 1.0, v166
	v_log_f32_e32 v165, v165
	v_min_f32_e32 v162, 0, v162
	v_fmac_f32_e32 v162, 0xbf317218, v164
	v_min_f32_e32 v163, 0, v163
	v_fma_f32 v164, v170, s31, 0
	v_fmac_f32_e32 v163, 0xbf317218, v165
	v_fmamk_f32 v165, v171, 0x3d800000, v164
	v_fmamk_f32 v166, v172, 0x3d800000, v165
	v_fmamk_f32 v107, v107, 0x3d800000, v166
	v_fmamk_f32 v167, v173, 0x3d800000, v107
	v_fmamk_f32 v168, v175, 0x3d800000, v167
	v_fmamk_f32 v169, v174, 0x3d800000, v168
	v_fmamk_f32 v170, v176, 0x3d800000, v169
	v_fmamk_f32 v171, v177, 0x3d800000, v170
	v_fmamk_f32 v1, v1, 0x3d800000, v171
	v_fmamk_f32 v108, v108, 0x3d800000, v1
	v_fmamk_f32 v109, v109, 0x3d800000, v108
	v_fmamk_f32 v160, v160, 0x3d800000, v109
	v_fmamk_f32 v161, v161, 0x3d800000, v160
	v_fmamk_f32 v162, v162, 0x3d800000, v161
	v_fmamk_f32 v163, v163, 0x3d800000, v162
	ds_bpermute_b32 v172, v137, v163
	ds_bpermute_b32 v173, v138, v163
	ds_bpermute_b32 v174, v139, v163
	s_waitcnt lgkmcnt(2)
	v_cndmask_b32_e64 v172, v172, 0, s[10:11]
	s_waitcnt lgkmcnt(1)
	v_cndmask_b32_e64 v173, 0, v173, s[12:13]
	v_add_f32_e32 v172, v172, v173
	s_waitcnt lgkmcnt(0)
	v_cndmask_b32_e64 v173, 0, v174, s[6:7]
	v_add_f32_e32 v172, v172, v173
	v_add_f32_e32 v164, v164, v172
	v_add_f32_e32 v165, v165, v172
	ds_write2st64_b32 v141, v164, v165 offset0:24 offset1:26
	v_add_f32_e32 v164, v166, v172
	v_add_f32_e32 v107, v107, v172
	ds_write2st64_b32 v141, v164, v107 offset0:28 offset1:30
	v_add_f32_e32 v107, v167, v172
	v_add_f32_e32 v164, v168, v172
	ds_write2st64_b32 v141, v107, v164 offset0:32 offset1:34
	v_add_f32_e32 v107, v169, v172
	v_add_f32_e32 v164, v170, v172
	ds_write2st64_b32 v141, v107, v164 offset0:36 offset1:38
	v_add_f32_e32 v107, v171, v172
	v_add_f32_e32 v1, v1, v172
	ds_write2st64_b32 v141, v107, v1 offset0:40 offset1:42
	v_add_f32_e32 v1, v172, v108
	v_add_f32_e32 v107, v172, v109
	ds_write2st64_b32 v141, v1, v107 offset0:44 offset1:46
	v_add_f32_e32 v1, v172, v160
	v_add_f32_e32 v107, v172, v161
	ds_write2st64_b32 v141, v1, v107 offset0:48 offset1:50
	v_add_f32_e32 v1, v172, v162
	v_add_f32_e32 v107, v172, v163
	ds_write2st64_b32 v141, v1, v107 offset0:52 offset1:54
	s_waitcnt lgkmcnt(0)
	s_barrier
	s_and_saveexec_b64 s[50:51], s[4:5]
	s_cbranch_execz .LBB0_504
	ds_read_b32 v1, v127 offset:38400
	v_lshl_add_u32 v107, s79, 9, v127
	s_waitcnt lgkmcnt(0)
	v_mul_f32_e32 v255, 0x3fb8aa3b, v1
	v_exp_f32_e32 v255, v255
	s_nop 0
	ds_write_b32 v107, v255 offset:4096

.LBB0_663:
	ds_read_b128 v[134:137], v201 offset:6144
	ds_read_b128 v[138:141], v201 offset:6160
	s_waitcnt vmcnt(6)
	v_lshlrev_b32_e32 v144, 16, v98
	v_and_b32_e32 v145, 0xffff0000, v98
	v_add_u32_e32 v215, 0x9800, v212
	s_waitcnt lgkmcnt(1)
	v_mul_f32_e32 v109, 0xbfb8aa3b, v134
	v_exp_f32_e32 v142, v109
	v_mul_f32_e32 v109, 0xbfb8aa3b, v135
	v_exp_f32_e32 v143, v109
	v_mul_f32_e32 v109, 0xbfb8aa3b, v136
	v_cvt_pk_bf16_f32 v156, v10, v11
	v_cvt_pk_bf16_f32 v157, v12, v13
	v_pk_mul_f32 v[142:143], v[142:143], v[144:145]
	v_lshlrev_b32_e32 v144, 16, v99
	v_cvt_pk_bf16_f32 v98, v142, v143
	v_exp_f32_e32 v142, v109
	v_mul_f32_e32 v109, 0xbfb8aa3b, v137
	v_exp_f32_e32 v143, v109
	v_and_b32_e32 v145, 0xffff0000, v99
	s_waitcnt lgkmcnt(0)
	v_mul_f32_e32 v109, 0xbfb8aa3b, v138
	v_cvt_pk_bf16_f32 v158, v26, v27
	v_pk_mul_f32 v[142:143], v[142:143], v[144:145]
	v_lshlrev_b32_e32 v144, 16, v100
	v_cvt_pk_bf16_f32 v99, v142, v143
	v_exp_f32_e32 v142, v109
	v_mul_f32_e32 v109, 0xbfb8aa3b, v139
	v_exp_f32_e32 v143, v109
	v_and_b32_e32 v145, 0xffff0000, v100
	v_mul_f32_e32 v109, 0xbfb8aa3b, v140
	v_cvt_pk_bf16_f32 v159, v28, v29
	v_pk_mul_f32 v[142:143], v[142:143], v[144:145]
	v_lshlrev_b32_e32 v144, 16, v101
	v_cvt_pk_bf16_f32 v100, v142, v143
	v_exp_f32_e32 v142, v109
	v_mul_f32_e32 v109, 0xbfb8aa3b, v141
	v_exp_f32_e32 v143, v109
	v_and_b32_e32 v145, 0xffff0000, v101
	v_add_u32_e32 v216, 0xa800, v212
	v_add_u32_e32 v217, 0xb800, v212
	v_pk_mul_f32 v[142:143], v[142:143], v[144:145]
	v_add_u32_e32 v218, 0xc800, v212
	v_cvt_pk_bf16_f32 v101, v142, v143
	ds_write_b128 v181, v[98:101] offset:56320
	v_mul_f32_e32 v98, 0x3fb8aa3b, v134
	v_mul_f32_e32 v99, 0x3fb8aa3b, v135
	v_exp_f32_e32 v98, v98
	v_exp_f32_e32 v99, v99
	v_lshlrev_b32_e32 v100, 16, v94
	v_and_b32_e32 v101, 0xffff0000, v94
	s_mov_b32 s62, 0x8000
	v_pk_mul_f32 v[98:99], v[98:99], s[50:51] op_sel_hi:[1,0]
	s_add_u32 s76, s76, 0x60000
	v_pk_mul_f32 v[98:99], v[98:99], v[100:101]
	v_lshlrev_b32_e32 v100, 16, v95
	v_cvt_pk_bf16_f32 v94, v98, v99
	v_mul_f32_e32 v98, 0x3fb8aa3b, v136
	v_mul_f32_e32 v99, 0x3fb8aa3b, v137
	v_exp_f32_e32 v98, v98
	v_exp_f32_e32 v99, v99
	v_and_b32_e32 v101, 0xffff0000, v95
	s_waitcnt vmcnt(4)
	v_lshlrev_b32_e32 v136, 16, v90
	v_and_b32_e32 v137, 0xffff0000, v90
	v_pk_mul_f32 v[98:99], v[98:99], s[50:51] op_sel_hi:[1,0]
	s_addc_u32 s77, s77, 0
	v_pk_mul_f32 v[98:99], v[98:99], v[100:101]
	v_lshlrev_b32_e32 v100, 16, v96
	v_cvt_pk_bf16_f32 v95, v98, v99
	v_mul_f32_e32 v98, 0x3fb8aa3b, v138
	v_mul_f32_e32 v99, 0x3fb8aa3b, v139
	v_exp_f32_e32 v98, v98
	v_exp_f32_e32 v99, v99
	v_and_b32_e32 v101, 0xffff0000, v96
	s_add_i32 s64, s64, 64
	v_pk_mul_f32 v[98:99], v[98:99], s[50:51] op_sel_hi:[1,0]
	s_nop 0
	v_pk_mul_f32 v[98:99], v[98:99], v[100:101]
	v_lshlrev_b32_e32 v100, 16, v97
	v_cvt_pk_bf16_f32 v96, v98, v99
	v_mul_f32_e32 v98, 0x3fb8aa3b, v140
	v_mul_f32_e32 v99, 0x3fb8aa3b, v141
	v_exp_f32_e32 v98, v98
	v_exp_f32_e32 v99, v99
	v_and_b32_e32 v101, 0xffff0000, v97
	v_pk_mul_f32 v[98:99], v[98:99], s[50:51] op_sel_hi:[1,0]
	s_nop 0
	v_pk_mul_f32 v[98:99], v[98:99], v[100:101]
	s_nop 0
	v_cvt_pk_bf16_f32 v97, v98, v99
	ds_write_b128 v181, v[94:97] offset:38912
	ds_read_b128 v[94:97], v202 offset:6144
	ds_read_b128 v[98:101], v202 offset:6160
	s_waitcnt lgkmcnt(1)
	v_mul_f32_e32 v109, 0xbfb8aa3b, v94
	v_exp_f32_e32 v134, v109
	v_mul_f32_e32 v109, 0xbfb8aa3b, v95
	v_exp_f32_e32 v135, v109
	v_mul_f32_e32 v109, 0xbfb8aa3b, v96
	v_pk_mul_f32 v[134:135], v[134:135], v[136:137]
	s_nop 0
	v_cvt_pk_bf16_f32 v90, v134, v135
	v_exp_f32_e32 v134, v109
	v_mul_f32_e32 v109, 0xbfb8aa3b, v97
	v_exp_f32_e32 v135, v109
	v_lshlrev_b32_e32 v136, 16, v91
	v_and_b32_e32 v137, 0xffff0000, v91
	s_waitcnt lgkmcnt(0)
	v_mul_f32_e32 v109, 0xbfb8aa3b, v98
	v_pk_mul_f32 v[134:135], v[134:135], v[136:137]
	v_lshlrev_b32_e32 v136, 16, v92
	v_cvt_pk_bf16_f32 v91, v134, v135
	v_exp_f32_e32 v134, v109
	v_mul_f32_e32 v109, 0xbfb8aa3b, v99
	v_exp_f32_e32 v135, v109
	v_and_b32_e32 v137, 0xffff0000, v92
	v_mul_f32_e32 v109, 0xbfb8aa3b, v100
	v_pk_mul_f32 v[134:135], v[134:135], v[136:137]
	s_nop 0
	v_cvt_pk_bf16_f32 v92, v134, v135
	v_exp_f32_e32 v134, v109
	v_mul_f32_e32 v109, 0xbfb8aa3b, v101
	v_exp_f32_e32 v135, v109
	v_lshlrev_b32_e32 v136, 16, v93
	v_and_b32_e32 v137, 0xffff0000, v93
	v_pk_mul_f32 v[134:135], v[134:135], v[136:137]
	s_nop 0
	v_cvt_pk_bf16_f32 v93, v134, v135
	ds_write_b128 v182, v[90:93] offset:56320
	v_mul_f32_e32 v90, 0x3fb8aa3b, v94
	v_mul_f32_e32 v91, 0x3fb8aa3b, v95
	v_exp_f32_e32 v90, v90
	v_exp_f32_e32 v91, v91
	v_lshlrev_b32_e32 v92, 16, v70
	v_and_b32_e32 v93, 0xffff0000, v70
	v_pk_mul_f32 v[90:91], v[90:91], s[50:51] op_sel_hi:[1,0]
	s_nop 0
	v_pk_mul_f32 v[90:91], v[90:91], v[92:93]
	v_lshlrev_b32_e32 v92, 16, v71
	v_cvt_pk_bf16_f32 v70, v90, v91
	v_mul_f32_e32 v90, 0x3fb8aa3b, v96
	v_mul_f32_e32 v91, 0x3fb8aa3b, v97
	v_exp_f32_e32 v90, v90
	v_exp_f32_e32 v91, v91
	v_and_b32_e32 v93, 0xffff0000, v71
	v_pk_mul_f32 v[90:91], v[90:91], s[50:51] op_sel_hi:[1,0]
	s_nop 0
	v_pk_mul_f32 v[90:91], v[90:91], v[92:93]
	v_lshlrev_b32_e32 v92, 16, v72
	v_cvt_pk_bf16_f32 v71, v90, v91
	v_mul_f32_e32 v90, 0x3fb8aa3b, v98
	v_mul_f32_e32 v91, 0x3fb8aa3b, v99
	v_exp_f32_e32 v90, v90
	v_exp_f32_e32 v91, v91
	v_and_b32_e32 v93, 0xffff0000, v72
	v_pk_mul_f32 v[90:91], v[90:91], s[50:51] op_sel_hi:[1,0]
	s_nop 0
	v_pk_mul_f32 v[90:91], v[90:91], v[92:93]
	v_lshlrev_b32_e32 v92, 16, v73
	v_cvt_pk_bf16_f32 v72, v90, v91
	v_mul_f32_e32 v90, 0x3fb8aa3b, v100
	v_mul_f32_e32 v91, 0x3fb8aa3b, v101
	v_exp_f32_e32 v90, v90
	v_exp_f32_e32 v91, v91
	v_and_b32_e32 v93, 0xffff0000, v73
	v_pk_mul_f32 v[90:91], v[90:91], s[50:51] op_sel_hi:[1,0]
	s_nop 0
	v_pk_mul_f32 v[90:91], v[90:91], v[92:93]
	s_nop 0
	v_cvt_pk_bf16_f32 v73, v90, v91
	ds_write_b128 v182, v[70:73] offset:38912
	s_waitcnt vmcnt(3)
	ds_write_b128 v203, v[74:77]
	s_waitcnt vmcnt(2)
	ds_write_b128 v204, v[78:81]
	s_waitcnt vmcnt(1)
	ds_write_b128 v203, v[82:85] offset:16896
	s_waitcnt vmcnt(0)
	ds_write_b128 v205, v[86:89]
	s_waitcnt lgkmcnt(0)
	s_barrier
	s_waitcnt lgkmcnt(0)
	ds_read_b128 v[70:73], v206 offset:56320
	ds_read_b128 v[232:235], v180 offset:38912
	ds_read_b128 v[236:239], v206 offset:56384
	ds_read_b128 v[82:85], v180 offset:38976
	ds_read_b128 v[244:247], v206 offset:56448
	ds_read_b128 v[86:89], v180 offset:39040
	ds_read_b128 v[78:81], v206 offset:56512
	ds_read_b128 v[90:93], v180 offset:39104
	s_waitcnt lgkmcnt(6)
	v_mfma_f32_16x16x32_bf16 v[70:73], v[70:73], v[232:235], 0
	s_waitcnt lgkmcnt(4)
	v_mfma_f32_16x16x32_bf16 v[70:73], v[236:239], v[82:85], v[70:73]
	s_nop 0
	s_nop 0
	s_waitcnt lgkmcnt(2)
	v_mfma_f32_16x16x32_bf16 v[70:73], v[244:247], v[86:89], v[70:73]
	s_nop 0
	s_nop 0
	s_waitcnt lgkmcnt(0)
	v_mfma_f32_16x16x32_bf16 v[70:73], v[78:81], v[90:93], v[70:73]
	v_mov_b32_e32 v78, s49
	s_nop 6
	v_cndmask_b32_e64 v78, v70, v78, s[12:13]
	v_cndmask_b32_e64 v70, v78, v70, s[14:15]
	v_cndmask_b32_e64 v71, 0, v71, s[14:15]
	v_cndmask_b32_e64 v72, v72, 0, s[16:17]
	v_cndmask_b32_e64 v73, v73, 0, s[18:19]
	v_cvt_pk_bf16_f32 v70, v70, v71
	v_cvt_pk_bf16_f32 v71, v72, v73
	ds_write_b64 v207, v[70:71]
	ds_read_b128 v[236:239], v208 offset:56320
	ds_read_b128 v[244:247], v208 offset:56384
	s_waitcnt lgkmcnt(1)
	v_mfma_f32_16x16x32_bf16 v[70:73], v[236:239], v[232:235], 0
	ds_read_b128 v[232:235], v208 offset:56448
	ds_read_b128 v[74:77], v208 offset:56512
	s_nop 0
	s_waitcnt lgkmcnt(2)
	v_mfma_f32_16x16x32_bf16 v[70:73], v[244:247], v[82:85], v[70:73]
	s_nop 0
	s_waitcnt lgkmcnt(1)
	v_mfma_f32_16x16x32_bf16 v[70:73], v[232:235], v[86:89], v[70:73]
	s_nop 0
	s_waitcnt lgkmcnt(0)
	v_mfma_f32_16x16x32_bf16 v[70:73], v[74:77], v[90:93], v[70:73]
	v_mov_b32_e32 v74, s49
	s_nop 6
	v_cndmask_b32_e64 v74, v70, v74, s[20:21]
	v_cndmask_b32_e64 v70, v74, v70, s[22:23]
	v_cndmask_b32_e64 v71, 0, v71, s[22:23]
	v_cndmask_b32_e64 v72, v72, 0, s[24:25]
	v_cndmask_b32_e64 v73, v73, 0, s[26:27]
	v_cvt_pk_bf16_f32 v70, v70, v71
	v_cvt_pk_bf16_f32 v71, v72, v73
	ds_write_b64 v209, v[70:71]
	s_waitcnt lgkmcnt(0)
	s_barrier
	s_waitcnt lgkmcnt(0)
	ds_read_b64_tr_b16 v[80:81], v210 offset:2112
	ds_read_b64_tr_b16 v[78:79], v210
	ds_read_b64_tr_b16 v[82:83], v210 offset:32
	ds_read_b64_tr_b16 v[70:71], v210 offset:16896
	ds_read_b64_tr_b16 v[72:73], v210 offset:19008
	ds_read_b64_tr_b16 v[84:85], v210 offset:2144
	ds_read_b64_tr_b16 v[74:75], v210 offset:16928
	ds_read_b64_tr_b16 v[76:77], v210 offset:19040
	ds_read_b128 v[232:235], v211
	ds_read_b128 v[236:239], v211 offset:64
	ds_read_b128 v[244:247], v211 offset:2368
	ds_read_b128 v[142:145], v211 offset:4672
	ds_read_b128 v[150:153], v211 offset:6976
	ds_read2_b64 v[160:163], v215 offset1:4
	s_waitcnt lgkmcnt(5)
	v_mfma_f32_16x16x32_bf16 v[90:93], v[78:81], v[232:235], 0
	s_nop 0
	s_nop 0
	s_nop 0
	v_mfma_f32_16x16x32_bf16 v[86:89], v[82:85], v[232:235], 0
	ds_read_b128 v[232:235], v211 offset:2304
	s_waitcnt lgkmcnt(5)
	v_mfma_f32_16x16x32_bf16 v[90:93], v[70:73], v[236:239], v[90:93]
	v_mfma_f32_16x16x32_bf16 v[86:89], v[74:77], v[236:239], v[86:89]
	ds_read_b128 v[236:239], v211 offset:4608
	s_nop 0
	s_waitcnt lgkmcnt(1)
	v_mfma_f32_16x16x32_bf16 v[98:101], v[78:81], v[232:235], 0
	v_mfma_f32_16x16x32_bf16 v[94:97], v[82:85], v[232:235], 0
	ds_read_b128 v[232:235], v211 offset:6912
	v_mfma_f32_16x16x32_bf16 v[98:101], v[70:73], v[244:247], v[98:101]
	v_mfma_f32_16x16x32_bf16 v[94:97], v[74:77], v[244:247], v[94:97]
	ds_read2_b64 v[244:247], v216 offset0:32 offset1:36
	s_nop 0
	s_waitcnt lgkmcnt(2)
	v_mfma_f32_16x16x32_bf16 v[138:141], v[78:81], v[236:239], 0
	v_mfma_f32_16x16x32_bf16 v[134:137], v[82:85], v[236:239], 0
	ds_read2_b64 v[236:239], v217 offset0:64 offset1:68
	v_mfma_f32_16x16x32_bf16 v[138:141], v[70:73], v[142:145], v[138:141]
	v_mfma_f32_16x16x32_bf16 v[134:137], v[74:77], v[142:145], v[134:137]
	s_nop 0
	s_waitcnt lgkmcnt(2)
	v_mfma_f32_16x16x32_bf16 v[146:149], v[78:81], v[232:235], 0
	v_mfma_f32_16x16x32_bf16 v[142:145], v[82:85], v[232:235], 0
	ds_read2_b64 v[232:235], v218 offset0:96 offset1:100
	v_mfma_f32_16x16x32_bf16 v[146:149], v[70:73], v[150:153], v[146:149]
	v_mfma_f32_16x16x32_bf16 v[142:145], v[74:77], v[150:153], v[142:145]
	v_cvt_pk_bf16_f32 v150, v6, v7
	v_cvt_pk_bf16_f32 v151, v8, v9
	v_cvt_pk_bf16_f32 v152, v22, v23
	v_cvt_pk_bf16_f32 v153, v24, v25
	v_mfma_f32_16x16x32_bf16 v[86:89], v[156:159], v[160:163], v[86:89]
	s_nop 0
	v_mfma_f32_16x16x32_bf16 v[90:93], v[150:153], v[160:163], v[90:93]
	s_nop 0
	s_waitcnt lgkmcnt(2)
	v_mfma_f32_16x16x32_bf16 v[98:101], v[150:153], v[244:247], v[98:101]
	v_mfma_f32_16x16x32_bf16 v[94:97], v[156:159], v[244:247], v[94:97]
	ds_read2_b64 v[244:247], v215 offset0:8 offset1:12
	s_nop 0
	s_waitcnt lgkmcnt(2)
	v_mfma_f32_16x16x32_bf16 v[138:141], v[150:153], v[236:239], v[138:141]
	v_mfma_f32_16x16x32_bf16 v[134:137], v[156:159], v[236:239], v[134:137]
	ds_read2_b64 v[236:239], v216 offset0:40 offset1:44
	s_nop 0
	s_waitcnt lgkmcnt(2)
	v_mfma_f32_16x16x32_bf16 v[146:149], v[150:153], v[232:235], v[146:149]
	v_cvt_pk_bf16_f32 v150, v14, v15
	v_cvt_pk_bf16_f32 v151, v16, v17
	v_cvt_pk_bf16_f32 v152, v38, v39
	v_mfma_f32_16x16x32_bf16 v[142:145], v[156:159], v[232:235], v[142:145]
	ds_read2_b64 v[232:235], v217 offset0:72 offset1:76
	v_cvt_pk_bf16_f32 v153, v40, v41
	v_cvt_pk_bf16_f32 v156, v18, v19
	v_cvt_pk_bf16_f32 v157, v20, v21
	v_cvt_pk_bf16_f32 v158, v42, v43
	v_cvt_pk_bf16_f32 v159, v44, v45
	s_nop 0
	s_waitcnt lgkmcnt(2)
	v_mfma_f32_16x16x32_bf16 v[90:93], v[150:153], v[244:247], v[90:93]
	v_mfma_f32_16x16x32_bf16 v[86:89], v[156:159], v[244:247], v[86:89]
	ds_read2_b64 v[244:247], v218 offset0:104 offset1:108
	s_nop 0
	s_waitcnt lgkmcnt(2)
	v_mfma_f32_16x16x32_bf16 v[98:101], v[150:153], v[236:239], v[98:101]
	v_mfma_f32_16x16x32_bf16 v[94:97], v[156:159], v[236:239], v[94:97]
	ds_read2_b64 v[236:239], v215 offset0:16 offset1:20
	s_nop 0
	s_waitcnt lgkmcnt(2)
	v_mfma_f32_16x16x32_bf16 v[138:141], v[150:153], v[232:235], v[138:141]
	v_mfma_f32_16x16x32_bf16 v[134:137], v[156:159], v[232:235], v[134:137]
	ds_read2_b64 v[232:235], v216 offset0:48 offset1:52
	s_nop 0
	s_waitcnt lgkmcnt(2)
	v_mfma_f32_16x16x32_bf16 v[146:149], v[150:153], v[244:247], v[146:149]
	v_cvt_pk_bf16_f32 v150, v30, v31
	v_cvt_pk_bf16_f32 v151, v32, v33
	v_cvt_pk_bf16_f32 v152, v46, v47
	v_mfma_f32_16x16x32_bf16 v[142:145], v[156:159], v[244:247], v[142:145]
	ds_read2_b64 v[244:247], v217 offset0:80 offset1:84
	v_cvt_pk_bf16_f32 v153, v48, v49
	v_cvt_pk_bf16_f32 v156, v34, v35
	v_cvt_pk_bf16_f32 v157, v36, v37
	v_cvt_pk_bf16_f32 v158, v54, v55
	v_cvt_pk_bf16_f32 v159, v56, v57
	s_nop 0
	s_waitcnt lgkmcnt(2)
	v_mfma_f32_16x16x32_bf16 v[90:93], v[150:153], v[236:239], v[90:93]
	v_mfma_f32_16x16x32_bf16 v[86:89], v[156:159], v[236:239], v[86:89]
	ds_read2_b64 v[236:239], v218 offset0:112 offset1:116
	s_nop 0
	s_waitcnt lgkmcnt(2)
	v_mfma_f32_16x16x32_bf16 v[98:101], v[150:153], v[232:235], v[98:101]
	v_mfma_f32_16x16x32_bf16 v[94:97], v[156:159], v[232:235], v[94:97]
	ds_read2_b64 v[232:235], v215 offset0:24 offset1:28
	s_nop 0
	s_waitcnt lgkmcnt(2)
	v_mfma_f32_16x16x32_bf16 v[138:141], v[150:153], v[244:247], v[138:141]
	v_mfma_f32_16x16x32_bf16 v[134:137], v[156:159], v[244:247], v[134:137]
	ds_read2_b64 v[244:247], v216 offset0:56 offset1:60
	s_nop 0
	s_waitcnt lgkmcnt(2)
	v_mfma_f32_16x16x32_bf16 v[146:149], v[150:153], v[236:239], v[146:149]
	v_cvt_pk_bf16_f32 v150, v50, v51
	v_cvt_pk_bf16_f32 v151, v52, v53
	v_cvt_pk_bf16_f32 v152, v62, v63
	v_mfma_f32_16x16x32_bf16 v[142:145], v[156:159], v[236:239], v[142:145]
	ds_read2_b64 v[236:239], v217 offset0:88 offset1:92
	ds_read2_b64 v[160:163], v218 offset0:120 offset1:124
	v_cvt_pk_bf16_f32 v153, v64, v65
	v_cvt_pk_bf16_f32 v156, v58, v59
	v_cvt_pk_bf16_f32 v157, v60, v61
	v_cvt_pk_bf16_f32 v158, v66, v67
	v_cvt_pk_bf16_f32 v159, v68, v69
	s_nop 0
	s_waitcnt lgkmcnt(3)
	v_mfma_f32_16x16x32_bf16 v[90:93], v[150:153], v[232:235], v[90:93]
	v_mfma_f32_16x16x32_bf16 v[86:89], v[156:159], v[232:235], v[86:89]
	ds_read_b64_tr_b16 v[234:235], v213 offset:57408
	ds_read_b64_tr_b16 v[232:233], v213 offset:56320
	s_nop 0
	s_nop 5
	v_cvt_pk_bf16_f32 v90, v90, v91
	v_cvt_pk_bf16_f32 v91, v92, v93
	s_waitcnt lgkmcnt(4)
	v_mfma_f32_16x16x32_bf16 v[98:101], v[150:153], v[244:247], v[98:101]
	v_lshl_add_u64 v[92:93], s[74:75], 0, v[116:117]
	v_cvt_pk_bf16_f32 v86, v86, v87
	v_cvt_pk_bf16_f32 v87, v88, v89
	v_mfma_f32_16x16x32_bf16 v[94:97], v[156:159], v[244:247], v[94:97]
	s_nop 0
	v_add_co_u32_e32 v88, vcc, s62, v92
	s_waitcnt lgkmcnt(3)
	v_mfma_f32_16x16x32_bf16 v[138:141], v[150:153], v[236:239], v[138:141]
	global_store_dwordx2 v[92:93], v[86:87], off offset:32
	v_cvt_pk_bf16_f32 v86, v98, v99
	v_cvt_pk_bf16_f32 v87, v100, v101
	v_mfma_f32_16x16x32_bf16 v[134:137], v[156:159], v[236:239], v[134:137]
	s_nop 0
	v_addc_co_u32_e32 v89, vcc, 0, v93, vcc
	global_store_dwordx2 v[88:89], v[86:87], off
	v_cvt_pk_bf16_f32 v86, v94, v95
	v_cvt_pk_bf16_f32 v87, v96, v97
	s_mov_b32 s62, 0x10000
	s_waitcnt lgkmcnt(2)
	v_mfma_f32_16x16x32_bf16 v[146:149], v[150:153], v[160:163], v[146:149]
	global_store_dwordx2 v[88:89], v[86:87], off offset:32
	v_add_co_u32_e32 v88, vcc, s62, v92
	v_mfma_f32_16x16x32_bf16 v[142:145], v[156:159], v[160:163], v[142:145]
	v_cvt_pk_bf16_f32 v86, v138, v139
	v_cvt_pk_bf16_f32 v87, v140, v141
	v_addc_co_u32_e32 v89, vcc, 0, v93, vcc
	global_store_dwordx2 v[88:89], v[86:87], off
	v_cvt_pk_bf16_f32 v86, v134, v135
	v_cvt_pk_bf16_f32 v87, v136, v137
	global_store_dwordx2 v[88:89], v[86:87], off offset:32
	v_add_co_u32_e32 v88, vcc, s81, v92
	v_cvt_pk_bf16_f32 v86, v146, v147
	v_cvt_pk_bf16_f32 v87, v148, v149
	v_addc_co_u32_e32 v89, vcc, 0, v93, vcc
	global_store_dwordx2 v[88:89], v[86:87], off
	v_cvt_pk_bf16_f32 v86, v142, v143
	v_cvt_pk_bf16_f32 v87, v144, v145
	global_store_dwordx2 v[92:93], v[90:91], off
	ds_read_b64_tr_b16 v[90:91], v213 offset:56352
	ds_read_b64_tr_b16 v[244:245], v213 offset:65024
	ds_read_b64_tr_b16 v[246:247], v214 offset:57408
	ds_read_b64_tr_b16 v[94:95], v214 offset:57440
	ds_read_b64_tr_b16 v[92:93], v213 offset:57440
	global_store_dwordx2 v[88:89], v[86:87], off offset:32
	s_nop 0
	s_nop 0
	s_nop 0
	s_waitcnt lgkmcnt(5)
	v_mfma_f32_16x16x32_bf16 v[6:9], v[232:235], v[78:81], v[6:9]
	s_add_u32 s74, s74, 0x20000
	s_addc_u32 s75, s75, 0
	s_add_i32 s92, s92, 1
	v_mfma_f32_16x16x32_bf16 v[10:13], v[232:235], v[82:85], v[10:13]
	s_nop 0
	s_nop 0
	s_nop 0
	s_nop 0
	s_cmp_lg_u32 s76, 0x300000
	s_waitcnt lgkmcnt(2)
	v_mfma_f32_16x16x32_bf16 v[6:9], v[244:247], v[70:73], v[6:9]
	v_mfma_f32_16x16x32_bf16 v[10:13], v[244:247], v[74:77], v[10:13]
	s_waitcnt lgkmcnt(0)
	v_mfma_f32_16x16x32_bf16 v[22:25], v[90:93], v[78:81], v[22:25]
	v_mfma_f32_16x16x32_bf16 v[26:29], v[90:93], v[82:85], v[26:29]
	ds_read_b64_tr_b16 v[92:93], v213 offset:65056
	ds_read_b64_tr_b16 v[236:237], v213 offset:56384
	ds_read_b64_tr_b16 v[238:239], v213 offset:57472
	ds_read_b64_tr_b16 v[232:233], v213 offset:65088
	ds_read_b64_tr_b16 v[234:235], v214 offset:57472
	ds_read_b64_tr_b16 v[244:245], v213 offset:56416
	ds_read_b64_tr_b16 v[246:247], v213 offset:57504
	s_waitcnt lgkmcnt(4)
	v_mfma_f32_16x16x32_bf16 v[14:17], v[236:239], v[78:81], v[14:17]
	v_mfma_f32_16x16x32_bf16 v[18:21], v[236:239], v[82:85], v[18:21]
	ds_read_b64_tr_b16 v[236:237], v213 offset:65120
	ds_read_b64_tr_b16 v[238:239], v214 offset:57504
	s_nop 0
	s_nop 0
	s_waitcnt lgkmcnt(4)
	v_mfma_f32_16x16x32_bf16 v[14:17], v[232:235], v[70:73], v[14:17]
	v_mfma_f32_16x16x32_bf16 v[18:21], v[232:235], v[74:77], v[18:21]
	ds_read_b64_tr_b16 v[232:233], v213 offset:56448
	ds_read_b64_tr_b16 v[234:235], v213 offset:57536
	s_nop 0
	s_nop 0
	s_waitcnt lgkmcnt(4)
	v_mfma_f32_16x16x32_bf16 v[38:41], v[244:247], v[78:81], v[38:41]
	v_mfma_f32_16x16x32_bf16 v[42:45], v[244:247], v[82:85], v[42:45]
	ds_read_b64_tr_b16 v[244:245], v213 offset:65152
	ds_read_b64_tr_b16 v[246:247], v214 offset:57536
	s_nop 0
	s_nop 0
	s_waitcnt lgkmcnt(4)
	v_mfma_f32_16x16x32_bf16 v[38:41], v[236:239], v[70:73], v[38:41]
	v_mfma_f32_16x16x32_bf16 v[42:45], v[236:239], v[74:77], v[42:45]
	ds_read_b64_tr_b16 v[236:237], v213 offset:56480
	ds_read_b64_tr_b16 v[238:239], v213 offset:57568
	s_nop 0
	s_nop 0
	s_waitcnt lgkmcnt(4)
	v_mfma_f32_16x16x32_bf16 v[30:33], v[232:235], v[78:81], v[30:33]
	v_mfma_f32_16x16x32_bf16 v[34:37], v[232:235], v[82:85], v[34:37]
	ds_read_b64_tr_b16 v[232:233], v213 offset:65184
	ds_read_b64_tr_b16 v[234:235], v214 offset:57568
	s_nop 0
	s_nop 0
	s_waitcnt lgkmcnt(4)
	v_mfma_f32_16x16x32_bf16 v[30:33], v[244:247], v[70:73], v[30:33]
	v_mfma_f32_16x16x32_bf16 v[34:37], v[244:247], v[74:77], v[34:37]
	ds_read_b64_tr_b16 v[244:245], v213 offset:56512
	ds_read_b64_tr_b16 v[246:247], v213 offset:57600
	s_nop 0
	s_nop 0
	s_waitcnt lgkmcnt(4)
	v_mfma_f32_16x16x32_bf16 v[46:49], v[236:239], v[78:81], v[46:49]
	v_mfma_f32_16x16x32_bf16 v[54:57], v[236:239], v[82:85], v[54:57]
	ds_read_b64_tr_b16 v[236:237], v213 offset:65216
	ds_read_b64_tr_b16 v[238:239], v214 offset:57600
	ds_read_b64_tr_b16 v[86:87], v213 offset:56544
	ds_read_b64_tr_b16 v[88:89], v213 offset:57632
	s_nop 0
	s_nop 0
	s_waitcnt lgkmcnt(6)
	v_mfma_f32_16x16x32_bf16 v[46:49], v[232:235], v[70:73], v[46:49]
	v_mfma_f32_16x16x32_bf16 v[54:57], v[232:235], v[74:77], v[54:57]
	s_nop 0
	s_nop 0
	s_waitcnt lgkmcnt(4)
	v_mfma_f32_16x16x32_bf16 v[50:53], v[244:247], v[78:81], v[50:53]
	v_mfma_f32_16x16x32_bf16 v[58:61], v[244:247], v[82:85], v[58:61]
	s_nop 0
	s_nop 0
	s_waitcnt lgkmcnt(2)
	v_mfma_f32_16x16x32_bf16 v[50:53], v[236:239], v[70:73], v[50:53]
	v_mfma_f32_16x16x32_bf16 v[58:61], v[236:239], v[74:77], v[58:61]
	s_nop 0
	s_nop 0
	s_waitcnt lgkmcnt(0)
	v_mfma_f32_16x16x32_bf16 v[62:65], v[86:89], v[78:81], v[62:65]
	ds_read_b64_tr_b16 v[78:79], v213 offset:65248
	ds_read_b64_tr_b16 v[80:81], v214 offset:57632
	v_mfma_f32_16x16x32_bf16 v[66:69], v[86:89], v[82:85], v[66:69]
	v_mfma_f32_16x16x32_bf16 v[22:25], v[92:95], v[70:73], v[22:25]
	s_waitcnt lgkmcnt(0)
	v_mfma_f32_16x16x32_bf16 v[62:65], v[78:81], v[70:73], v[62:65]
	v_lshl_add_u32 v70, s93, 9, v179
	ds_read_b128 v[232:235], v70 offset:4096
	ds_read_b128 v[244:247], v70 offset:4160
	ds_read_b128 v[236:239], v70 offset:4224
	v_mfma_f32_16x16x32_bf16 v[26:29], v[92:95], v[74:77], v[26:29]
	v_mfma_f32_16x16x32_bf16 v[66:69], v[78:81], v[74:77], v[66:69]
	s_nop 0
	s_nop 0
	s_waitcnt lgkmcnt(2)
	v_mov_b32_e32 v72, v232
	s_nop 0
	v_mov_b32_e32 v73, v233
	s_nop 0
	v_mov_b32_e32 v74, v234
	s_nop 0
	v_mov_b32_e32 v75, v235
	ds_read_b128 v[232:235], v70 offset:4288
	v_pk_mul_f32 v[6:7], v[6:7], v[72:73]
	v_pk_mul_f32 v[10:11], v[10:11], v[72:73]
	v_pk_mul_f32 v[8:9], v[8:9], v[74:75]
	v_pk_mul_f32 v[12:13], v[12:13], v[74:75]
	s_nop 0
	s_nop 0
	s_waitcnt lgkmcnt(2)
	v_mov_b32_e32 v72, v244
	s_nop 0
	v_mov_b32_e32 v73, v245
	s_nop 0
	v_mov_b32_e32 v74, v246
	s_nop 0
	v_mov_b32_e32 v75, v247
	ds_read_b128 v[244:247], v70 offset:4352
	v_pk_mul_f32 v[22:23], v[22:23], v[72:73]
	v_pk_mul_f32 v[26:27], v[26:27], v[72:73]
	v_pk_mul_f32 v[24:25], v[24:25], v[74:75]
	v_pk_mul_f32 v[28:29], v[28:29], v[74:75]
	s_nop 0
	s_nop 0
	s_waitcnt lgkmcnt(2)
	v_mov_b32_e32 v72, v236
	s_nop 0
	v_mov_b32_e32 v73, v237
	s_nop 0
	v_mov_b32_e32 v74, v238
	s_nop 0
	v_mov_b32_e32 v75, v239
	ds_read_b128 v[236:239], v70 offset:4416
	v_pk_mul_f32 v[14:15], v[14:15], v[72:73]
	v_pk_mul_f32 v[18:19], v[18:19], v[72:73]
	v_pk_mul_f32 v[16:17], v[16:17], v[74:75]
	v_pk_mul_f32 v[20:21], v[20:21], v[74:75]
	s_nop 0
	s_nop 0
	s_waitcnt lgkmcnt(2)
	v_mov_b32_e32 v72, v232
	s_nop 0
	v_mov_b32_e32 v73, v233
	s_nop 0
	v_mov_b32_e32 v74, v234
	s_nop 0
	v_mov_b32_e32 v75, v235
	ds_read_b128 v[232:235], v70 offset:4480
	v_pk_mul_f32 v[38:39], v[38:39], v[72:73]
	v_pk_mul_f32 v[42:43], v[42:43], v[72:73]
	v_pk_mul_f32 v[40:41], v[40:41], v[74:75]
	v_pk_mul_f32 v[44:45], v[44:45], v[74:75]
	s_nop 0
	s_nop 0
	s_waitcnt lgkmcnt(2)
	v_mov_b32_e32 v72, v244
	s_nop 0
	v_mov_b32_e32 v73, v245
	s_nop 0
	v_mov_b32_e32 v74, v246
	s_nop 0
	v_mov_b32_e32 v75, v247
	v_pk_mul_f32 v[30:31], v[30:31], v[72:73]
	v_pk_mul_f32 v[34:35], v[34:35], v[72:73]
	v_pk_mul_f32 v[32:33], v[32:33], v[74:75]
	v_pk_mul_f32 v[36:37], v[36:37], v[74:75]
	s_nop 0
	s_nop 0
	s_waitcnt lgkmcnt(1)
	v_mov_b32_e32 v72, v236
	s_nop 0
	v_mov_b32_e32 v73, v237
	s_nop 0
	v_mov_b32_e32 v74, v238
	s_nop 0
	v_mov_b32_e32 v75, v239
	v_pk_mul_f32 v[46:47], v[46:47], v[72:73]
	v_pk_mul_f32 v[54:55], v[54:55], v[72:73]
	v_pk_mul_f32 v[48:49], v[48:49], v[74:75]
	v_pk_mul_f32 v[56:57], v[56:57], v[74:75]
	s_nop 0
	s_nop 0
	s_waitcnt lgkmcnt(0)
	v_mov_b32_e32 v72, v232
	s_nop 0
	v_mov_b32_e32 v73, v233
	s_nop 0
	v_mov_b32_e32 v74, v234
	s_nop 0
	v_mov_b32_e32 v75, v235
	v_pk_mul_f32 v[50:51], v[50:51], v[72:73]
	v_pk_mul_f32 v[58:59], v[58:59], v[72:73]
	ds_read_b128 v[70:73], v70 offset:4544
	v_pk_mul_f32 v[52:53], v[52:53], v[74:75]
	v_pk_mul_f32 v[60:61], v[60:61], v[74:75]
	s_nop 0
	s_nop 0
	s_nop 0
	s_nop 0
	s_nop 0
	s_nop 0
	s_nop 0
	s_nop 0
	s_waitcnt lgkmcnt(0)
	v_pk_mul_f32 v[62:63], v[62:63], v[70:71]
	v_pk_mul_f32 v[66:67], v[66:67], v[70:71]
	v_pk_mul_f32 v[64:65], v[64:65], v[72:73]
	v_pk_mul_f32 v[68:69], v[68:69], v[72:73]
	s_waitcnt lgkmcnt(0)
	s_cbranch_scc0 .LBB0_672
.LBB0_664:
	s_add_u32 s62, s61, s76
	s_addc_u32 s63, s91, s77
	v_lshl_add_u64 v[70:71], s[62:63], 0, v[112:113]
	s_add_u32 s62, s55, s76
	s_addc_u32 s63, s57, s77
	s_add_u32 s62, s62, s68
	v_add_co_u32_e32 v74, vcc, s95, v70
	s_addc_u32 s63, s63, 0
	s_nop 0
	v_addc_co_u32_e32 v75, vcc, 0, v71, vcc
	v_lshl_add_u64 v[86:87], s[62:63], 0, v[114:115]
	v_add_co_u32_e32 v78, vcc, s81, v86
	s_and_b32 s93, s92, 1
	s_add_i32 s69, s66, 0xf0
	v_addc_co_u32_e32 v79, vcc, 0, v87, vcc
	s_cmp_eq_u32 s93, 0
	v_add_co_u32_e32 v82, vcc, s95, v86
	s_cselect_b64 s[78:79], -1, 0
	s_nop 0
	v_addc_co_u32_e32 v83, vcc, 0, v87, vcc
	s_and_b64 s[62:63], s[78:79], exec
	global_load_dwordx4 v[94:97], v[70:71], off
	global_load_dwordx4 v[98:101], v[70:71], off offset:1024
	s_nop 0
	global_load_dwordx4 v[70:73], v[74:75], off
	global_load_dwordx4 v[90:93], v[74:75], off offset:1024
	s_cselect_b32 s62, 0xf0, s69
	global_load_dwordx4 v[74:77], v[86:87], off
	v_add_co_u32_e32 v86, vcc, s96, v86
	v_and_b32_e32 v137, 63, v154
	v_lshl_add_u32 v137, v137, 2, s62
	s_nop 0
	v_addc_co_u32_e32 v87, vcc, 0, v87, vcc
	global_load_dwordx4 v[78:81], v[78:79], off
	s_nop 0
	global_load_dwordx4 v[82:85], v[82:83], off
	s_nop 0
	global_load_dwordx4 v[86:89], v[86:87], off
	s_waitcnt lgkmcnt(0)
	ds_read2st64_b32 v[134:135], v137 offset1:1
	ds_read2st64_b32 v[232:233], v137 offset0:2 offset1:3
	ds_read2st64_b32 v[146:147], v137 offset0:8 offset1:9
	ds_read2st64_b32 v[236:237], v137 offset0:4 offset1:5
	ds_read2st64_b32 v[244:245], v137 offset0:6 offset1:7
	s_waitcnt lgkmcnt(4)
	v_mfma_f32_16x16x4_f32 v[138:141], v134, v104, 0
	s_nop 0
	v_mfma_f32_16x16x4_f32 v[138:141], v135, v105, v[138:141]
	s_waitcnt lgkmcnt(3)
	v_mfma_f32_16x16x4_f32 v[138:141], v232, v106, v[138:141]
	v_mfma_f32_16x16x4_f32 v[138:141], v233, v107, v[138:141]
	ds_read2st64_b32 v[232:233], v137 offset0:10 offset1:11
	s_nop 0
	s_nop 8
	v_add_f32_e32 v134, v108, v138
	v_min_f32_e32 v109, 0, v134
	v_mul_f32_e64 v134, |v134|, s97
	v_exp_f32_e32 v134, v134
	v_add_f32_e32 v135, v108, v139
	v_add_f32_e32 v136, v108, v140
	v_add_f32_e32 v138, v108, v141
	v_add_f32_e32 v134, 1.0, v134
	v_log_f32_e32 v134, v134
	s_nop 0
	v_fmac_f32_e32 v109, 0xbf317218, v134
	v_min_f32_e32 v134, 0, v135
	v_mul_f32_e64 v135, |v135|, s97
	v_exp_f32_e32 v135, v135
	v_fma_f32 v109, v109, s0, 0
	v_add_f32_e32 v135, 1.0, v135
	v_log_f32_e32 v135, v135
	s_nop 0
	v_fmac_f32_e32 v134, 0xbf317218, v135
	v_min_f32_e32 v135, 0, v136
	v_mul_f32_e64 v136, |v136|, s97
	v_exp_f32_e32 v136, v136
	v_fmamk_f32 v134, v134, 0x3d800000, v109
	v_add_f32_e32 v136, 1.0, v136
	v_log_f32_e32 v136, v136
	s_nop 0
	v_fmac_f32_e32 v135, 0xbf317218, v136
	v_min_f32_e32 v136, 0, v138
	v_mul_f32_e64 v138, |v138|, s97
	v_exp_f32_e32 v138, v138
	v_fmamk_f32 v135, v135, 0x3d800000, v134
	v_add_f32_e32 v138, 1.0, v138
	v_log_f32_e32 v138, v138
	s_nop 0
	v_fmac_f32_e32 v136, 0xbf317218, v138
	s_waitcnt lgkmcnt(2)
	v_mfma_f32_16x16x4_f32 v[138:141], v236, v104, 0
	v_fmamk_f32 v136, v136, 0x3d800000, v135
	v_mfma_f32_16x16x4_f32 v[138:141], v237, v105, v[138:141]
	ds_read2st64_b32 v[236:237], v137 offset0:12 offset1:13
	s_nop 0
	s_waitcnt lgkmcnt(2)
	v_mfma_f32_16x16x4_f32 v[138:141], v244, v106, v[138:141]
	v_mfma_f32_16x16x4_f32 v[138:141], v245, v107, v[138:141]
	ds_read2st64_b32 v[244:245], v137 offset0:14 offset1:15
	s_nop 9
	v_add_f32_e32 v142, v108, v138
	v_min_f32_e32 v138, 0, v142
	v_mul_f32_e64 v142, |v142|, s97
	v_exp_f32_e32 v142, v142
	s_nop 0
	v_add_f32_e32 v142, 1.0, v142
	v_log_f32_e32 v142, v142
	s_nop 0
	v_fmac_f32_e32 v138, 0xbf317218, v142
	v_add_f32_e32 v142, v108, v139
	v_min_f32_e32 v139, 0, v142
	v_mul_f32_e64 v142, |v142|, s97
	v_exp_f32_e32 v142, v142
	s_nop 0
	v_add_f32_e32 v142, 1.0, v142
	v_log_f32_e32 v142, v142
	s_nop 0
	v_fmac_f32_e32 v139, 0xbf317218, v142
	v_add_f32_e32 v142, v108, v140
	v_min_f32_e32 v140, 0, v142
	v_mul_f32_e64 v142, |v142|, s97
	v_exp_f32_e32 v142, v142
	s_nop 0
	v_add_f32_e32 v142, 1.0, v142
	v_log_f32_e32 v142, v142
	s_nop 0
	v_fmac_f32_e32 v140, 0xbf317218, v142
	v_add_f32_e32 v142, v108, v141
	v_min_f32_e32 v141, 0, v142
	v_mul_f32_e64 v142, |v142|, s97
	v_exp_f32_e32 v142, v142
	s_nop 0
	v_add_f32_e32 v142, 1.0, v142
	v_log_f32_e32 v142, v142
	s_nop 0
	v_fmac_f32_e32 v141, 0xbf317218, v142
	v_mfma_f32_16x16x4_f32 v[142:145], v146, v104, 0
	v_mfma_f32_16x16x4_f32 v[142:145], v147, v105, v[142:145]
	s_nop 0
	s_waitcnt lgkmcnt(2)
	v_mfma_f32_16x16x4_f32 v[142:145], v232, v106, v[142:145]
	v_mfma_f32_16x16x4_f32 v[142:145], v233, v107, v[142:145]
	s_nop 0
	s_nop 8
	v_add_f32_e32 v142, v108, v142
	v_min_f32_e32 v148, 0, v142
	v_mul_f32_e64 v142, |v142|, s97
	v_exp_f32_e32 v142, v142
	s_nop 0
	v_add_f32_e32 v142, 1.0, v142
	v_log_f32_e32 v142, v142
	s_nop 0
	v_fmac_f32_e32 v148, 0xbf317218, v142
	v_add_f32_e32 v142, v108, v143
	v_min_f32_e32 v149, 0, v142
	v_mul_f32_e64 v142, |v142|, s97
	v_exp_f32_e32 v142, v142
	s_nop 0
	v_add_f32_e32 v142, 1.0, v142
	v_log_f32_e32 v142, v142
	s_nop 0
	v_fmac_f32_e32 v149, 0xbf317218, v142
	v_add_f32_e32 v142, v108, v144
	v_min_f32_e32 v150, 0, v142
	v_mul_f32_e64 v142, |v142|, s97
	v_exp_f32_e32 v142, v142
	s_nop 0
	v_add_f32_e32 v142, 1.0, v142
	v_log_f32_e32 v142, v142
	s_nop 0
	v_fmac_f32_e32 v150, 0xbf317218, v142
	v_add_f32_e32 v142, v108, v145
	v_min_f32_e32 v151, 0, v142
	v_mul_f32_e64 v142, |v142|, s97
	v_exp_f32_e32 v142, v142
	s_nop 0
	v_add_f32_e32 v142, 1.0, v142
	v_log_f32_e32 v142, v142
	s_nop 0
	v_fmac_f32_e32 v151, 0xbf317218, v142
	s_waitcnt lgkmcnt(1)
	v_mfma_f32_16x16x4_f32 v[142:145], v236, v104, 0
	v_mfma_f32_16x16x4_f32 v[142:145], v237, v105, v[142:145]
	s_nop 0
	s_waitcnt lgkmcnt(0)
	v_mfma_f32_16x16x4_f32 v[142:145], v244, v106, v[142:145]
	v_mfma_f32_16x16x4_f32 v[142:145], v245, v107, v[142:145]
	s_nop 9
	v_add_f32_e32 v137, v108, v142
	v_min_f32_e32 v142, 0, v137
	v_mul_f32_e64 v137, |v137|, s97
	v_exp_f32_e32 v137, v137
	s_nop 0
	v_add_f32_e32 v137, 1.0, v137
	v_log_f32_e32 v137, v137
	s_nop 0
	v_fmac_f32_e32 v142, 0xbf317218, v137
	v_add_f32_e32 v137, v108, v143
	v_min_f32_e32 v143, 0, v137
	v_mul_f32_e64 v137, |v137|, s97
	v_exp_f32_e32 v137, v137
	s_nop 0
	v_add_f32_e32 v137, 1.0, v137
	v_log_f32_e32 v137, v137
	s_nop 0
	v_fmac_f32_e32 v143, 0xbf317218, v137
	v_add_f32_e32 v137, v108, v144
	v_min_f32_e32 v144, 0, v137
	v_mul_f32_e64 v137, |v137|, s97
	v_exp_f32_e32 v137, v137
	s_nop 0
	v_add_f32_e32 v137, 1.0, v137
	v_log_f32_e32 v137, v137
	s_nop 0
	v_fmac_f32_e32 v144, 0xbf317218, v137
	v_add_f32_e32 v137, v108, v145
	v_min_f32_e32 v145, 0, v137
	v_mul_f32_e64 v137, |v137|, s97
	v_exp_f32_e32 v137, v137
	s_nop 0
	v_add_f32_e32 v137, 1.0, v137
	v_log_f32_e32 v137, v137
	s_nop 0
	v_fmac_f32_e32 v145, 0xbf317218, v137
	v_fmamk_f32 v137, v138, 0x3d800000, v136
	v_fmamk_f32 v138, v139, 0x3d800000, v137
	v_fmamk_f32 v139, v140, 0x3d800000, v138
	v_fmamk_f32 v140, v141, 0x3d800000, v139
	v_fmamk_f32 v141, v148, 0x3d800000, v140
	v_fmamk_f32 v146, v149, 0x3d800000, v141
	v_fmamk_f32 v147, v150, 0x3d800000, v146
	v_fmamk_f32 v148, v151, 0x3d800000, v147
	v_fmamk_f32 v142, v142, 0x3d800000, v148
	v_fmamk_f32 v143, v143, 0x3d800000, v142
	v_fmamk_f32 v144, v144, 0x3d800000, v143
	v_fmamk_f32 v145, v145, 0x3d800000, v144
	ds_bpermute_b32 v149, v186, v145
	ds_bpermute_b32 v150, v187, v145
	ds_bpermute_b32 v151, v188, v145
	s_waitcnt lgkmcnt(2)
	v_cndmask_b32_e64 v149, v149, 0, s[4:5]
	s_waitcnt lgkmcnt(1)
	v_cndmask_b32_e64 v150, 0, v150, s[6:7]
	v_add_f32_e32 v149, v149, v150
	s_waitcnt lgkmcnt(0)
	v_cndmask_b32_e64 v150, 0, v151, s[8:9]
	v_add_f32_e32 v149, v149, v150
	v_add_f32_e32 v109, v109, v149
	v_add_f32_e32 v134, v134, v149
	ds_write2st64_b32 v200, v109, v134 offset0:24 offset1:26
	v_add_f32_e32 v109, v135, v149
	v_add_f32_e32 v134, v136, v149
	ds_write2st64_b32 v200, v109, v134 offset0:28 offset1:30
	v_add_f32_e32 v109, v137, v149
	v_add_f32_e32 v134, v138, v149
	ds_write2st64_b32 v200, v109, v134 offset0:32 offset1:34
	v_add_f32_e32 v109, v139, v149
	v_add_f32_e32 v134, v140, v149
	ds_write2st64_b32 v200, v109, v134 offset0:36 offset1:38
	v_add_f32_e32 v109, v141, v149
	v_add_f32_e32 v134, v146, v149
	ds_write2st64_b32 v200, v109, v134 offset0:40 offset1:42
	v_add_f32_e32 v109, v149, v147
	v_add_f32_e32 v134, v149, v148
	ds_write2st64_b32 v200, v109, v134 offset0:44 offset1:46
	v_add_f32_e32 v109, v149, v142
	v_add_f32_e32 v134, v149, v143
	ds_write2st64_b32 v200, v109, v134 offset0:48 offset1:50
	v_add_f32_e32 v109, v149, v144
	v_add_f32_e32 v134, v149, v145
	ds_write2st64_b32 v200, v109, v134 offset0:52 offset1:54
	s_waitcnt lgkmcnt(0)
	s_barrier
	s_and_saveexec_b64 s[62:63], s[10:11]
	s_cbranch_execz .LBB0_666
	ds_read_b32 v109, v178 offset:38400
	v_lshl_add_u32 v134, s93, 9, v178
	s_waitcnt lgkmcnt(0)
	v_mul_f32_e32 v255, 0x3fb8aa3b, v109
	v_exp_f32_e32 v255, v255
	s_nop 0
	ds_write_b32 v134, v255 offset:4096

.LBB0_679:
	s_or_b64 exec, exec, s[62:63]
	s_waitcnt lgkmcnt(0)
	s_barrier
	s_waitcnt lgkmcnt(0)
	ds_read_b128 v[136:139], v184
	ds_read_b128 v[142:145], v184 offset:16
	s_waitcnt vmcnt(8)
	v_lshlrev_b32_e32 v156, 16, v166
	v_and_b32_e32 v157, 0xffff0000, v166
	v_lshlrev_b32_e32 v166, 16, v167
	s_waitcnt lgkmcnt(1)
	v_mov_b32_e32 v81, v138
	v_lshlrev_b32_e32 v138, 16, v168
	v_mov_b32_e32 v80, v137
	v_mov_b32_e32 v137, v139
	v_and_b32_e32 v139, 0xffff0000, v168
	v_mul_f32_e32 v0, 0xbfb8aa3b, v138
	v_pk_add_f32 v[80:81], v[80:81], v[136:137]
	s_waitcnt lgkmcnt(0)
	v_mov_b32_e32 v136, v144
	v_exp_f32_e32 v0, v0
	v_mul_f32_e32 v144, 0xbfb8aa3b, v139
	v_exp_f32_e32 v144, v144
	v_mov_b32_e32 v137, v142
	v_mov_b32_e32 v142, v145
	v_add_f32_e32 v0, 1.0, v0
	v_pk_add_f32 v[146:147], v[136:137], v[142:143]
	v_rcp_f32_e32 v136, v0
	v_add_f32_e32 v0, 1.0, v144
	v_lshlrev_b32_e32 v142, 16, v169
	v_rcp_f32_e32 v137, v0
	v_and_b32_e32 v143, 0xffff0000, v169
	v_mul_f32_e32 v0, 0xbfb8aa3b, v142
	v_exp_f32_e32 v0, v0
	v_mul_f32_e32 v144, 0xbfb8aa3b, v143
	v_exp_f32_e32 v144, v144
	v_pk_mul_f32 v[148:149], v[136:137], v[138:139]
	v_add_f32_e32 v0, 1.0, v0
	v_rcp_f32_e32 v136, v0
	v_add_f32_e32 v0, 1.0, v144
	v_rcp_f32_e32 v137, v0
	v_mul_f32_e32 v0, 0xbfb8aa3b, v156
	v_exp_f32_e32 v0, v0
	v_mul_f32_e32 v138, 0xbfb8aa3b, v157
	v_exp_f32_e32 v138, v138
	v_and_b32_e32 v167, 0xffff0000, v167
	v_add_f32_e32 v0, 1.0, v0
	v_rcp_f32_e32 v224, v0
	v_add_f32_e32 v0, 1.0, v138
	v_rcp_f32_e32 v225, v0
	v_mul_f32_e32 v0, 0xbfb8aa3b, v166
	v_pk_mul_f32 v[168:169], v[136:137], v[142:143]
	v_exp_f32_e32 v0, v0
	v_mul_f32_e32 v136, 0xbfb8aa3b, v167
	v_exp_f32_e32 v142, v136
	ds_read_b128 v[136:139], v184 offset:512
	v_add_f32_e32 v0, 1.0, v0
	v_rcp_f32_e32 v226, v0
	v_add_f32_e32 v0, 1.0, v142
	ds_read_b128 v[142:145], v184 offset:528
	s_waitcnt lgkmcnt(1)
	v_mov_b32_e32 v228, v137
	v_mov_b32_e32 v229, v138
	v_mov_b32_e32 v137, v139
	v_pk_add_f32 v[136:137], v[228:229], v[136:137]
	s_waitcnt lgkmcnt(0)
	v_mov_b32_e32 v138, v144
	v_mov_b32_e32 v139, v142
	v_mov_b32_e32 v142, v145
	v_pk_add_f32 v[138:139], v[138:139], v[142:143]
	v_mov_b32_e32 v142, v136
	v_mov_b32_e32 v143, v80
	v_mov_b32_e32 v80, v137
	v_pk_add_f32 v[80:81], v[142:143], v[80:81]
	v_mov_b32_e32 v136, v139
	v_mov_b32_e32 v137, v147
	v_pk_add_f32 v[80:81], v[80:81], v[136:137]
	v_mov_b32_e32 v139, v146
	s_mov_b32 s62, 0x358637bd
	v_pk_add_f32 v[136:137], v[138:139], v[80:81]
	v_mov_b64_e32 v[80:81], s[62:63]
	v_pk_fma_f32 v[136:137], v[136:137], s[52:53], v[80:81] op_sel_hi:[1,0,0]
	v_rcp_f32_e32 v227, v0
	v_mul_f32_e32 v0, 0x4b800000, v137
	v_cmp_gt_f32_e32 vcc, s1, v137
	v_pk_mul_f32 v[142:143], v[224:225], v[156:157]
	v_pk_mul_f32 v[144:145], v[226:227], v[166:167]
	v_cndmask_b32_e32 v0, v137, v0, vcc
	v_rsq_f32_e32 v0, v0
	v_lshl_add_u64 v[138:139], s[56:57], 0, v[116:117]
	s_waitcnt vmcnt(4)
	v_lshlrev_b32_e32 v146, 16, v159
	v_and_b32_e32 v147, 0xffff0000, v159
	v_mul_f32_e32 v137, 0x45800000, v0
	v_cndmask_b32_e32 v0, v0, v137, vcc
	v_pk_mul_f32 v[106:107], v[106:107], v[0:1] op_sel_hi:[1,0]
	v_pk_mul_f32 v[108:109], v[108:109], v[0:1] op_sel_hi:[1,0]
	v_pk_mul_f32 v[102:103], v[102:103], v[0:1] op_sel_hi:[1,0]
	v_pk_mul_f32 v[104:105], v[104:105], v[0:1] op_sel_hi:[1,0]
	v_mul_f32_e32 v0, 0x4b800000, v136
	v_cmp_gt_f32_e32 vcc, s1, v136
	s_waitcnt vmcnt(0)
	v_pk_mul_f32 v[102:103], v[70:71], v[102:103]
	v_pk_mul_f32 v[104:105], v[72:73], v[104:105]
	v_cndmask_b32_e32 v0, v136, v0, vcc
	v_pk_mul_f32 v[102:103], v[142:143], v[102:103]
	v_pk_mul_f32 v[104:105], v[144:145], v[104:105]
	v_rsq_f32_e32 v0, v0
	v_cvt_pk_bf16_f32 v102, v102, v103
	v_cvt_pk_bf16_f32 v103, v104, v105
	global_store_dwordx2 v[138:139], v[102:103], off offset:32
	v_lshlrev_b32_e32 v102, 16, v164
	v_mul_f32_e32 v103, 0xbfb8aa3b, v102
	v_exp_f32_e32 v104, v103
	v_mul_f32_e32 v103, 0x45800000, v0
	v_cndmask_b32_e32 v0, v0, v103, vcc
	v_and_b32_e32 v103, 0xffff0000, v164
	v_mul_f32_e32 v105, 0xbfb8aa3b, v103
	v_exp_f32_e32 v105, v105
	v_pk_mul_f32 v[106:107], v[74:75], v[106:107]
	v_pk_mul_f32 v[108:109], v[76:77], v[108:109]
	v_pk_mul_f32 v[106:107], v[148:149], v[106:107]
	v_pk_mul_f32 v[108:109], v[168:169], v[108:109]
	v_cvt_pk_bf16_f32 v106, v106, v107
	v_cvt_pk_bf16_f32 v107, v108, v109
	v_lshlrev_b32_e32 v108, 16, v165
	v_and_b32_e32 v109, 0xffff0000, v165
	v_add_f32_e32 v104, 1.0, v104
	v_add_f32_e32 v105, 1.0, v105
	v_mul_f32_e32 v136, 0xbfb8aa3b, v108
	v_mul_f32_e32 v137, 0xbfb8aa3b, v109
	v_rcp_f32_e32 v104, v104
	v_rcp_f32_e32 v105, v105
	v_exp_f32_e32 v136, v136
	v_exp_f32_e32 v137, v137
	global_store_dwordx2 v[138:139], v[106:107], off
	v_pk_mul_f32 v[102:103], v[104:105], v[102:103]
	v_add_f32_e32 v104, 1.0, v136
	v_add_f32_e32 v105, 1.0, v137
	v_rcp_f32_e32 v104, v104
	v_rcp_f32_e32 v105, v105
	v_pk_mul_f32 v[106:107], v[152:153], v[0:1] op_sel_hi:[1,0]
	v_pk_mul_f32 v[100:101], v[100:101], v[0:1] op_sel_hi:[1,0]
	v_pk_mul_f32 v[106:107], v[74:75], v[106:107]
	v_pk_mul_f32 v[100:101], v[76:77], v[100:101]
	v_pk_mul_f32 v[104:105], v[104:105], v[108:109]
	v_pk_mul_f32 v[102:103], v[102:103], v[106:107]
	v_pk_mul_f32 v[100:101], v[104:105], v[100:101]
	v_cvt_pk_bf16_f32 v102, v102, v103
	v_cvt_pk_bf16_f32 v103, v100, v101
	v_lshlrev_b32_e32 v100, 16, v162
	v_mul_f32_e32 v101, 0xbfb8aa3b, v100
	v_exp_f32_e32 v106, v101
	v_lshl_add_u64 v[104:105], s[56:57], 0, v[120:121]
	v_and_b32_e32 v101, 0xffff0000, v162
	global_store_dwordx2 v[104:105], v[102:103], off
	v_mul_f32_e32 v103, 0xbfb8aa3b, v101
	v_exp_f32_e32 v103, v103
	v_lshlrev_b32_e32 v104, 16, v163
	v_and_b32_e32 v105, 0xffff0000, v163
	v_add_f32_e32 v102, 1.0, v106
	v_add_f32_e32 v103, 1.0, v103
	v_mul_f32_e32 v106, 0xbfb8aa3b, v104
	v_mul_f32_e32 v107, 0xbfb8aa3b, v105
	v_rcp_f32_e32 v102, v102
	v_rcp_f32_e32 v103, v103
	v_exp_f32_e32 v106, v106
	v_exp_f32_e32 v107, v107
	v_pk_mul_f32 v[98:99], v[98:99], v[0:1] op_sel_hi:[1,0]
	v_pk_mul_f32 v[100:101], v[102:103], v[100:101]
	v_add_f32_e32 v102, 1.0, v106
	v_add_f32_e32 v103, 1.0, v107
	v_rcp_f32_e32 v102, v102
	v_rcp_f32_e32 v103, v103
	v_pk_mul_f32 v[98:99], v[70:71], v[98:99]
	v_pk_mul_f32 v[96:97], v[96:97], v[0:1] op_sel_hi:[1,0]
	v_pk_mul_f32 v[98:99], v[100:101], v[98:99]
	v_pk_mul_f32 v[96:97], v[72:73], v[96:97]
	v_pk_mul_f32 v[100:101], v[102:103], v[104:105]
	v_cvt_pk_bf16_f32 v102, v98, v99
	v_pk_mul_f32 v[100:101], v[100:101], v[96:97]
	ds_read_b128 v[96:99], v184 offset:1024
	v_cvt_pk_bf16_f32 v103, v100, v101
	v_lshl_add_u64 v[100:101], s[56:57], 0, v[122:123]
	global_store_dwordx2 v[100:101], v[102:103], off
	ds_read_b128 v[100:103], v184 offset:1040
	s_waitcnt lgkmcnt(1)
	v_mov_b32_e32 v105, v98
	v_lshlrev_b32_e32 v98, 16, v160
	v_mov_b32_e32 v104, v97
	v_mov_b32_e32 v97, v99
	v_and_b32_e32 v99, 0xffff0000, v160
	v_mul_f32_e32 v0, 0xbfb8aa3b, v98
	v_pk_add_f32 v[104:105], v[104:105], v[96:97]
	v_exp_f32_e32 v0, v0
	v_mul_f32_e32 v97, 0xbfb8aa3b, v99
	s_waitcnt lgkmcnt(0)
	v_mov_b32_e32 v96, v102
	v_exp_f32_e32 v102, v97
	v_lshlrev_b32_e32 v108, 16, v161
	v_mov_b32_e32 v97, v100
	v_add_f32_e32 v0, 1.0, v0
	v_and_b32_e32 v109, 0xffff0000, v161
	v_mul_f32_e32 v100, 0xbfb8aa3b, v108
	v_rcp_f32_e32 v106, v0
	v_add_f32_e32 v0, 1.0, v102
	v_exp_f32_e32 v100, v100
	v_mul_f32_e32 v102, 0xbfb8aa3b, v109
	v_exp_f32_e32 v102, v102
	v_rcp_f32_e32 v107, v0
	v_add_f32_e32 v0, 1.0, v100
	v_rcp_f32_e32 v136, v0
	v_add_f32_e32 v0, 1.0, v102
	v_rcp_f32_e32 v137, v0
	v_mov_b32_e32 v100, v103
	v_pk_add_f32 v[138:139], v[96:97], v[100:101]
	v_pk_mul_f32 v[106:107], v[106:107], v[98:99]
	v_pk_mul_f32 v[108:109], v[136:137], v[108:109]
	v_lshlrev_b32_e32 v136, 16, v158
	v_and_b32_e32 v137, 0xffff0000, v158
	v_mul_f32_e32 v0, 0xbfb8aa3b, v136
	v_exp_f32_e32 v0, v0
	v_mul_f32_e32 v96, 0xbfb8aa3b, v137
	v_exp_f32_e32 v96, v96
	v_lshl_add_u64 v[142:143], s[56:57], 0, v[124:125]
	v_add_f32_e32 v0, 1.0, v0
	v_rcp_f32_e32 v144, v0
	v_add_f32_e32 v0, 1.0, v96
	v_rcp_f32_e32 v145, v0
	v_mul_f32_e32 v0, 0xbfb8aa3b, v146
	v_exp_f32_e32 v0, v0
	v_mul_f32_e32 v96, 0xbfb8aa3b, v147
	v_exp_f32_e32 v100, v96
	ds_read_b128 v[96:99], v184 offset:1536
	v_add_f32_e32 v0, 1.0, v0
	v_rcp_f32_e32 v148, v0
	v_add_f32_e32 v0, 1.0, v100
	ds_read_b128 v[100:103], v184 offset:1552
	ds_read_b64_tr_b16 v[234:235], v213 offset:57408
	ds_read_b64_tr_b16 v[232:233], v213 offset:56320
	s_waitcnt lgkmcnt(3)
	v_mov_b32_e32 v152, v97
	v_mov_b32_e32 v153, v98
	v_mov_b32_e32 v97, v99
	v_pk_add_f32 v[96:97], v[152:153], v[96:97]
	s_waitcnt lgkmcnt(2)
	v_mov_b32_e32 v98, v102
	v_mov_b32_e32 v99, v100
	v_mov_b32_e32 v100, v103
	v_pk_add_f32 v[98:99], v[98:99], v[100:101]
	v_mov_b32_e32 v100, v96
	v_mov_b32_e32 v101, v104
	v_mov_b32_e32 v104, v97
	v_pk_add_f32 v[96:97], v[100:101], v[104:105]
	v_mov_b32_e32 v100, v99
	v_mov_b32_e32 v101, v139
	v_pk_add_f32 v[96:97], v[96:97], v[100:101]
	v_mov_b32_e32 v99, v138
	v_pk_add_f32 v[96:97], v[98:99], v[96:97]
	v_rcp_f32_e32 v149, v0
	v_pk_fma_f32 v[80:81], v[96:97], s[52:53], v[80:81] op_sel_hi:[1,0,0]
	v_pk_mul_f32 v[96:97], v[144:145], v[136:137]
	v_mul_f32_e32 v0, 0x4b800000, v81
	v_cmp_gt_f32_e32 vcc, s1, v81
	v_pk_mul_f32 v[152:153], v[148:149], v[146:147]
	v_lshl_add_u64 v[168:169], s[56:57], 0, v[126:127]
	v_cndmask_b32_e32 v0, v81, v0, vcc
	v_rsq_f32_e32 v0, v0
	s_add_i32 s75, s75, 1
	s_add_u32 s60, s60, 0xfffa0000
	s_addc_u32 s61, s61, -1
	v_mul_f32_e32 v81, 0x45800000, v0
	v_cndmask_b32_e32 v0, v0, v81, vcc
	v_pk_mul_f32 v[90:91], v[90:91], v[0:1] op_sel_hi:[1,0]
	v_pk_mul_f32 v[94:95], v[94:95], v[0:1] op_sel_hi:[1,0]
	v_pk_mul_f32 v[90:91], v[74:75], v[90:91]
	v_pk_mul_f32 v[94:95], v[76:77], v[94:95]
	v_pk_mul_f32 v[90:91], v[106:107], v[90:91]
	v_pk_mul_f32 v[94:95], v[108:109], v[94:95]
	v_cvt_pk_bf16_f32 v90, v90, v91
	v_cvt_pk_bf16_f32 v91, v94, v95
	ds_read_b64_tr_b16 v[94:95], v210 offset:2112
	global_store_dwordx2 v[142:143], v[90:91], off
	v_pk_mul_f32 v[90:91], v[92:93], v[0:1] op_sel_hi:[1,0]
	ds_read_b64_tr_b16 v[92:93], v210
	ds_read_b64_tr_b16 v[98:99], v210 offset:2144
	v_pk_mul_f32 v[88:89], v[88:89], v[0:1] op_sel_hi:[1,0]
	v_mul_f32_e32 v0, 0x4b800000, v80
	v_cmp_gt_f32_e32 vcc, s1, v80
	v_pk_mul_f32 v[90:91], v[70:71], v[90:91]
	v_pk_mul_f32 v[224:225], v[72:73], v[88:89]
	v_cndmask_b32_e32 v0, v80, v0, vcc
	v_pk_mul_f32 v[108:109], v[96:97], v[90:91]
	ds_read_b64_tr_b16 v[96:97], v210 offset:32
	ds_read_b64_tr_b16 v[100:101], v213 offset:56352
	ds_read_b64_tr_b16 v[104:105], v213 offset:56384
	ds_read_b64_tr_b16 v[136:137], v213 offset:56416
	ds_read_b64_tr_b16 v[102:103], v213 offset:57440
	ds_read_b64_tr_b16 v[106:107], v213 offset:57472
	ds_read_b64_tr_b16 v[138:139], v213 offset:57504
	ds_read_b64_tr_b16 v[142:143], v213 offset:65024
	ds_read_b64_tr_b16 v[144:145], v214 offset:57408
	ds_read_b64_tr_b16 v[146:147], v210 offset:16896
	ds_read_b64_tr_b16 v[148:149], v210 offset:19008
	ds_read_b64_tr_b16 v[158:159], v210 offset:19040
	ds_read_b64_tr_b16 v[156:157], v210 offset:16928
	ds_read_b64_tr_b16 v[236:237], v213 offset:65056
	ds_read_b64_tr_b16 v[160:161], v213 offset:65088
	ds_read_b64_tr_b16 v[164:165], v213 offset:65120
	ds_read_b64_tr_b16 v[238:239], v214 offset:57440
	ds_read_b64_tr_b16 v[162:163], v214 offset:57472
	ds_read_b64_tr_b16 v[166:167], v214 offset:57504
	ds_read_b64_tr_b16 v[244:245], v213 offset:56448
	ds_read_b64_tr_b16 v[246:247], v213 offset:57536
	s_nop 0
	s_nop 0
	s_nop 0
	s_nop 0
	s_nop 0
	s_nop 0
	s_nop 0
	s_nop 0
	s_nop 0
	s_nop 0
	s_nop 0
	s_nop 0
	v_rsq_f32_e32 v0, v0
	s_nop 0
	s_nop 0
	s_nop 0
	s_nop 0
	s_nop 0
	s_nop 0
	s_waitcnt lgkmcnt(15)
	v_mfma_f32_16x16x32_bf16 v[10:13], v[100:103], v[92:95], v[10:13]
	v_and_b32_e32 v81, 0xffff0000, v150
	v_mul_f32_e32 v80, 0x45800000, v0
	v_cndmask_b32_e32 v0, v0, v80, vcc
	v_mfma_f32_16x16x32_bf16 v[18:21], v[100:103], v[96:99], v[18:21]
	v_lshlrev_b32_e32 v80, 16, v150
	v_mul_f32_e32 v100, 0xbfb8aa3b, v80
	v_mul_f32_e32 v101, 0xbfb8aa3b, v81
	v_mfma_f32_16x16x32_bf16 v[30:33], v[232:235], v[92:95], v[30:33]
	v_exp_f32_e32 v100, v100
	v_pk_mul_f32 v[86:87], v[86:87], v[0:1] op_sel_hi:[1,0]
	v_pk_mul_f32 v[152:153], v[152:153], v[224:225]
	v_mfma_f32_16x16x32_bf16 v[6:9], v[232:235], v[96:99], v[6:9]
	s_nop 0
	s_nop 0
	s_nop 0
	s_nop 0
	s_nop 0
	s_nop 0
	v_pk_mul_f32 v[74:75], v[74:75], v[86:87]
	v_lshlrev_b32_e32 v86, 16, v151
	s_waitcnt lgkmcnt(4)
	v_mfma_f32_16x16x32_bf16 v[10:13], v[236:239], v[146:149], v[10:13]
	v_mul_f32_e32 v87, 0xbfb8aa3b, v86
	v_cvt_pk_bf16_f32 v108, v108, v109
	v_cvt_pk_bf16_f32 v109, v152, v153
	v_mfma_f32_16x16x32_bf16 v[18:21], v[236:239], v[156:159], v[18:21]
	v_exp_f32_e32 v89, v101
	v_add_f32_e32 v88, 1.0, v100
	v_rcp_f32_e32 v88, v88
	global_store_dwordx2 v[168:169], v[108:109], off
	v_add_f32_e32 v89, 1.0, v89
	v_rcp_f32_e32 v89, v89
	v_mfma_f32_16x16x32_bf16 v[14:17], v[104:107], v[92:95], v[14:17]
	v_mul_f32_e64 v82, v82, v0
	v_mul_f32_e64 v83, v83, v0
	v_pk_mul_f32 v[78:79], v[78:79], v[0:1] op_sel_hi:[1,0]
	v_pk_mul_f32 v[80:81], v[88:89], v[80:81]
	v_exp_f32_e32 v88, v87
	v_pk_mul_f32 v[80:81], v[80:81], v[74:75]
	v_and_b32_e32 v87, 0xffff0000, v151
	v_mfma_f32_16x16x32_bf16 v[26:29], v[104:107], v[96:99], v[26:29]
	v_add_f32_e32 v74, 1.0, v88
	v_rcp_f32_e32 v88, v74
	v_mul_f32_e32 v74, 0xbfb8aa3b, v87
	v_exp_f32_e32 v89, v74
	v_pk_mul_f32 v[74:75], v[84:85], v[0:1] op_sel_hi:[1,0]
	ds_read_b64_tr_b16 v[84:85], v213 offset:56480
	v_mfma_f32_16x16x32_bf16 v[38:41], v[136:139], v[92:95], v[38:41]
	v_mul_f32_e64 v108, v76, v74
	v_mul_f32_e64 v109, v77, v75
	v_add_f32_e32 v74, 1.0, v89
	v_rcp_f32_e32 v89, v74
	s_nop 0
	s_nop 0
	v_mfma_f32_16x16x32_bf16 v[50:53], v[136:139], v[96:99], v[50:53]
	v_cvt_pk_bf16_f32 v80, v80, v81
	v_pk_mul_f32 v[136:137], v[88:89], v[86:87]
	ds_read_b64_tr_b16 v[88:89], v213 offset:56512
	ds_read_b64_tr_b16 v[100:101], v213 offset:56544
	ds_read_b64_tr_b16 v[86:87], v213 offset:57568
	ds_read_b64_tr_b16 v[90:91], v213 offset:57600
	ds_read_b64_tr_b16 v[102:103], v213 offset:57632
	ds_read_b64_tr_b16 v[104:105], v213 offset:65152
	ds_read_b64_tr_b16 v[106:107], v214 offset:57536
	ds_read_b64_tr_b16 v[232:233], v213 offset:65184
	s_nop 0
	s_nop 0
	s_nop 0
	s_nop 0
	s_nop 0
	s_nop 0
	s_nop 0
	s_nop 0
	s_waitcnt lgkmcnt(9)
	v_mfma_f32_16x16x32_bf16 v[22:25], v[244:247], v[92:95], v[22:25]
	v_mul_f32_e64 v108, v136, v108
	v_mul_f32_e64 v109, v137, v109
	ds_read_b64_tr_b16 v[136:137], v213 offset:65216
	v_pk_mul_f32 v[70:71], v[70:71], v[82:83]
	v_cvt_pk_bf16_f32 v81, v108, v109
	v_mfma_f32_16x16x32_bf16 v[34:37], v[244:247], v[96:99], v[34:37]
	v_lshl_add_u64 v[108:109], s[56:57], 0, v[128:129]
	v_pk_mul_f32 v[72:73], v[72:73], v[78:79]
	v_lshl_add_u32 v0, s67, 9, v179
	v_mfma_f32_16x16x32_bf16 v[30:33], v[142:145], v[146:149], v[30:33]
	s_sub_i32 s54, s54, 64
	v_mfma_f32_16x16x32_bf16 v[6:9], v[142:145], v[156:159], v[6:9]
	ds_read_b64_tr_b16 v[142:143], v213 offset:65248
	ds_read_b64_tr_b16 v[234:235], v214 offset:57568
	ds_read_b64_tr_b16 v[138:139], v214 offset:57600
	ds_read_b64_tr_b16 v[144:145], v214 offset:57632
	ds_read_b128 v[236:239], v0 offset:4096
	ds_read_b128 v[244:247], v0 offset:4160
	s_nop 0
	s_nop 0
	s_nop 0
	s_nop 0
	s_nop 0
	s_nop 0
	global_store_dwordx2 v[108:109], v[80:81], off
	v_lshlrev_b32_e32 v80, 16, v140
	v_and_b32_e32 v81, 0xffff0000, v140
	s_waitcnt lgkmcnt(8)
	v_mfma_f32_16x16x32_bf16 v[22:25], v[104:107], v[146:149], v[22:25]
	v_mfma_f32_16x16x32_bf16 v[34:37], v[104:107], v[156:159], v[34:37]
	v_mul_f32_e32 v104, 0xbfb8aa3b, v80
	v_mul_f32_e32 v105, 0xbfb8aa3b, v81
	v_exp_f32_e32 v104, v104
	v_mfma_f32_16x16x32_bf16 v[42:45], v[84:87], v[92:95], v[42:45]
	v_mfma_f32_16x16x32_bf16 v[54:57], v[84:87], v[96:99], v[54:57]
	v_exp_f32_e32 v85, v105
	v_add_f32_e32 v84, 1.0, v104
	v_rcp_f32_e32 v84, v84
	s_waitcnt lgkmcnt(4)
	v_mfma_f32_16x16x32_bf16 v[42:45], v[232:235], v[146:149], v[42:45]
	v_add_f32_e32 v85, 1.0, v85
	v_rcp_f32_e32 v85, v85
	v_mfma_f32_16x16x32_bf16 v[54:57], v[232:235], v[156:159], v[54:57]
	ds_read_b128 v[232:235], v0 offset:4224
	v_mul_f32_e64 v74, v84, v80
	v_mul_f32_e64 v75, v85, v81
	v_pk_mul_f32 v[70:71], v[74:75], v[70:71]
	v_lshlrev_b32_e32 v74, 16, v141
	v_and_b32_e32 v75, 0xffff0000, v141
	v_mul_f32_e32 v76, 0xbfb8aa3b, v74
	v_mul_f32_e32 v77, 0xbfb8aa3b, v75
	v_exp_f32_e32 v76, v76
	v_exp_f32_e32 v77, v77
	v_cvt_pk_bf16_f32 v78, v70, v71
	v_lshl_add_u64 v[80:81], s[56:57], 0, v[130:131]
	v_add_f32_e32 v76, 1.0, v76
	v_add_f32_e32 v77, 1.0, v77
	v_rcp_f32_e32 v76, v76
	v_rcp_f32_e32 v77, v77
	v_mfma_f32_16x16x32_bf16 v[14:17], v[160:163], v[146:149], v[14:17]
	s_add_u32 s56, s56, 0xfffe0000
	s_addc_u32 s57, s57, -1
	v_pk_mul_f32 v[74:75], v[76:77], v[74:75]
	v_mfma_f32_16x16x32_bf16 v[26:29], v[160:163], v[156:159], v[26:29]
	v_mul_f32_e64 v74, v74, v72
	v_mul_f32_e64 v75, v75, v73
	s_nop 0
	v_cvt_pk_bf16_f32 v79, v74, v75
	s_nop 0
	global_store_dwordx2 v[80:81], v[78:79], off
	v_mfma_f32_16x16x32_bf16 v[38:41], v[164:167], v[146:149], v[38:41]
	s_nop 0
	s_waitcnt lgkmcnt(2)
	v_mov_b32_e32 v82, v236
	v_mov_b32_e32 v83, v237
	v_mov_b32_e32 v70, v238
	v_mov_b32_e32 v71, v239
	ds_read_b128 v[236:239], v0 offset:4288
	s_nop 0
	s_nop 0
	s_nop 0
	v_mfma_f32_16x16x32_bf16 v[50:53], v[164:167], v[156:159], v[50:53]
	s_add_u32 s58, s58, 0xfffe0000
	v_pk_mul_f32 v[32:33], v[32:33], v[70:71]
	v_pk_mul_f32 v[8:9], v[8:9], v[70:71]
	s_waitcnt lgkmcnt(2)
	v_mov_b32_e32 v70, v244
	v_mov_b32_e32 v71, v246
	v_mov_b32_e32 v78, v70
	v_mov_b32_e32 v70, v245
	v_mov_b32_e32 v80, v71
	s_nop 0
	v_mov_b32_e32 v81, v247
	ds_read_b128 v[244:247], v0 offset:4352
	v_mov_b32_e32 v79, v70
	s_nop 0
	s_nop 0
	v_pk_mul_f32 v[30:31], v[30:31], v[82:83]
	v_pk_mul_f32 v[6:7], v[6:7], v[82:83]
	v_pk_mul_f32 v[12:13], v[12:13], v[80:81]
	s_nop 0
	s_waitcnt lgkmcnt(2)
	v_mov_b32_e32 v82, v232
	v_mov_b32_e32 v83, v233
	v_mov_b32_e32 v70, v234
	v_mov_b32_e32 v71, v235
	ds_read_b128 v[232:235], v0 offset:4416
	s_nop 0
	s_nop 0
	v_pk_mul_f32 v[10:11], v[10:11], v[78:79]
	v_pk_mul_f32 v[20:21], v[20:21], v[80:81]
	v_pk_mul_f32 v[18:19], v[18:19], v[78:79]
	v_pk_mul_f32 v[16:17], v[16:17], v[70:71]
	v_pk_mul_f32 v[28:29], v[28:29], v[70:71]
	s_waitcnt lgkmcnt(2)
	v_mov_b32_e32 v70, v236
	v_mov_b32_e32 v71, v238
	v_mov_b32_e32 v78, v70
	v_mov_b32_e32 v70, v237
	v_mov_b32_e32 v80, v71
	s_nop 0
	v_mov_b32_e32 v81, v239
	ds_read_b128 v[236:239], v0 offset:4480
	v_mov_b32_e32 v79, v70
	s_nop 0
	s_nop 0
	s_nop 0
	v_pk_mul_f32 v[40:41], v[40:41], v[80:81]
	v_pk_mul_f32 v[38:39], v[38:39], v[78:79]
	s_nop 0
	v_pk_mul_f32 v[14:15], v[14:15], v[82:83]
	v_pk_mul_f32 v[26:27], v[26:27], v[82:83]
	s_waitcnt lgkmcnt(2)
	v_mov_b32_e32 v82, v244
	v_mov_b32_e32 v83, v245
	v_mov_b32_e32 v70, v246
	v_mov_b32_e32 v71, v247
	ds_read_b128 v[244:247], v0 offset:4544
	s_nop 0
	s_nop 0
	v_pk_mul_f32 v[52:53], v[52:53], v[80:81]
	v_pk_mul_f32 v[50:51], v[50:51], v[78:79]
	v_mfma_f32_16x16x32_bf16 v[46:49], v[88:91], v[92:95], v[46:49]
	v_mul_f32_e64 v24, v24, v70
	v_mul_f32_e64 v25, v25, v71
	v_pk_mul_f32 v[36:37], v[36:37], v[70:71]
	s_waitcnt lgkmcnt(2)
	v_mov_b32_e32 v70, v232
	v_mov_b32_e32 v71, v234
	v_mov_b32_e32 v78, v70
	v_mov_b32_e32 v70, v233
	v_mov_b32_e32 v80, v71
	s_nop 0
	v_mov_b32_e32 v81, v235
	v_mov_b32_e32 v79, v70
	s_nop 0
	s_nop 0
	v_mfma_f32_16x16x32_bf16 v[62:65], v[88:91], v[96:99], v[62:65]
	s_nop 0
	s_addc_u32 s59, s59, -1
	s_nop 0
	s_waitcnt lgkmcnt(1)
	v_mov_b32_e32 v70, v236
	v_mov_b32_e32 v0, v237
	v_mov_b32_e32 v71, v238
	v_mfma_f32_16x16x32_bf16 v[58:61], v[100:103], v[92:95], v[58:61]
	v_mov_b32_e32 v72, v71
	s_nop 0
	v_mov_b32_e32 v73, v239
	v_mfma_f32_16x16x32_bf16 v[66:69], v[100:103], v[96:99], v[66:69]
	v_mov_b32_e32 v71, v0
	s_nop 0
	s_waitcnt lgkmcnt(0)
	v_mov_b32_e32 v74, v244
	v_mov_b32_e32 v0, v245
	v_mov_b32_e32 v75, v246
	v_mov_b32_e32 v76, v75
	v_mov_b32_e32 v75, v247
	v_mfma_f32_16x16x32_bf16 v[46:49], v[136:139], v[146:149], v[46:49]
	v_mov_b32_e32 v77, v75
	v_mov_b32_e32 v75, v0
	v_pk_mul_f32 v[22:23], v[22:23], v[82:83]
	v_mfma_f32_16x16x32_bf16 v[62:65], v[136:139], v[156:159], v[62:65]
	v_mul_f32_e64 v34, v34, v82
	v_mul_f32_e64 v35, v35, v83
	v_pk_mul_f32 v[44:45], v[44:45], v[80:81]
	v_pk_mul_f32 v[42:43], v[42:43], v[78:79]
	v_mfma_f32_16x16x32_bf16 v[58:61], v[142:145], v[146:149], v[58:61]
	v_mul_f32_e64 v56, v56, v80
	v_mul_f32_e64 v57, v57, v81
	v_pk_mul_f32 v[54:55], v[54:55], v[78:79]
	v_pk_mul_f32 v[48:49], v[48:49], v[72:73]
	v_mfma_f32_16x16x32_bf16 v[66:69], v[142:145], v[156:159], v[66:69]
	v_mul_f32_e64 v46, v46, v70
	v_mul_f32_e64 v47, v47, v71
	v_pk_mul_f32 v[64:65], v[64:65], v[72:73]
	v_pk_mul_f32 v[62:63], v[62:63], v[70:71]
	v_pk_mul_f32 v[60:61], v[60:61], v[76:77]
	v_pk_mul_f32 v[58:59], v[58:59], v[74:75]
	s_nop 1
	v_pk_mul_f32 v[68:69], v[68:69], v[76:77]
	s_cmp_lg_u32 s75, 8
	v_pk_mul_f32 v[66:67], v[66:67], v[74:75]
	s_waitcnt lgkmcnt(0)
	s_cbranch_scc0 .LBB0_654
.LBB0_680:
	s_add_u32 s62, s71, s60
	s_addc_u32 s63, s74, s61
	s_add_u32 s72, s48, s60
	s_addc_u32 s73, s70, s61
	s_add_u32 s55, s72, s68
	v_lshl_add_u64 v[70:71], s[62:63], 0, v[112:113]
	s_addc_u32 s63, s73, 0
	s_add_u32 s62, s55, 0xafc0800
	v_add_co_u32_e32 v74, vcc, s95, v70
	s_addc_u32 s63, s63, 0
	s_nop 0
	v_addc_co_u32_e32 v75, vcc, 0, v71, vcc
	v_lshl_add_u64 v[86:87], s[62:63], 0, v[114:115]
	v_add_co_u32_e32 v78, vcc, s81, v86
	s_and_b32 s67, s75, 1
	s_nop 0
	v_addc_co_u32_e32 v79, vcc, 0, v87, vcc
	s_cmp_eq_u32 s67, 0
	v_add_co_u32_e32 v82, vcc, s95, v86
	s_cselect_b64 s[64:65], -1, 0
	s_nop 0
	v_addc_co_u32_e32 v83, vcc, 0, v87, vcc
	s_and_b64 s[62:63], s[64:65], exec
	global_load_dwordx4 v[94:97], v[70:71], off
	global_load_dwordx4 v[98:101], v[70:71], off offset:1024
	s_nop 0
	global_load_dwordx4 v[70:73], v[74:75], off
	global_load_dwordx4 v[90:93], v[74:75], off offset:1024
	s_cselect_b32 s55, 0xf0, s69
	global_load_dwordx4 v[74:77], v[86:87], off
	v_add_co_u32_e32 v86, vcc, s96, v86
	v_and_b32_e32 v105, 63, v154
	v_lshl_add_u32 v105, v105, 2, s55
	s_nop 0
	v_addc_co_u32_e32 v87, vcc, 0, v87, vcc
	global_load_dwordx4 v[78:81], v[78:79], off
	s_nop 0
	global_load_dwordx4 v[82:85], v[82:83], off
	s_nop 0
	global_load_dwordx4 v[86:89], v[86:87], off
	s_waitcnt lgkmcnt(0)
	ds_read2st64_b32 v[102:103], v105 offset1:1
	ds_read2st64_b32 v[232:233], v105 offset0:2 offset1:3
	ds_read2st64_b32 v[140:141], v105 offset0:8 offset1:9
	ds_read2st64_b32 v[236:237], v105 offset0:4 offset1:5
	ds_read2st64_b32 v[244:245], v105 offset0:6 offset1:7
	s_waitcnt vmcnt(12)
	s_waitcnt lgkmcnt(4)
	v_mfma_f32_16x16x4_f32 v[106:109], v102, v219, 0
	s_nop 0
	s_waitcnt vmcnt(11)
	v_mfma_f32_16x16x4_f32 v[106:109], v103, v220, v[106:109]
	s_waitcnt vmcnt(10)
	s_waitcnt lgkmcnt(3)
	v_mfma_f32_16x16x4_f32 v[106:109], v232, v221, v[106:109]
	s_waitcnt vmcnt(9)
	v_mfma_f32_16x16x4_f32 v[106:109], v233, v222, v[106:109]
	ds_read2st64_b32 v[232:233], v105 offset0:10 offset1:11
	s_nop 0
	s_waitcnt vmcnt(8)
	s_nop 7
	v_add_f32_e32 v102, v223, v106
	v_min_f32_e32 v0, 0, v102
	v_mul_f32_e64 v102, |v102|, s97
	v_exp_f32_e32 v102, v102
	v_add_f32_e32 v103, v223, v107
	v_add_f32_e32 v104, v223, v108
	v_add_f32_e32 v106, v223, v109
	v_add_f32_e32 v102, 1.0, v102
	v_log_f32_e32 v102, v102
	s_nop 0
	v_fmac_f32_e32 v0, 0xbf317218, v102
	v_min_f32_e32 v102, 0, v103
	v_mul_f32_e64 v103, |v103|, s97
	v_exp_f32_e32 v103, v103
	s_nop 0
	v_add_f32_e32 v103, 1.0, v103
	v_log_f32_e32 v103, v103
	s_nop 0
	v_fmac_f32_e32 v102, 0xbf317218, v103
	v_min_f32_e32 v103, 0, v104
	v_mul_f32_e64 v104, |v104|, s97
	v_exp_f32_e32 v104, v104
	s_nop 0
	v_add_f32_e32 v104, 1.0, v104
	v_log_f32_e32 v104, v104
	s_nop 0
	v_fmac_f32_e32 v103, 0xbf317218, v104
	v_min_f32_e32 v104, 0, v106
	v_mul_f32_e64 v106, |v106|, s97
	v_exp_f32_e32 v106, v106
	s_nop 0
	v_add_f32_e32 v106, 1.0, v106
	v_log_f32_e32 v106, v106
	s_nop 0
	v_fmac_f32_e32 v104, 0xbf317218, v106
	s_waitcnt lgkmcnt(2)
	v_mfma_f32_16x16x4_f32 v[106:109], v236, v219, 0
	v_mfma_f32_16x16x4_f32 v[106:109], v237, v220, v[106:109]
	ds_read2st64_b32 v[236:237], v105 offset0:12 offset1:13
	s_nop 0
	s_waitcnt lgkmcnt(2)
	v_mfma_f32_16x16x4_f32 v[106:109], v244, v221, v[106:109]
	v_mfma_f32_16x16x4_f32 v[106:109], v245, v222, v[106:109]
	ds_read2st64_b32 v[244:245], v105 offset0:14 offset1:15
	s_nop 9
	v_add_f32_e32 v136, v223, v106
	v_min_f32_e32 v106, 0, v136
	v_mul_f32_e64 v136, |v136|, s97
	v_exp_f32_e32 v136, v136
	s_nop 0
	v_add_f32_e32 v136, 1.0, v136
	v_log_f32_e32 v136, v136
	s_nop 0
	v_fmac_f32_e32 v106, 0xbf317218, v136
	v_add_f32_e32 v136, v223, v107
	v_min_f32_e32 v107, 0, v136
	v_mul_f32_e64 v136, |v136|, s97
	v_exp_f32_e32 v136, v136
	s_nop 0
	v_add_f32_e32 v136, 1.0, v136
	v_log_f32_e32 v136, v136
	s_nop 0
	v_fmac_f32_e32 v107, 0xbf317218, v136
	v_add_f32_e32 v136, v223, v108
	v_min_f32_e32 v108, 0, v136
	v_mul_f32_e64 v136, |v136|, s97
	v_exp_f32_e32 v136, v136
	s_nop 0
	v_add_f32_e32 v136, 1.0, v136
	v_log_f32_e32 v136, v136
	s_nop 0
	v_fmac_f32_e32 v108, 0xbf317218, v136
	v_add_f32_e32 v136, v223, v109
	v_min_f32_e32 v109, 0, v136
	v_mul_f32_e64 v136, |v136|, s97
	v_exp_f32_e32 v136, v136
	s_nop 0
	v_add_f32_e32 v136, 1.0, v136
	v_log_f32_e32 v136, v136
	s_nop 0
	v_fmac_f32_e32 v109, 0xbf317218, v136
	v_mfma_f32_16x16x4_f32 v[136:139], v140, v219, 0
	v_mfma_f32_16x16x4_f32 v[136:139], v141, v220, v[136:139]
	s_nop 0
	s_waitcnt lgkmcnt(2)
	v_mfma_f32_16x16x4_f32 v[136:139], v232, v221, v[136:139]
	v_mfma_f32_16x16x4_f32 v[136:139], v233, v222, v[136:139]
	s_nop 0
	s_nop 8
	v_add_f32_e32 v136, v223, v136
	v_min_f32_e32 v142, 0, v136
	v_mul_f32_e64 v136, |v136|, s97
	v_exp_f32_e32 v136, v136
	s_nop 0
	v_add_f32_e32 v136, 1.0, v136
	v_log_f32_e32 v136, v136
	s_nop 0
	v_fmac_f32_e32 v142, 0xbf317218, v136
	v_add_f32_e32 v136, v223, v137
	v_min_f32_e32 v143, 0, v136
	v_mul_f32_e64 v136, |v136|, s97
	v_exp_f32_e32 v136, v136
	s_nop 0
	v_add_f32_e32 v136, 1.0, v136
	v_log_f32_e32 v136, v136
	s_nop 0
	v_fmac_f32_e32 v143, 0xbf317218, v136
	v_add_f32_e32 v136, v223, v138
	v_min_f32_e32 v144, 0, v136
	v_mul_f32_e64 v136, |v136|, s97
	v_exp_f32_e32 v136, v136
	s_nop 0
	v_add_f32_e32 v136, 1.0, v136
	v_log_f32_e32 v136, v136
	s_nop 0
	v_fmac_f32_e32 v144, 0xbf317218, v136
	v_add_f32_e32 v136, v223, v139
	v_min_f32_e32 v145, 0, v136
	v_mul_f32_e64 v136, |v136|, s97
	v_exp_f32_e32 v136, v136
	s_nop 0
	v_add_f32_e32 v136, 1.0, v136
	v_log_f32_e32 v136, v136
	s_nop 0
	v_fmac_f32_e32 v145, 0xbf317218, v136
	s_waitcnt lgkmcnt(1)
	v_mfma_f32_16x16x4_f32 v[136:139], v236, v219, 0
	v_mfma_f32_16x16x4_f32 v[136:139], v237, v220, v[136:139]
	s_nop 0
	s_waitcnt lgkmcnt(0)
	v_mfma_f32_16x16x4_f32 v[136:139], v244, v221, v[136:139]
	v_mfma_f32_16x16x4_f32 v[136:139], v245, v222, v[136:139]
	s_nop 9
	v_add_f32_e32 v105, v223, v136
	v_min_f32_e32 v136, 0, v105
	v_mul_f32_e64 v105, |v105|, s97
	v_exp_f32_e32 v105, v105
	s_nop 0
	v_add_f32_e32 v105, 1.0, v105
	v_log_f32_e32 v105, v105
	s_nop 0
	v_fmac_f32_e32 v136, 0xbf317218, v105
	v_add_f32_e32 v105, v223, v137
	v_min_f32_e32 v137, 0, v105
	v_mul_f32_e64 v105, |v105|, s97
	v_exp_f32_e32 v105, v105
	s_nop 0
	v_add_f32_e32 v105, 1.0, v105
	v_log_f32_e32 v105, v105
	s_nop 0
	v_fmac_f32_e32 v137, 0xbf317218, v105
	v_add_f32_e32 v105, v223, v138
	v_min_f32_e32 v138, 0, v105
	v_mul_f32_e64 v105, |v105|, s97
	v_exp_f32_e32 v105, v105
	s_nop 0
	v_add_f32_e32 v105, 1.0, v105
	v_log_f32_e32 v105, v105
	s_nop 0
	v_fmac_f32_e32 v138, 0xbf317218, v105
	v_add_f32_e32 v105, v223, v139
	v_min_f32_e32 v139, 0, v105
	v_mul_f32_e64 v105, |v105|, s97
	v_exp_f32_e32 v105, v105
	s_nop 0
	v_add_f32_e32 v105, 1.0, v105
	v_log_f32_e32 v105, v105
	s_nop 0
	v_fmac_f32_e32 v139, 0xbf317218, v105
	v_fma_f32 v105, v139, s0, 0
	v_fmamk_f32 v138, v138, 0x3d800000, v105
	v_fmamk_f32 v137, v137, 0x3d800000, v138
	v_fmamk_f32 v136, v136, 0x3d800000, v137
	v_fmamk_f32 v139, v145, 0x3d800000, v136
	v_fmamk_f32 v140, v144, 0x3d800000, v139
	v_fmamk_f32 v141, v143, 0x3d800000, v140
	v_fmamk_f32 v142, v142, 0x3d800000, v141
	v_fmamk_f32 v109, v109, 0x3d800000, v142
	v_fmamk_f32 v108, v108, 0x3d800000, v109
	v_fmamk_f32 v107, v107, 0x3d800000, v108
	v_fmamk_f32 v106, v106, 0x3d800000, v107
	v_fmamk_f32 v104, v104, 0x3d800000, v106
	v_fmamk_f32 v103, v103, 0x3d800000, v104
	v_fmamk_f32 v102, v102, 0x3d800000, v103
	v_fmamk_f32 v0, v0, 0x3d800000, v102
	ds_bpermute_b32 v144, v188, v0
	ds_bpermute_b32 v145, v189, v0
	ds_bpermute_b32 v143, v187, v0
	s_waitcnt lgkmcnt(2)
	v_cndmask_b32_e64 v144, 0, v144, s[28:29]
	s_waitcnt lgkmcnt(1)
	v_cndmask_b32_e64 v145, v145, 0, s[8:9]
	v_add_f32_e32 v144, v144, v145
	s_waitcnt lgkmcnt(0)
	v_cndmask_b32_e64 v143, 0, v143, s[4:5]
	v_add_f32_e32 v143, v143, v144
	v_add_f32_e32 v0, v143, v0
	v_add_f32_e32 v102, v143, v102
	ds_write2st64_b32 v200, v0, v102 offset0:24 offset1:26
	v_add_f32_e32 v0, v143, v103
	v_add_f32_e32 v102, v143, v104
	ds_write2st64_b32 v200, v0, v102 offset0:28 offset1:30
	v_add_f32_e32 v0, v143, v106
	v_add_f32_e32 v102, v143, v107
	ds_write2st64_b32 v200, v0, v102 offset0:32 offset1:34
	v_add_f32_e32 v0, v143, v108
	v_add_f32_e32 v102, v143, v109
	ds_write2st64_b32 v200, v0, v102 offset0:36 offset1:38
	v_add_f32_e32 v0, v143, v142
	v_add_f32_e32 v102, v143, v141
	ds_write2st64_b32 v200, v0, v102 offset0:40 offset1:42
	v_add_f32_e32 v0, v143, v140
	v_add_f32_e32 v102, v143, v139
	ds_write2st64_b32 v200, v0, v102 offset0:44 offset1:46
	v_add_f32_e32 v0, v143, v136
	v_add_f32_e32 v102, v143, v137
	ds_write2st64_b32 v200, v0, v102 offset0:48 offset1:50
	v_add_f32_e32 v0, v143, v138
	v_add_f32_e32 v102, v143, v105
	ds_write2st64_b32 v200, v0, v102 offset0:52 offset1:54
	s_waitcnt lgkmcnt(0)
	s_barrier
	s_and_saveexec_b64 s[62:63], s[10:11]
	s_cbranch_execz .LBB0_682
	ds_read_b32 v0, v178 offset:6144
	v_lshl_add_u32 v102, s67, 9, v178
	s_waitcnt lgkmcnt(0)
	v_mul_f32_e32 v255, 0x3fb8aa3b, v0
	v_exp_f32_e32 v255, v255
	s_nop 0
	ds_write_b32 v102, v255 offset:4096

.LBB0_689:
	ds_read_b128 v[102:105], v201 offset:6144
	ds_read_b128 v[106:109], v201 offset:6160
	s_waitcnt vmcnt(6)
	v_lshlrev_b32_e32 v138, 16, v98
	v_and_b32_e32 v139, 0xffff0000, v98
	s_waitcnt lgkmcnt(1)
	v_mul_f32_e32 v0, 0xbfb8aa3b, v102
	v_exp_f32_e32 v136, v0
	v_mul_f32_e32 v0, 0xbfb8aa3b, v103
	v_exp_f32_e32 v137, v0
	v_mul_f32_e32 v0, 0xbfb8aa3b, v104
	v_pk_mul_f32 v[136:137], v[136:137], v[138:139]
	s_nop 0
	v_cvt_pk_bf16_f32 v98, v136, v137
	v_exp_f32_e32 v136, v0
	v_mul_f32_e32 v0, 0xbfb8aa3b, v105
	v_exp_f32_e32 v137, v0
	v_lshlrev_b32_e32 v138, 16, v99
	v_and_b32_e32 v139, 0xffff0000, v99
	s_waitcnt lgkmcnt(0)
	v_mul_f32_e32 v0, 0xbfb8aa3b, v106
	v_pk_mul_f32 v[136:137], v[136:137], v[138:139]
	v_lshlrev_b32_e32 v138, 16, v100
	v_cvt_pk_bf16_f32 v99, v136, v137
	v_exp_f32_e32 v136, v0
	v_mul_f32_e32 v0, 0xbfb8aa3b, v107
	v_exp_f32_e32 v137, v0
	v_and_b32_e32 v139, 0xffff0000, v100
	v_mul_f32_e32 v0, 0xbfb8aa3b, v108
	v_pk_mul_f32 v[136:137], v[136:137], v[138:139]
	s_nop 0
	v_cvt_pk_bf16_f32 v100, v136, v137
	v_exp_f32_e32 v136, v0
	v_mul_f32_e32 v0, 0xbfb8aa3b, v109
	v_exp_f32_e32 v137, v0
	v_lshlrev_b32_e32 v138, 16, v101
	v_and_b32_e32 v139, 0xffff0000, v101
	v_mul_f32_e32 v0, 0x3fb8aa3b, v102
	v_pk_mul_f32 v[136:137], v[136:137], v[138:139]
	s_nop 0
	v_cvt_pk_bf16_f32 v101, v136, v137
	ds_write_b128 v181, v[98:101] offset:56320
	v_exp_f32_e32 v98, v0
	v_mul_f32_e32 v0, 0x3fb8aa3b, v103
	v_exp_f32_e32 v99, v0
	v_lshlrev_b32_e32 v100, 16, v94
	v_and_b32_e32 v101, 0xffff0000, v94
	v_mul_f32_e32 v0, 0x3fb8aa3b, v104
	v_pk_mul_f32 v[98:99], v[98:99], s[50:51] op_sel_hi:[1,0]
	s_waitcnt vmcnt(4)
	v_lshlrev_b32_e32 v104, 16, v90
	v_pk_mul_f32 v[98:99], v[98:99], v[100:101]
	v_lshlrev_b32_e32 v100, 16, v95
	v_cvt_pk_bf16_f32 v94, v98, v99
	v_exp_f32_e32 v98, v0
	v_mul_f32_e32 v0, 0x3fb8aa3b, v105
	v_exp_f32_e32 v99, v0
	v_and_b32_e32 v101, 0xffff0000, v95
	v_mul_f32_e32 v0, 0x3fb8aa3b, v106
	v_and_b32_e32 v105, 0xffff0000, v90
	v_pk_mul_f32 v[98:99], v[98:99], s[50:51] op_sel_hi:[1,0]
	s_nop 0
	v_pk_mul_f32 v[98:99], v[98:99], v[100:101]
	v_lshlrev_b32_e32 v100, 16, v96
	v_cvt_pk_bf16_f32 v95, v98, v99
	v_exp_f32_e32 v98, v0
	v_mul_f32_e32 v0, 0x3fb8aa3b, v107
	v_exp_f32_e32 v99, v0
	v_and_b32_e32 v101, 0xffff0000, v96
	v_mul_f32_e32 v0, 0x3fb8aa3b, v108
	v_pk_mul_f32 v[98:99], v[98:99], s[50:51] op_sel_hi:[1,0]
	s_nop 0
	v_pk_mul_f32 v[98:99], v[98:99], v[100:101]
	v_lshlrev_b32_e32 v100, 16, v97
	v_cvt_pk_bf16_f32 v96, v98, v99
	v_exp_f32_e32 v98, v0
	v_mul_f32_e32 v0, 0x3fb8aa3b, v109
	v_exp_f32_e32 v99, v0
	v_and_b32_e32 v101, 0xffff0000, v97
	v_pk_mul_f32 v[98:99], v[98:99], s[50:51] op_sel_hi:[1,0]
	s_nop 0
	v_pk_mul_f32 v[98:99], v[98:99], v[100:101]
	s_nop 0
	v_cvt_pk_bf16_f32 v97, v98, v99
	ds_write_b128 v181, v[94:97] offset:38912
	ds_read_b128 v[94:97], v202 offset:6144
	ds_read_b128 v[98:101], v202 offset:6160
	s_waitcnt lgkmcnt(1)
	v_mul_f32_e32 v0, 0xbfb8aa3b, v94
	v_exp_f32_e32 v102, v0
	v_mul_f32_e32 v0, 0xbfb8aa3b, v95
	v_exp_f32_e32 v103, v0
	v_mul_f32_e32 v0, 0xbfb8aa3b, v96
	v_pk_mul_f32 v[102:103], v[102:103], v[104:105]
	s_nop 0
	v_cvt_pk_bf16_f32 v90, v102, v103
	v_exp_f32_e32 v102, v0
	v_mul_f32_e32 v0, 0xbfb8aa3b, v97
	v_exp_f32_e32 v103, v0
	v_lshlrev_b32_e32 v104, 16, v91
	v_and_b32_e32 v105, 0xffff0000, v91
	s_waitcnt lgkmcnt(0)
	v_mul_f32_e32 v0, 0xbfb8aa3b, v98
	v_pk_mul_f32 v[102:103], v[102:103], v[104:105]
	v_lshlrev_b32_e32 v104, 16, v92
	v_cvt_pk_bf16_f32 v91, v102, v103
	v_exp_f32_e32 v102, v0
	v_mul_f32_e32 v0, 0xbfb8aa3b, v99
	v_exp_f32_e32 v103, v0
	v_and_b32_e32 v105, 0xffff0000, v92
	v_mul_f32_e32 v0, 0xbfb8aa3b, v100
	v_pk_mul_f32 v[102:103], v[102:103], v[104:105]
	s_nop 0
	v_cvt_pk_bf16_f32 v92, v102, v103
	v_exp_f32_e32 v102, v0
	v_mul_f32_e32 v0, 0xbfb8aa3b, v101
	v_exp_f32_e32 v103, v0
	v_lshlrev_b32_e32 v104, 16, v93
	v_and_b32_e32 v105, 0xffff0000, v93
	v_mul_f32_e32 v0, 0x3fb8aa3b, v94
	v_pk_mul_f32 v[102:103], v[102:103], v[104:105]
	s_nop 0
	v_cvt_pk_bf16_f32 v93, v102, v103
	ds_write_b128 v182, v[90:93] offset:56320
	v_exp_f32_e32 v90, v0
	v_mul_f32_e32 v0, 0x3fb8aa3b, v95
	v_exp_f32_e32 v91, v0
	v_lshlrev_b32_e32 v92, 16, v70
	v_and_b32_e32 v93, 0xffff0000, v70
	v_mul_f32_e32 v0, 0x3fb8aa3b, v96
	v_pk_mul_f32 v[90:91], v[90:91], s[50:51] op_sel_hi:[1,0]
	s_nop 0
	v_pk_mul_f32 v[90:91], v[90:91], v[92:93]
	v_lshlrev_b32_e32 v92, 16, v71
	v_cvt_pk_bf16_f32 v70, v90, v91
	v_exp_f32_e32 v90, v0
	v_mul_f32_e32 v0, 0x3fb8aa3b, v97
	v_exp_f32_e32 v91, v0
	v_and_b32_e32 v93, 0xffff0000, v71
	v_mul_f32_e32 v0, 0x3fb8aa3b, v98
	v_pk_mul_f32 v[90:91], v[90:91], s[50:51] op_sel_hi:[1,0]
	s_nop 0
	v_pk_mul_f32 v[90:91], v[90:91], v[92:93]
	v_lshlrev_b32_e32 v92, 16, v72
	v_cvt_pk_bf16_f32 v71, v90, v91
	v_exp_f32_e32 v90, v0
	v_mul_f32_e32 v0, 0x3fb8aa3b, v99
	v_exp_f32_e32 v91, v0
	v_and_b32_e32 v93, 0xffff0000, v72
	v_mul_f32_e32 v0, 0x3fb8aa3b, v100
	v_pk_mul_f32 v[90:91], v[90:91], s[50:51] op_sel_hi:[1,0]
	s_nop 0
	v_pk_mul_f32 v[90:91], v[90:91], v[92:93]
	v_lshlrev_b32_e32 v92, 16, v73
	v_cvt_pk_bf16_f32 v72, v90, v91
	v_exp_f32_e32 v90, v0
	v_mul_f32_e32 v0, 0x3fb8aa3b, v101
	v_exp_f32_e32 v91, v0
	v_and_b32_e32 v93, 0xffff0000, v73
	v_pk_mul_f32 v[90:91], v[90:91], s[50:51] op_sel_hi:[1,0]
	s_nop 0
	v_pk_mul_f32 v[90:91], v[90:91], v[92:93]
	s_nop 0
	v_cvt_pk_bf16_f32 v73, v90, v91
	ds_write_b128 v182, v[70:73] offset:38912
	s_waitcnt vmcnt(3)
	ds_write_b128 v203, v[74:77]
	s_waitcnt vmcnt(2)
	ds_write_b128 v204, v[78:81]
	s_waitcnt vmcnt(1)
	ds_write_b128 v203, v[82:85] offset:16896
	s_waitcnt vmcnt(0)
	ds_write_b128 v205, v[86:89]
	v_lshl_add_u64 v[70:71], s[58:59], 0, v[116:117]
	v_lshl_add_u64 v[72:73], s[58:59], 0, v[120:121]
	v_lshl_add_u64 v[74:75], s[58:59], 0, v[122:123]
	global_load_dwordx2 v[156:157], v[70:71], off
	global_load_dwordx2 v[152:153], v[70:71], off offset:32
	global_load_dwordx2 v[148:149], v[72:73], off
	global_load_dwordx2 v[146:147], v[74:75], off
	v_lshl_add_u64 v[70:71], s[58:59], 0, v[124:125]
	v_lshl_add_u64 v[72:73], s[58:59], 0, v[126:127]
	v_lshl_add_u64 v[74:75], s[58:59], 0, v[128:129]
	v_lshl_add_u64 v[76:77], s[58:59], 0, v[130:131]
	global_load_dwordx2 v[144:145], v[70:71], off
	global_load_dwordx2 v[142:143], v[72:73], off
	global_load_dwordx2 v[138:139], v[74:75], off
	global_load_dwordx2 v[136:137], v[76:77], off
	s_waitcnt lgkmcnt(0)
	s_barrier
	s_waitcnt lgkmcnt(0)
	ds_read_b128 v[70:73], v206 offset:56320
	ds_read_b128 v[232:235], v180 offset:38912
	ds_read_b128 v[236:239], v206 offset:56384
	ds_read_b128 v[82:85], v180 offset:38976
	ds_read_b128 v[244:247], v206 offset:56448
	ds_read_b128 v[86:89], v180 offset:39040
	ds_read_b128 v[78:81], v206 offset:56512
	ds_read_b128 v[90:93], v180 offset:39104
	s_waitcnt lgkmcnt(6)
	v_mfma_f32_16x16x32_bf16 v[70:73], v[70:73], v[232:235], 0
	v_mov_b32_e32 v0, s49
	v_cvt_pk_bf16_f32 v166, v62, v63
	v_cvt_pk_bf16_f32 v167, v64, v65
	s_waitcnt lgkmcnt(4)
	v_mfma_f32_16x16x32_bf16 v[70:73], v[236:239], v[82:85], v[70:73]
	s_nop 0
	s_nop 0
	v_cvt_pk_bf16_f32 v168, v66, v67
	v_cvt_pk_bf16_f32 v169, v68, v69
	s_waitcnt lgkmcnt(2)
	v_mfma_f32_16x16x32_bf16 v[70:73], v[244:247], v[86:89], v[70:73]
	s_nop 0
	s_nop 0
	s_add_u32 s55, s72, s68
	s_addc_u32 s63, s73, 0
	s_waitcnt lgkmcnt(0)
	v_mfma_f32_16x16x32_bf16 v[70:73], v[78:81], v[90:93], v[70:73]
	s_add_u32 s62, s55, 0xafc1000
	s_addc_u32 s63, s63, 0
	s_waitcnt vmcnt(7)
	v_lshlrev_b32_e32 v224, 16, v156
	s_nop 3
	v_cndmask_b32_e64 v0, v70, v0, s[14:15]
	v_cndmask_b32_e64 v70, v71, 0, s[30:31]
	v_cndmask_b32_e64 v71, v72, 0, s[34:35]
	v_cndmask_b32_e64 v72, v73, 0, s[36:37]
	v_cvt_pk_bf16_f32 v70, v0, v70
	v_cvt_pk_bf16_f32 v71, v71, v72
	ds_write_b64 v207, v[70:71]
	ds_read_b128 v[236:239], v208 offset:56320
	ds_read_b128 v[244:247], v208 offset:56384
	s_waitcnt lgkmcnt(1)
	v_mfma_f32_16x16x32_bf16 v[70:73], v[236:239], v[232:235], 0
	ds_read_b128 v[232:235], v208 offset:56448
	ds_read_b128 v[74:77], v208 offset:56512
	s_nop 0
	v_mov_b32_e32 v0, s49
	v_and_b32_e32 v225, 0xffff0000, v156
	s_waitcnt lgkmcnt(2)
	v_mfma_f32_16x16x32_bf16 v[70:73], v[244:247], v[82:85], v[70:73]
	s_nop 0
	v_lshlrev_b32_e32 v156, 16, v157
	v_and_b32_e32 v157, 0xffff0000, v157
	s_waitcnt lgkmcnt(1)
	v_mfma_f32_16x16x32_bf16 v[70:73], v[232:235], v[86:89], v[70:73]
	s_nop 0
	s_waitcnt vmcnt(6)
	v_lshlrev_b32_e32 v226, 16, v152
	v_and_b32_e32 v227, 0xffff0000, v152
	s_waitcnt lgkmcnt(0)
	v_mfma_f32_16x16x32_bf16 v[70:73], v[74:77], v[90:93], v[70:73]
	v_lshlrev_b32_e32 v152, 16, v153
	v_and_b32_e32 v153, 0xffff0000, v153
	s_nop 5
	v_cndmask_b32_e64 v0, v70, v0, s[22:23]
	v_cndmask_b32_e64 v70, v71, 0, s[38:39]
	v_cndmask_b32_e64 v71, v72, 0, s[40:41]
	v_cndmask_b32_e64 v72, v73, 0, s[42:43]
	v_cvt_pk_bf16_f32 v70, v0, v70
	v_cvt_pk_bf16_f32 v71, v71, v72
	ds_write_b64 v209, v[70:71]
	s_waitcnt lgkmcnt(0)
	s_barrier
	s_waitcnt lgkmcnt(0)
	ds_read_b64_tr_b16 v[72:73], v210 offset:2112
	ds_read_b64_tr_b16 v[70:71], v210
	ds_read_b64_tr_b16 v[232:233], v210 offset:32
	ds_read_b64_tr_b16 v[236:237], v210 offset:16896
	ds_read_b64_tr_b16 v[238:239], v210 offset:19008
	ds_read_b64_tr_b16 v[234:235], v210 offset:2144
	ds_read_b64_tr_b16 v[244:245], v210 offset:16928
	ds_read_b64_tr_b16 v[246:247], v210 offset:19040
	ds_read_b128 v[86:89], v211
	ds_read_b128 v[94:97], v211 offset:64
	ds_read_b128 v[102:105], v211 offset:2368
	ds_read_b128 v[158:161], v211 offset:4672
	s_waitcnt lgkmcnt(3)
	v_mfma_f32_16x16x32_bf16 v[90:93], v[70:73], v[86:89], 0
	s_nop 0
	v_mfma_f32_16x16x32_bf16 v[86:89], v[232:235], v[86:89], 0
	s_waitcnt lgkmcnt(2)
	v_mfma_f32_16x16x32_bf16 v[90:93], v[236:239], v[94:97], v[90:93]
	v_mfma_f32_16x16x32_bf16 v[86:89], v[244:247], v[94:97], v[86:89]
	ds_read_b128 v[94:97], v211 offset:2304
	s_waitcnt lgkmcnt(0)
	v_mfma_f32_16x16x32_bf16 v[98:101], v[70:73], v[94:97], 0
	v_mfma_f32_16x16x32_bf16 v[94:97], v[232:235], v[94:97], 0
	v_mfma_f32_16x16x32_bf16 v[98:101], v[236:239], v[102:105], v[98:101]
	v_mfma_f32_16x16x32_bf16 v[94:97], v[244:247], v[102:105], v[94:97]
	ds_read_b128 v[102:105], v211 offset:4608
	s_waitcnt lgkmcnt(0)
	v_mfma_f32_16x16x32_bf16 v[106:109], v[70:73], v[102:105], 0
	v_mfma_f32_16x16x32_bf16 v[102:105], v[232:235], v[102:105], 0
	v_mfma_f32_16x16x32_bf16 v[106:109], v[236:239], v[158:161], v[106:109]
	v_mfma_f32_16x16x32_bf16 v[102:105], v[244:247], v[158:161], v[102:105]
	ds_read_b128 v[158:161], v211 offset:6912
	s_waitcnt lgkmcnt(0)
	v_mfma_f32_16x16x32_bf16 v[70:73], v[70:73], v[158:161], 0
	v_mfma_f32_16x16x32_bf16 v[74:77], v[232:235], v[158:161], 0
	ds_read_b128 v[232:235], v211 offset:6976
	s_waitcnt lgkmcnt(0)
	v_mfma_f32_16x16x32_bf16 v[70:73], v[236:239], v[232:235], v[70:73]
	ds_read2_b64 v[236:239], v215 offset1:4
	v_cvt_pk_bf16_f32 v78, v30, v31
	v_cvt_pk_bf16_f32 v79, v32, v33
	v_cvt_pk_bf16_f32 v80, v10, v11
	v_mfma_f32_16x16x32_bf16 v[74:77], v[244:247], v[232:235], v[74:77]
	ds_read2_b64 v[232:235], v216 offset0:32 offset1:36
	ds_read2_b64 v[244:247], v217 offset0:64 offset1:68
	v_cvt_pk_bf16_f32 v81, v12, v13
	v_cvt_pk_bf16_f32 v82, v6, v7
	v_cvt_pk_bf16_f32 v83, v8, v9
	v_cvt_pk_bf16_f32 v84, v18, v19
	v_cvt_pk_bf16_f32 v85, v20, v21
	s_nop 0
	s_waitcnt lgkmcnt(2)
	v_mfma_f32_16x16x32_bf16 v[90:93], v[78:81], v[236:239], v[90:93]
	v_mfma_f32_16x16x32_bf16 v[86:89], v[82:85], v[236:239], v[86:89]
	ds_read2_b64 v[236:239], v218 offset0:96 offset1:100
	s_nop 0
	s_waitcnt lgkmcnt(2)
	v_mfma_f32_16x16x32_bf16 v[98:101], v[78:81], v[232:235], v[98:101]
	v_mfma_f32_16x16x32_bf16 v[94:97], v[82:85], v[232:235], v[94:97]
	ds_read2_b64 v[232:235], v215 offset0:8 offset1:12
	s_nop 0
	s_waitcnt lgkmcnt(2)
	v_mfma_f32_16x16x32_bf16 v[106:109], v[78:81], v[244:247], v[106:109]
	v_mfma_f32_16x16x32_bf16 v[102:105], v[82:85], v[244:247], v[102:105]
	ds_read2_b64 v[244:247], v216 offset0:40 offset1:44
	s_nop 0
	s_waitcnt lgkmcnt(2)
	v_mfma_f32_16x16x32_bf16 v[70:73], v[78:81], v[236:239], v[70:73]
	v_cvt_pk_bf16_f32 v78, v14, v15
	v_cvt_pk_bf16_f32 v79, v16, v17
	v_cvt_pk_bf16_f32 v80, v38, v39
	v_mfma_f32_16x16x32_bf16 v[74:77], v[82:85], v[236:239], v[74:77]
	ds_read2_b64 v[236:239], v217 offset0:72 offset1:76
	v_cvt_pk_bf16_f32 v81, v40, v41
	v_cvt_pk_bf16_f32 v82, v26, v27
	v_cvt_pk_bf16_f32 v83, v28, v29
	v_cvt_pk_bf16_f32 v84, v50, v51
	v_cvt_pk_bf16_f32 v85, v52, v53
	s_nop 0
	s_waitcnt lgkmcnt(2)
	v_mfma_f32_16x16x32_bf16 v[90:93], v[78:81], v[232:235], v[90:93]
	v_mfma_f32_16x16x32_bf16 v[86:89], v[82:85], v[232:235], v[86:89]
	ds_read2_b64 v[232:235], v218 offset0:104 offset1:108
	s_nop 0
	s_waitcnt lgkmcnt(2)
	v_mfma_f32_16x16x32_bf16 v[98:101], v[78:81], v[244:247], v[98:101]
	v_mfma_f32_16x16x32_bf16 v[94:97], v[82:85], v[244:247], v[94:97]
	ds_read2_b64 v[244:247], v215 offset0:16 offset1:20
	s_nop 0
	s_waitcnt lgkmcnt(2)
	v_mfma_f32_16x16x32_bf16 v[106:109], v[78:81], v[236:239], v[106:109]
	v_mfma_f32_16x16x32_bf16 v[102:105], v[82:85], v[236:239], v[102:105]
	ds_read2_b64 v[236:239], v216 offset0:48 offset1:52
	s_nop 0
	s_waitcnt lgkmcnt(2)
	v_mfma_f32_16x16x32_bf16 v[70:73], v[78:81], v[232:235], v[70:73]
	v_cvt_pk_bf16_f32 v78, v22, v23
	v_cvt_pk_bf16_f32 v79, v24, v25
	v_cvt_pk_bf16_f32 v80, v42, v43
	v_mfma_f32_16x16x32_bf16 v[74:77], v[82:85], v[232:235], v[74:77]
	ds_read2_b64 v[232:235], v217 offset0:80 offset1:84
	v_cvt_pk_bf16_f32 v81, v44, v45
	v_cvt_pk_bf16_f32 v82, v34, v35
	v_cvt_pk_bf16_f32 v83, v36, v37
	v_cvt_pk_bf16_f32 v84, v54, v55
	v_cvt_pk_bf16_f32 v85, v56, v57
	s_nop 0
	s_waitcnt lgkmcnt(2)
	v_mfma_f32_16x16x32_bf16 v[90:93], v[78:81], v[244:247], v[90:93]
	v_mfma_f32_16x16x32_bf16 v[86:89], v[82:85], v[244:247], v[86:89]
	ds_read2_b64 v[244:247], v218 offset0:112 offset1:116
	s_nop 0
	s_waitcnt lgkmcnt(2)
	v_mfma_f32_16x16x32_bf16 v[98:101], v[78:81], v[236:239], v[98:101]
	v_mfma_f32_16x16x32_bf16 v[94:97], v[82:85], v[236:239], v[94:97]
	ds_read2_b64 v[236:239], v215 offset0:24 offset1:28
	s_nop 0
	s_waitcnt lgkmcnt(2)
	v_mfma_f32_16x16x32_bf16 v[162:165], v[78:81], v[232:235], v[106:109]
	v_mfma_f32_16x16x32_bf16 v[158:161], v[82:85], v[232:235], v[102:105]
	ds_read2_b64 v[232:235], v216 offset0:56 offset1:60
	s_nop 2
	s_nop 0
	s_waitcnt lgkmcnt(2)
	v_mfma_f32_16x16x32_bf16 v[70:73], v[78:81], v[244:247], v[70:73]
	v_cvt_pk_bf16_f32 v78, v46, v47
	v_cvt_pk_bf16_f32 v79, v48, v49
	v_cvt_pk_bf16_f32 v80, v58, v59
	v_mfma_f32_16x16x32_bf16 v[74:77], v[82:85], v[244:247], v[74:77]
	ds_read2_b64 v[244:247], v217 offset0:88 offset1:92
	v_cvt_pk_bf16_f32 v81, v60, v61
	s_nop 0
	s_waitcnt lgkmcnt(2)
	v_mfma_f32_16x16x32_bf16 v[106:109], v[78:81], v[236:239], v[90:93]
	v_mfma_f32_16x16x32_bf16 v[102:105], v[166:169], v[236:239], v[86:89]
	ds_read2_b64 v[236:239], v218 offset0:120 offset1:124
	s_nop 0
	s_nop 5
	v_pk_add_f32 v[106:107], v[106:107], v[224:225]
	v_pk_add_f32 v[108:109], v[108:109], v[156:157]
	s_waitcnt lgkmcnt(2)
	v_mfma_f32_16x16x32_bf16 v[98:101], v[78:81], v[232:235], v[98:101]
	v_mul_f32_e64 v156, v106, v106
	v_mul_f32_e64 v157, v107, v107
	v_pk_mul_f32 v[224:225], v[108:109], v[108:109]
	v_add_f32_e32 v0, v156, v157
	v_mfma_f32_16x16x32_bf16 v[94:97], v[166:169], v[232:235], v[94:97]
	s_nop 0
	v_pk_add_f32 v[102:103], v[102:103], v[226:227]
	v_add_f32_e32 v0, v224, v0
	s_waitcnt lgkmcnt(1)
	v_mfma_f32_16x16x32_bf16 v[86:89], v[166:169], v[244:247], v[158:161]
	v_add_f32_e64 v104, v104, v152
	v_add_f32_e64 v105, v105, v153
	s_nop 0
	s_nop 0
	v_pk_mul_f32 v[152:153], v[102:103], v[102:103]
	v_mfma_f32_16x16x32_bf16 v[90:93], v[78:81], v[244:247], v[162:165]
	v_add_f32_e32 v0, v225, v0
	v_add_f32_e32 v0, v152, v0
	v_pk_mul_f32 v[226:227], v[104:105], v[104:105]
	s_waitcnt lgkmcnt(0)
	v_mfma_f32_16x16x32_bf16 v[82:85], v[78:81], v[236:239], v[70:73]
	v_add_f32_e32 v0, v153, v0
	v_add_f32_e32 v0, v226, v0
	v_add_f32_e32 v0, v227, v0
	v_lshl_add_u64 v[70:71], s[62:63], 0, v[118:119]
	v_add_co_u32_e32 v72, vcc, s81, v70
	v_mfma_f32_16x16x32_bf16 v[78:81], v[166:169], v[236:239], v[74:77]
	s_nop 0
	v_addc_co_u32_e32 v73, vcc, 0, v71, vcc
	global_load_dwordx2 v[168:169], v[70:71], off
	global_load_dwordx2 v[166:167], v[70:71], off offset:32
	global_load_dwordx2 v[164:165], v[72:73], off
	global_load_dwordx2 v[162:163], v[72:73], off offset:32
	v_add_co_u32_e32 v72, vcc, s95, v70
	v_mov_b32_e32 v152, v0
	s_nop 1
	v_permlane16_swap_b32_e32 v152, v0
	s_nop 0
	v_addc_co_u32_e32 v73, vcc, 0, v71, vcc
	v_add_co_u32_e32 v70, vcc, s96, v70
	global_load_dwordx2 v[160:161], v[72:73], off
	global_load_dwordx2 v[158:159], v[72:73], off offset:32
	v_addc_co_u32_e32 v71, vcc, 0, v71, vcc
	global_load_dwordx2 v[150:151], v[70:71], off
	global_load_dwordx2 v[140:141], v[70:71], off offset:32
	global_load_dwordx4 v[74:77], v[134:135], off
	s_nop 0
	global_load_dwordx4 v[70:73], v[134:135], off offset:64
	v_add_f32_e32 v0, v0, v152
	v_mov_b32_e32 v152, v0
	s_nop 1
	v_permlane32_swap_b32_e32 v152, v0
	s_and_saveexec_b64 s[62:63], s[4:5]
	s_waitcnt lgkmcnt(0)
	s_cbranch_execz .LBB0_691
	s_waitcnt lgkmcnt(0)
	v_add_f32_e32 v0, v0, v152
	ds_write_b32 v185, v0

.LBB0_2085:
	s_waitcnt lgkmcnt(0)
	ds_read_b128 v[136:139], v119 offset:6144
	ds_read_b128 v[140:143], v119 offset:6160
	s_waitcnt vmcnt(5)
	v_lshlrev_b32_e32 v144, 16, v54
	v_and_b32_e32 v145, 0xffff0000, v54
	s_add_i32 s24, s25, s24
	s_waitcnt lgkmcnt(1)
	v_mul_f32_e32 v136, 0xbfb8aa3b, v136
	v_mul_f32_e32 v137, 0xbfb8aa3b, v137
	v_exp_f32_e32 v136, v136
	v_exp_f32_e32 v137, v137
	v_mul_f32_e32 v54, 0xbfb8aa3b, v138
	v_exp_f32_e32 v138, v54
	v_mul_f32_e32 v54, 0xbfb8aa3b, v139
	v_exp_f32_e32 v139, v54
	v_pk_mul_f32 v[136:137], v[136:137], v[144:145]
	s_add_i32 s57, s57, 1
	v_cvt_pk_bf16_f32 v54, v136, v137
	v_lshlrev_b32_e32 v136, 16, v55
	v_and_b32_e32 v137, 0xffff0000, v55
	s_waitcnt lgkmcnt(0)
	v_mul_f32_e32 v55, 0xbfb8aa3b, v140
	v_pk_mul_f32 v[136:137], v[138:139], v[136:137]
	v_exp_f32_e32 v138, v55
	v_mul_f32_e32 v55, 0xbfb8aa3b, v141
	v_exp_f32_e32 v139, v55
	v_cvt_pk_bf16_f32 v55, v136, v137
	v_lshlrev_b32_e32 v136, 16, v56
	v_and_b32_e32 v137, 0xffff0000, v56
	v_mul_f32_e32 v56, 0xbfb8aa3b, v142
	v_pk_mul_f32 v[136:137], v[138:139], v[136:137]
	v_exp_f32_e32 v138, v56
	v_mul_f32_e32 v56, 0xbfb8aa3b, v143
	v_exp_f32_e32 v139, v56
	v_cvt_pk_bf16_f32 v56, v136, v137
	v_lshlrev_b32_e32 v136, 16, v57
	v_and_b32_e32 v137, 0xffff0000, v57
	v_pk_mul_f32 v[136:137], v[138:139], v[136:137]
	s_waitcnt vmcnt(4)
	v_lshlrev_b32_e32 v140, 16, v6
	v_cvt_pk_bf16_f32 v57, v136, v137
	ds_write_b128 v120, v[54:57] offset:56320
	ds_read_b128 v[224:227], v121 offset:6144
	ds_read_b128 v[136:139], v121 offset:6160
	v_and_b32_e32 v141, 0xffff0000, v6
	s_mul_i32 s31, s24, 0x1800
	s_mul_hi_i32 s30, s24, 0x1800
	s_waitcnt lgkmcnt(1)
	v_mul_f32_e32 v54, 0xbfb8aa3b, v224
	v_mul_f32_e32 v55, 0xbfb8aa3b, v225
	v_exp_f32_e32 v54, v54
	v_exp_f32_e32 v55, v55
	v_mul_f32_e32 v6, 0xbfb8aa3b, v226
	v_exp_f32_e32 v56, v6
	v_mul_f32_e32 v6, 0xbfb8aa3b, v227
	v_exp_f32_e32 v57, v6
	v_pk_mul_f32 v[54:55], v[54:55], v[140:141]
	s_add_u32 s28, s61, s31
	v_cvt_pk_bf16_f32 v6, v54, v55
	v_lshlrev_b32_e32 v54, 16, v7
	v_and_b32_e32 v55, 0xffff0000, v7
	s_waitcnt lgkmcnt(0)
	v_mul_f32_e32 v7, 0xbfb8aa3b, v136
	v_pk_mul_f32 v[54:55], v[56:57], v[54:55]
	v_exp_f32_e32 v56, v7
	v_mul_f32_e32 v7, 0xbfb8aa3b, v137
	v_exp_f32_e32 v57, v7
	v_cvt_pk_bf16_f32 v7, v54, v55
	v_lshlrev_b32_e32 v54, 16, v8
	v_and_b32_e32 v55, 0xffff0000, v8
	v_mul_f32_e32 v8, 0xbfb8aa3b, v138
	v_pk_mul_f32 v[54:55], v[56:57], v[54:55]
	v_exp_f32_e32 v56, v8
	v_mul_f32_e32 v8, 0xbfb8aa3b, v139
	v_exp_f32_e32 v57, v8
	v_cvt_pk_bf16_f32 v8, v54, v55
	v_lshlrev_b32_e32 v54, 16, v9
	v_and_b32_e32 v55, 0xffff0000, v9
	v_pk_mul_f32 v[54:55], v[56:57], v[54:55]
	s_addc_u32 s29, s62, s30
	v_cvt_pk_bf16_f32 v9, v54, v55
	ds_write_b128 v122, v[6:9] offset:56320
	s_waitcnt vmcnt(3)
	ds_write_b128 v123, v[2:5]
	s_waitcnt vmcnt(2)
	ds_write_b128 v124, v[10:13]
	s_waitcnt vmcnt(1)
	ds_write_b128 v123, v[14:17] offset:16896
	s_waitcnt vmcnt(0)
	ds_write_b128 v125, v[18:21]
	v_lshl_add_u64 v[2:3], s[28:29], 0, v[96:97]
	s_add_u32 s28, s20, s31
	s_addc_u32 s29, s21, s30
	s_add_u32 s28, s28, s56
	s_addc_u32 s29, s29, 0
	s_add_u32 s28, s28, 0xad20800
	v_add_co_u32_e32 v4, vcc, s42, v2
	s_addc_u32 s29, s29, 0
	s_nop 0
	v_addc_co_u32_e32 v5, vcc, 0, v3, vcc
	v_lshl_add_u64 v[14:15], s[28:29], 0, v[98:99]
	v_add_co_u32_e32 v10, vcc, s43, v14
	global_load_dwordx4 v[54:57], v[2:3], off offset:1024
	global_load_dwordx4 v[6:9], v[4:5], off offset:1024
	v_addc_co_u32_e32 v11, vcc, 0, v15, vcc
	v_add_co_u32_e32 v16, vcc, s42, v14
	global_load_dwordx4 v[2:5], v[14:15], off
	s_nop 0
	global_load_dwordx4 v[10:13], v[10:11], off
	v_addc_co_u32_e32 v17, vcc, 0, v15, vcc
	v_add_co_u32_e32 v18, vcc, s44, v14
	s_cmp_eq_u32 s23, s57
	s_nop 0
	v_addc_co_u32_e32 v19, vcc, 0, v15, vcc
	global_load_dwordx4 v[14:17], v[16:17], off
	s_nop 0
	global_load_dwordx4 v[18:21], v[18:19], off
	s_waitcnt lgkmcnt(0)
	s_barrier
	s_waitcnt lgkmcnt(0)
	ds_read_b64_tr_b16 v[138:139], v127 offset:57408
	ds_read_b64_tr_b16 v[136:137], v127 offset:56320
	ds_read_b64_tr_b16 v[142:143], v126 offset:2112
	ds_read_b64_tr_b16 v[140:141], v126
	ds_read_b64_tr_b16 v[146:147], v126 offset:2144
	ds_read_b64_tr_b16 v[144:145], v126 offset:32
	ds_read_b64_tr_b16 v[224:225], v127 offset:56352
	ds_read_b64_tr_b16 v[156:157], v127 offset:56384
	ds_read_b64_tr_b16 v[160:161], v127 offset:56416
	ds_read_b64_tr_b16 v[226:227], v127 offset:57440
	ds_read_b64_tr_b16 v[158:159], v127 offset:57472
	ds_read_b64_tr_b16 v[162:163], v127 offset:57504
	ds_read_b64_tr_b16 v[164:165], v127 offset:65024
	ds_read_b64_tr_b16 v[166:167], v128 offset:57408
	ds_read_b64_tr_b16 v[168:169], v126 offset:16896
	ds_read_b64_tr_b16 v[170:171], v126 offset:19008
	ds_read_b64_tr_b16 v[174:175], v126 offset:19040
	ds_read_b64_tr_b16 v[172:173], v126 offset:16928
	ds_read_b64_tr_b16 v[228:229], v127 offset:65056
	ds_read_b64_tr_b16 v[176:177], v127 offset:65088
	ds_read_b64_tr_b16 v[180:181], v127 offset:65120
	ds_read_b64_tr_b16 v[230:231], v128 offset:57440
	ds_read_b64_tr_b16 v[178:179], v128 offset:57472
	ds_read_b64_tr_b16 v[182:183], v128 offset:57504
	ds_read_b64_tr_b16 v[232:233], v127 offset:56448
	ds_read_b64_tr_b16 v[234:235], v127 offset:57536
	ds_read_b64_tr_b16 v[148:149], v127 offset:56480
	s_waitcnt lgkmcnt(15)
	v_mfma_f32_16x16x32_bf16 v[58:61], v[224:227], v[140:143], v[58:61]
	v_mfma_f32_16x16x32_bf16 v[78:81], v[224:227], v[144:147], v[78:81]
	v_mfma_f32_16x16x32_bf16 v[66:69], v[136:139], v[140:143], v[66:69]
	v_mfma_f32_16x16x32_bf16 v[62:65], v[136:139], v[144:147], v[62:65]
	s_nop 0
	s_nop 0
	s_nop 0
	s_nop 0
	s_nop 0
	s_nop 0
	s_waitcnt lgkmcnt(5)
	v_mfma_f32_16x16x32_bf16 v[58:61], v[228:231], v[168:171], v[58:61]
	v_mfma_f32_16x16x32_bf16 v[78:81], v[228:231], v[172:175], v[78:81]
	s_nop 0
	s_nop 0
	v_mfma_f32_16x16x32_bf16 v[74:77], v[156:159], v[140:143], v[74:77]
	v_mfma_f32_16x16x32_bf16 v[70:73], v[156:159], v[144:147], v[70:73]
	ds_read_b64_tr_b16 v[156:157], v127 offset:56512
	v_mfma_f32_16x16x32_bf16 v[82:85], v[160:163], v[140:143], v[82:85]
	v_mfma_f32_16x16x32_bf16 v[86:89], v[160:163], v[144:147], v[86:89]
	ds_read_b64_tr_b16 v[160:161], v127 offset:56544
	ds_read_b64_tr_b16 v[150:151], v127 offset:57568
	ds_read_b64_tr_b16 v[158:159], v127 offset:57600
	ds_read_b64_tr_b16 v[162:163], v127 offset:57632
	s_nop 0
	s_nop 0
	s_nop 0
	s_nop 0
	s_nop 0
	s_nop 0
	s_waitcnt lgkmcnt(2)
	v_mfma_f32_16x16x32_bf16 v[22:25], v[148:151], v[140:143], v[22:25]
	v_mfma_f32_16x16x32_bf16 v[50:53], v[148:151], v[144:147], v[50:53]
	v_lshl_add_u32 v150, s63, 9, v111
	v_mfma_f32_16x16x32_bf16 v[66:69], v[164:167], v[168:171], v[66:69]
	v_mfma_f32_16x16x32_bf16 v[62:65], v[164:167], v[172:175], v[62:65]
	ds_read_b64_tr_b16 v[164:165], v127 offset:65152
	ds_read_b64_tr_b16 v[166:167], v128 offset:57536
	ds_read_b64_tr_b16 v[236:237], v127 offset:65184
	v_mfma_f32_16x16x32_bf16 v[74:77], v[176:179], v[168:171], v[74:77]
	v_mfma_f32_16x16x32_bf16 v[70:73], v[176:179], v[172:175], v[70:73]
	ds_read_b64_tr_b16 v[176:177], v127 offset:65216
	v_mfma_f32_16x16x32_bf16 v[82:85], v[180:183], v[168:171], v[82:85]
	v_mfma_f32_16x16x32_bf16 v[86:89], v[180:183], v[172:175], v[86:89]
	ds_read_b64_tr_b16 v[180:181], v127 offset:65248
	ds_read_b64_tr_b16 v[238:239], v128 offset:57568
	ds_read_b64_tr_b16 v[178:179], v128 offset:57600
	ds_read_b64_tr_b16 v[182:183], v128 offset:57632
	ds_read_b128 v[244:247], v150 offset:4096
	ds_read_b128 v[224:227], v150 offset:4160
	ds_read_b128 v[228:231], v150 offset:4224
	v_mfma_f32_16x16x32_bf16 v[30:33], v[232:235], v[140:143], v[30:33]
	v_mfma_f32_16x16x32_bf16 v[26:29], v[232:235], v[144:147], v[26:29]
	ds_read_b128 v[232:235], v150 offset:4288
	s_nop 0
	s_nop 0
	s_nop 0
	s_nop 0
	s_nop 0
	s_nop 0
	s_waitcnt lgkmcnt(6)
	v_mfma_f32_16x16x32_bf16 v[22:25], v[236:239], v[168:171], v[22:25]
	v_mfma_f32_16x16x32_bf16 v[50:53], v[236:239], v[172:175], v[50:53]
	ds_read_b128 v[236:239], v150 offset:4352
	s_nop 0
	v_mfma_f32_16x16x32_bf16 v[34:37], v[156:159], v[140:143], v[34:37]
	v_mfma_f32_16x16x32_bf16 v[38:41], v[160:163], v[140:143], v[38:41]
	s_nop 0
	s_nop 0
	v_mfma_f32_16x16x32_bf16 v[46:49], v[156:159], v[144:147], v[46:49]
	v_mfma_f32_16x16x32_bf16 v[42:45], v[160:163], v[144:147], v[42:45]
	s_waitcnt lgkmcnt(4)
	v_mov_b32_e32 v144, v244
	v_mov_b32_e32 v145, v245
	v_mov_b32_e32 v136, v246
	v_mov_b32_e32 v137, v247
	ds_read_b128 v[244:247], v150 offset:4416
	s_nop 0
	s_nop 0
	s_nop 0
	v_mfma_f32_16x16x32_bf16 v[30:33], v[164:167], v[168:171], v[30:33]
	v_mul_f32_e64 v68, v68, v136
	v_mul_f32_e64 v69, v69, v137
	v_pk_mul_f32 v[64:65], v[64:65], v[136:137]
	s_waitcnt lgkmcnt(4)
	v_mov_b32_e32 v136, v224
	v_mov_b32_e32 v137, v226
	v_mov_b32_e32 v146, v136
	v_mov_b32_e32 v136, v225
	v_mov_b32_e32 v148, v137
	s_nop 0
	v_mov_b32_e32 v149, v227
	v_mov_b32_e32 v147, v136
	s_nop 0
	s_nop 0
	v_pk_mul_f32 v[66:67], v[66:67], v[144:145]
	v_pk_mul_f32 v[62:63], v[62:63], v[144:145]
	v_pk_mul_f32 v[60:61], v[60:61], v[148:149]
	s_nop 0
	s_waitcnt lgkmcnt(3)
	v_mov_b32_e32 v144, v228
	v_mov_b32_e32 v145, v229
	v_mov_b32_e32 v136, v230
	v_mov_b32_e32 v137, v231
	s_nop 0
	s_nop 0
	v_pk_mul_f32 v[58:59], v[58:59], v[146:147]
	v_pk_mul_f32 v[80:81], v[80:81], v[148:149]
	v_pk_mul_f32 v[78:79], v[78:79], v[146:147]
	v_pk_mul_f32 v[76:77], v[76:77], v[136:137]
	v_pk_mul_f32 v[72:73], v[72:73], v[136:137]
	s_waitcnt lgkmcnt(2)
	v_mov_b32_e32 v136, v232
	v_mov_b32_e32 v137, v234
	v_mov_b32_e32 v146, v136
	v_mov_b32_e32 v136, v233
	v_mov_b32_e32 v148, v137
	s_nop 0
	v_mov_b32_e32 v149, v235
	v_mov_b32_e32 v147, v136
	s_nop 0
	s_nop 0
	s_nop 0
	v_mfma_f32_16x16x32_bf16 v[26:29], v[164:167], v[172:175], v[26:29]
	v_mul_f32_e64 v84, v84, v148
	v_mul_f32_e64 v85, v85, v149
	s_nop 0
	v_pk_mul_f32 v[74:75], v[74:75], v[144:145]
	v_pk_mul_f32 v[70:71], v[70:71], v[144:145]
	s_waitcnt lgkmcnt(1)
	v_mov_b32_e32 v144, v236
	v_mov_b32_e32 v145, v237
	v_mov_b32_e32 v136, v238
	v_mov_b32_e32 v137, v239
	s_nop 0
	s_nop 0
	v_pk_mul_f32 v[82:83], v[82:83], v[146:147]
	v_pk_mul_f32 v[88:89], v[88:89], v[148:149]
	v_pk_mul_f32 v[86:87], v[86:87], v[146:147]
	v_pk_mul_f32 v[32:33], v[32:33], v[136:137]
	v_pk_mul_f32 v[28:29], v[28:29], v[136:137]
	s_waitcnt lgkmcnt(0)
	v_mov_b32_e32 v136, v244
	v_mov_b32_e32 v137, v246
	v_mov_b32_e32 v146, v136
	v_mov_b32_e32 v136, v245
	v_mov_b32_e32 v148, v137
	s_nop 0
	v_mov_b32_e32 v149, v247
	v_mov_b32_e32 v147, v136
	ds_read_b128 v[136:139], v150 offset:4480
	ds_read_b128 v[140:143], v150 offset:4544
	v_mfma_f32_16x16x32_bf16 v[34:37], v[176:179], v[168:171], v[34:37]
	s_nop 0
	v_pk_mul_f32 v[24:25], v[24:25], v[148:149]
	s_nop 0
	s_nop 0
	s_nop 0
	s_nop 0
	s_nop 0
	s_nop 0
	s_nop 0
	s_nop 0
	v_mfma_f32_16x16x32_bf16 v[46:49], v[176:179], v[172:175], v[46:49]
	s_nop 0
	s_nop 0
	s_nop 0
	v_mfma_f32_16x16x32_bf16 v[38:41], v[180:183], v[168:171], v[38:41]
	s_nop 0
	s_nop 0
	s_nop 0
	v_mfma_f32_16x16x32_bf16 v[42:45], v[180:183], v[172:175], v[42:45]
	s_nop 0
	s_nop 0
	v_pk_mul_f32 v[30:31], v[30:31], v[144:145]
	v_pk_mul_f32 v[26:27], v[26:27], v[144:145]
	v_pk_mul_f32 v[22:23], v[22:23], v[146:147]
	v_pk_mul_f32 v[52:53], v[52:53], v[148:149]
	v_pk_mul_f32 v[50:51], v[50:51], v[146:147]
	s_waitcnt lgkmcnt(1)
	v_pk_mul_f32 v[36:37], v[36:37], v[138:139]
	v_pk_mul_f32 v[34:35], v[34:35], v[136:137]
	v_pk_mul_f32 v[48:49], v[48:49], v[138:139]
	v_pk_mul_f32 v[46:47], v[46:47], v[136:137]
	s_waitcnt lgkmcnt(0)
	v_pk_mul_f32 v[40:41], v[40:41], v[142:143]
	v_pk_mul_f32 v[38:39], v[38:39], v[140:141]
	v_pk_mul_f32 v[44:45], v[44:45], v[142:143]
	v_pk_mul_f32 v[42:43], v[42:43], v[140:141]
	s_waitcnt lgkmcnt(0)
	s_cbranch_scc1 .LBB0_2101
.LBB0_2086:
	s_and_b32 s63, s57, 1
	s_cmp_eq_u32 s63, 0
	s_cselect_b64 s[28:29], -1, 0
	s_and_b64 s[14:15], s[28:29], exec
	s_cselect_b32 s14, 0xf0, s46
	v_lshlrev_b32_e32 v135, 2, v104
	v_and_b32_e32 v155, 63, v154
	v_lshl_add_u32 v155, v155, 2, s14
	s_waitcnt lgkmcnt(0)
	ds_read2st64_b32 v[144:145], v155 offset1:1
	ds_read2st64_b32 v[226:227], v155 offset0:4 offset1:5
	ds_read2st64_b32 v[224:225], v155 offset0:2 offset1:3
	ds_read2st64_b32 v[228:229], v155 offset0:6 offset1:7
	ds_read2st64_b32 v[232:233], v155 offset0:8 offset1:9
	ds_read2st64_b32 v[236:237], v155 offset0:10 offset1:11
	ds_read2st64_b32 v[244:245], v155 offset0:12 offset1:13
	s_andn2_b64 vcc, exec, s[26:27]
	s_mov_b64 s[30:31], -1
	s_waitcnt lgkmcnt(6)
	v_mfma_f32_16x16x4_f32 v[136:139], v144, v134, 0
	v_mfma_f32_16x16x4_f32 v[136:139], v145, v133, v[136:139]
	s_nop 0
	s_waitcnt lgkmcnt(4)
	v_mfma_f32_16x16x4_f32 v[136:139], v224, v132, v[136:139]
	v_mfma_f32_16x16x4_f32 v[140:143], v226, v134, 0
	v_mfma_f32_16x16x4_f32 v[136:139], v225, v131, v[136:139]
	s_nop 0
	v_mfma_f32_16x16x4_f32 v[140:143], v227, v133, v[140:143]
	s_nop 7
	v_add_f32_e32 v138, v130, v138
	v_min_f32_e32 v148, 0, v138
	v_mul_f32_e64 v138, |v138|, s47
	v_exp_f32_e32 v138, v138
	v_add_f32_e32 v139, v130, v139
	v_mul_f32_e64 v149, |v139|, s47
	v_exp_f32_e32 v149, v149
	s_waitcnt lgkmcnt(3)
	v_mfma_f32_16x16x4_f32 v[140:143], v228, v132, v[140:143]
	v_add_f32_e32 v138, 1.0, v138
	v_log_f32_e32 v138, v138
	v_add_f32_e32 v136, v130, v136
	v_add_f32_e32 v137, v130, v137
	v_min_f32_e32 v146, 0, v136
	v_mul_f32_e64 v136, |v136|, s47
	v_min_f32_e32 v147, 0, v137
	v_mfma_f32_16x16x4_f32 v[140:143], v229, v131, v[140:143]
	v_mul_f32_e64 v137, |v137|, s47
	v_exp_f32_e32 v136, v136
	v_exp_f32_e32 v137, v137
	v_add_f32_e32 v149, 1.0, v149
	v_fmac_f32_e32 v148, 0xbf317218, v138
	v_log_f32_e32 v144, v149
	v_mul_f32_e32 v138, 0x3d800000, v148
	s_nop 0
	s_nop 1
	v_add_f32_e32 v140, v130, v140
	v_mul_f32_e64 v145, |v140|, s47
	v_add_f32_e32 v136, 1.0, v136
	v_add_f32_e32 v137, 1.0, v137
	v_exp_f32_e32 v145, v145
	v_log_f32_e32 v136, v136
	v_log_f32_e32 v137, v137
	v_min_f32_e32 v139, 0, v139
	v_fmac_f32_e32 v139, 0xbf317218, v144
	v_add_f32_e32 v144, 1.0, v145
	v_add_f32_e32 v141, v130, v141
	v_fmac_f32_e32 v146, 0xbf317218, v136
	v_fmac_f32_e32 v147, 0xbf317218, v137
	v_log_f32_e32 v150, v144
	v_mul_f32_e64 v144, |v141|, s47
	v_mul_f32_e32 v136, 0x3d800000, v146
	v_mul_f32_e32 v137, 0x3d800000, v147
	v_exp_f32_e32 v151, v144
	s_waitcnt lgkmcnt(2)
	v_mfma_f32_16x16x4_f32 v[144:147], v232, v134, 0
	v_min_f32_e32 v140, 0, v140
	v_fmac_f32_e32 v140, 0xbf317218, v150
	v_add_f32_e32 v148, 1.0, v151
	s_nop 0
	v_add_f32_e32 v152, v130, v142
	v_mul_f32_e64 v142, |v152|, s47
	v_exp_f32_e32 v142, v142
	v_mfma_f32_16x16x4_f32 v[144:147], v233, v133, v[144:147]
	v_log_f32_e32 v148, v148
	v_min_f32_e32 v141, 0, v141
	v_add_f32_e32 v142, 1.0, v142
	v_add_f32_e32 v149, v130, v143
	v_fmac_f32_e32 v141, 0xbf317218, v148
	v_log_f32_e32 v148, v142
	v_mul_f32_e32 v139, 0x3d800000, v139
	s_waitcnt lgkmcnt(1)
	v_mfma_f32_16x16x4_f32 v[142:145], v236, v132, v[144:147]
	s_nop 0
	v_mul_f32_e64 v146, |v149|, s47
	v_exp_f32_e32 v146, v146
	v_min_f32_e32 v150, 0, v152
	v_fmac_f32_e32 v150, 0xbf317218, v148
	s_nop 0
	v_add_f32_e32 v146, 1.0, v146
	v_log_f32_e32 v148, v146
	v_mfma_f32_16x16x4_f32 v[144:147], v237, v131, v[142:145]
	v_min_f32_e32 v149, 0, v149
	v_mul_f32_e32 v140, 0x3d800000, v140
	v_fmac_f32_e32 v149, 0xbf317218, v148
	v_mul_f32_e32 v141, 0x3d800000, v141
	s_nop 5
	v_add_f32_e32 v144, v130, v144
	v_mul_f32_e64 v142, |v144|, s47
	v_exp_f32_e32 v143, v142
	v_add_f32_e32 v145, v130, v145
	v_mul_f32_e32 v142, 0x3d800000, v150
	v_min_f32_e32 v144, 0, v144
	v_add_f32_e32 v143, 1.0, v143
	v_log_f32_e32 v148, v143
	v_mul_f32_e64 v143, |v145|, s47
	v_exp_f32_e32 v150, v143
	v_mul_f32_e32 v143, 0x3d800000, v149
	v_fmac_f32_e32 v144, 0xbf317218, v148
	v_min_f32_e32 v145, 0, v145
	v_add_f32_e32 v148, 1.0, v150
	v_log_f32_e32 v156, v148
	s_waitcnt lgkmcnt(0)
	v_mfma_f32_16x16x4_f32 v[148:151], v244, v134, 0
	v_add_f32_e32 v146, v130, v146
	v_min_f32_e32 v152, 0, v146
	v_fmac_f32_e32 v145, 0xbf317218, v156
	ds_read2st64_b32 v[156:157], v155 offset0:14 offset1:15
	v_mul_f32_e64 v146, |v146|, s47
	v_exp_f32_e32 v146, v146
	v_mul_f32_e32 v144, 0x3d800000, v144
	v_mfma_f32_16x16x4_f32 v[148:151], v245, v133, v[148:151]
	v_add_f32_e32 v153, v130, v147
	v_mul_f32_e64 v147, |v153|, s47
	v_add_f32_e32 v146, 1.0, v146
	v_exp_f32_e32 v155, v147
	v_log_f32_e32 v158, v146
	v_mul_f32_e32 v145, 0x3d800000, v145
	v_fmac_f32_e32 v152, 0xbf317218, v158
	s_waitcnt lgkmcnt(0)
	v_mfma_f32_16x16x4_f32 v[146:149], v156, v132, v[148:151]
	s_nop 0
	v_add_f32_e32 v150, 1.0, v155
	v_log_f32_e32 v150, v150
	v_min_f32_e32 v151, 0, v153
	v_mul_f32_e32 v163, 0x3d800000, v152
	v_fmac_f32_e32 v151, 0xbf317218, v150
	v_mul_f32_e32 v164, 0x3d800000, v151
	v_mfma_f32_16x16x4_f32 v[146:149], v157, v131, v[146:149]
	s_nop 9
	v_add_f32_e32 v146, v130, v146
	v_mul_f32_e64 v150, |v146|, s47
	v_exp_f32_e32 v150, v150
	v_add_f32_e32 v147, v130, v147
	v_mul_f32_e64 v151, |v147|, s47
	v_exp_f32_e32 v151, v151
	v_add_f32_e32 v150, 1.0, v150
	v_log_f32_e32 v150, v150
	v_min_f32_e32 v146, 0, v146
	v_add_f32_e32 v151, 1.0, v151
	v_log_f32_e32 v151, v151
	v_fmac_f32_e32 v146, 0xbf317218, v150
	v_mul_f32_e32 v165, 0x3d800000, v146
	v_min_f32_e32 v146, 0, v147
	v_fmac_f32_e32 v146, 0xbf317218, v151
	v_mul_f32_e32 v166, 0x3d800000, v146
	v_add_f32_e32 v146, v130, v148
	v_mul_f32_e64 v147, |v146|, s47
	v_exp_f32_e32 v147, v147
	v_add_f32_e32 v148, v130, v149
	v_mul_f32_e64 v149, |v148|, s47
	v_exp_f32_e32 v149, v149
	v_add_f32_e32 v147, 1.0, v147
	v_log_f32_e32 v147, v147
	v_min_f32_e32 v146, 0, v146
	v_add_f32_e32 v149, 1.0, v149
	v_log_f32_e32 v149, v149
	v_fmac_f32_e32 v146, 0xbf317218, v147
	v_mul_f32_e32 v167, 0x3d800000, v146
	v_min_f32_e32 v146, 0, v148
	v_fmac_f32_e32 v146, 0xbf317218, v149
	v_mul_f32_e32 v168, 0x3d800000, v146
	v_cndmask_b32_e64 v146, 0, 1, s[26:27]
	v_cmp_ne_u32_e64 s[14:15], 1, v146
	s_waitcnt lgkmcnt(0)
	s_cbranch_vccnz .LBB0_2088
	v_add_f32_e32 v146, 0, v168
	v_add_f32_e32 v147, v167, v146
	v_add_f32_e32 v148, v166, v147
	v_add_f32_e32 v149, v165, v148
	v_add_f32_e32 v150, v164, v149
	v_add_f32_e32 v151, v163, v150
	v_add_f32_e32 v152, v145, v151
	v_add_f32_e32 v153, v144, v152
	v_add_f32_e32 v155, v143, v153
	v_add_f32_e32 v156, v142, v155
	v_add_f32_e32 v157, v141, v156
	v_add_f32_e32 v158, v140, v157
	v_add_f32_e32 v159, v139, v158
	v_add_f32_e32 v160, v138, v159
	v_add_f32_e32 v161, v137, v160
	v_add_f32_e32 v162, v136, v161
	s_mov_b64 s[30:31], 0

.LBB0_2101:
	v_and_b32_e32 v148, 63, v154
	v_lshl_add_u32 v148, v148, 2, s46
	s_waitcnt lgkmcnt(0)
	ds_read2st64_b32 v[136:137], v148 offset1:1
	ds_read2st64_b32 v[224:225], v148 offset0:2 offset1:3
	ds_read2st64_b32 v[226:227], v148 offset0:4 offset1:5
	ds_read2st64_b32 v[228:229], v148 offset0:6 offset1:7
	ds_read2st64_b32 v[232:233], v148 offset0:8 offset1:9
	s_and_b64 vcc, exec, s[14:15]
	s_mov_b64 s[24:25], -1
	s_waitcnt lgkmcnt(4)
	v_mfma_f32_16x16x4_f32 v[90:93], v136, v134, 0
	v_mfma_f32_16x16x4_f32 v[90:93], v137, v133, v[90:93]
	s_waitcnt lgkmcnt(3)
	v_mfma_f32_16x16x4_f32 v[90:93], v224, v132, v[90:93]
	s_waitcnt lgkmcnt(2)
	v_mfma_f32_16x16x4_f32 v[136:139], v226, v134, 0
	v_mfma_f32_16x16x4_f32 v[90:93], v225, v131, v[90:93]
	v_mfma_f32_16x16x4_f32 v[136:139], v227, v133, v[136:139]
	s_nop 8
	v_add_f32_e32 v90, v130, v90
	v_min_f32_e32 v135, 0, v90
	v_mul_f32_e64 v90, |v90|, s47
	v_exp_f32_e32 v90, v90
	v_add_f32_e32 v91, v130, v91
	v_min_f32_e32 v140, 0, v91
	v_mul_f32_e64 v91, |v91|, s47
	s_waitcnt lgkmcnt(1)
	v_mfma_f32_16x16x4_f32 v[136:139], v228, v132, v[136:139]
	v_add_f32_e32 v90, 1.0, v90
	v_exp_f32_e32 v91, v91
	v_log_f32_e32 v90, v90
	v_add_f32_e32 v92, v130, v92
	v_add_f32_e32 v93, v130, v93
	v_add_f32_e32 v91, 1.0, v91
	v_fmac_f32_e32 v135, 0xbf317218, v90
	v_mfma_f32_16x16x4_f32 v[136:139], v229, v131, v[136:139]
	v_mul_f32_e64 v141, |v92|, s47
	v_log_f32_e32 v91, v91
	v_mul_f32_e32 v90, 0x3d800000, v135
	v_mul_f32_e64 v135, |v93|, s47
	v_exp_f32_e32 v141, v141
	v_exp_f32_e32 v135, v135
	s_nop 0
	v_fmac_f32_e32 v140, 0xbf317218, v91
	s_nop 1
	v_add_f32_e32 v136, v130, v136
	v_add_f32_e32 v141, 1.0, v141
	v_mul_f32_e32 v91, 0x3d800000, v140
	v_add_f32_e32 v135, 1.0, v135
	v_mul_f32_e64 v140, |v136|, s47
	v_log_f32_e32 v141, v141
	v_log_f32_e32 v135, v135
	v_exp_f32_e32 v140, v140
	v_min_f32_e32 v92, 0, v92
	v_min_f32_e32 v93, 0, v93
	v_fmac_f32_e32 v92, 0xbf317218, v141
	v_fmac_f32_e32 v93, 0xbf317218, v135
	v_add_f32_e32 v135, 1.0, v140
	s_waitcnt lgkmcnt(0)
	v_mfma_f32_16x16x4_f32 v[140:143], v232, v134, 0
	v_add_f32_e32 v146, v130, v137
	v_mul_f32_e64 v137, |v146|, s47
	v_log_f32_e32 v135, v135
	v_exp_f32_e32 v137, v137
	v_min_f32_e32 v144, 0, v136
	v_add_f32_e32 v149, v130, v138
	v_fmac_f32_e32 v144, 0xbf317218, v135
	v_add_f32_e32 v135, 1.0, v137
	ds_read2st64_b32 v[136:137], v148 offset0:10 offset1:11
	ds_read2st64_b32 v[236:237], v148 offset0:12 offset1:13
	v_mfma_f32_16x16x4_f32 v[140:143], v233, v133, v[140:143]
	v_log_f32_e32 v147, v135
	v_mul_f32_e64 v135, |v149|, s47
	v_exp_f32_e32 v138, v135
	v_mul_f32_e32 v135, 0x3d800000, v144
	v_min_f32_e32 v144, 0, v146
	v_add_f32_e32 v146, v130, v139
	v_add_f32_e32 v138, 1.0, v138
	v_log_f32_e32 v145, v138
	s_waitcnt lgkmcnt(1)
	v_mfma_f32_16x16x4_f32 v[138:141], v136, v132, v[140:143]
	v_mul_f32_e64 v136, |v146|, s47
	v_exp_f32_e32 v142, v136
	v_fmac_f32_e32 v144, 0xbf317218, v147
	v_mul_f32_e32 v136, 0x3d800000, v144
	v_min_f32_e32 v143, 0, v149
	v_add_f32_e32 v142, 1.0, v142
	v_fmac_f32_e32 v143, 0xbf317218, v145
	v_mfma_f32_16x16x4_f32 v[138:141], v137, v131, v[138:141]
	v_log_f32_e32 v142, v142
	v_mul_f32_e32 v92, 0x3d800000, v92
	v_mul_f32_e32 v93, 0x3d800000, v93
	s_nop 6
	v_add_f32_e32 v144, v130, v138
	v_mul_f32_e64 v137, |v144|, s47
	v_exp_f32_e32 v138, v137
	v_mul_f32_e32 v137, 0x3d800000, v143
	v_min_f32_e32 v143, 0, v146
	s_nop 0
	v_add_f32_e32 v138, 1.0, v138
	v_add_f32_e32 v139, v130, v139
	v_fmac_f32_e32 v143, 0xbf317218, v142
	v_log_f32_e32 v142, v138
	v_mul_f32_e64 v138, |v139|, s47
	v_exp_f32_e32 v145, v138
	v_min_f32_e32 v149, 0, v144
	v_fmac_f32_e32 v149, 0xbf317218, v142
	v_mul_f32_e32 v138, 0x3d800000, v143
	v_add_f32_e32 v142, 1.0, v145
	v_log_f32_e32 v150, v142
	s_waitcnt lgkmcnt(0)
	v_mfma_f32_16x16x4_f32 v[142:145], v236, v134, 0
	v_mul_f32_e32 v134, 0x3d800000, v149
	ds_read2st64_b32 v[148:149], v148 offset0:14 offset1:15
	v_add_f32_e32 v140, v130, v140
	v_min_f32_e32 v139, 0, v139
	v_min_f32_e32 v146, 0, v140
	v_fmac_f32_e32 v139, 0xbf317218, v150
	v_mul_f32_e32 v139, 0x3d800000, v139
	v_mfma_f32_16x16x4_f32 v[142:145], v237, v133, v[142:145]
	v_add_f32_e32 v147, v130, v141
	v_mul_f32_e64 v133, |v140|, s47
	v_mul_f32_e64 v140, |v147|, s47
	v_exp_f32_e32 v150, v140
	v_exp_f32_e32 v133, v133
	s_nop 0
	v_add_f32_e32 v133, 1.0, v133
	s_waitcnt lgkmcnt(0)
	v_mfma_f32_16x16x4_f32 v[140:143], v148, v132, v[142:145]
	v_log_f32_e32 v133, v133
	v_add_f32_e32 v132, 1.0, v150
	v_log_f32_e32 v132, v132
	v_fmac_f32_e32 v146, 0xbf317218, v133
	v_min_f32_e32 v133, 0, v147
	v_fmac_f32_e32 v133, 0xbf317218, v132
	v_mfma_f32_16x16x4_f32 v[140:143], v149, v131, v[140:143]
	v_mul_f32_e32 v153, 0x3d800000, v133
	v_mul_f32_e32 v152, 0x3d800000, v146
	s_nop 7
	v_add_f32_e32 v131, v130, v140
	v_mul_f32_e64 v132, |v131|, s47
	v_exp_f32_e32 v132, v132
	v_add_f32_e32 v133, v130, v141
	v_mul_f32_e64 v140, |v133|, s47
	v_exp_f32_e32 v140, v140
	v_add_f32_e32 v132, 1.0, v132
	v_log_f32_e32 v132, v132
	v_min_f32_e32 v131, 0, v131
	v_add_f32_e32 v140, 1.0, v140
	v_log_f32_e32 v140, v140
	v_fmac_f32_e32 v131, 0xbf317218, v132
	v_mul_f32_e32 v155, 0x3d800000, v131
	v_min_f32_e32 v131, 0, v133
	v_fmac_f32_e32 v131, 0xbf317218, v140
	v_mul_f32_e32 v156, 0x3d800000, v131
	v_add_f32_e32 v131, v130, v142
	v_add_f32_e32 v130, v130, v143
	v_mul_f32_e64 v132, |v131|, s47
	v_mul_f32_e64 v133, |v130|, s47
	v_exp_f32_e32 v132, v132
	v_exp_f32_e32 v133, v133
	v_min_f32_e32 v131, 0, v131
	v_min_f32_e32 v130, 0, v130
	v_add_f32_e32 v132, 1.0, v132
	v_add_f32_e32 v133, 1.0, v133
	v_log_f32_e32 v132, v132
	v_log_f32_e32 v133, v133
	v_fmac_f32_e32 v131, 0xbf317218, v132
	v_fmac_f32_e32 v130, 0xbf317218, v133
	v_mul_f32_e32 v157, 0x3d800000, v131
	v_mul_f32_e32 v158, 0x3d800000, v130
	s_waitcnt lgkmcnt(0)
	s_cbranch_vccnz .LBB0_2103
	v_add_f32_e32 v130, 0, v158
	v_add_f32_e32 v131, v157, v130
	v_add_f32_e32 v132, v156, v131
	v_add_f32_e32 v133, v155, v132
	v_add_f32_e32 v140, v153, v133
	v_add_f32_e32 v141, v152, v140
	v_add_f32_e32 v142, v139, v141
	v_add_f32_e32 v143, v134, v142
	v_add_f32_e32 v144, v138, v143
	v_add_f32_e32 v145, v137, v144
	v_add_f32_e32 v146, v136, v145
	v_add_f32_e32 v147, v135, v146
	v_add_f32_e32 v148, v93, v147
	v_add_f32_e32 v149, v92, v148
	v_add_f32_e32 v150, v91, v149
	v_add_f32_e32 v151, v90, v150
	s_mov_b64 s[24:25], 0

.LBB0_2111:
	s_or_b64 exec, exec, s[14:15]
	s_waitcnt lgkmcnt(0)
	ds_read_b128 v[90:93], v119 offset:6144
	ds_read_b128 v[130:133], v119 offset:6160
	s_waitcnt vmcnt(5)
	v_lshlrev_b32_e32 v134, 16, v54
	v_and_b32_e32 v135, 0xffff0000, v54
	s_waitcnt lgkmcnt(1)
	v_mul_f32_e32 v90, 0xbfb8aa3b, v90
	v_mul_f32_e32 v91, 0xbfb8aa3b, v91
	v_exp_f32_e32 v90, v90
	v_exp_f32_e32 v91, v91
	v_mul_f32_e32 v54, 0xbfb8aa3b, v92
	v_exp_f32_e32 v92, v54
	v_mul_f32_e32 v54, 0xbfb8aa3b, v93
	v_exp_f32_e32 v93, v54
	v_pk_mul_f32 v[90:91], v[90:91], v[134:135]
	s_nop 0
	v_cvt_pk_bf16_f32 v54, v90, v91
	v_lshlrev_b32_e32 v90, 16, v55
	v_and_b32_e32 v91, 0xffff0000, v55
	s_waitcnt lgkmcnt(0)
	v_mul_f32_e32 v55, 0xbfb8aa3b, v130
	v_pk_mul_f32 v[90:91], v[92:93], v[90:91]
	v_exp_f32_e32 v92, v55
	v_mul_f32_e32 v55, 0xbfb8aa3b, v131
	v_exp_f32_e32 v93, v55
	v_cvt_pk_bf16_f32 v55, v90, v91
	v_lshlrev_b32_e32 v90, 16, v56
	v_and_b32_e32 v91, 0xffff0000, v56
	v_mul_f32_e32 v56, 0xbfb8aa3b, v132
	v_pk_mul_f32 v[90:91], v[92:93], v[90:91]
	v_exp_f32_e32 v92, v56
	v_mul_f32_e32 v56, 0xbfb8aa3b, v133
	v_exp_f32_e32 v93, v56
	v_cvt_pk_bf16_f32 v56, v90, v91
	v_lshlrev_b32_e32 v90, 16, v57
	v_and_b32_e32 v91, 0xffff0000, v57
	v_pk_mul_f32 v[90:91], v[92:93], v[90:91]
	s_waitcnt vmcnt(4)
	v_lshlrev_b32_e32 v130, 16, v6
	v_cvt_pk_bf16_f32 v57, v90, v91
	ds_write_b128 v120, v[54:57] offset:56320
	ds_read_b128 v[224:227], v121 offset:6144
	ds_read_b128 v[90:93], v121 offset:6160
	v_and_b32_e32 v131, 0xffff0000, v6
	s_waitcnt lgkmcnt(1)
	v_mul_f32_e32 v54, 0xbfb8aa3b, v224
	v_mul_f32_e32 v55, 0xbfb8aa3b, v225
	v_exp_f32_e32 v54, v54
	v_exp_f32_e32 v55, v55
	v_mul_f32_e32 v6, 0xbfb8aa3b, v226
	v_exp_f32_e32 v56, v6
	v_mul_f32_e32 v6, 0xbfb8aa3b, v227
	v_exp_f32_e32 v57, v6
	v_pk_mul_f32 v[54:55], v[54:55], v[130:131]
	s_nop 0
	v_cvt_pk_bf16_f32 v6, v54, v55
	v_lshlrev_b32_e32 v54, 16, v7
	v_and_b32_e32 v55, 0xffff0000, v7
	s_waitcnt lgkmcnt(0)
	v_mul_f32_e32 v7, 0xbfb8aa3b, v90
	v_pk_mul_f32 v[54:55], v[56:57], v[54:55]
	v_exp_f32_e32 v56, v7
	v_mul_f32_e32 v7, 0xbfb8aa3b, v91
	v_exp_f32_e32 v57, v7
	v_cvt_pk_bf16_f32 v7, v54, v55
	v_lshlrev_b32_e32 v54, 16, v8
	v_and_b32_e32 v55, 0xffff0000, v8
	v_mul_f32_e32 v8, 0xbfb8aa3b, v92
	v_pk_mul_f32 v[54:55], v[56:57], v[54:55]
	v_exp_f32_e32 v56, v8
	v_mul_f32_e32 v8, 0xbfb8aa3b, v93
	v_exp_f32_e32 v57, v8
	v_cvt_pk_bf16_f32 v8, v54, v55
	v_lshlrev_b32_e32 v54, 16, v9
	v_and_b32_e32 v55, 0xffff0000, v9
	v_pk_mul_f32 v[54:55], v[56:57], v[54:55]
	s_nop 0
	v_cvt_pk_bf16_f32 v9, v54, v55
	ds_write_b128 v122, v[6:9] offset:56320
	s_waitcnt vmcnt(3)
	ds_write_b128 v123, v[2:5]
	s_waitcnt vmcnt(2)
	ds_write_b128 v124, v[10:13]
	s_waitcnt vmcnt(1)
	ds_write_b128 v123, v[14:17] offset:16896
	s_waitcnt vmcnt(0)
	ds_write_b128 v125, v[18:21]
	s_waitcnt lgkmcnt(0)
	s_barrier
	s_waitcnt lgkmcnt(0)
	ds_read_b64_tr_b16 v[4:5], v127 offset:57408
	ds_read_b64_tr_b16 v[2:3], v127 offset:56320
	ds_read_b64_tr_b16 v[8:9], v126 offset:2112
	ds_read_b64_tr_b16 v[6:7], v126
	ds_read_b64_tr_b16 v[12:13], v126 offset:2144
	ds_read_b64_tr_b16 v[10:11], v126 offset:32
	ds_read_b64_tr_b16 v[14:15], v127 offset:56352
	ds_read_b64_tr_b16 v[18:19], v127 offset:56384
	ds_read_b64_tr_b16 v[224:225], v127 offset:56416
	ds_read_b64_tr_b16 v[16:17], v127 offset:57440
	ds_read_b64_tr_b16 v[20:21], v127 offset:57472
	ds_read_b64_tr_b16 v[226:227], v127 offset:57504
	ds_read_b64_tr_b16 v[228:229], v127 offset:65024
	ds_read_b64_tr_b16 v[230:231], v128 offset:57408
	ds_read_b64_tr_b16 v[130:131], v126 offset:16896
	ds_read_b64_tr_b16 v[132:133], v126 offset:19008
	ds_read_b64_tr_b16 v[136:137], v126 offset:19040
	ds_read_b64_tr_b16 v[134:135], v126 offset:16928
	ds_read_b64_tr_b16 v[232:233], v127 offset:65056
	ds_read_b64_tr_b16 v[138:139], v127 offset:65088
	ds_read_b64_tr_b16 v[142:143], v127 offset:65120
	ds_read_b64_tr_b16 v[234:235], v128 offset:57440
	ds_read_b64_tr_b16 v[140:141], v128 offset:57472
	ds_read_b64_tr_b16 v[144:145], v128 offset:57504
	ds_read_b64_tr_b16 v[236:237], v127 offset:56448
	ds_read_b64_tr_b16 v[238:239], v127 offset:57536
	s_waitcnt lgkmcnt(15)
	v_mfma_f32_16x16x32_bf16 v[58:61], v[14:17], v[6:9], v[58:61]
	v_mfma_f32_16x16x32_bf16 v[14:17], v[14:17], v[10:13], v[78:81]
	ds_read_b64_tr_b16 v[78:79], v127 offset:56480
	v_mfma_f32_16x16x32_bf16 v[66:69], v[2:5], v[6:9], v[66:69]
	v_mfma_f32_16x16x32_bf16 v[2:5], v[2:5], v[10:13], v[62:65]
	s_nop 2
	s_nop 0
	s_nop 0
	s_nop 0
	s_nop 0
	s_nop 0
	s_nop 0
	s_waitcnt lgkmcnt(5)
	v_mfma_f32_16x16x32_bf16 v[58:61], v[232:235], v[130:133], v[58:61]
	v_mfma_f32_16x16x32_bf16 v[14:17], v[232:235], v[134:137], v[14:17]
	v_mfma_f32_16x16x32_bf16 v[62:65], v[18:21], v[6:9], v[74:77]
	s_nop 2
	s_nop 0
	s_nop 0
	v_mfma_f32_16x16x32_bf16 v[18:21], v[18:21], v[10:13], v[70:73]
	v_mfma_f32_16x16x32_bf16 v[70:73], v[224:227], v[6:9], v[82:85]
	ds_read_b64_tr_b16 v[82:83], v127 offset:56512
	v_mfma_f32_16x16x32_bf16 v[54:57], v[224:227], v[10:13], v[86:89]
	ds_read_b64_tr_b16 v[86:87], v127 offset:56544
	ds_read_b64_tr_b16 v[80:81], v127 offset:57568
	ds_read_b64_tr_b16 v[84:85], v127 offset:57600
	ds_read_b64_tr_b16 v[88:89], v127 offset:57632
	ds_read_b64_tr_b16 v[90:91], v127 offset:65152
	ds_read_b64_tr_b16 v[92:93], v128 offset:57536
	ds_read_b64_tr_b16 v[244:245], v127 offset:65184
	s_nop 0
	s_nop 0
	s_nop 0
	s_nop 0
	s_nop 0
	s_nop 0
	s_nop 0
	s_waitcnt lgkmcnt(4)
	v_mfma_f32_16x16x32_bf16 v[34:37], v[82:85], v[6:9], v[34:37]
	v_mfma_f32_16x16x32_bf16 v[46:49], v[82:85], v[10:13], v[46:49]
	v_add_u32_e32 v82, s23, v111
	s_ashr_i32 s23, s22, 31
	s_lshl_b64 s[14:15], s[22:23], 17
	v_mfma_f32_16x16x32_bf16 v[66:69], v[228:231], v[130:133], v[66:69]
	v_mfma_f32_16x16x32_bf16 v[2:5], v[228:231], v[134:137], v[2:5]
	s_nop 0
	s_nop 0
	v_mfma_f32_16x16x32_bf16 v[62:65], v[138:141], v[130:133], v[62:65]
	v_mfma_f32_16x16x32_bf16 v[18:21], v[138:141], v[134:137], v[18:21]
	ds_read_b64_tr_b16 v[138:139], v127 offset:65216
	v_mfma_f32_16x16x32_bf16 v[70:73], v[142:145], v[130:133], v[70:73]
	v_mfma_f32_16x16x32_bf16 v[54:57], v[142:145], v[134:137], v[54:57]
	ds_read_b64_tr_b16 v[142:143], v127 offset:65248
	ds_read_b64_tr_b16 v[246:247], v128 offset:57568
	ds_read_b64_tr_b16 v[140:141], v128 offset:57600
	ds_read_b64_tr_b16 v[144:145], v128 offset:57632
	ds_read_b128 v[232:235], v82 offset:4096
	ds_read_b128 v[224:227], v82 offset:4160
	ds_read_b128 v[228:231], v82 offset:4224
	v_mfma_f32_16x16x32_bf16 v[30:33], v[236:239], v[6:9], v[30:33]
	v_mfma_f32_16x16x32_bf16 v[26:29], v[236:239], v[10:13], v[26:29]
	ds_read_b128 v[236:239], v82 offset:4288
	s_nop 0
	s_nop 0
	s_nop 0
	s_nop 0
	s_nop 0
	s_nop 0
	v_mfma_f32_16x16x32_bf16 v[22:25], v[78:81], v[6:9], v[22:25]
	s_waitcnt lgkmcnt(12)
	v_mfma_f32_16x16x32_bf16 v[6:9], v[86:89], v[6:9], v[38:41]
	s_nop 2
	s_nop 0
	v_mfma_f32_16x16x32_bf16 v[50:53], v[78:81], v[10:13], v[50:53]
	v_mfma_f32_16x16x32_bf16 v[10:13], v[86:89], v[10:13], v[42:45]
	s_nop 2
	s_nop 0
	s_nop 0
	s_waitcnt lgkmcnt(6)
	v_mfma_f32_16x16x32_bf16 v[22:25], v[244:247], v[130:133], v[22:25]
	s_nop 0
	v_mfma_f32_16x16x32_bf16 v[50:53], v[244:247], v[134:137], v[50:53]
	ds_read_b128 v[244:247], v82 offset:4352
	s_waitcnt lgkmcnt(4)
	v_mov_b32_e32 v74, v232
	v_mov_b32_e32 v38, v233
	v_mov_b32_e32 v39, v234
	v_mov_b32_e32 v76, v39
	s_nop 0
	v_mov_b32_e32 v77, v235
	ds_read_b128 v[232:235], v82 offset:4416
	v_mov_b32_e32 v75, v38
	v_mfma_f32_16x16x32_bf16 v[30:33], v[90:93], v[130:133], v[30:33]
	v_mul_f32_e64 v40, v68, v76
	v_mul_f32_e64 v41, v69, v77
	v_pk_mul_f32 v[4:5], v[4:5], v[76:77]
	s_waitcnt lgkmcnt(4)
	v_mov_b32_e32 v76, v224
	v_mov_b32_e32 v42, v225
	v_mov_b32_e32 v43, v226
	v_mov_b32_e32 v78, v43
	s_nop 0
	v_mov_b32_e32 v79, v227
	v_mov_b32_e32 v77, v42
	s_nop 0
	v_pk_mul_f32 v[38:39], v[66:67], v[74:75]
	s_nop 0
	v_pk_mul_f32 v[2:3], v[2:3], v[74:75]
	v_pk_mul_f32 v[60:61], v[60:61], v[78:79]
	s_nop 0
	s_waitcnt lgkmcnt(3)
	v_mov_b32_e32 v74, v228
	v_mov_b32_e32 v42, v229
	v_mov_b32_e32 v43, v230
	v_mov_b32_e32 v75, v42
	v_mov_b32_e32 v80, v43
	s_nop 0
	v_mov_b32_e32 v81, v231
	v_pk_mul_f32 v[42:43], v[62:63], v[74:75]
	s_waitcnt lgkmcnt(2)
	v_mov_b32_e32 v62, v236
	v_mov_b32_e32 v63, v238
	v_pk_mul_f32 v[58:59], v[58:59], v[76:77]
	v_pk_mul_f32 v[16:17], v[16:17], v[78:79]
	v_pk_mul_f32 v[14:15], v[14:15], v[76:77]
	v_mov_b32_e32 v76, v62
	v_mov_b32_e32 v62, v237
	v_mov_b32_e32 v78, v63
	v_mov_b32_e32 v63, v239
	v_pk_mul_f32 v[44:45], v[64:65], v[80:81]
	v_mov_b32_e32 v79, v63
	v_mov_b32_e32 v77, v62
	s_nop 0
	v_pk_mul_f32 v[18:19], v[18:19], v[74:75]
	v_pk_mul_f32 v[68:69], v[72:73], v[78:79]
	v_pk_mul_f32 v[66:67], v[70:71], v[76:77]
	s_nop 0
	s_nop 0
	s_waitcnt lgkmcnt(1)
	v_mov_b32_e32 v74, v244
	v_mov_b32_e32 v75, v245
	v_mov_b32_e32 v62, v246
	v_mov_b32_e32 v63, v247
	v_mfma_f32_16x16x32_bf16 v[26:29], v[90:93], v[134:137], v[26:29]
	s_nop 0
	s_nop 0
	v_pk_mul_f32 v[56:57], v[56:57], v[78:79]
	v_pk_mul_f32 v[54:55], v[54:55], v[76:77]
	v_mfma_f32_16x16x32_bf16 v[34:37], v[138:141], v[130:133], v[34:37]
	v_mul_f32_e64 v32, v32, v62
	v_mul_f32_e64 v33, v33, v63
	s_nop 0
	v_pk_mul_f32 v[28:29], v[28:29], v[62:63]
	s_waitcnt lgkmcnt(0)
	v_mov_b32_e32 v62, v232
	v_mov_b32_e32 v63, v234
	v_mov_b32_e32 v76, v62
	v_mov_b32_e32 v62, v233
	v_mov_b32_e32 v78, v63
	s_nop 0
	v_mov_b32_e32 v79, v235
	v_mov_b32_e32 v77, v62
	ds_read_b128 v[62:65], v82 offset:4480
	ds_read_b128 v[70:73], v82 offset:4544
	v_mfma_f32_16x16x32_bf16 v[46:49], v[138:141], v[134:137], v[46:49]
	v_mul_f32_e64 v20, v20, v80
	v_mul_f32_e64 v21, v21, v81
	s_nop 0
	s_nop 0
	s_nop 0
	s_nop 0
	s_nop 0
	v_pk_mul_f32 v[30:31], v[30:31], v[74:75]
	v_pk_mul_f32 v[26:27], v[26:27], v[74:75]
	s_nop 0
	s_waitcnt lgkmcnt(1)
	v_pk_mul_f32 v[34:35], v[34:35], v[62:63]
	v_pk_mul_f32 v[46:47], v[46:47], v[62:63]
	v_lshl_add_u64 v[62:63], v[102:103], 0, s[14:15]
	global_store_dwordx4 v[62:63], v[38:41], off
	s_nop 0
	v_pk_mul_f32 v[24:25], v[24:25], v[78:79]
	v_add_co_u32_e32 v38, vcc, s40, v62
	v_pk_mul_f32 v[22:23], v[22:23], v[76:77]
	s_nop 0
	v_addc_co_u32_e32 v39, vcc, 0, v63, vcc
	global_store_dwordx4 v[38:39], v[2:5], off
	s_nop 0
	s_nop 0
	v_add_co_u32_e32 v2, vcc, s34, v62
	v_pk_mul_f32 v[52:53], v[52:53], v[78:79]
	s_nop 0
	v_addc_co_u32_e32 v3, vcc, 0, v63, vcc
	global_store_dwordx4 v[2:3], v[58:61], off
	v_add_co_u32_e32 v2, vcc, s41, v62
	v_pk_mul_f32 v[50:51], v[50:51], v[76:77]
	s_nop 0
	v_addc_co_u32_e32 v3, vcc, 0, v63, vcc
	global_store_dwordx4 v[2:3], v[14:17], off
	v_add_co_u32_e32 v2, vcc, s39, v62
	s_nop 0
	v_addc_co_u32_e32 v3, vcc, 0, v63, vcc
	global_store_dwordx4 v[2:3], v[42:45], off
	v_add_co_u32_e32 v2, vcc, s48, v62
	s_nop 0
	s_nop 0
	v_addc_co_u32_e32 v3, vcc, 0, v63, vcc
	global_store_dwordx4 v[2:3], v[18:21], off
	v_add_co_u32_e32 v2, vcc, s49, v62
	s_nop 0
	s_nop 0
	v_addc_co_u32_e32 v3, vcc, 0, v63, vcc
	global_store_dwordx4 v[2:3], v[66:69], off
	v_add_co_u32_e32 v2, vcc, s50, v62
	s_nop 0
	s_nop 0
	v_addc_co_u32_e32 v3, vcc, 0, v63, vcc
	global_store_dwordx4 v[2:3], v[54:57], off
	v_add_co_u32_e32 v2, vcc, s51, v62
	v_mfma_f32_16x16x32_bf16 v[6:9], v[142:145], v[130:133], v[6:9]
	s_nop 0
	v_addc_co_u32_e32 v3, vcc, 0, v63, vcc
	global_store_dwordx4 v[2:3], v[30:33], off
	v_add_co_u32_e32 v2, vcc, s45, v62
	v_pk_mul_f32 v[36:37], v[36:37], v[64:65]
	s_nop 0
	v_addc_co_u32_e32 v3, vcc, 0, v63, vcc
	global_store_dwordx4 v[2:3], v[26:29], off
	v_add_co_u32_e32 v2, vcc, s52, v62
	s_nop 0
	s_nop 0
	v_addc_co_u32_e32 v3, vcc, 0, v63, vcc
	global_store_dwordx4 v[2:3], v[22:25], off
	v_add_co_u32_e32 v2, vcc, s53, v62
	s_nop 0
	s_nop 0
	v_addc_co_u32_e32 v3, vcc, 0, v63, vcc
	global_store_dwordx4 v[2:3], v[50:53], off
	v_add_co_u32_e32 v2, vcc, s43, v62
	s_nop 0
	s_nop 0
	v_addc_co_u32_e32 v3, vcc, 0, v63, vcc
	global_store_dwordx4 v[2:3], v[34:37], off
	v_add_co_u32_e32 v2, vcc, s54, v62
	v_mfma_f32_16x16x32_bf16 v[10:13], v[142:145], v[134:137], v[10:13]
	v_mul_f32_e64 v48, v48, v64
	v_mul_f32_e64 v49, v49, v65
	v_addc_co_u32_e32 v3, vcc, 0, v63, vcc
	global_store_dwordx4 v[2:3], v[46:49], off
	v_add_co_u32_e32 v2, vcc, 0x1c000, v62
	s_waitcnt lgkmcnt(0)
	v_pk_mul_f32 v[8:9], v[8:9], v[72:73]
	v_pk_mul_f32 v[6:7], v[6:7], v[70:71]
	v_addc_co_u32_e32 v3, vcc, 0, v63, vcc
	global_store_dwordx4 v[2:3], v[6:9], off
	v_add_co_u32_e32 v2, vcc, 0x1e000, v62
	v_pk_mul_f32 v[12:13], v[12:13], v[72:73]
	v_pk_mul_f32 v[10:11], v[10:11], v[70:71]
	v_addc_co_u32_e32 v3, vcc, 0, v63, vcc
	global_store_dwordx4 v[2:3], v[10:13], off
	s_and_saveexec_b64 s[14:15], s[4:5]
	s_waitcnt lgkmcnt(0)
	s_cbranch_execz .LBB0_2073
	v_mul_f32_e32 v1, 0x3fb8aa3b, v1
	v_exp_f32_e32 v1, v1
	s_lshl_b64 s[24:25], s[22:23], 9
	v_lshl_add_u64 v[2:3], v[100:101], 0, s[24:25]
	global_store_dword v[2:3], v1, off
	s_branch .LBB0_2073

.LBB0_2266:
	ds_read_b128 v[138:141], v205 offset:6144
	ds_read_b128 v[142:145], v205 offset:6160
	s_waitcnt vmcnt(6)
	v_lshlrev_b32_e32 v146, 16, v98
	v_and_b32_e32 v147, 0xffff0000, v98
	v_add_u32_e32 v219, 0x9800, v216
	s_waitcnt lgkmcnt(1)
	v_mul_f32_e32 v107, 0xbfb8aa3b, v138
	v_exp_f32_e32 v108, v107
	v_mul_f32_e32 v107, 0xbfb8aa3b, v139
	v_exp_f32_e32 v109, v107
	v_mul_f32_e32 v107, 0xbfb8aa3b, v140
	v_cvt_pk_bf16_f32 v160, v10, v11
	v_cvt_pk_bf16_f32 v161, v12, v13
	v_pk_mul_f32 v[108:109], v[108:109], v[146:147]
	v_lshlrev_b32_e32 v146, 16, v99
	v_cvt_pk_bf16_f32 v98, v108, v109
	v_exp_f32_e32 v108, v107
	v_mul_f32_e32 v107, 0xbfb8aa3b, v141
	v_exp_f32_e32 v109, v107
	v_and_b32_e32 v147, 0xffff0000, v99
	s_waitcnt lgkmcnt(0)
	v_mul_f32_e32 v107, 0xbfb8aa3b, v142
	v_cvt_pk_bf16_f32 v162, v26, v27
	v_pk_mul_f32 v[108:109], v[108:109], v[146:147]
	v_lshlrev_b32_e32 v146, 16, v100
	v_cvt_pk_bf16_f32 v99, v108, v109
	v_exp_f32_e32 v108, v107
	v_mul_f32_e32 v107, 0xbfb8aa3b, v143
	v_exp_f32_e32 v109, v107
	v_and_b32_e32 v147, 0xffff0000, v100
	v_mul_f32_e32 v107, 0xbfb8aa3b, v144
	v_cvt_pk_bf16_f32 v163, v28, v29
	v_pk_mul_f32 v[108:109], v[108:109], v[146:147]
	v_lshlrev_b32_e32 v146, 16, v101
	v_cvt_pk_bf16_f32 v100, v108, v109
	v_exp_f32_e32 v108, v107
	v_mul_f32_e32 v107, 0xbfb8aa3b, v145
	v_exp_f32_e32 v109, v107
	v_and_b32_e32 v147, 0xffff0000, v101
	v_add_u32_e32 v220, 0xa800, v216
	v_add_u32_e32 v221, 0xb800, v216
	v_pk_mul_f32 v[108:109], v[108:109], v[146:147]
	v_add_u32_e32 v222, 0xc800, v216
	v_cvt_pk_bf16_f32 v101, v108, v109
	ds_write_b128 v184, v[98:101] offset:56320
	v_mul_f32_e32 v98, 0x3fb8aa3b, v138
	v_mul_f32_e32 v99, 0x3fb8aa3b, v139
	v_exp_f32_e32 v98, v98
	v_exp_f32_e32 v99, v99
	v_lshlrev_b32_e32 v100, 16, v94
	v_and_b32_e32 v101, 0xffff0000, v94
	s_waitcnt vmcnt(4)
	v_lshlrev_b32_e32 v138, 16, v90
	v_pk_mul_f32 v[98:99], v[98:99], s[48:49] op_sel_hi:[1,0]
	v_and_b32_e32 v139, 0xffff0000, v90
	v_pk_mul_f32 v[98:99], v[98:99], v[100:101]
	v_lshlrev_b32_e32 v100, 16, v95
	v_cvt_pk_bf16_f32 v94, v98, v99
	v_mul_f32_e32 v98, 0x3fb8aa3b, v140
	v_mul_f32_e32 v99, 0x3fb8aa3b, v141
	v_exp_f32_e32 v98, v98
	v_exp_f32_e32 v99, v99
	v_and_b32_e32 v101, 0xffff0000, v95
	s_mov_b32 s61, 0x8000
	s_add_u32 s74, s74, 0x60000
	v_pk_mul_f32 v[98:99], v[98:99], s[48:49] op_sel_hi:[1,0]
	s_addc_u32 s75, s75, 0
	v_pk_mul_f32 v[98:99], v[98:99], v[100:101]
	v_lshlrev_b32_e32 v100, 16, v96
	v_cvt_pk_bf16_f32 v95, v98, v99
	v_mul_f32_e32 v98, 0x3fb8aa3b, v142
	v_mul_f32_e32 v99, 0x3fb8aa3b, v143
	v_exp_f32_e32 v98, v98
	v_exp_f32_e32 v99, v99
	v_and_b32_e32 v101, 0xffff0000, v96
	s_add_i32 s60, s60, 64
	v_pk_mul_f32 v[98:99], v[98:99], s[48:49] op_sel_hi:[1,0]
	s_nop 0
	v_pk_mul_f32 v[98:99], v[98:99], v[100:101]
	v_lshlrev_b32_e32 v100, 16, v97
	v_cvt_pk_bf16_f32 v96, v98, v99
	v_mul_f32_e32 v98, 0x3fb8aa3b, v144
	v_mul_f32_e32 v99, 0x3fb8aa3b, v145
	v_exp_f32_e32 v98, v98
	v_exp_f32_e32 v99, v99
	v_and_b32_e32 v101, 0xffff0000, v97
	v_pk_mul_f32 v[98:99], v[98:99], s[48:49] op_sel_hi:[1,0]
	s_nop 0
	v_pk_mul_f32 v[98:99], v[98:99], v[100:101]
	s_nop 0
	v_cvt_pk_bf16_f32 v97, v98, v99
	ds_write_b128 v184, v[94:97] offset:38912
	ds_read_b128 v[94:97], v206 offset:6144
	ds_read_b128 v[98:101], v206 offset:6160
	s_waitcnt lgkmcnt(1)
	v_mul_f32_e32 v107, 0xbfb8aa3b, v94
	v_exp_f32_e32 v108, v107
	v_mul_f32_e32 v107, 0xbfb8aa3b, v95
	v_exp_f32_e32 v109, v107
	v_mul_f32_e32 v107, 0xbfb8aa3b, v96
	v_pk_mul_f32 v[108:109], v[108:109], v[138:139]
	s_nop 0
	v_cvt_pk_bf16_f32 v90, v108, v109
	v_exp_f32_e32 v108, v107
	v_mul_f32_e32 v107, 0xbfb8aa3b, v97
	v_exp_f32_e32 v109, v107
	v_lshlrev_b32_e32 v138, 16, v91
	v_and_b32_e32 v139, 0xffff0000, v91
	s_waitcnt lgkmcnt(0)
	v_mul_f32_e32 v107, 0xbfb8aa3b, v98
	v_pk_mul_f32 v[108:109], v[108:109], v[138:139]
	v_lshlrev_b32_e32 v138, 16, v92
	v_cvt_pk_bf16_f32 v91, v108, v109
	v_exp_f32_e32 v108, v107
	v_mul_f32_e32 v107, 0xbfb8aa3b, v99
	v_exp_f32_e32 v109, v107
	v_and_b32_e32 v139, 0xffff0000, v92
	v_mul_f32_e32 v107, 0xbfb8aa3b, v100
	v_pk_mul_f32 v[108:109], v[108:109], v[138:139]
	s_nop 0
	v_cvt_pk_bf16_f32 v92, v108, v109
	v_exp_f32_e32 v108, v107
	v_mul_f32_e32 v107, 0xbfb8aa3b, v101
	v_exp_f32_e32 v109, v107
	v_lshlrev_b32_e32 v138, 16, v93
	v_and_b32_e32 v139, 0xffff0000, v93
	v_pk_mul_f32 v[108:109], v[108:109], v[138:139]
	s_nop 0
	v_cvt_pk_bf16_f32 v93, v108, v109
	ds_write_b128 v185, v[90:93] offset:56320
	v_mul_f32_e32 v90, 0x3fb8aa3b, v94
	v_mul_f32_e32 v91, 0x3fb8aa3b, v95
	v_exp_f32_e32 v90, v90
	v_exp_f32_e32 v91, v91
	v_lshlrev_b32_e32 v92, 16, v70
	v_and_b32_e32 v93, 0xffff0000, v70
	v_pk_mul_f32 v[90:91], v[90:91], s[48:49] op_sel_hi:[1,0]
	s_nop 0
	v_pk_mul_f32 v[90:91], v[90:91], v[92:93]
	v_lshlrev_b32_e32 v92, 16, v71
	v_cvt_pk_bf16_f32 v70, v90, v91
	v_mul_f32_e32 v90, 0x3fb8aa3b, v96
	v_mul_f32_e32 v91, 0x3fb8aa3b, v97
	v_exp_f32_e32 v90, v90
	v_exp_f32_e32 v91, v91
	v_and_b32_e32 v93, 0xffff0000, v71
	v_pk_mul_f32 v[90:91], v[90:91], s[48:49] op_sel_hi:[1,0]
	s_nop 0
	v_pk_mul_f32 v[90:91], v[90:91], v[92:93]
	v_lshlrev_b32_e32 v92, 16, v72
	v_cvt_pk_bf16_f32 v71, v90, v91
	v_mul_f32_e32 v90, 0x3fb8aa3b, v98
	v_mul_f32_e32 v91, 0x3fb8aa3b, v99
	v_exp_f32_e32 v90, v90
	v_exp_f32_e32 v91, v91
	v_and_b32_e32 v93, 0xffff0000, v72
	v_pk_mul_f32 v[90:91], v[90:91], s[48:49] op_sel_hi:[1,0]
	s_nop 0
	v_pk_mul_f32 v[90:91], v[90:91], v[92:93]
	v_lshlrev_b32_e32 v92, 16, v73
	v_cvt_pk_bf16_f32 v72, v90, v91
	v_mul_f32_e32 v90, 0x3fb8aa3b, v100
	v_mul_f32_e32 v91, 0x3fb8aa3b, v101
	v_exp_f32_e32 v90, v90
	v_exp_f32_e32 v91, v91
	v_and_b32_e32 v93, 0xffff0000, v73
	v_pk_mul_f32 v[90:91], v[90:91], s[48:49] op_sel_hi:[1,0]
	s_nop 0
	v_pk_mul_f32 v[90:91], v[90:91], v[92:93]
	s_nop 0
	v_cvt_pk_bf16_f32 v73, v90, v91
	ds_write_b128 v185, v[70:73] offset:38912
	s_waitcnt vmcnt(3)
	ds_write_b128 v207, v[74:77]
	s_waitcnt vmcnt(2)
	ds_write_b128 v208, v[78:81]
	s_waitcnt vmcnt(1)
	ds_write_b128 v207, v[82:85] offset:16896
	s_waitcnt vmcnt(0)
	ds_write_b128 v209, v[86:89]
	s_waitcnt lgkmcnt(0)
	s_barrier
	s_waitcnt lgkmcnt(0)
	ds_read_b128 v[70:73], v210 offset:56320
	ds_read_b128 v[236:239], v183 offset:38912
	ds_read_b128 v[244:247], v210 offset:56384
	ds_read_b128 v[82:85], v183 offset:38976
	s_waitcnt lgkmcnt(2)
	v_mfma_f32_16x16x32_bf16 v[70:73], v[70:73], v[236:239], 0
	s_waitcnt lgkmcnt(0)
	v_mfma_f32_16x16x32_bf16 v[70:73], v[244:247], v[82:85], v[70:73]
	ds_read_b128 v[244:247], v210 offset:56448
	ds_read_b128 v[86:89], v183 offset:39040
	ds_read_b128 v[78:81], v210 offset:56512
	ds_read_b128 v[90:93], v183 offset:39104
	s_waitcnt lgkmcnt(2)
	v_mfma_f32_16x16x32_bf16 v[70:73], v[244:247], v[86:89], v[70:73]
	s_nop 0
	s_nop 0
	s_waitcnt lgkmcnt(0)
	v_mfma_f32_16x16x32_bf16 v[70:73], v[78:81], v[90:93], v[70:73]
	v_mov_b32_e32 v78, s93
	s_nop 6
	v_cndmask_b32_e64 v78, v70, v78, s[12:13]
	v_cndmask_b32_e64 v70, v78, v70, s[14:15]
	v_cndmask_b32_e64 v71, 0, v71, s[14:15]
	v_cndmask_b32_e64 v72, v72, 0, s[16:17]
	v_cndmask_b32_e64 v73, v73, 0, s[18:19]
	v_cvt_pk_bf16_f32 v70, v70, v71
	v_cvt_pk_bf16_f32 v71, v72, v73
	ds_write_b64 v211, v[70:71]
	ds_read_b128 v[244:247], v212 offset:56320
	s_waitcnt lgkmcnt(0)
	v_mfma_f32_16x16x32_bf16 v[70:73], v[244:247], v[236:239], 0
	ds_read_b128 v[236:239], v212 offset:56384
	ds_read_b128 v[244:247], v212 offset:56448
	ds_read_b128 v[74:77], v212 offset:56512
	s_waitcnt lgkmcnt(2)
	v_mfma_f32_16x16x32_bf16 v[70:73], v[236:239], v[82:85], v[70:73]
	s_nop 0
	s_waitcnt lgkmcnt(1)
	v_mfma_f32_16x16x32_bf16 v[70:73], v[244:247], v[86:89], v[70:73]
	s_nop 0
	s_waitcnt lgkmcnt(0)
	v_mfma_f32_16x16x32_bf16 v[70:73], v[74:77], v[90:93], v[70:73]
	v_mov_b32_e32 v74, s93
	s_nop 6
	v_cndmask_b32_e64 v74, v70, v74, s[20:21]
	v_cndmask_b32_e64 v70, v74, v70, s[22:23]
	v_cndmask_b32_e64 v71, 0, v71, s[22:23]
	v_cndmask_b32_e64 v72, v72, 0, s[24:25]
	v_cndmask_b32_e64 v73, v73, 0, s[26:27]
	v_cvt_pk_bf16_f32 v70, v70, v71
	v_cvt_pk_bf16_f32 v71, v72, v73
	ds_write_b64 v213, v[70:71]
	s_waitcnt lgkmcnt(0)
	s_barrier
	s_waitcnt lgkmcnt(0)
	ds_read_b64_tr_b16 v[80:81], v214 offset:2112
	ds_read_b64_tr_b16 v[78:79], v214
	ds_read_b64_tr_b16 v[82:83], v214 offset:32
	ds_read_b64_tr_b16 v[70:71], v214 offset:16896
	ds_read_b64_tr_b16 v[72:73], v214 offset:19008
	ds_read_b64_tr_b16 v[84:85], v214 offset:2144
	ds_read_b64_tr_b16 v[74:75], v214 offset:16928
	ds_read_b64_tr_b16 v[76:77], v214 offset:19040
	ds_read_b128 v[236:239], v215
	ds_read_b128 v[244:247], v215 offset:64
	ds_read_b128 v[138:141], v215 offset:2368
	ds_read_b128 v[146:149], v215 offset:4672
	ds_read_b128 v[156:159], v215 offset:6976
	ds_read2_b64 v[164:167], v219 offset1:4
	s_waitcnt lgkmcnt(5)
	v_mfma_f32_16x16x32_bf16 v[90:93], v[78:81], v[236:239], 0
	s_nop 0
	s_nop 0
	s_nop 0
	v_mfma_f32_16x16x32_bf16 v[86:89], v[82:85], v[236:239], 0
	ds_read_b128 v[236:239], v215 offset:2304
	s_waitcnt lgkmcnt(5)
	v_mfma_f32_16x16x32_bf16 v[90:93], v[70:73], v[244:247], v[90:93]
	v_mfma_f32_16x16x32_bf16 v[86:89], v[74:77], v[244:247], v[86:89]
	ds_read_b128 v[244:247], v215 offset:4608
	s_nop 0
	s_waitcnt lgkmcnt(1)
	v_mfma_f32_16x16x32_bf16 v[98:101], v[78:81], v[236:239], 0
	v_mfma_f32_16x16x32_bf16 v[94:97], v[82:85], v[236:239], 0
	ds_read_b128 v[236:239], v215 offset:6912
	v_mfma_f32_16x16x32_bf16 v[98:101], v[70:73], v[138:141], v[98:101]
	v_mfma_f32_16x16x32_bf16 v[94:97], v[74:77], v[138:141], v[94:97]
	s_nop 0
	s_waitcnt lgkmcnt(1)
	v_mfma_f32_16x16x32_bf16 v[142:145], v[78:81], v[244:247], 0
	v_mfma_f32_16x16x32_bf16 v[138:141], v[82:85], v[244:247], 0
	ds_read2_b64 v[244:247], v220 offset0:32 offset1:36
	v_mfma_f32_16x16x32_bf16 v[142:145], v[70:73], v[146:149], v[142:145]
	v_mfma_f32_16x16x32_bf16 v[138:141], v[74:77], v[146:149], v[138:141]
	s_nop 0
	s_waitcnt lgkmcnt(1)
	v_mfma_f32_16x16x32_bf16 v[150:153], v[78:81], v[236:239], 0
	v_mfma_f32_16x16x32_bf16 v[146:149], v[82:85], v[236:239], 0
	ds_read2_b64 v[236:239], v221 offset0:64 offset1:68
	v_mfma_f32_16x16x32_bf16 v[150:153], v[70:73], v[156:159], v[150:153]
	v_mfma_f32_16x16x32_bf16 v[146:149], v[74:77], v[156:159], v[146:149]
	v_cvt_pk_bf16_f32 v156, v6, v7
	v_cvt_pk_bf16_f32 v157, v8, v9
	v_cvt_pk_bf16_f32 v158, v22, v23
	v_cvt_pk_bf16_f32 v159, v24, v25
	v_mfma_f32_16x16x32_bf16 v[86:89], v[160:163], v[164:167], v[86:89]
	s_nop 0
	v_mfma_f32_16x16x32_bf16 v[90:93], v[156:159], v[164:167], v[90:93]
	s_nop 0
	s_waitcnt lgkmcnt(1)
	v_mfma_f32_16x16x32_bf16 v[98:101], v[156:159], v[244:247], v[98:101]
	v_mfma_f32_16x16x32_bf16 v[94:97], v[160:163], v[244:247], v[94:97]
	ds_read2_b64 v[244:247], v222 offset0:96 offset1:100
	s_nop 0
	s_waitcnt lgkmcnt(1)
	v_mfma_f32_16x16x32_bf16 v[142:145], v[156:159], v[236:239], v[142:145]
	v_mfma_f32_16x16x32_bf16 v[138:141], v[160:163], v[236:239], v[138:141]
	ds_read2_b64 v[236:239], v219 offset0:8 offset1:12
	s_nop 0
	s_waitcnt lgkmcnt(1)
	v_mfma_f32_16x16x32_bf16 v[150:153], v[156:159], v[244:247], v[150:153]
	v_cvt_pk_bf16_f32 v156, v14, v15
	v_cvt_pk_bf16_f32 v157, v16, v17
	v_cvt_pk_bf16_f32 v158, v38, v39
	v_mfma_f32_16x16x32_bf16 v[146:149], v[160:163], v[244:247], v[146:149]
	ds_read2_b64 v[244:247], v220 offset0:40 offset1:44
	v_cvt_pk_bf16_f32 v159, v40, v41
	v_cvt_pk_bf16_f32 v160, v18, v19
	v_cvt_pk_bf16_f32 v161, v20, v21
	v_cvt_pk_bf16_f32 v162, v42, v43
	v_cvt_pk_bf16_f32 v163, v44, v45
	s_nop 0
	s_waitcnt lgkmcnt(1)
	v_mfma_f32_16x16x32_bf16 v[90:93], v[156:159], v[236:239], v[90:93]
	v_mfma_f32_16x16x32_bf16 v[86:89], v[160:163], v[236:239], v[86:89]
	ds_read2_b64 v[236:239], v221 offset0:72 offset1:76
	s_nop 0
	s_waitcnt lgkmcnt(1)
	v_mfma_f32_16x16x32_bf16 v[98:101], v[156:159], v[244:247], v[98:101]
	v_mfma_f32_16x16x32_bf16 v[94:97], v[160:163], v[244:247], v[94:97]
	ds_read2_b64 v[244:247], v222 offset0:104 offset1:108
	s_nop 0
	s_waitcnt lgkmcnt(1)
	v_mfma_f32_16x16x32_bf16 v[142:145], v[156:159], v[236:239], v[142:145]
	v_mfma_f32_16x16x32_bf16 v[138:141], v[160:163], v[236:239], v[138:141]
	ds_read2_b64 v[236:239], v219 offset0:16 offset1:20
	s_nop 0
	s_waitcnt lgkmcnt(1)
	v_mfma_f32_16x16x32_bf16 v[150:153], v[156:159], v[244:247], v[150:153]
	v_cvt_pk_bf16_f32 v156, v30, v31
	v_cvt_pk_bf16_f32 v157, v32, v33
	v_cvt_pk_bf16_f32 v158, v46, v47
	v_mfma_f32_16x16x32_bf16 v[146:149], v[160:163], v[244:247], v[146:149]
	ds_read2_b64 v[244:247], v220 offset0:48 offset1:52
	v_cvt_pk_bf16_f32 v159, v48, v49
	v_cvt_pk_bf16_f32 v160, v34, v35
	v_cvt_pk_bf16_f32 v161, v36, v37
	v_cvt_pk_bf16_f32 v162, v54, v55
	v_cvt_pk_bf16_f32 v163, v56, v57
	s_nop 0
	s_waitcnt lgkmcnt(1)
	v_mfma_f32_16x16x32_bf16 v[90:93], v[156:159], v[236:239], v[90:93]
	v_mfma_f32_16x16x32_bf16 v[86:89], v[160:163], v[236:239], v[86:89]
	ds_read2_b64 v[236:239], v221 offset0:80 offset1:84
	s_nop 0
	s_waitcnt lgkmcnt(1)
	v_mfma_f32_16x16x32_bf16 v[98:101], v[156:159], v[244:247], v[98:101]
	v_mfma_f32_16x16x32_bf16 v[94:97], v[160:163], v[244:247], v[94:97]
	ds_read2_b64 v[244:247], v222 offset0:112 offset1:116
	s_nop 0
	s_waitcnt lgkmcnt(1)
	v_mfma_f32_16x16x32_bf16 v[142:145], v[156:159], v[236:239], v[142:145]
	v_mfma_f32_16x16x32_bf16 v[138:141], v[160:163], v[236:239], v[138:141]
	ds_read2_b64 v[236:239], v219 offset0:24 offset1:28
	s_nop 0
	s_waitcnt lgkmcnt(1)
	v_mfma_f32_16x16x32_bf16 v[150:153], v[156:159], v[244:247], v[150:153]
	v_cvt_pk_bf16_f32 v156, v50, v51
	v_cvt_pk_bf16_f32 v157, v52, v53
	v_cvt_pk_bf16_f32 v158, v62, v63
	v_mfma_f32_16x16x32_bf16 v[146:149], v[160:163], v[244:247], v[146:149]
	ds_read2_b64 v[244:247], v220 offset0:56 offset1:60
	v_cvt_pk_bf16_f32 v159, v64, v65
	v_cvt_pk_bf16_f32 v160, v58, v59
	v_cvt_pk_bf16_f32 v161, v60, v61
	v_cvt_pk_bf16_f32 v162, v66, v67
	v_cvt_pk_bf16_f32 v163, v68, v69
	s_nop 0
	s_waitcnt lgkmcnt(1)
	v_mfma_f32_16x16x32_bf16 v[90:93], v[156:159], v[236:239], v[90:93]
	v_mfma_f32_16x16x32_bf16 v[86:89], v[160:163], v[236:239], v[86:89]
	ds_read2_b64 v[236:239], v221 offset0:88 offset1:92
	ds_read2_b64 v[164:167], v222 offset0:120 offset1:124
	s_nop 0
	s_nop 5
	v_cvt_pk_bf16_f32 v90, v90, v91
	v_cvt_pk_bf16_f32 v91, v92, v93
	s_waitcnt lgkmcnt(2)
	v_mfma_f32_16x16x32_bf16 v[98:101], v[156:159], v[244:247], v[98:101]
	v_lshl_add_u64 v[92:93], s[64:65], 0, v[118:119]
	v_cvt_pk_bf16_f32 v86, v86, v87
	v_cvt_pk_bf16_f32 v87, v88, v89
	v_mfma_f32_16x16x32_bf16 v[94:97], v[160:163], v[244:247], v[94:97]
	ds_read_b64_tr_b16 v[246:247], v217 offset:57408
	ds_read_b64_tr_b16 v[244:245], v217 offset:56320
	s_nop 0
	v_add_co_u32_e32 v88, vcc, s61, v92
	s_waitcnt lgkmcnt(3)
	v_mfma_f32_16x16x32_bf16 v[142:145], v[156:159], v[236:239], v[142:145]
	global_store_dwordx2 v[92:93], v[86:87], off offset:32
	v_cvt_pk_bf16_f32 v86, v98, v99
	v_cvt_pk_bf16_f32 v87, v100, v101
	v_mfma_f32_16x16x32_bf16 v[138:141], v[160:163], v[236:239], v[138:141]
	s_nop 0
	v_addc_co_u32_e32 v89, vcc, 0, v93, vcc
	global_store_dwordx2 v[88:89], v[86:87], off
	v_cvt_pk_bf16_f32 v86, v94, v95
	v_cvt_pk_bf16_f32 v87, v96, v97
	s_mov_b32 s61, 0x10000
	s_waitcnt lgkmcnt(2)
	v_mfma_f32_16x16x32_bf16 v[150:153], v[156:159], v[164:167], v[150:153]
	global_store_dwordx2 v[88:89], v[86:87], off offset:32
	v_add_co_u32_e32 v88, vcc, s61, v92
	v_mfma_f32_16x16x32_bf16 v[146:149], v[160:163], v[164:167], v[146:149]
	v_cvt_pk_bf16_f32 v86, v142, v143
	v_cvt_pk_bf16_f32 v87, v144, v145
	v_addc_co_u32_e32 v89, vcc, 0, v93, vcc
	global_store_dwordx2 v[88:89], v[86:87], off
	v_cvt_pk_bf16_f32 v86, v138, v139
	v_cvt_pk_bf16_f32 v87, v140, v141
	global_store_dwordx2 v[88:89], v[86:87], off offset:32
	v_add_co_u32_e32 v88, vcc, s81, v92
	v_cvt_pk_bf16_f32 v86, v150, v151
	v_cvt_pk_bf16_f32 v87, v152, v153
	v_addc_co_u32_e32 v89, vcc, 0, v93, vcc
	global_store_dwordx2 v[88:89], v[86:87], off
	v_cvt_pk_bf16_f32 v86, v146, v147
	v_cvt_pk_bf16_f32 v87, v148, v149
	global_store_dwordx2 v[92:93], v[90:91], off
	ds_read_b64_tr_b16 v[90:91], v217 offset:56352
	ds_read_b64_tr_b16 v[236:237], v217 offset:65024
	ds_read_b64_tr_b16 v[238:239], v218 offset:57408
	ds_read_b64_tr_b16 v[94:95], v218 offset:57440
	ds_read_b64_tr_b16 v[92:93], v217 offset:57440
	global_store_dwordx2 v[88:89], v[86:87], off offset:32
	s_nop 0
	s_nop 0
	s_nop 0
	s_waitcnt lgkmcnt(5)
	v_mfma_f32_16x16x32_bf16 v[6:9], v[244:247], v[78:81], v[6:9]
	s_add_u32 s64, s64, 0x20000
	s_addc_u32 s65, s65, 0
	s_add_i32 s95, s95, 1
	v_mfma_f32_16x16x32_bf16 v[10:13], v[244:247], v[82:85], v[10:13]
	s_nop 0
	s_nop 0
	s_nop 0
	s_nop 0
	s_cmp_lg_u32 s74, 0x300000
	s_waitcnt lgkmcnt(2)
	v_mfma_f32_16x16x32_bf16 v[6:9], v[236:239], v[70:73], v[6:9]
	v_mfma_f32_16x16x32_bf16 v[10:13], v[236:239], v[74:77], v[10:13]
	s_waitcnt lgkmcnt(0)
	v_mfma_f32_16x16x32_bf16 v[22:25], v[90:93], v[78:81], v[22:25]
	v_mfma_f32_16x16x32_bf16 v[26:29], v[90:93], v[82:85], v[26:29]
	ds_read_b64_tr_b16 v[92:93], v217 offset:65056
	ds_read_b64_tr_b16 v[244:245], v217 offset:56384
	ds_read_b64_tr_b16 v[246:247], v217 offset:57472
	ds_read_b64_tr_b16 v[236:237], v217 offset:65088
	ds_read_b64_tr_b16 v[238:239], v218 offset:57472
	s_waitcnt lgkmcnt(2)
	v_mfma_f32_16x16x32_bf16 v[14:17], v[244:247], v[78:81], v[14:17]
	v_mfma_f32_16x16x32_bf16 v[18:21], v[244:247], v[82:85], v[18:21]
	ds_read_b64_tr_b16 v[244:245], v217 offset:56416
	ds_read_b64_tr_b16 v[246:247], v217 offset:57504
	s_nop 0
	s_nop 0
	s_waitcnt lgkmcnt(2)
	v_mfma_f32_16x16x32_bf16 v[14:17], v[236:239], v[70:73], v[14:17]
	v_mfma_f32_16x16x32_bf16 v[18:21], v[236:239], v[74:77], v[18:21]
	ds_read_b64_tr_b16 v[236:237], v217 offset:65120
	ds_read_b64_tr_b16 v[238:239], v218 offset:57504
	s_nop 0
	s_nop 0
	s_waitcnt lgkmcnt(2)
	v_mfma_f32_16x16x32_bf16 v[38:41], v[244:247], v[78:81], v[38:41]
	v_mfma_f32_16x16x32_bf16 v[42:45], v[244:247], v[82:85], v[42:45]
	ds_read_b64_tr_b16 v[244:245], v217 offset:56448
	ds_read_b64_tr_b16 v[246:247], v217 offset:57536
	s_nop 0
	s_nop 0
	s_waitcnt lgkmcnt(2)
	v_mfma_f32_16x16x32_bf16 v[38:41], v[236:239], v[70:73], v[38:41]
	v_mfma_f32_16x16x32_bf16 v[42:45], v[236:239], v[74:77], v[42:45]
	ds_read_b64_tr_b16 v[236:237], v217 offset:65152
	ds_read_b64_tr_b16 v[238:239], v218 offset:57536
	s_nop 0
	s_nop 0
	s_waitcnt lgkmcnt(2)
	v_mfma_f32_16x16x32_bf16 v[30:33], v[244:247], v[78:81], v[30:33]
	v_mfma_f32_16x16x32_bf16 v[34:37], v[244:247], v[82:85], v[34:37]
	ds_read_b64_tr_b16 v[244:245], v217 offset:56480
	ds_read_b64_tr_b16 v[246:247], v217 offset:57568
	s_nop 0
	s_nop 0
	s_waitcnt lgkmcnt(2)
	v_mfma_f32_16x16x32_bf16 v[30:33], v[236:239], v[70:73], v[30:33]
	v_mfma_f32_16x16x32_bf16 v[34:37], v[236:239], v[74:77], v[34:37]
	ds_read_b64_tr_b16 v[236:237], v217 offset:65184
	ds_read_b64_tr_b16 v[238:239], v218 offset:57568
	s_nop 0
	s_nop 0
	s_waitcnt lgkmcnt(2)
	v_mfma_f32_16x16x32_bf16 v[46:49], v[244:247], v[78:81], v[46:49]
	v_mfma_f32_16x16x32_bf16 v[54:57], v[244:247], v[82:85], v[54:57]
	ds_read_b64_tr_b16 v[244:245], v217 offset:56512
	ds_read_b64_tr_b16 v[246:247], v217 offset:57600
	s_nop 0
	s_nop 0
	s_waitcnt lgkmcnt(2)
	v_mfma_f32_16x16x32_bf16 v[46:49], v[236:239], v[70:73], v[46:49]
	v_mfma_f32_16x16x32_bf16 v[54:57], v[236:239], v[74:77], v[54:57]
	ds_read_b64_tr_b16 v[236:237], v217 offset:65216
	ds_read_b64_tr_b16 v[238:239], v218 offset:57600
	ds_read_b64_tr_b16 v[86:87], v217 offset:56544
	ds_read_b64_tr_b16 v[88:89], v217 offset:57632
	s_nop 0
	s_nop 0
	s_waitcnt lgkmcnt(4)
	v_mfma_f32_16x16x32_bf16 v[50:53], v[244:247], v[78:81], v[50:53]
	v_mfma_f32_16x16x32_bf16 v[58:61], v[244:247], v[82:85], v[58:61]
	s_nop 0
	s_nop 0
	s_waitcnt lgkmcnt(2)
	v_mfma_f32_16x16x32_bf16 v[50:53], v[236:239], v[70:73], v[50:53]
	v_mfma_f32_16x16x32_bf16 v[58:61], v[236:239], v[74:77], v[58:61]
	s_nop 0
	s_nop 0
	s_waitcnt lgkmcnt(0)
	v_mfma_f32_16x16x32_bf16 v[62:65], v[86:89], v[78:81], v[62:65]
	ds_read_b64_tr_b16 v[78:79], v217 offset:65248
	ds_read_b64_tr_b16 v[80:81], v218 offset:57632
	v_mfma_f32_16x16x32_bf16 v[66:69], v[86:89], v[82:85], v[66:69]
	v_mfma_f32_16x16x32_bf16 v[22:25], v[92:95], v[70:73], v[22:25]
	s_waitcnt lgkmcnt(0)
	v_mfma_f32_16x16x32_bf16 v[62:65], v[78:81], v[70:73], v[62:65]
	v_lshl_add_u32 v70, s49, 9, v182
	ds_read_b128 v[244:247], v70 offset:4096
	ds_read_b128 v[236:239], v70 offset:4160
	v_mfma_f32_16x16x32_bf16 v[26:29], v[92:95], v[74:77], v[26:29]
	v_mfma_f32_16x16x32_bf16 v[66:69], v[78:81], v[74:77], v[66:69]
	s_nop 0
	s_nop 0
	s_waitcnt lgkmcnt(1)
	v_mov_b32_e32 v72, v244
	s_nop 0
	v_mov_b32_e32 v73, v245
	s_nop 0
	v_mov_b32_e32 v74, v246
	s_nop 0
	v_mov_b32_e32 v75, v247
	ds_read_b128 v[244:247], v70 offset:4224
	v_pk_mul_f32 v[6:7], v[6:7], v[72:73]
	v_pk_mul_f32 v[10:11], v[10:11], v[72:73]
	v_pk_mul_f32 v[8:9], v[8:9], v[74:75]
	v_pk_mul_f32 v[12:13], v[12:13], v[74:75]
	s_nop 0
	s_nop 0
	s_waitcnt lgkmcnt(1)
	v_mov_b32_e32 v72, v236
	s_nop 0
	v_mov_b32_e32 v73, v237
	s_nop 0
	v_mov_b32_e32 v74, v238
	s_nop 0
	v_mov_b32_e32 v75, v239
	ds_read_b128 v[236:239], v70 offset:4288
	v_pk_mul_f32 v[22:23], v[22:23], v[72:73]
	v_pk_mul_f32 v[26:27], v[26:27], v[72:73]
	v_pk_mul_f32 v[24:25], v[24:25], v[74:75]
	v_pk_mul_f32 v[28:29], v[28:29], v[74:75]
	s_nop 0
	s_nop 0
	s_waitcnt lgkmcnt(1)
	v_mov_b32_e32 v72, v244
	s_nop 0
	v_mov_b32_e32 v73, v245
	s_nop 0
	v_mov_b32_e32 v74, v246
	s_nop 0
	v_mov_b32_e32 v75, v247
	ds_read_b128 v[244:247], v70 offset:4352
	v_pk_mul_f32 v[14:15], v[14:15], v[72:73]
	v_pk_mul_f32 v[18:19], v[18:19], v[72:73]
	v_pk_mul_f32 v[16:17], v[16:17], v[74:75]
	v_pk_mul_f32 v[20:21], v[20:21], v[74:75]
	s_nop 0
	s_nop 0
	s_waitcnt lgkmcnt(1)
	v_mov_b32_e32 v72, v236
	s_nop 0
	v_mov_b32_e32 v73, v237
	s_nop 0
	v_mov_b32_e32 v74, v238
	s_nop 0
	v_mov_b32_e32 v75, v239
	ds_read_b128 v[236:239], v70 offset:4416
	v_pk_mul_f32 v[38:39], v[38:39], v[72:73]
	v_pk_mul_f32 v[42:43], v[42:43], v[72:73]
	v_pk_mul_f32 v[40:41], v[40:41], v[74:75]
	v_pk_mul_f32 v[44:45], v[44:45], v[74:75]
	s_nop 0
	s_nop 0
	s_waitcnt lgkmcnt(1)
	v_mov_b32_e32 v72, v244
	s_nop 0
	v_mov_b32_e32 v73, v245
	s_nop 0
	v_mov_b32_e32 v74, v246
	s_nop 0
	v_mov_b32_e32 v75, v247
	ds_read_b128 v[244:247], v70 offset:4480
	v_pk_mul_f32 v[30:31], v[30:31], v[72:73]
	v_pk_mul_f32 v[34:35], v[34:35], v[72:73]
	v_pk_mul_f32 v[32:33], v[32:33], v[74:75]
	v_pk_mul_f32 v[36:37], v[36:37], v[74:75]
	s_nop 0
	s_nop 0
	s_waitcnt lgkmcnt(1)
	v_mov_b32_e32 v72, v236
	s_nop 0
	v_mov_b32_e32 v73, v237
	s_nop 0
	v_mov_b32_e32 v74, v238
	s_nop 0
	v_mov_b32_e32 v75, v239
	v_pk_mul_f32 v[46:47], v[46:47], v[72:73]
	v_pk_mul_f32 v[54:55], v[54:55], v[72:73]
	v_pk_mul_f32 v[48:49], v[48:49], v[74:75]
	v_pk_mul_f32 v[56:57], v[56:57], v[74:75]
	s_nop 0
	s_nop 0
	s_waitcnt lgkmcnt(0)
	v_mov_b32_e32 v72, v244
	s_nop 0
	v_mov_b32_e32 v73, v245
	s_nop 0
	v_mov_b32_e32 v74, v246
	s_nop 0
	v_mov_b32_e32 v75, v247
	v_pk_mul_f32 v[50:51], v[50:51], v[72:73]
	v_pk_mul_f32 v[58:59], v[58:59], v[72:73]
	ds_read_b128 v[70:73], v70 offset:4544
	v_pk_mul_f32 v[52:53], v[52:53], v[74:75]
	v_pk_mul_f32 v[60:61], v[60:61], v[74:75]
	s_nop 0
	s_nop 0
	s_nop 0
	s_nop 0
	s_nop 0
	s_nop 0
	s_nop 0
	s_nop 0
	s_waitcnt lgkmcnt(0)
	v_pk_mul_f32 v[62:63], v[62:63], v[70:71]
	v_pk_mul_f32 v[66:67], v[66:67], v[70:71]
	v_pk_mul_f32 v[64:65], v[64:65], v[72:73]
	v_pk_mul_f32 v[68:69], v[68:69], v[72:73]
	s_waitcnt lgkmcnt(0)
	s_cbranch_scc0 .LBB0_2275
.LBB0_2267:
	s_add_u32 s62, s92, s74
	s_addc_u32 s63, s94, s75
	s_add_u32 s49, s53, s74
	s_addc_u32 s61, s55, s75
	v_lshl_add_u64 v[70:71], s[62:63], 0, v[112:113]
	s_add_u32 s62, s49, s0
	v_add_co_u32_e32 v74, vcc, s72, v70
	s_addc_u32 s63, s61, 0
	s_nop 0
	v_addc_co_u32_e32 v75, vcc, 0, v71, vcc
	v_lshl_add_u64 v[86:87], s[62:63], 0, v[114:115]
	v_add_co_u32_e32 v78, vcc, s81, v86
	s_and_b32 s49, s95, 1
	s_add_i32 s89, s1, 0xf0
	v_addc_co_u32_e32 v79, vcc, 0, v87, vcc
	s_cmp_eq_u32 s49, 0
	v_add_co_u32_e32 v82, vcc, s72, v86
	s_cselect_b64 s[76:77], -1, 0
	s_nop 0
	v_addc_co_u32_e32 v83, vcc, 0, v87, vcc
	s_and_b64 s[62:63], s[76:77], exec
	global_load_dwordx4 v[94:97], v[70:71], off
	global_load_dwordx4 v[98:101], v[70:71], off offset:1024
	s_nop 0
	global_load_dwordx4 v[70:73], v[74:75], off
	global_load_dwordx4 v[90:93], v[74:75], off offset:1024
	s_cselect_b32 s61, 0xf0, s89
	global_load_dwordx4 v[74:77], v[86:87], off
	v_add_co_u32_e32 v86, vcc, s73, v86
	v_and_b32_e32 v137, 63, v154
	v_lshl_add_u32 v137, v137, 2, s61
	s_nop 0
	v_addc_co_u32_e32 v87, vcc, 0, v87, vcc
	global_load_dwordx4 v[78:81], v[78:79], off
	s_nop 0
	global_load_dwordx4 v[82:85], v[82:83], off
	s_nop 0
	global_load_dwordx4 v[86:89], v[86:87], off
	s_waitcnt lgkmcnt(0)
	ds_read2st64_b32 v[108:109], v137 offset1:1
	ds_read2st64_b32 v[236:237], v137 offset0:2 offset1:3
	ds_read2st64_b32 v[146:147], v137 offset0:8 offset1:9
	ds_read2st64_b32 v[244:245], v137 offset0:4 offset1:5
	s_waitcnt lgkmcnt(3)
	v_mfma_f32_16x16x4_f32 v[138:141], v108, v102, 0
	s_nop 0
	v_mfma_f32_16x16x4_f32 v[138:141], v109, v103, v[138:141]
	s_waitcnt lgkmcnt(2)
	v_mfma_f32_16x16x4_f32 v[138:141], v236, v104, v[138:141]
	v_mfma_f32_16x16x4_f32 v[138:141], v237, v105, v[138:141]
	ds_read2st64_b32 v[236:237], v137 offset0:6 offset1:7
	s_nop 0
	s_nop 8
	v_add_f32_e32 v108, v106, v138
	v_min_f32_e32 v107, 0, v108
	v_mul_f32_e64 v108, |v108|, s66
	v_exp_f32_e32 v108, v108
	v_add_f32_e32 v109, v106, v139
	v_add_f32_e32 v135, v106, v140
	v_add_f32_e32 v138, v106, v141
	v_add_f32_e32 v108, 1.0, v108
	v_log_f32_e32 v108, v108
	s_nop 0
	v_fmac_f32_e32 v107, 0xbf317218, v108
	v_min_f32_e32 v108, 0, v109
	v_mul_f32_e64 v109, |v109|, s66
	v_exp_f32_e32 v109, v109
	v_fma_f32 v107, v107, s67, 0
	v_add_f32_e32 v109, 1.0, v109
	v_log_f32_e32 v109, v109
	s_nop 0
	v_fmac_f32_e32 v108, 0xbf317218, v109
	v_min_f32_e32 v109, 0, v135
	v_mul_f32_e64 v135, |v135|, s66
	v_exp_f32_e32 v135, v135
	v_fmamk_f32 v108, v108, 0x3d800000, v107
	v_add_f32_e32 v135, 1.0, v135
	v_log_f32_e32 v135, v135
	s_nop 0
	v_fmac_f32_e32 v109, 0xbf317218, v135
	v_min_f32_e32 v135, 0, v138
	v_mul_f32_e64 v138, |v138|, s66
	v_exp_f32_e32 v138, v138
	v_fmamk_f32 v109, v109, 0x3d800000, v108
	v_add_f32_e32 v138, 1.0, v138
	v_log_f32_e32 v138, v138
	s_nop 0
	v_fmac_f32_e32 v135, 0xbf317218, v138
	s_waitcnt lgkmcnt(1)
	v_mfma_f32_16x16x4_f32 v[138:141], v244, v102, 0
	v_fmamk_f32 v135, v135, 0x3d800000, v109
	v_mfma_f32_16x16x4_f32 v[138:141], v245, v103, v[138:141]
	ds_read2st64_b32 v[244:245], v137 offset0:10 offset1:11
	s_nop 0
	s_waitcnt lgkmcnt(1)
	v_mfma_f32_16x16x4_f32 v[138:141], v236, v104, v[138:141]
	v_mfma_f32_16x16x4_f32 v[138:141], v237, v105, v[138:141]
	ds_read2st64_b32 v[236:237], v137 offset0:12 offset1:13
	s_nop 9
	v_add_f32_e32 v142, v106, v138
	v_min_f32_e32 v138, 0, v142
	v_mul_f32_e64 v142, |v142|, s66
	v_exp_f32_e32 v142, v142
	s_nop 0
	v_add_f32_e32 v142, 1.0, v142
	v_log_f32_e32 v142, v142
	s_nop 0
	v_fmac_f32_e32 v138, 0xbf317218, v142
	v_add_f32_e32 v142, v106, v139
	v_min_f32_e32 v139, 0, v142
	v_mul_f32_e64 v142, |v142|, s66
	v_exp_f32_e32 v142, v142
	s_nop 0
	v_add_f32_e32 v142, 1.0, v142
	v_log_f32_e32 v142, v142
	s_nop 0
	v_fmac_f32_e32 v139, 0xbf317218, v142
	v_add_f32_e32 v142, v106, v140
	v_min_f32_e32 v140, 0, v142
	v_mul_f32_e64 v142, |v142|, s66
	v_exp_f32_e32 v142, v142
	s_nop 0
	v_add_f32_e32 v142, 1.0, v142
	v_log_f32_e32 v142, v142
	s_nop 0
	v_fmac_f32_e32 v140, 0xbf317218, v142
	v_add_f32_e32 v142, v106, v141
	v_min_f32_e32 v141, 0, v142
	v_mul_f32_e64 v142, |v142|, s66
	v_exp_f32_e32 v142, v142
	s_nop 0
	v_add_f32_e32 v142, 1.0, v142
	v_log_f32_e32 v142, v142
	s_nop 0
	v_fmac_f32_e32 v141, 0xbf317218, v142
	v_mfma_f32_16x16x4_f32 v[142:145], v146, v102, 0
	v_mfma_f32_16x16x4_f32 v[142:145], v147, v103, v[142:145]
	s_nop 0
	s_waitcnt lgkmcnt(1)
	v_mfma_f32_16x16x4_f32 v[142:145], v244, v104, v[142:145]
	v_mfma_f32_16x16x4_f32 v[142:145], v245, v105, v[142:145]
	ds_read2st64_b32 v[244:245], v137 offset0:14 offset1:15
	s_nop 0
	s_nop 8
	v_add_f32_e32 v142, v106, v142
	v_min_f32_e32 v148, 0, v142
	v_mul_f32_e64 v142, |v142|, s66
	v_exp_f32_e32 v142, v142
	s_nop 0
	v_add_f32_e32 v142, 1.0, v142
	v_log_f32_e32 v142, v142
	s_nop 0
	v_fmac_f32_e32 v148, 0xbf317218, v142
	v_add_f32_e32 v142, v106, v143
	v_min_f32_e32 v149, 0, v142
	v_mul_f32_e64 v142, |v142|, s66
	v_exp_f32_e32 v142, v142
	s_nop 0
	v_add_f32_e32 v142, 1.0, v142
	v_log_f32_e32 v142, v142
	s_nop 0
	v_fmac_f32_e32 v149, 0xbf317218, v142
	v_add_f32_e32 v142, v106, v144
	v_min_f32_e32 v150, 0, v142
	v_mul_f32_e64 v142, |v142|, s66
	v_exp_f32_e32 v142, v142
	s_nop 0
	v_add_f32_e32 v142, 1.0, v142
	v_log_f32_e32 v142, v142
	s_nop 0
	v_fmac_f32_e32 v150, 0xbf317218, v142
	v_add_f32_e32 v142, v106, v145
	v_min_f32_e32 v151, 0, v142
	v_mul_f32_e64 v142, |v142|, s66
	v_exp_f32_e32 v142, v142
	s_nop 0
	v_add_f32_e32 v142, 1.0, v142
	v_log_f32_e32 v142, v142
	s_nop 0
	v_fmac_f32_e32 v151, 0xbf317218, v142
	s_waitcnt lgkmcnt(1)
	v_mfma_f32_16x16x4_f32 v[142:145], v236, v102, 0
	v_mfma_f32_16x16x4_f32 v[142:145], v237, v103, v[142:145]
	s_nop 0
	s_waitcnt lgkmcnt(0)
	v_mfma_f32_16x16x4_f32 v[142:145], v244, v104, v[142:145]
	v_mfma_f32_16x16x4_f32 v[142:145], v245, v105, v[142:145]
	s_nop 9
	v_add_f32_e32 v137, v106, v142
	v_min_f32_e32 v142, 0, v137
	v_mul_f32_e64 v137, |v137|, s66
	v_exp_f32_e32 v137, v137
	s_nop 0
	v_add_f32_e32 v137, 1.0, v137
	v_log_f32_e32 v137, v137
	s_nop 0
	v_fmac_f32_e32 v142, 0xbf317218, v137
	v_add_f32_e32 v137, v106, v143
	v_min_f32_e32 v143, 0, v137
	v_mul_f32_e64 v137, |v137|, s66
	v_exp_f32_e32 v137, v137
	s_nop 0
	v_add_f32_e32 v137, 1.0, v137
	v_log_f32_e32 v137, v137
	s_nop 0
	v_fmac_f32_e32 v143, 0xbf317218, v137
	v_add_f32_e32 v137, v106, v144
	v_min_f32_e32 v144, 0, v137
	v_mul_f32_e64 v137, |v137|, s66
	v_exp_f32_e32 v137, v137
	s_nop 0
	v_add_f32_e32 v137, 1.0, v137
	v_log_f32_e32 v137, v137
	s_nop 0
	v_fmac_f32_e32 v144, 0xbf317218, v137
	v_add_f32_e32 v137, v106, v145
	v_min_f32_e32 v145, 0, v137
	v_mul_f32_e64 v137, |v137|, s66
	v_exp_f32_e32 v137, v137
	s_nop 0
	v_add_f32_e32 v137, 1.0, v137
	v_log_f32_e32 v137, v137
	s_nop 0
	v_fmac_f32_e32 v145, 0xbf317218, v137
	v_fmamk_f32 v137, v138, 0x3d800000, v135
	v_fmamk_f32 v138, v139, 0x3d800000, v137
	v_fmamk_f32 v139, v140, 0x3d800000, v138
	v_fmamk_f32 v140, v141, 0x3d800000, v139
	v_fmamk_f32 v141, v148, 0x3d800000, v140
	v_fmamk_f32 v146, v149, 0x3d800000, v141
	v_fmamk_f32 v147, v150, 0x3d800000, v146
	v_fmamk_f32 v148, v151, 0x3d800000, v147
	v_fmamk_f32 v142, v142, 0x3d800000, v148
	v_fmamk_f32 v143, v143, 0x3d800000, v142
	v_fmamk_f32 v144, v144, 0x3d800000, v143
	v_fmamk_f32 v145, v145, 0x3d800000, v144
	ds_bpermute_b32 v149, v190, v145
	ds_bpermute_b32 v150, v191, v145
	ds_bpermute_b32 v151, v192, v145
	s_waitcnt lgkmcnt(2)
	v_cndmask_b32_e64 v149, v149, 0, s[4:5]
	s_waitcnt lgkmcnt(1)
	v_cndmask_b32_e64 v150, 0, v150, s[6:7]
	v_add_f32_e32 v149, v149, v150
	s_waitcnt lgkmcnt(0)
	v_cndmask_b32_e64 v150, 0, v151, s[8:9]
	v_add_f32_e32 v149, v149, v150
	v_add_f32_e32 v107, v107, v149
	v_add_f32_e32 v108, v108, v149
	ds_write2st64_b32 v204, v107, v108 offset0:24 offset1:26
	v_add_f32_e32 v107, v109, v149
	v_add_f32_e32 v108, v135, v149
	ds_write2st64_b32 v204, v107, v108 offset0:28 offset1:30
	v_add_f32_e32 v107, v137, v149
	v_add_f32_e32 v108, v138, v149
	ds_write2st64_b32 v204, v107, v108 offset0:32 offset1:34
	v_add_f32_e32 v107, v139, v149
	v_add_f32_e32 v108, v140, v149
	ds_write2st64_b32 v204, v107, v108 offset0:36 offset1:38
	v_add_f32_e32 v107, v141, v149
	v_add_f32_e32 v108, v146, v149
	ds_write2st64_b32 v204, v107, v108 offset0:40 offset1:42
	v_add_f32_e32 v107, v149, v147
	v_add_f32_e32 v108, v149, v148
	ds_write2st64_b32 v204, v107, v108 offset0:44 offset1:46
	v_add_f32_e32 v107, v149, v142
	v_add_f32_e32 v108, v149, v143
	ds_write2st64_b32 v204, v107, v108 offset0:48 offset1:50
	v_add_f32_e32 v107, v149, v144
	v_add_f32_e32 v108, v149, v145
	ds_write2st64_b32 v204, v107, v108 offset0:52 offset1:54
	s_waitcnt lgkmcnt(0)
	s_barrier
	s_and_saveexec_b64 s[62:63], s[10:11]
	s_cbranch_execz .LBB0_2269
	ds_read_b32 v107, v181 offset:38400
	v_lshl_add_u32 v108, s49, 9, v181
	s_waitcnt lgkmcnt(0)
	v_mul_f32_e32 v255, 0x3fb8aa3b, v107
	v_exp_f32_e32 v255, v255
	s_nop 0
	ds_write_b32 v108, v255 offset:4096

.LBB0_2282:
	s_or_b64 exec, exec, s[60:61]
	s_waitcnt lgkmcnt(0)
	s_barrier
	s_waitcnt lgkmcnt(0)
	ds_read_b128 v[140:143], v188
	ds_read_b128 v[146:149], v188 offset:16
	s_waitcnt vmcnt(8)
	v_lshlrev_b32_e32 v160, 16, v170
	v_and_b32_e32 v161, 0xffff0000, v170
	v_lshlrev_b32_e32 v170, 16, v171
	s_waitcnt lgkmcnt(1)
	v_mov_b32_e32 v81, v142
	v_lshlrev_b32_e32 v142, 16, v172
	v_mov_b32_e32 v80, v141
	v_mov_b32_e32 v141, v143
	v_and_b32_e32 v143, 0xffff0000, v172
	v_mul_f32_e32 v0, 0xbfb8aa3b, v142
	v_exp_f32_e32 v0, v0
	v_mul_f32_e32 v135, 0xbfb8aa3b, v143
	v_exp_f32_e32 v135, v135
	v_pk_add_f32 v[80:81], v[80:81], v[140:141]
	s_waitcnt lgkmcnt(0)
	v_mov_b32_e32 v140, v148
	v_mov_b32_e32 v141, v146
	v_mov_b32_e32 v146, v149
	v_add_f32_e32 v0, 1.0, v0
	v_pk_add_f32 v[150:151], v[140:141], v[146:147]
	v_rcp_f32_e32 v140, v0
	v_add_f32_e32 v0, 1.0, v135
	v_lshlrev_b32_e32 v146, 16, v173
	v_rcp_f32_e32 v141, v0
	v_and_b32_e32 v147, 0xffff0000, v173
	v_mul_f32_e32 v0, 0xbfb8aa3b, v146
	v_exp_f32_e32 v0, v0
	v_mul_f32_e32 v135, 0xbfb8aa3b, v147
	v_exp_f32_e32 v135, v135
	v_pk_mul_f32 v[152:153], v[140:141], v[142:143]
	v_add_f32_e32 v0, 1.0, v0
	v_rcp_f32_e32 v140, v0
	v_add_f32_e32 v0, 1.0, v135
	v_rcp_f32_e32 v141, v0
	v_mul_f32_e32 v0, 0xbfb8aa3b, v160
	v_exp_f32_e32 v0, v0
	v_mul_f32_e32 v135, 0xbfb8aa3b, v161
	v_exp_f32_e32 v135, v135
	v_pk_mul_f32 v[172:173], v[140:141], v[146:147]
	ds_read_b128 v[140:143], v188 offset:512
	ds_read_b128 v[146:149], v188 offset:528
	v_add_f32_e32 v0, 1.0, v0
	v_rcp_f32_e32 v228, v0
	v_add_f32_e32 v0, 1.0, v135
	v_rcp_f32_e32 v229, v0
	v_mul_f32_e32 v0, 0xbfb8aa3b, v170
	v_and_b32_e32 v171, 0xffff0000, v171
	s_waitcnt lgkmcnt(1)
	v_mov_b32_e32 v232, v141
	v_mov_b32_e32 v233, v142
	v_mov_b32_e32 v141, v143
	v_exp_f32_e32 v0, v0
	v_mul_f32_e32 v135, 0xbfb8aa3b, v171
	v_pk_add_f32 v[140:141], v[232:233], v[140:141]
	s_waitcnt lgkmcnt(0)
	v_mov_b32_e32 v142, v148
	v_mov_b32_e32 v143, v146
	v_mov_b32_e32 v146, v149
	v_exp_f32_e32 v135, v135
	v_pk_add_f32 v[142:143], v[142:143], v[146:147]
	v_mov_b32_e32 v146, v140
	v_mov_b32_e32 v147, v80
	v_mov_b32_e32 v80, v141
	v_pk_add_f32 v[80:81], v[146:147], v[80:81]
	v_mov_b32_e32 v140, v143
	v_mov_b32_e32 v141, v151
	v_pk_add_f32 v[80:81], v[80:81], v[140:141]
	v_mov_b32_e32 v143, v150
	s_mov_b32 s60, 0x358637bd
	v_add_f32_e32 v0, 1.0, v0
	v_pk_add_f32 v[140:141], v[142:143], v[80:81]
	v_mov_b64_e32 v[80:81], s[60:61]
	v_rcp_f32_e32 v230, v0
	v_add_f32_e32 v0, 1.0, v135
	v_pk_fma_f32 v[140:141], v[140:141], s[50:51], v[80:81] op_sel_hi:[1,0,0]
	v_rcp_f32_e32 v231, v0
	v_mul_f32_e32 v0, 0x4b800000, v141
	v_cmp_gt_f32_e32 vcc, s80, v141
	v_pk_mul_f32 v[146:147], v[228:229], v[160:161]
	v_pk_mul_f32 v[148:149], v[230:231], v[170:171]
	v_cndmask_b32_e32 v0, v141, v0, vcc
	v_rsq_f32_e32 v0, v0
	v_lshl_add_u64 v[142:143], s[54:55], 0, v[118:119]
	s_waitcnt vmcnt(4)
	v_lshlrev_b32_e32 v150, 16, v163
	v_and_b32_e32 v151, 0xffff0000, v163
	v_mul_f32_e32 v135, 0x45800000, v0
	v_cndmask_b32_e32 v0, v0, v135, vcc
	v_pk_mul_f32 v[106:107], v[106:107], v[0:1] op_sel_hi:[1,0]
	v_pk_mul_f32 v[108:109], v[108:109], v[0:1] op_sel_hi:[1,0]
	v_pk_mul_f32 v[102:103], v[102:103], v[0:1] op_sel_hi:[1,0]
	v_pk_mul_f32 v[104:105], v[104:105], v[0:1] op_sel_hi:[1,0]
	v_mul_f32_e32 v0, 0x4b800000, v140
	v_cmp_gt_f32_e32 vcc, s80, v140
	s_waitcnt vmcnt(0)
	v_pk_mul_f32 v[102:103], v[70:71], v[102:103]
	v_pk_mul_f32 v[104:105], v[72:73], v[104:105]
	v_cndmask_b32_e32 v0, v140, v0, vcc
	v_pk_mul_f32 v[102:103], v[146:147], v[102:103]
	v_pk_mul_f32 v[104:105], v[148:149], v[104:105]
	v_rsq_f32_e32 v0, v0
	v_cvt_pk_bf16_f32 v102, v102, v103
	v_cvt_pk_bf16_f32 v103, v104, v105
	global_store_dwordx2 v[142:143], v[102:103], off offset:32
	v_lshlrev_b32_e32 v102, 16, v168
	v_mul_f32_e32 v103, 0xbfb8aa3b, v102
	v_exp_f32_e32 v104, v103
	v_mul_f32_e32 v103, 0x45800000, v0
	v_cndmask_b32_e32 v0, v0, v103, vcc
	v_and_b32_e32 v103, 0xffff0000, v168
	v_mul_f32_e32 v105, 0xbfb8aa3b, v103
	v_exp_f32_e32 v105, v105
	v_pk_mul_f32 v[106:107], v[74:75], v[106:107]
	v_pk_mul_f32 v[108:109], v[76:77], v[108:109]
	v_pk_mul_f32 v[106:107], v[152:153], v[106:107]
	v_pk_mul_f32 v[108:109], v[172:173], v[108:109]
	v_cvt_pk_bf16_f32 v106, v106, v107
	v_cvt_pk_bf16_f32 v107, v108, v109
	v_lshlrev_b32_e32 v108, 16, v169
	v_and_b32_e32 v109, 0xffff0000, v169
	v_add_f32_e32 v104, 1.0, v104
	v_add_f32_e32 v105, 1.0, v105
	v_mul_f32_e32 v135, 0xbfb8aa3b, v108
	v_mul_f32_e32 v137, 0xbfb8aa3b, v109
	v_rcp_f32_e32 v104, v104
	v_rcp_f32_e32 v105, v105
	v_exp_f32_e32 v135, v135
	v_exp_f32_e32 v137, v137
	global_store_dwordx2 v[142:143], v[106:107], off
	v_pk_mul_f32 v[102:103], v[104:105], v[102:103]
	v_add_f32_e32 v104, 1.0, v135
	v_add_f32_e32 v105, 1.0, v137
	v_rcp_f32_e32 v104, v104
	v_rcp_f32_e32 v105, v105
	v_pk_mul_f32 v[106:107], v[158:159], v[0:1] op_sel_hi:[1,0]
	v_pk_mul_f32 v[100:101], v[100:101], v[0:1] op_sel_hi:[1,0]
	v_pk_mul_f32 v[106:107], v[74:75], v[106:107]
	v_pk_mul_f32 v[100:101], v[76:77], v[100:101]
	v_pk_mul_f32 v[104:105], v[104:105], v[108:109]
	v_pk_mul_f32 v[102:103], v[102:103], v[106:107]
	v_pk_mul_f32 v[100:101], v[104:105], v[100:101]
	v_cvt_pk_bf16_f32 v102, v102, v103
	v_cvt_pk_bf16_f32 v103, v100, v101
	v_lshlrev_b32_e32 v100, 16, v166
	v_mul_f32_e32 v101, 0xbfb8aa3b, v100
	v_exp_f32_e32 v106, v101
	v_lshl_add_u64 v[104:105], s[54:55], 0, v[122:123]
	v_and_b32_e32 v101, 0xffff0000, v166
	global_store_dwordx2 v[104:105], v[102:103], off
	v_mul_f32_e32 v103, 0xbfb8aa3b, v101
	v_exp_f32_e32 v103, v103
	v_lshlrev_b32_e32 v104, 16, v167
	v_and_b32_e32 v105, 0xffff0000, v167
	v_add_f32_e32 v102, 1.0, v106
	v_add_f32_e32 v103, 1.0, v103
	v_mul_f32_e32 v106, 0xbfb8aa3b, v104
	v_mul_f32_e32 v107, 0xbfb8aa3b, v105
	v_rcp_f32_e32 v102, v102
	v_rcp_f32_e32 v103, v103
	v_exp_f32_e32 v106, v106
	v_exp_f32_e32 v107, v107
	v_pk_mul_f32 v[98:99], v[98:99], v[0:1] op_sel_hi:[1,0]
	v_pk_mul_f32 v[100:101], v[102:103], v[100:101]
	v_add_f32_e32 v102, 1.0, v106
	v_add_f32_e32 v103, 1.0, v107
	v_rcp_f32_e32 v102, v102
	v_rcp_f32_e32 v103, v103
	v_pk_mul_f32 v[98:99], v[70:71], v[98:99]
	v_pk_mul_f32 v[96:97], v[96:97], v[0:1] op_sel_hi:[1,0]
	v_pk_mul_f32 v[98:99], v[100:101], v[98:99]
	v_pk_mul_f32 v[96:97], v[72:73], v[96:97]
	v_pk_mul_f32 v[100:101], v[102:103], v[104:105]
	v_cvt_pk_bf16_f32 v102, v98, v99
	v_pk_mul_f32 v[100:101], v[100:101], v[96:97]
	ds_read_b128 v[96:99], v188 offset:1024
	v_cvt_pk_bf16_f32 v103, v100, v101
	v_lshl_add_u64 v[100:101], s[54:55], 0, v[124:125]
	global_store_dwordx2 v[100:101], v[102:103], off
	ds_read_b128 v[100:103], v188 offset:1040
	s_waitcnt lgkmcnt(1)
	v_mov_b32_e32 v105, v98
	v_lshlrev_b32_e32 v98, 16, v164
	v_mov_b32_e32 v104, v97
	v_mov_b32_e32 v97, v99
	v_and_b32_e32 v99, 0xffff0000, v164
	v_mul_f32_e32 v0, 0xbfb8aa3b, v98
	v_pk_add_f32 v[104:105], v[104:105], v[96:97]
	v_exp_f32_e32 v0, v0
	v_mul_f32_e32 v97, 0xbfb8aa3b, v99
	s_waitcnt lgkmcnt(0)
	v_mov_b32_e32 v96, v102
	v_exp_f32_e32 v102, v97
	v_lshlrev_b32_e32 v108, 16, v165
	v_mov_b32_e32 v97, v100
	v_add_f32_e32 v0, 1.0, v0
	v_and_b32_e32 v109, 0xffff0000, v165
	v_mul_f32_e32 v100, 0xbfb8aa3b, v108
	v_rcp_f32_e32 v106, v0
	v_add_f32_e32 v0, 1.0, v102
	v_exp_f32_e32 v100, v100
	v_mul_f32_e32 v102, 0xbfb8aa3b, v109
	v_exp_f32_e32 v102, v102
	v_rcp_f32_e32 v107, v0
	v_add_f32_e32 v0, 1.0, v100
	v_rcp_f32_e32 v140, v0
	v_add_f32_e32 v0, 1.0, v102
	v_rcp_f32_e32 v141, v0
	v_mov_b32_e32 v100, v103
	v_pk_add_f32 v[142:143], v[96:97], v[100:101]
	v_pk_mul_f32 v[106:107], v[106:107], v[98:99]
	v_pk_mul_f32 v[108:109], v[140:141], v[108:109]
	v_lshlrev_b32_e32 v140, 16, v162
	v_and_b32_e32 v141, 0xffff0000, v162
	v_mul_f32_e32 v0, 0xbfb8aa3b, v140
	v_exp_f32_e32 v0, v0
	v_mul_f32_e32 v96, 0xbfb8aa3b, v141
	v_exp_f32_e32 v96, v96
	v_lshl_add_u64 v[146:147], s[54:55], 0, v[126:127]
	v_add_f32_e32 v0, 1.0, v0
	v_rcp_f32_e32 v148, v0
	v_add_f32_e32 v0, 1.0, v96
	v_rcp_f32_e32 v149, v0
	v_mul_f32_e32 v0, 0xbfb8aa3b, v150
	v_exp_f32_e32 v0, v0
	v_mul_f32_e32 v96, 0xbfb8aa3b, v151
	v_exp_f32_e32 v100, v96
	ds_read_b128 v[96:99], v188 offset:1536
	v_add_f32_e32 v0, 1.0, v0
	v_rcp_f32_e32 v152, v0
	v_add_f32_e32 v0, 1.0, v100
	ds_read_b128 v[100:103], v188 offset:1552
	ds_read_b64_tr_b16 v[238:239], v217 offset:57408
	ds_read_b64_tr_b16 v[236:237], v217 offset:56320
	s_waitcnt lgkmcnt(3)
	v_mov_b32_e32 v158, v97
	v_mov_b32_e32 v159, v98
	v_mov_b32_e32 v97, v99
	v_pk_add_f32 v[96:97], v[158:159], v[96:97]
	s_waitcnt lgkmcnt(2)
	v_mov_b32_e32 v98, v102
	v_mov_b32_e32 v99, v100
	v_mov_b32_e32 v100, v103
	v_pk_add_f32 v[98:99], v[98:99], v[100:101]
	v_mov_b32_e32 v100, v96
	v_mov_b32_e32 v101, v104
	v_mov_b32_e32 v104, v97
	v_pk_add_f32 v[96:97], v[100:101], v[104:105]
	v_mov_b32_e32 v100, v99
	v_mov_b32_e32 v101, v143
	v_pk_add_f32 v[96:97], v[96:97], v[100:101]
	v_mov_b32_e32 v99, v142
	v_pk_add_f32 v[96:97], v[98:99], v[96:97]
	v_rcp_f32_e32 v153, v0
	v_pk_fma_f32 v[80:81], v[96:97], s[50:51], v[80:81] op_sel_hi:[1,0,0]
	v_pk_mul_f32 v[96:97], v[148:149], v[140:141]
	v_mul_f32_e32 v0, 0x4b800000, v81
	v_cmp_gt_f32_e32 vcc, s80, v81
	v_pk_mul_f32 v[170:171], v[152:153], v[150:151]
	v_lshl_add_u64 v[172:173], s[54:55], 0, v[128:129]
	v_cndmask_b32_e32 v0, v81, v0, vcc
	v_rsq_f32_e32 v0, v0
	s_add_i32 s74, s74, 1
	s_add_u32 s58, s58, 0xfffa0000
	s_addc_u32 s59, s59, -1
	v_mul_f32_e32 v81, 0x45800000, v0
	v_cndmask_b32_e32 v0, v0, v81, vcc
	v_pk_mul_f32 v[90:91], v[90:91], v[0:1] op_sel_hi:[1,0]
	v_pk_mul_f32 v[94:95], v[94:95], v[0:1] op_sel_hi:[1,0]
	v_pk_mul_f32 v[90:91], v[74:75], v[90:91]
	v_pk_mul_f32 v[94:95], v[76:77], v[94:95]
	v_pk_mul_f32 v[90:91], v[106:107], v[90:91]
	v_pk_mul_f32 v[94:95], v[108:109], v[94:95]
	v_cvt_pk_bf16_f32 v90, v90, v91
	v_cvt_pk_bf16_f32 v91, v94, v95
	ds_read_b64_tr_b16 v[94:95], v214 offset:2112
	global_store_dwordx2 v[146:147], v[90:91], off
	v_pk_mul_f32 v[90:91], v[92:93], v[0:1] op_sel_hi:[1,0]
	ds_read_b64_tr_b16 v[92:93], v214
	ds_read_b64_tr_b16 v[98:99], v214 offset:2144
	v_pk_mul_f32 v[88:89], v[88:89], v[0:1] op_sel_hi:[1,0]
	v_mul_f32_e32 v0, 0x4b800000, v80
	v_cmp_gt_f32_e32 vcc, s80, v80
	v_pk_mul_f32 v[90:91], v[70:71], v[90:91]
	v_pk_mul_f32 v[228:229], v[72:73], v[88:89]
	v_cndmask_b32_e32 v0, v80, v0, vcc
	v_pk_mul_f32 v[108:109], v[96:97], v[90:91]
	ds_read_b64_tr_b16 v[96:97], v214 offset:32
	ds_read_b64_tr_b16 v[100:101], v217 offset:56352
	ds_read_b64_tr_b16 v[104:105], v217 offset:56384
	ds_read_b64_tr_b16 v[140:141], v217 offset:56416
	ds_read_b64_tr_b16 v[102:103], v217 offset:57440
	ds_read_b64_tr_b16 v[106:107], v217 offset:57472
	ds_read_b64_tr_b16 v[142:143], v217 offset:57504
	ds_read_b64_tr_b16 v[146:147], v217 offset:65024
	ds_read_b64_tr_b16 v[148:149], v218 offset:57408
	ds_read_b64_tr_b16 v[150:151], v214 offset:16896
	ds_read_b64_tr_b16 v[152:153], v214 offset:19008
	ds_read_b64_tr_b16 v[160:161], v214 offset:19040
	ds_read_b64_tr_b16 v[158:159], v214 offset:16928
	ds_read_b64_tr_b16 v[244:245], v217 offset:65056
	ds_read_b64_tr_b16 v[162:163], v217 offset:65088
	ds_read_b64_tr_b16 v[166:167], v217 offset:65120
	ds_read_b64_tr_b16 v[246:247], v218 offset:57440
	ds_read_b64_tr_b16 v[164:165], v218 offset:57472
	ds_read_b64_tr_b16 v[168:169], v218 offset:57504
	s_nop 0
	s_nop 0
	s_nop 0
	s_nop 0
	s_nop 0
	s_nop 0
	s_nop 0
	s_nop 0
	s_nop 0
	s_nop 0
	s_nop 0
	s_nop 0
	v_rsq_f32_e32 v0, v0
	s_nop 0
	s_nop 0
	s_nop 0
	s_nop 0
	s_nop 0
	s_nop 0
	s_waitcnt lgkmcnt(14)
	v_mfma_f32_16x16x32_bf16 v[10:13], v[100:103], v[92:95], v[10:13]
	v_and_b32_e32 v81, 0xffff0000, v156
	v_mul_f32_e32 v80, 0x45800000, v0
	v_cndmask_b32_e32 v0, v0, v80, vcc
	v_mfma_f32_16x16x32_bf16 v[18:21], v[100:103], v[96:99], v[18:21]
	v_lshlrev_b32_e32 v80, 16, v156
	v_mul_f32_e32 v100, 0xbfb8aa3b, v80
	v_mul_f32_e32 v101, 0xbfb8aa3b, v81
	v_mfma_f32_16x16x32_bf16 v[30:33], v[236:239], v[92:95], v[30:33]
	v_exp_f32_e32 v100, v100
	v_pk_mul_f32 v[86:87], v[86:87], v[0:1] op_sel_hi:[1,0]
	v_pk_mul_f32 v[170:171], v[170:171], v[228:229]
	v_mfma_f32_16x16x32_bf16 v[6:9], v[236:239], v[96:99], v[6:9]
	ds_read_b64_tr_b16 v[236:237], v217 offset:56448
	ds_read_b64_tr_b16 v[238:239], v217 offset:57536
	s_nop 0
	s_nop 0
	s_nop 0
	s_nop 0
	s_nop 0
	s_nop 0
	v_pk_mul_f32 v[74:75], v[74:75], v[86:87]
	v_lshlrev_b32_e32 v86, 16, v157
	s_waitcnt lgkmcnt(4)
	v_mfma_f32_16x16x32_bf16 v[10:13], v[244:247], v[150:153], v[10:13]
	v_mul_f32_e32 v87, 0xbfb8aa3b, v86
	v_cvt_pk_bf16_f32 v108, v108, v109
	v_cvt_pk_bf16_f32 v109, v170, v171
	v_mfma_f32_16x16x32_bf16 v[18:21], v[244:247], v[158:161], v[18:21]
	v_exp_f32_e32 v89, v101
	v_add_f32_e32 v88, 1.0, v100
	v_rcp_f32_e32 v88, v88
	global_store_dwordx2 v[172:173], v[108:109], off
	v_add_f32_e32 v89, 1.0, v89
	v_rcp_f32_e32 v89, v89
	v_mfma_f32_16x16x32_bf16 v[14:17], v[104:107], v[92:95], v[14:17]
	v_mul_f32_e64 v82, v82, v0
	v_mul_f32_e64 v83, v83, v0
	v_pk_mul_f32 v[78:79], v[78:79], v[0:1] op_sel_hi:[1,0]
	v_pk_mul_f32 v[80:81], v[88:89], v[80:81]
	v_exp_f32_e32 v88, v87
	v_pk_mul_f32 v[80:81], v[80:81], v[74:75]
	v_and_b32_e32 v87, 0xffff0000, v157
	v_mfma_f32_16x16x32_bf16 v[26:29], v[104:107], v[96:99], v[26:29]
	v_add_f32_e32 v74, 1.0, v88
	v_rcp_f32_e32 v88, v74
	v_mul_f32_e32 v74, 0xbfb8aa3b, v87
	v_exp_f32_e32 v89, v74
	v_pk_mul_f32 v[74:75], v[84:85], v[0:1] op_sel_hi:[1,0]
	ds_read_b64_tr_b16 v[84:85], v217 offset:56480
	v_mfma_f32_16x16x32_bf16 v[38:41], v[140:143], v[92:95], v[38:41]
	v_mul_f32_e64 v108, v76, v74
	v_mul_f32_e64 v109, v77, v75
	v_add_f32_e32 v74, 1.0, v89
	v_rcp_f32_e32 v89, v74
	s_nop 0
	s_nop 0
	v_mfma_f32_16x16x32_bf16 v[50:53], v[140:143], v[96:99], v[50:53]
	v_cvt_pk_bf16_f32 v80, v80, v81
	v_pk_mul_f32 v[140:141], v[88:89], v[86:87]
	ds_read_b64_tr_b16 v[88:89], v217 offset:56512
	ds_read_b64_tr_b16 v[100:101], v217 offset:56544
	ds_read_b64_tr_b16 v[86:87], v217 offset:57568
	ds_read_b64_tr_b16 v[90:91], v217 offset:57600
	ds_read_b64_tr_b16 v[102:103], v217 offset:57632
	ds_read_b64_tr_b16 v[104:105], v217 offset:65152
	ds_read_b64_tr_b16 v[106:107], v218 offset:57536
	ds_read_b64_tr_b16 v[244:245], v217 offset:65184
	s_nop 0
	s_nop 0
	s_nop 0
	s_nop 0
	s_nop 0
	s_nop 0
	s_nop 0
	s_nop 0
	s_waitcnt lgkmcnt(9)
	v_mfma_f32_16x16x32_bf16 v[22:25], v[236:239], v[92:95], v[22:25]
	v_mul_f32_e64 v108, v140, v108
	v_mul_f32_e64 v109, v141, v109
	ds_read_b64_tr_b16 v[140:141], v217 offset:65216
	v_pk_mul_f32 v[70:71], v[70:71], v[82:83]
	v_cvt_pk_bf16_f32 v81, v108, v109
	v_mfma_f32_16x16x32_bf16 v[34:37], v[236:239], v[96:99], v[34:37]
	v_lshl_add_u64 v[108:109], s[54:55], 0, v[130:131]
	v_pk_mul_f32 v[72:73], v[72:73], v[78:79]
	v_lshl_add_u32 v0, s68, 9, v182
	v_mfma_f32_16x16x32_bf16 v[30:33], v[146:149], v[150:153], v[30:33]
	s_sub_i32 s52, s52, 64
	v_mfma_f32_16x16x32_bf16 v[6:9], v[146:149], v[158:161], v[6:9]
	ds_read_b64_tr_b16 v[146:147], v217 offset:65248
	ds_read_b64_tr_b16 v[246:247], v218 offset:57568
	ds_read_b64_tr_b16 v[142:143], v218 offset:57600
	ds_read_b64_tr_b16 v[148:149], v218 offset:57632
	ds_read_b128 v[236:239], v0 offset:4096
	s_nop 0
	s_nop 0
	s_nop 0
	s_nop 0
	s_nop 0
	s_nop 0
	global_store_dwordx2 v[108:109], v[80:81], off
	v_lshlrev_b32_e32 v80, 16, v144
	v_and_b32_e32 v81, 0xffff0000, v144
	s_waitcnt lgkmcnt(7)
	v_mfma_f32_16x16x32_bf16 v[22:25], v[104:107], v[150:153], v[22:25]
	v_mfma_f32_16x16x32_bf16 v[34:37], v[104:107], v[158:161], v[34:37]
	v_mul_f32_e32 v104, 0xbfb8aa3b, v80
	v_mul_f32_e32 v105, 0xbfb8aa3b, v81
	v_exp_f32_e32 v104, v104
	v_mfma_f32_16x16x32_bf16 v[42:45], v[84:87], v[92:95], v[42:45]
	v_mfma_f32_16x16x32_bf16 v[54:57], v[84:87], v[96:99], v[54:57]
	v_exp_f32_e32 v85, v105
	v_add_f32_e32 v84, 1.0, v104
	v_rcp_f32_e32 v84, v84
	s_waitcnt lgkmcnt(3)
	v_mfma_f32_16x16x32_bf16 v[42:45], v[244:247], v[150:153], v[42:45]
	v_add_f32_e32 v85, 1.0, v85
	v_rcp_f32_e32 v85, v85
	v_mfma_f32_16x16x32_bf16 v[54:57], v[244:247], v[158:161], v[54:57]
	ds_read_b128 v[244:247], v0 offset:4160
	v_mul_f32_e64 v74, v84, v80
	v_mul_f32_e64 v75, v85, v81
	v_pk_mul_f32 v[70:71], v[74:75], v[70:71]
	v_lshlrev_b32_e32 v74, 16, v145
	v_and_b32_e32 v75, 0xffff0000, v145
	v_mul_f32_e32 v76, 0xbfb8aa3b, v74
	v_mul_f32_e32 v77, 0xbfb8aa3b, v75
	v_exp_f32_e32 v76, v76
	v_exp_f32_e32 v77, v77
	v_cvt_pk_bf16_f32 v78, v70, v71
	v_lshl_add_u64 v[80:81], s[54:55], 0, v[132:133]
	v_add_f32_e32 v76, 1.0, v76
	v_add_f32_e32 v77, 1.0, v77
	v_rcp_f32_e32 v76, v76
	v_rcp_f32_e32 v77, v77
	v_mfma_f32_16x16x32_bf16 v[14:17], v[162:165], v[150:153], v[14:17]
	s_add_u32 s54, s54, 0xfffe0000
	s_addc_u32 s55, s55, -1
	v_pk_mul_f32 v[74:75], v[76:77], v[74:75]
	v_mfma_f32_16x16x32_bf16 v[26:29], v[162:165], v[158:161], v[26:29]
	v_mul_f32_e64 v74, v74, v72
	v_mul_f32_e64 v75, v75, v73
	s_nop 0
	v_cvt_pk_bf16_f32 v79, v74, v75
	s_nop 0
	global_store_dwordx2 v[80:81], v[78:79], off
	v_mfma_f32_16x16x32_bf16 v[38:41], v[166:169], v[150:153], v[38:41]
	s_nop 0
	s_waitcnt lgkmcnt(1)
	v_mov_b32_e32 v82, v236
	v_mov_b32_e32 v83, v237
	v_mov_b32_e32 v70, v238
	v_mov_b32_e32 v71, v239
	ds_read_b128 v[236:239], v0 offset:4224
	s_nop 0
	s_nop 0
	s_nop 0
	v_mfma_f32_16x16x32_bf16 v[50:53], v[166:169], v[158:161], v[50:53]
	s_add_u32 s56, s56, 0xfffe0000
	v_pk_mul_f32 v[32:33], v[32:33], v[70:71]
	v_pk_mul_f32 v[8:9], v[8:9], v[70:71]
	s_waitcnt lgkmcnt(1)
	v_mov_b32_e32 v70, v244
	v_mov_b32_e32 v71, v246
	v_mov_b32_e32 v78, v70
	v_mov_b32_e32 v70, v245
	v_mov_b32_e32 v80, v71
	s_nop 0
	v_mov_b32_e32 v81, v247
	ds_read_b128 v[244:247], v0 offset:4288
	v_mov_b32_e32 v79, v70
	s_nop 0
	s_nop 0
	v_pk_mul_f32 v[30:31], v[30:31], v[82:83]
	v_pk_mul_f32 v[6:7], v[6:7], v[82:83]
	v_pk_mul_f32 v[12:13], v[12:13], v[80:81]
	s_nop 0
	s_waitcnt lgkmcnt(1)
	v_mov_b32_e32 v82, v236
	v_mov_b32_e32 v83, v237
	v_mov_b32_e32 v70, v238
	v_mov_b32_e32 v71, v239
	ds_read_b128 v[236:239], v0 offset:4352
	s_nop 0
	s_nop 0
	v_pk_mul_f32 v[10:11], v[10:11], v[78:79]
	v_pk_mul_f32 v[20:21], v[20:21], v[80:81]
	v_pk_mul_f32 v[18:19], v[18:19], v[78:79]
	v_pk_mul_f32 v[16:17], v[16:17], v[70:71]
	v_pk_mul_f32 v[28:29], v[28:29], v[70:71]
	s_waitcnt lgkmcnt(1)
	v_mov_b32_e32 v70, v244
	v_mov_b32_e32 v71, v246
	v_mov_b32_e32 v78, v70
	v_mov_b32_e32 v70, v245
	v_mov_b32_e32 v80, v71
	s_nop 0
	v_mov_b32_e32 v81, v247
	ds_read_b128 v[244:247], v0 offset:4416
	v_mov_b32_e32 v79, v70
	s_nop 0
	s_nop 0
	s_nop 0
	v_pk_mul_f32 v[40:41], v[40:41], v[80:81]
	v_pk_mul_f32 v[38:39], v[38:39], v[78:79]
	s_nop 0
	v_pk_mul_f32 v[14:15], v[14:15], v[82:83]
	v_pk_mul_f32 v[26:27], v[26:27], v[82:83]
	s_waitcnt lgkmcnt(1)
	v_mov_b32_e32 v82, v236
	v_mov_b32_e32 v83, v237
	v_mov_b32_e32 v70, v238
	v_mov_b32_e32 v71, v239
	ds_read_b128 v[236:239], v0 offset:4480
	s_nop 0
	s_nop 0
	v_pk_mul_f32 v[52:53], v[52:53], v[80:81]
	v_pk_mul_f32 v[50:51], v[50:51], v[78:79]
	v_mfma_f32_16x16x32_bf16 v[46:49], v[88:91], v[92:95], v[46:49]
	v_mul_f32_e64 v24, v24, v70
	v_mul_f32_e64 v25, v25, v71
	v_pk_mul_f32 v[36:37], v[36:37], v[70:71]
	s_waitcnt lgkmcnt(1)
	v_mov_b32_e32 v70, v244
	v_mov_b32_e32 v71, v246
	v_mov_b32_e32 v78, v70
	v_mov_b32_e32 v70, v245
	v_mov_b32_e32 v80, v71
	s_nop 0
	v_mov_b32_e32 v81, v247
	ds_read_b128 v[244:247], v0 offset:4544
	v_mov_b32_e32 v79, v70
	s_nop 0
	s_nop 0
	v_mfma_f32_16x16x32_bf16 v[62:65], v[88:91], v[96:99], v[62:65]
	s_nop 0
	s_addc_u32 s57, s57, -1
	s_nop 0
	s_waitcnt lgkmcnt(1)
	v_mov_b32_e32 v70, v236
	v_mov_b32_e32 v0, v237
	v_mov_b32_e32 v71, v238
	v_mfma_f32_16x16x32_bf16 v[58:61], v[100:103], v[92:95], v[58:61]
	v_mov_b32_e32 v72, v71
	s_nop 0
	v_mov_b32_e32 v73, v239
	v_mfma_f32_16x16x32_bf16 v[66:69], v[100:103], v[96:99], v[66:69]
	v_mov_b32_e32 v71, v0
	s_nop 0
	s_waitcnt lgkmcnt(0)
	v_mov_b32_e32 v74, v244
	v_mov_b32_e32 v0, v245
	v_mov_b32_e32 v75, v246
	v_mov_b32_e32 v76, v75
	v_mov_b32_e32 v75, v247
	v_mfma_f32_16x16x32_bf16 v[46:49], v[140:143], v[150:153], v[46:49]
	v_mov_b32_e32 v77, v75
	v_mov_b32_e32 v75, v0
	v_pk_mul_f32 v[22:23], v[22:23], v[82:83]
	v_mfma_f32_16x16x32_bf16 v[62:65], v[140:143], v[158:161], v[62:65]
	v_mul_f32_e64 v34, v34, v82
	v_mul_f32_e64 v35, v35, v83
	v_pk_mul_f32 v[44:45], v[44:45], v[80:81]
	v_pk_mul_f32 v[42:43], v[42:43], v[78:79]
	v_mfma_f32_16x16x32_bf16 v[58:61], v[146:149], v[150:153], v[58:61]
	v_mul_f32_e64 v56, v56, v80
	v_mul_f32_e64 v57, v57, v81
	v_pk_mul_f32 v[54:55], v[54:55], v[78:79]
	v_pk_mul_f32 v[48:49], v[48:49], v[72:73]
	v_mfma_f32_16x16x32_bf16 v[66:69], v[146:149], v[158:161], v[66:69]
	v_mul_f32_e64 v46, v46, v70
	v_mul_f32_e64 v47, v47, v71
	v_pk_mul_f32 v[64:65], v[64:65], v[72:73]
	v_pk_mul_f32 v[62:63], v[62:63], v[70:71]
	v_pk_mul_f32 v[60:61], v[60:61], v[76:77]
	v_pk_mul_f32 v[58:59], v[58:59], v[74:75]
	s_nop 1
	v_pk_mul_f32 v[68:69], v[68:69], v[76:77]
	s_cmp_lg_u32 s74, 8
	v_pk_mul_f32 v[66:67], v[66:67], v[74:75]
	s_waitcnt lgkmcnt(0)
	s_cbranch_scc0 .LBB0_2257
.LBB0_2283:
	s_add_u32 s60, s70, s58
	s_addc_u32 s61, s71, s59
	s_add_u32 s49, s64, s58
	s_addc_u32 s69, s65, s59
	s_add_u32 s53, s49, s0
	v_lshl_add_u64 v[70:71], s[60:61], 0, v[112:113]
	s_addc_u32 s61, s69, 0
	s_add_u32 s60, s53, 0xafc0800
	v_add_co_u32_e32 v74, vcc, s72, v70
	s_addc_u32 s61, s61, 0
	s_nop 0
	v_addc_co_u32_e32 v75, vcc, 0, v71, vcc
	v_lshl_add_u64 v[86:87], s[60:61], 0, v[114:115]
	v_add_co_u32_e32 v78, vcc, s81, v86
	s_and_b32 s68, s74, 1
	s_nop 0
	v_addc_co_u32_e32 v79, vcc, 0, v87, vcc
	s_cmp_eq_u32 s68, 0
	v_add_co_u32_e32 v82, vcc, s72, v86
	s_cselect_b64 s[60:61], -1, 0
	s_nop 0
	v_addc_co_u32_e32 v83, vcc, 0, v87, vcc
	s_and_b64 s[62:63], s[60:61], exec
	global_load_dwordx4 v[94:97], v[70:71], off
	global_load_dwordx4 v[98:101], v[70:71], off offset:1024
	s_nop 0
	global_load_dwordx4 v[70:73], v[74:75], off
	global_load_dwordx4 v[90:93], v[74:75], off offset:1024
	s_cselect_b32 s53, 0xf0, s89
	global_load_dwordx4 v[74:77], v[86:87], off
	v_add_co_u32_e32 v86, vcc, s73, v86
	v_and_b32_e32 v105, 63, v154
	v_lshl_add_u32 v105, v105, 2, s53
	s_nop 0
	v_addc_co_u32_e32 v87, vcc, 0, v87, vcc
	global_load_dwordx4 v[78:81], v[78:79], off
	s_nop 0
	global_load_dwordx4 v[82:85], v[82:83], off
	s_nop 0
	global_load_dwordx4 v[86:89], v[86:87], off
	s_waitcnt lgkmcnt(0)
	ds_read2st64_b32 v[102:103], v105 offset1:1
	ds_read2st64_b32 v[236:237], v105 offset0:2 offset1:3
	ds_read2st64_b32 v[144:145], v105 offset0:8 offset1:9
	ds_read2st64_b32 v[244:245], v105 offset0:4 offset1:5
	s_waitcnt vmcnt(12)
	s_waitcnt lgkmcnt(3)
	v_mfma_f32_16x16x4_f32 v[106:109], v102, v223, 0
	s_nop 0
	s_waitcnt vmcnt(11)
	v_mfma_f32_16x16x4_f32 v[106:109], v103, v224, v[106:109]
	s_waitcnt vmcnt(10)
	s_waitcnt lgkmcnt(2)
	v_mfma_f32_16x16x4_f32 v[106:109], v236, v225, v[106:109]
	s_waitcnt vmcnt(9)
	v_mfma_f32_16x16x4_f32 v[106:109], v237, v226, v[106:109]
	ds_read2st64_b32 v[236:237], v105 offset0:6 offset1:7
	s_nop 0
	s_waitcnt vmcnt(8)
	s_nop 7
	v_add_f32_e32 v102, v227, v106
	v_min_f32_e32 v0, 0, v102
	v_mul_f32_e64 v102, |v102|, s66
	v_exp_f32_e32 v102, v102
	v_add_f32_e32 v103, v227, v107
	v_add_f32_e32 v104, v227, v108
	v_add_f32_e32 v106, v227, v109
	v_add_f32_e32 v102, 1.0, v102
	v_log_f32_e32 v102, v102
	s_nop 0
	v_fmac_f32_e32 v0, 0xbf317218, v102
	v_min_f32_e32 v102, 0, v103
	v_mul_f32_e64 v103, |v103|, s66
	v_exp_f32_e32 v103, v103
	s_nop 0
	v_add_f32_e32 v103, 1.0, v103
	v_log_f32_e32 v103, v103
	s_nop 0
	v_fmac_f32_e32 v102, 0xbf317218, v103
	v_min_f32_e32 v103, 0, v104
	v_mul_f32_e64 v104, |v104|, s66
	v_exp_f32_e32 v104, v104
	s_nop 0
	v_add_f32_e32 v104, 1.0, v104
	v_log_f32_e32 v104, v104
	s_nop 0
	v_fmac_f32_e32 v103, 0xbf317218, v104
	v_min_f32_e32 v104, 0, v106
	v_mul_f32_e64 v106, |v106|, s66
	v_exp_f32_e32 v106, v106
	s_nop 0
	v_add_f32_e32 v106, 1.0, v106
	v_log_f32_e32 v106, v106
	s_nop 0
	v_fmac_f32_e32 v104, 0xbf317218, v106
	s_waitcnt lgkmcnt(1)
	v_mfma_f32_16x16x4_f32 v[106:109], v244, v223, 0
	v_mfma_f32_16x16x4_f32 v[106:109], v245, v224, v[106:109]
	ds_read2st64_b32 v[244:245], v105 offset0:10 offset1:11
	s_nop 0
	s_waitcnt lgkmcnt(1)
	v_mfma_f32_16x16x4_f32 v[106:109], v236, v225, v[106:109]
	v_mfma_f32_16x16x4_f32 v[106:109], v237, v226, v[106:109]
	ds_read2st64_b32 v[236:237], v105 offset0:12 offset1:13
	v_mfma_f32_16x16x4_f32 v[140:143], v144, v223, 0
	s_nop 8
	v_add_f32_e32 v135, v227, v106
	v_min_f32_e32 v106, 0, v135
	v_mul_f32_e64 v135, |v135|, s66
	v_exp_f32_e32 v135, v135
	s_nop 0
	v_add_f32_e32 v135, 1.0, v135
	v_log_f32_e32 v135, v135
	v_mfma_f32_16x16x4_f32 v[140:143], v145, v224, v[140:143]
	s_nop 0
	v_fmac_f32_e32 v106, 0xbf317218, v135
	v_add_f32_e32 v135, v227, v107
	v_min_f32_e32 v107, 0, v135
	v_mul_f32_e64 v135, |v135|, s66
	v_exp_f32_e32 v135, v135
	s_waitcnt lgkmcnt(1)
	v_mfma_f32_16x16x4_f32 v[140:143], v244, v225, v[140:143]
	v_add_f32_e32 v135, 1.0, v135
	v_log_f32_e32 v135, v135
	s_nop 0
	v_fmac_f32_e32 v107, 0xbf317218, v135
	v_add_f32_e32 v135, v227, v108
	v_min_f32_e32 v108, 0, v135
	v_mul_f32_e64 v135, |v135|, s66
	v_exp_f32_e32 v135, v135
	v_mfma_f32_16x16x4_f32 v[140:143], v245, v226, v[140:143]
	ds_read2st64_b32 v[244:245], v105 offset0:14 offset1:15
	s_nop 0
	v_add_f32_e32 v135, 1.0, v135
	v_log_f32_e32 v135, v135
	s_nop 0
	v_fmac_f32_e32 v108, 0xbf317218, v135
	v_add_f32_e32 v135, v227, v109
	v_min_f32_e32 v109, 0, v135
	v_mul_f32_e64 v135, |v135|, s66
	v_exp_f32_e32 v135, v135
	s_nop 0
	v_add_f32_e32 v135, 1.0, v135
	v_log_f32_e32 v135, v135
	s_nop 0
	v_fmac_f32_e32 v109, 0xbf317218, v135
	v_add_f32_e32 v135, v227, v140
	v_min_f32_e32 v137, 0, v135
	v_mul_f32_e64 v135, |v135|, s66
	v_exp_f32_e32 v135, v135
	s_nop 0
	v_add_f32_e32 v135, 1.0, v135
	v_log_f32_e32 v135, v135
	s_nop 0
	v_fmac_f32_e32 v137, 0xbf317218, v135
	v_add_f32_e32 v135, v227, v141
	v_min_f32_e32 v146, 0, v135
	v_mul_f32_e64 v135, |v135|, s66
	v_exp_f32_e32 v135, v135
	s_nop 0
	v_add_f32_e32 v135, 1.0, v135
	v_log_f32_e32 v135, v135
	s_nop 0
	v_fmac_f32_e32 v146, 0xbf317218, v135
	v_add_f32_e32 v135, v227, v142
	v_min_f32_e32 v147, 0, v135
	v_mul_f32_e64 v135, |v135|, s66
	v_exp_f32_e32 v135, v135
	s_nop 0
	v_add_f32_e32 v135, 1.0, v135
	v_log_f32_e32 v135, v135
	s_nop 0
	v_fmac_f32_e32 v147, 0xbf317218, v135
	v_add_f32_e32 v135, v227, v143
	s_waitcnt lgkmcnt(1)
	v_mfma_f32_16x16x4_f32 v[140:143], v236, v223, 0
	v_min_f32_e32 v148, 0, v135
	v_mul_f32_e64 v135, |v135|, s66
	v_exp_f32_e32 v135, v135
	s_nop 0
	v_add_f32_e32 v135, 1.0, v135
	v_mfma_f32_16x16x4_f32 v[140:143], v237, v224, v[140:143]
	s_nop 0
	v_log_f32_e32 v135, v135
	s_nop 0
	v_fmac_f32_e32 v148, 0xbf317218, v135
	s_waitcnt lgkmcnt(0)
	v_mfma_f32_16x16x4_f32 v[140:143], v244, v225, v[140:143]
	v_mfma_f32_16x16x4_f32 v[140:143], v245, v226, v[140:143]
	s_nop 9
	v_add_f32_e32 v105, v227, v140
	v_min_f32_e32 v135, 0, v105
	v_mul_f32_e64 v105, |v105|, s66
	v_exp_f32_e32 v105, v105
	s_nop 0
	v_add_f32_e32 v105, 1.0, v105
	v_log_f32_e32 v105, v105
	s_nop 0
	v_fmac_f32_e32 v135, 0xbf317218, v105
	v_add_f32_e32 v105, v227, v141
	v_min_f32_e32 v140, 0, v105
	v_mul_f32_e64 v105, |v105|, s66
	v_exp_f32_e32 v105, v105
	s_nop 0
	v_add_f32_e32 v105, 1.0, v105
	v_log_f32_e32 v105, v105
	s_nop 0
	v_fmac_f32_e32 v140, 0xbf317218, v105
	v_add_f32_e32 v105, v227, v142
	v_min_f32_e32 v141, 0, v105
	v_mul_f32_e64 v105, |v105|, s66
	v_exp_f32_e32 v105, v105
	s_nop 0
	v_add_f32_e32 v105, 1.0, v105
	v_log_f32_e32 v105, v105
	s_nop 0
	v_fmac_f32_e32 v141, 0xbf317218, v105
	v_add_f32_e32 v105, v227, v143
	v_min_f32_e32 v142, 0, v105
	v_mul_f32_e64 v105, |v105|, s66
	v_exp_f32_e32 v105, v105
	s_nop 0
	v_add_f32_e32 v105, 1.0, v105
	v_log_f32_e32 v105, v105
	s_nop 0
	v_fmac_f32_e32 v142, 0xbf317218, v105
	v_fma_f32 v105, v142, s67, 0
	v_fmamk_f32 v141, v141, 0x3d800000, v105
	v_fmamk_f32 v140, v140, 0x3d800000, v141
	v_fmamk_f32 v135, v135, 0x3d800000, v140
	v_fmamk_f32 v142, v148, 0x3d800000, v135
	v_fmamk_f32 v143, v147, 0x3d800000, v142
	v_fmamk_f32 v144, v146, 0x3d800000, v143
	v_fmamk_f32 v137, v137, 0x3d800000, v144
	v_fmamk_f32 v109, v109, 0x3d800000, v137
	v_fmamk_f32 v108, v108, 0x3d800000, v109
	v_fmamk_f32 v107, v107, 0x3d800000, v108
	v_fmamk_f32 v106, v106, 0x3d800000, v107
	v_fmamk_f32 v104, v104, 0x3d800000, v106
	v_fmamk_f32 v103, v103, 0x3d800000, v104
	v_fmamk_f32 v102, v102, 0x3d800000, v103
	v_fmamk_f32 v0, v0, 0x3d800000, v102
	ds_bpermute_b32 v146, v192, v0
	ds_bpermute_b32 v147, v193, v0
	ds_bpermute_b32 v145, v191, v0
	s_waitcnt lgkmcnt(2)
	v_cndmask_b32_e64 v146, 0, v146, s[28:29]
	s_waitcnt lgkmcnt(1)
	v_cndmask_b32_e64 v147, v147, 0, s[8:9]
	v_add_f32_e32 v146, v146, v147
	s_waitcnt lgkmcnt(0)
	v_cndmask_b32_e64 v145, 0, v145, s[4:5]
	v_add_f32_e32 v145, v145, v146
	v_add_f32_e32 v0, v145, v0
	v_add_f32_e32 v102, v145, v102
	ds_write2st64_b32 v204, v0, v102 offset0:24 offset1:26
	v_add_f32_e32 v0, v145, v103
	v_add_f32_e32 v102, v145, v104
	ds_write2st64_b32 v204, v0, v102 offset0:28 offset1:30
	v_add_f32_e32 v0, v145, v106
	v_add_f32_e32 v102, v145, v107
	ds_write2st64_b32 v204, v0, v102 offset0:32 offset1:34
	v_add_f32_e32 v0, v145, v108
	v_add_f32_e32 v102, v145, v109
	ds_write2st64_b32 v204, v0, v102 offset0:36 offset1:38
	v_add_f32_e32 v0, v145, v137
	v_add_f32_e32 v102, v145, v144
	ds_write2st64_b32 v204, v0, v102 offset0:40 offset1:42
	v_add_f32_e32 v0, v145, v143
	v_add_f32_e32 v102, v145, v142
	ds_write2st64_b32 v204, v0, v102 offset0:44 offset1:46
	v_add_f32_e32 v0, v145, v135
	v_add_f32_e32 v102, v145, v140
	ds_write2st64_b32 v204, v0, v102 offset0:48 offset1:50
	v_add_f32_e32 v0, v145, v141
	v_add_f32_e32 v102, v145, v105
	ds_write2st64_b32 v204, v0, v102 offset0:52 offset1:54
	s_waitcnt lgkmcnt(0)
	s_barrier
	s_and_saveexec_b64 s[62:63], s[10:11]
	s_cbranch_execz .LBB0_2285
	ds_read_b32 v0, v181 offset:6144
	v_lshl_add_u32 v102, s68, 9, v181
	s_waitcnt lgkmcnt(0)
	v_mul_f32_e32 v255, 0x3fb8aa3b, v0
	v_exp_f32_e32 v255, v255
	s_nop 0
	ds_write_b32 v102, v255 offset:4096

.LBB0_2292:
	ds_read_b128 v[102:105], v205 offset:6144
	ds_read_b128 v[106:109], v205 offset:6160
	s_waitcnt vmcnt(6)
	v_lshlrev_b32_e32 v142, 16, v98
	v_and_b32_e32 v143, 0xffff0000, v98
	s_waitcnt lgkmcnt(1)
	v_mul_f32_e32 v0, 0xbfb8aa3b, v102
	v_exp_f32_e32 v140, v0
	v_mul_f32_e32 v0, 0xbfb8aa3b, v103
	v_exp_f32_e32 v141, v0
	v_mul_f32_e32 v0, 0xbfb8aa3b, v104
	v_pk_mul_f32 v[140:141], v[140:141], v[142:143]
	s_nop 0
	v_cvt_pk_bf16_f32 v98, v140, v141
	v_exp_f32_e32 v140, v0
	v_mul_f32_e32 v0, 0xbfb8aa3b, v105
	v_exp_f32_e32 v141, v0
	v_lshlrev_b32_e32 v142, 16, v99
	v_and_b32_e32 v143, 0xffff0000, v99
	s_waitcnt lgkmcnt(0)
	v_mul_f32_e32 v0, 0xbfb8aa3b, v106
	v_pk_mul_f32 v[140:141], v[140:141], v[142:143]
	v_lshlrev_b32_e32 v142, 16, v100
	v_cvt_pk_bf16_f32 v99, v140, v141
	v_exp_f32_e32 v140, v0
	v_mul_f32_e32 v0, 0xbfb8aa3b, v107
	v_exp_f32_e32 v141, v0
	v_and_b32_e32 v143, 0xffff0000, v100
	v_mul_f32_e32 v0, 0xbfb8aa3b, v108
	v_pk_mul_f32 v[140:141], v[140:141], v[142:143]
	s_nop 0
	v_cvt_pk_bf16_f32 v100, v140, v141
	v_exp_f32_e32 v140, v0
	v_mul_f32_e32 v0, 0xbfb8aa3b, v109
	v_exp_f32_e32 v141, v0
	v_lshlrev_b32_e32 v142, 16, v101
	v_and_b32_e32 v143, 0xffff0000, v101
	v_mul_f32_e32 v0, 0x3fb8aa3b, v102
	v_pk_mul_f32 v[140:141], v[140:141], v[142:143]
	s_nop 0
	v_cvt_pk_bf16_f32 v101, v140, v141
	ds_write_b128 v184, v[98:101] offset:56320
	v_exp_f32_e32 v98, v0
	v_mul_f32_e32 v0, 0x3fb8aa3b, v103
	v_exp_f32_e32 v99, v0
	v_lshlrev_b32_e32 v100, 16, v94
	v_and_b32_e32 v101, 0xffff0000, v94
	v_mul_f32_e32 v0, 0x3fb8aa3b, v104
	v_pk_mul_f32 v[98:99], v[98:99], s[48:49] op_sel_hi:[1,0]
	s_waitcnt vmcnt(4)
	v_lshlrev_b32_e32 v104, 16, v90
	v_pk_mul_f32 v[98:99], v[98:99], v[100:101]
	v_lshlrev_b32_e32 v100, 16, v95
	v_cvt_pk_bf16_f32 v94, v98, v99
	v_exp_f32_e32 v98, v0
	v_mul_f32_e32 v0, 0x3fb8aa3b, v105
	v_exp_f32_e32 v99, v0
	v_and_b32_e32 v101, 0xffff0000, v95
	v_mul_f32_e32 v0, 0x3fb8aa3b, v106
	v_and_b32_e32 v105, 0xffff0000, v90
	v_pk_mul_f32 v[98:99], v[98:99], s[48:49] op_sel_hi:[1,0]
	s_nop 0
	v_pk_mul_f32 v[98:99], v[98:99], v[100:101]
	v_lshlrev_b32_e32 v100, 16, v96
	v_cvt_pk_bf16_f32 v95, v98, v99
	v_exp_f32_e32 v98, v0
	v_mul_f32_e32 v0, 0x3fb8aa3b, v107
	v_exp_f32_e32 v99, v0
	v_and_b32_e32 v101, 0xffff0000, v96
	v_mul_f32_e32 v0, 0x3fb8aa3b, v108
	v_pk_mul_f32 v[98:99], v[98:99], s[48:49] op_sel_hi:[1,0]
	s_nop 0
	v_pk_mul_f32 v[98:99], v[98:99], v[100:101]
	v_lshlrev_b32_e32 v100, 16, v97
	v_cvt_pk_bf16_f32 v96, v98, v99
	v_exp_f32_e32 v98, v0
	v_mul_f32_e32 v0, 0x3fb8aa3b, v109
	v_exp_f32_e32 v99, v0
	v_and_b32_e32 v101, 0xffff0000, v97
	v_pk_mul_f32 v[98:99], v[98:99], s[48:49] op_sel_hi:[1,0]
	s_nop 0
	v_pk_mul_f32 v[98:99], v[98:99], v[100:101]
	s_nop 0
	v_cvt_pk_bf16_f32 v97, v98, v99
	ds_write_b128 v184, v[94:97] offset:38912
	ds_read_b128 v[94:97], v206 offset:6144
	ds_read_b128 v[98:101], v206 offset:6160
	s_waitcnt lgkmcnt(1)
	v_mul_f32_e32 v0, 0xbfb8aa3b, v94
	v_exp_f32_e32 v102, v0
	v_mul_f32_e32 v0, 0xbfb8aa3b, v95
	v_exp_f32_e32 v103, v0
	v_mul_f32_e32 v0, 0xbfb8aa3b, v96
	v_pk_mul_f32 v[102:103], v[102:103], v[104:105]
	s_nop 0
	v_cvt_pk_bf16_f32 v90, v102, v103
	v_exp_f32_e32 v102, v0
	v_mul_f32_e32 v0, 0xbfb8aa3b, v97
	v_exp_f32_e32 v103, v0
	v_lshlrev_b32_e32 v104, 16, v91
	v_and_b32_e32 v105, 0xffff0000, v91
	s_waitcnt lgkmcnt(0)
	v_mul_f32_e32 v0, 0xbfb8aa3b, v98
	v_pk_mul_f32 v[102:103], v[102:103], v[104:105]
	v_lshlrev_b32_e32 v104, 16, v92
	v_cvt_pk_bf16_f32 v91, v102, v103
	v_exp_f32_e32 v102, v0
	v_mul_f32_e32 v0, 0xbfb8aa3b, v99
	v_exp_f32_e32 v103, v0
	v_and_b32_e32 v105, 0xffff0000, v92
	v_mul_f32_e32 v0, 0xbfb8aa3b, v100
	v_pk_mul_f32 v[102:103], v[102:103], v[104:105]
	s_nop 0
	v_cvt_pk_bf16_f32 v92, v102, v103
	v_exp_f32_e32 v102, v0
	v_mul_f32_e32 v0, 0xbfb8aa3b, v101
	v_exp_f32_e32 v103, v0
	v_lshlrev_b32_e32 v104, 16, v93
	v_and_b32_e32 v105, 0xffff0000, v93
	v_mul_f32_e32 v0, 0x3fb8aa3b, v94
	v_pk_mul_f32 v[102:103], v[102:103], v[104:105]
	s_nop 0
	v_cvt_pk_bf16_f32 v93, v102, v103
	ds_write_b128 v185, v[90:93] offset:56320
	v_exp_f32_e32 v90, v0
	v_mul_f32_e32 v0, 0x3fb8aa3b, v95
	v_exp_f32_e32 v91, v0
	v_lshlrev_b32_e32 v92, 16, v70
	v_and_b32_e32 v93, 0xffff0000, v70
	v_mul_f32_e32 v0, 0x3fb8aa3b, v96
	v_pk_mul_f32 v[90:91], v[90:91], s[48:49] op_sel_hi:[1,0]
	s_nop 0
	v_pk_mul_f32 v[90:91], v[90:91], v[92:93]
	v_lshlrev_b32_e32 v92, 16, v71
	v_cvt_pk_bf16_f32 v70, v90, v91
	v_exp_f32_e32 v90, v0
	v_mul_f32_e32 v0, 0x3fb8aa3b, v97
	v_exp_f32_e32 v91, v0
	v_and_b32_e32 v93, 0xffff0000, v71
	v_mul_f32_e32 v0, 0x3fb8aa3b, v98
	v_pk_mul_f32 v[90:91], v[90:91], s[48:49] op_sel_hi:[1,0]
	s_nop 0
	v_pk_mul_f32 v[90:91], v[90:91], v[92:93]
	v_lshlrev_b32_e32 v92, 16, v72
	v_cvt_pk_bf16_f32 v71, v90, v91
	v_exp_f32_e32 v90, v0
	v_mul_f32_e32 v0, 0x3fb8aa3b, v99
	v_exp_f32_e32 v91, v0
	v_and_b32_e32 v93, 0xffff0000, v72
	v_mul_f32_e32 v0, 0x3fb8aa3b, v100
	v_pk_mul_f32 v[90:91], v[90:91], s[48:49] op_sel_hi:[1,0]
	s_nop 0
	v_pk_mul_f32 v[90:91], v[90:91], v[92:93]
	v_lshlrev_b32_e32 v92, 16, v73
	v_cvt_pk_bf16_f32 v72, v90, v91
	v_exp_f32_e32 v90, v0
	v_mul_f32_e32 v0, 0x3fb8aa3b, v101
	v_exp_f32_e32 v91, v0
	v_and_b32_e32 v93, 0xffff0000, v73
	v_pk_mul_f32 v[90:91], v[90:91], s[48:49] op_sel_hi:[1,0]
	s_nop 0
	v_pk_mul_f32 v[90:91], v[90:91], v[92:93]
	s_nop 0
	v_cvt_pk_bf16_f32 v73, v90, v91
	ds_write_b128 v185, v[70:73] offset:38912
	s_waitcnt vmcnt(3)
	ds_write_b128 v207, v[74:77]
	s_waitcnt vmcnt(2)
	ds_write_b128 v208, v[78:81]
	s_waitcnt vmcnt(1)
	ds_write_b128 v207, v[82:85] offset:16896
	s_waitcnt vmcnt(0)
	ds_write_b128 v209, v[86:89]
	v_lshl_add_u64 v[70:71], s[56:57], 0, v[118:119]
	v_lshl_add_u64 v[72:73], s[56:57], 0, v[122:123]
	v_lshl_add_u64 v[74:75], s[56:57], 0, v[124:125]
	global_load_dwordx2 v[160:161], v[70:71], off
	global_load_dwordx2 v[158:159], v[70:71], off offset:32
	global_load_dwordx2 v[152:153], v[72:73], off
	global_load_dwordx2 v[150:151], v[74:75], off
	v_lshl_add_u64 v[70:71], s[56:57], 0, v[126:127]
	v_lshl_add_u64 v[72:73], s[56:57], 0, v[128:129]
	v_lshl_add_u64 v[74:75], s[56:57], 0, v[130:131]
	v_lshl_add_u64 v[76:77], s[56:57], 0, v[132:133]
	global_load_dwordx2 v[148:149], v[70:71], off
	global_load_dwordx2 v[146:147], v[72:73], off
	global_load_dwordx2 v[142:143], v[74:75], off
	global_load_dwordx2 v[140:141], v[76:77], off
	s_waitcnt lgkmcnt(0)
	s_barrier
	s_waitcnt lgkmcnt(0)
	ds_read_b128 v[70:73], v210 offset:56320
	ds_read_b128 v[236:239], v183 offset:38912
	ds_read_b128 v[244:247], v210 offset:56384
	ds_read_b128 v[82:85], v183 offset:38976
	s_waitcnt lgkmcnt(2)
	v_mfma_f32_16x16x32_bf16 v[70:73], v[70:73], v[236:239], 0
	v_mov_b32_e32 v0, s93
	v_cvt_pk_bf16_f32 v170, v62, v63
	v_cvt_pk_bf16_f32 v171, v64, v65
	s_waitcnt lgkmcnt(0)
	v_mfma_f32_16x16x32_bf16 v[70:73], v[244:247], v[82:85], v[70:73]
	ds_read_b128 v[244:247], v210 offset:56448
	ds_read_b128 v[86:89], v183 offset:39040
	ds_read_b128 v[78:81], v210 offset:56512
	ds_read_b128 v[90:93], v183 offset:39104
	v_cvt_pk_bf16_f32 v172, v66, v67
	v_cvt_pk_bf16_f32 v173, v68, v69
	s_waitcnt lgkmcnt(2)
	v_mfma_f32_16x16x32_bf16 v[70:73], v[244:247], v[86:89], v[70:73]
	s_nop 0
	s_nop 0
	s_add_u32 s49, s49, s0
	s_addc_u32 s53, s69, 0
	s_waitcnt lgkmcnt(0)
	v_mfma_f32_16x16x32_bf16 v[70:73], v[78:81], v[90:93], v[70:73]
	s_add_u32 s60, s49, 0xafc1000
	s_addc_u32 s61, s53, 0
	s_waitcnt vmcnt(7)
	v_lshlrev_b32_e32 v228, 16, v160
	s_nop 3
	v_cndmask_b32_e64 v0, v70, v0, s[14:15]
	v_cndmask_b32_e64 v70, v71, 0, s[30:31]
	v_cndmask_b32_e64 v71, v72, 0, s[34:35]
	v_cndmask_b32_e64 v72, v73, 0, s[36:37]
	v_cvt_pk_bf16_f32 v70, v0, v70
	v_cvt_pk_bf16_f32 v71, v71, v72
	ds_write_b64 v211, v[70:71]
	ds_read_b128 v[244:247], v212 offset:56320
	s_waitcnt lgkmcnt(0)
	v_mfma_f32_16x16x32_bf16 v[70:73], v[244:247], v[236:239], 0
	ds_read_b128 v[236:239], v212 offset:56384
	ds_read_b128 v[244:247], v212 offset:56448
	ds_read_b128 v[74:77], v212 offset:56512
	v_mov_b32_e32 v0, s93
	v_and_b32_e32 v229, 0xffff0000, v160
	s_waitcnt lgkmcnt(2)
	v_mfma_f32_16x16x32_bf16 v[70:73], v[236:239], v[82:85], v[70:73]
	s_nop 0
	v_lshlrev_b32_e32 v160, 16, v161
	v_and_b32_e32 v161, 0xffff0000, v161
	s_waitcnt lgkmcnt(1)
	v_mfma_f32_16x16x32_bf16 v[70:73], v[244:247], v[86:89], v[70:73]
	s_nop 0
	s_waitcnt vmcnt(6)
	v_lshlrev_b32_e32 v230, 16, v158
	v_and_b32_e32 v231, 0xffff0000, v158
	s_waitcnt lgkmcnt(0)
	v_mfma_f32_16x16x32_bf16 v[70:73], v[74:77], v[90:93], v[70:73]
	v_lshlrev_b32_e32 v158, 16, v159
	v_and_b32_e32 v159, 0xffff0000, v159
	s_nop 5
	v_cndmask_b32_e64 v0, v70, v0, s[22:23]
	v_cndmask_b32_e64 v70, v71, 0, s[38:39]
	v_cndmask_b32_e64 v71, v72, 0, s[40:41]
	v_cndmask_b32_e64 v72, v73, 0, s[42:43]
	v_cvt_pk_bf16_f32 v70, v0, v70
	v_cvt_pk_bf16_f32 v71, v71, v72
	ds_write_b64 v213, v[70:71]
	s_waitcnt lgkmcnt(0)
	s_barrier
	s_waitcnt lgkmcnt(0)
	ds_read_b64_tr_b16 v[72:73], v214 offset:2112
	ds_read_b64_tr_b16 v[70:71], v214
	ds_read_b64_tr_b16 v[236:237], v214 offset:32
	ds_read_b64_tr_b16 v[244:245], v214 offset:16896
	ds_read_b64_tr_b16 v[246:247], v214 offset:19008
	ds_read_b64_tr_b16 v[238:239], v214 offset:2144
	ds_read_b64_tr_b16 v[82:83], v214 offset:16928
	ds_read_b64_tr_b16 v[84:85], v214 offset:19040
	ds_read_b128 v[86:89], v215
	ds_read_b128 v[94:97], v215 offset:64
	ds_read_b128 v[102:105], v215 offset:2368
	ds_read_b128 v[162:165], v215 offset:4672
	s_waitcnt lgkmcnt(3)
	v_mfma_f32_16x16x32_bf16 v[90:93], v[70:73], v[86:89], 0
	s_nop 0
	v_mfma_f32_16x16x32_bf16 v[86:89], v[236:239], v[86:89], 0
	s_waitcnt lgkmcnt(2)
	v_mfma_f32_16x16x32_bf16 v[90:93], v[244:247], v[94:97], v[90:93]
	v_mfma_f32_16x16x32_bf16 v[86:89], v[82:85], v[94:97], v[86:89]
	ds_read_b128 v[94:97], v215 offset:2304
	s_waitcnt lgkmcnt(0)
	v_mfma_f32_16x16x32_bf16 v[98:101], v[70:73], v[94:97], 0
	v_mfma_f32_16x16x32_bf16 v[94:97], v[236:239], v[94:97], 0
	v_mfma_f32_16x16x32_bf16 v[98:101], v[244:247], v[102:105], v[98:101]
	v_mfma_f32_16x16x32_bf16 v[94:97], v[82:85], v[102:105], v[94:97]
	ds_read_b128 v[102:105], v215 offset:4608
	s_waitcnt lgkmcnt(0)
	v_mfma_f32_16x16x32_bf16 v[106:109], v[70:73], v[102:105], 0
	v_mfma_f32_16x16x32_bf16 v[102:105], v[236:239], v[102:105], 0
	v_mfma_f32_16x16x32_bf16 v[106:109], v[244:247], v[162:165], v[106:109]
	v_mfma_f32_16x16x32_bf16 v[102:105], v[82:85], v[162:165], v[102:105]
	ds_read_b128 v[162:165], v215 offset:6912
	s_waitcnt lgkmcnt(0)
	v_mfma_f32_16x16x32_bf16 v[70:73], v[70:73], v[162:165], 0
	v_mfma_f32_16x16x32_bf16 v[74:77], v[236:239], v[162:165], 0
	ds_read_b128 v[236:239], v215 offset:6976
	s_waitcnt lgkmcnt(0)
	v_mfma_f32_16x16x32_bf16 v[70:73], v[244:247], v[236:239], v[70:73]
	ds_read2_b64 v[244:247], v219 offset1:4
	v_cvt_pk_bf16_f32 v78, v30, v31
	v_cvt_pk_bf16_f32 v79, v32, v33
	v_cvt_pk_bf16_f32 v80, v10, v11
	v_mfma_f32_16x16x32_bf16 v[74:77], v[82:85], v[236:239], v[74:77]
	ds_read2_b64 v[236:239], v220 offset0:32 offset1:36
	v_cvt_pk_bf16_f32 v81, v12, v13
	v_cvt_pk_bf16_f32 v82, v6, v7
	v_cvt_pk_bf16_f32 v83, v8, v9
	v_cvt_pk_bf16_f32 v84, v18, v19
	v_cvt_pk_bf16_f32 v85, v20, v21
	s_nop 0
	s_waitcnt lgkmcnt(1)
	v_mfma_f32_16x16x32_bf16 v[90:93], v[78:81], v[244:247], v[90:93]
	v_mfma_f32_16x16x32_bf16 v[86:89], v[82:85], v[244:247], v[86:89]
	ds_read2_b64 v[244:247], v221 offset0:64 offset1:68
	s_nop 0
	s_waitcnt lgkmcnt(1)
	v_mfma_f32_16x16x32_bf16 v[98:101], v[78:81], v[236:239], v[98:101]
	v_mfma_f32_16x16x32_bf16 v[94:97], v[82:85], v[236:239], v[94:97]
	ds_read2_b64 v[236:239], v222 offset0:96 offset1:100
	s_nop 0
	s_waitcnt lgkmcnt(1)
	v_mfma_f32_16x16x32_bf16 v[106:109], v[78:81], v[244:247], v[106:109]
	v_mfma_f32_16x16x32_bf16 v[102:105], v[82:85], v[244:247], v[102:105]
	ds_read2_b64 v[244:247], v219 offset0:8 offset1:12
	s_nop 0
	s_waitcnt lgkmcnt(1)
	v_mfma_f32_16x16x32_bf16 v[70:73], v[78:81], v[236:239], v[70:73]
	v_cvt_pk_bf16_f32 v78, v14, v15
	v_cvt_pk_bf16_f32 v79, v16, v17
	v_cvt_pk_bf16_f32 v80, v38, v39
	v_mfma_f32_16x16x32_bf16 v[74:77], v[82:85], v[236:239], v[74:77]
	ds_read2_b64 v[236:239], v220 offset0:40 offset1:44
	v_cvt_pk_bf16_f32 v81, v40, v41
	v_cvt_pk_bf16_f32 v82, v26, v27
	v_cvt_pk_bf16_f32 v83, v28, v29
	v_cvt_pk_bf16_f32 v84, v50, v51
	v_cvt_pk_bf16_f32 v85, v52, v53
	s_nop 0
	s_waitcnt lgkmcnt(1)
	v_mfma_f32_16x16x32_bf16 v[90:93], v[78:81], v[244:247], v[90:93]
	v_mfma_f32_16x16x32_bf16 v[86:89], v[82:85], v[244:247], v[86:89]
	ds_read2_b64 v[244:247], v221 offset0:72 offset1:76
	s_nop 0
	s_waitcnt lgkmcnt(1)
	v_mfma_f32_16x16x32_bf16 v[98:101], v[78:81], v[236:239], v[98:101]
	v_mfma_f32_16x16x32_bf16 v[94:97], v[82:85], v[236:239], v[94:97]
	ds_read2_b64 v[236:239], v222 offset0:104 offset1:108
	s_nop 0
	s_waitcnt lgkmcnt(1)
	v_mfma_f32_16x16x32_bf16 v[106:109], v[78:81], v[244:247], v[106:109]
	v_mfma_f32_16x16x32_bf16 v[102:105], v[82:85], v[244:247], v[102:105]
	ds_read2_b64 v[244:247], v219 offset0:16 offset1:20
	s_nop 0
	s_waitcnt lgkmcnt(1)
	v_mfma_f32_16x16x32_bf16 v[70:73], v[78:81], v[236:239], v[70:73]
	v_cvt_pk_bf16_f32 v78, v22, v23
	v_cvt_pk_bf16_f32 v79, v24, v25
	v_cvt_pk_bf16_f32 v80, v42, v43
	v_mfma_f32_16x16x32_bf16 v[74:77], v[82:85], v[236:239], v[74:77]
	ds_read2_b64 v[236:239], v220 offset0:48 offset1:52
	v_cvt_pk_bf16_f32 v81, v44, v45
	v_cvt_pk_bf16_f32 v82, v34, v35
	v_cvt_pk_bf16_f32 v83, v36, v37
	v_cvt_pk_bf16_f32 v84, v54, v55
	v_cvt_pk_bf16_f32 v85, v56, v57
	s_nop 0
	s_waitcnt lgkmcnt(1)
	v_mfma_f32_16x16x32_bf16 v[90:93], v[78:81], v[244:247], v[90:93]
	v_mfma_f32_16x16x32_bf16 v[86:89], v[82:85], v[244:247], v[86:89]
	ds_read2_b64 v[244:247], v221 offset0:80 offset1:84
	s_nop 0
	s_waitcnt lgkmcnt(1)
	v_mfma_f32_16x16x32_bf16 v[98:101], v[78:81], v[236:239], v[98:101]
	v_mfma_f32_16x16x32_bf16 v[94:97], v[82:85], v[236:239], v[94:97]
	ds_read2_b64 v[236:239], v222 offset0:112 offset1:116
	s_nop 0
	s_waitcnt lgkmcnt(1)
	v_mfma_f32_16x16x32_bf16 v[166:169], v[78:81], v[244:247], v[106:109]
	v_mfma_f32_16x16x32_bf16 v[162:165], v[82:85], v[244:247], v[102:105]
	ds_read2_b64 v[244:247], v219 offset0:24 offset1:28
	s_nop 2
	s_nop 0
	s_waitcnt lgkmcnt(1)
	v_mfma_f32_16x16x32_bf16 v[70:73], v[78:81], v[236:239], v[70:73]
	v_cvt_pk_bf16_f32 v78, v46, v47
	v_cvt_pk_bf16_f32 v79, v48, v49
	v_cvt_pk_bf16_f32 v80, v58, v59
	v_mfma_f32_16x16x32_bf16 v[74:77], v[82:85], v[236:239], v[74:77]
	ds_read2_b64 v[236:239], v220 offset0:56 offset1:60
	v_cvt_pk_bf16_f32 v81, v60, v61
	s_nop 0
	s_waitcnt lgkmcnt(1)
	v_mfma_f32_16x16x32_bf16 v[106:109], v[78:81], v[244:247], v[90:93]
	v_mfma_f32_16x16x32_bf16 v[102:105], v[170:173], v[244:247], v[86:89]
	ds_read2_b64 v[244:247], v221 offset0:88 offset1:92
	s_nop 0
	s_nop 5
	v_pk_add_f32 v[106:107], v[106:107], v[228:229]
	v_pk_add_f32 v[108:109], v[108:109], v[160:161]
	s_waitcnt lgkmcnt(1)
	v_mfma_f32_16x16x32_bf16 v[98:101], v[78:81], v[236:239], v[98:101]
	v_mul_f32_e64 v160, v106, v106
	v_mul_f32_e64 v161, v107, v107
	v_pk_mul_f32 v[228:229], v[108:109], v[108:109]
	v_add_f32_e32 v0, v160, v161
	v_mfma_f32_16x16x32_bf16 v[94:97], v[170:173], v[236:239], v[94:97]
	ds_read2_b64 v[236:239], v222 offset0:120 offset1:124
	s_nop 0
	v_pk_add_f32 v[102:103], v[102:103], v[230:231]
	v_add_f32_e32 v0, v228, v0
	s_waitcnt lgkmcnt(1)
	v_mfma_f32_16x16x32_bf16 v[86:89], v[170:173], v[244:247], v[162:165]
	v_add_f32_e64 v104, v104, v158
	v_add_f32_e64 v105, v105, v159
	s_nop 0
	s_nop 0
	v_pk_mul_f32 v[158:159], v[102:103], v[102:103]
	v_mfma_f32_16x16x32_bf16 v[90:93], v[78:81], v[244:247], v[166:169]
	v_add_f32_e32 v0, v229, v0
	v_add_f32_e32 v0, v158, v0
	v_pk_mul_f32 v[230:231], v[104:105], v[104:105]
	s_waitcnt lgkmcnt(0)
	v_mfma_f32_16x16x32_bf16 v[82:85], v[78:81], v[236:239], v[70:73]
	v_add_f32_e32 v0, v159, v0
	v_add_f32_e32 v0, v230, v0
	v_add_f32_e32 v0, v231, v0
	v_lshl_add_u64 v[70:71], s[60:61], 0, v[120:121]
	v_add_co_u32_e32 v72, vcc, s81, v70
	v_mfma_f32_16x16x32_bf16 v[78:81], v[170:173], v[236:239], v[74:77]
	s_nop 0
	v_addc_co_u32_e32 v73, vcc, 0, v71, vcc
	global_load_dwordx2 v[172:173], v[70:71], off
	global_load_dwordx2 v[170:171], v[70:71], off offset:32
	global_load_dwordx2 v[168:169], v[72:73], off
	global_load_dwordx2 v[166:167], v[72:73], off offset:32
	v_add_co_u32_e32 v72, vcc, s72, v70
	v_mov_b32_e32 v135, v0
	s_nop 1
	v_permlane16_swap_b32_e32 v135, v0
	s_nop 0
	v_addc_co_u32_e32 v73, vcc, 0, v71, vcc
	v_add_co_u32_e32 v70, vcc, s73, v70
	global_load_dwordx2 v[164:165], v[72:73], off
	global_load_dwordx2 v[162:163], v[72:73], off offset:32
	v_addc_co_u32_e32 v71, vcc, 0, v71, vcc
	global_load_dwordx2 v[156:157], v[70:71], off
	global_load_dwordx2 v[144:145], v[70:71], off offset:32
	global_load_dwordx4 v[74:77], v[138:139], off
	s_nop 0
	global_load_dwordx4 v[70:73], v[138:139], off offset:64
	v_add_f32_e32 v0, v0, v135
	v_mov_b32_e32 v135, v0
	s_nop 1
	v_permlane32_swap_b32_e32 v135, v0
	s_and_saveexec_b64 s[60:61], s[4:5]
	s_waitcnt lgkmcnt(0)
	s_cbranch_execz .LBB0_2294
	s_waitcnt lgkmcnt(0)
	v_add_f32_e32 v0, v0, v135
	ds_write_b32 v189, v0
